# GEMM K-loops: one static s_setprio 1 for waves 4-7 for the duration of the K-loop (no per-segment flips)
# speedup vs baseline: 1.0119x; 1.0001x over previous
; #define G_LOAD(KT) do { _Pragma("unroll") for (int i = 0; i < 4; ++i) { ra[i] = *(const u32x4*)(Ag + (size_t)i * 64 * lda + (KT) * 64); rb[i] = *(const u32x4*)(Bg + (size_t)i * 64 * K + (KT) * 64); } } while (0)
; #define G_STORE(BUF) do { u16* ad = As + (BUF) * 256 * 64 + sto; u16* bd = Bs + (BUF) * 256 * 64 + sto; _Pragma("unroll") for (int i = 0; i < 4; ++i) { *(u32x4*)(ad + i * 64 * 64) = ra[i]; *(u32x4*)(bd + i * 64 * 64) = rb[i]; } } while (0)
; template <int EPI>
; DI void gemm_phase(const u16* __restrict__ A, int lda, const u16* __restrict__ Bt, int K, int N, u16* outb, int ldo,
;                    const float* r0, const float* r1, float* outf, char* lds, int bid, int nb) {
;     ...
;   for (int it = 0; it < nIter; ++it) {
;     int tm, tn;
;     if (swz) { const int st = xcd + 8 * it, sm = st / nSN, sn = st - sm * nSN; tm = sm * GM + jb / GN; tn = sn * GN + (jb % GN); }
;     else { const int t = bid + it * nb; tm = t / nN; tn = t - tm * nN; }
;     const u16* Ag = A + (size_t)(tm * 256 + lrow) * lda + lch * 8;
;     const u16* Bg = Bt + (size_t)(tn * 256 + lrow) * K + lch * 8;
;     f32x4 acc[8][4];
; #pragma unroll
;     for (int i = 0; i < 8; ++i)
; #pragma unroll
;       for (int j = 0; j < 4; ++j) acc[i][j] = (f32x4){0.f, 0.f, 0.f, 0.f};
;     u32x4 ra[4], rb[4];
;     ...
;     G_LOAD(0);
;     G_STORE(0);
;     __syncthreads();
.LBB0_287:
	s_lshl_b32 s56, s56, 8
	v_or_b32_e32 v0, s56, v138
	s_lshl_b32 s57, s57, 8
	v_ashrrev_i32_e32 v1, 31, v0
	v_or_b32_e32 v2, s57, v138
	v_ashrrev_i32_e32 v3, 31, v2
	v_lshlrev_b64 v[64:65], 11, v[0:1]
	v_lshl_add_u64 v[0:1], v[130:131], 0, v[64:65]
	v_lshlrev_b64 v[2:3], 11, v[2:3]
	v_lshl_add_u64 v[134:135], v[128:129], 0, v[2:3]
	v_add_co_u32_e32 v2, vcc, s19, v0
	s_nop 1
	v_readfirstlane_b32 s98, v0
	v_readfirstlane_b32 s99, v1
	s_nop 1
	v_readfirstlane_b32 s100, v134
	v_readfirstlane_b32 s101, v135
	v_addc_co_u32_e32 v3, vcc, 0, v1, vcc
	v_add_co_u32_e32 v4, vcc, s19, v134
	s_mov_b32 s62, 0
	s_nop 0
	v_addc_co_u32_e32 v5, vcc, 0, v135, vcc
	v_add_co_u32_e32 v2, vcc, s20, v0
	s_mov_b64 s[12:13], 0
	s_nop 0
	v_addc_co_u32_e32 v3, vcc, 0, v1, vcc
	v_add_co_u32_e32 v4, vcc, s20, v134
	v_lshl_add_u64 v[136:137], v[132:133], 0, v[64:65]
	s_nop 0
	v_addc_co_u32_e32 v5, vcc, 0, v135, vcc
	v_add_co_u32_e32 v0, vcc, s21, v0
	v_addc_co_u32_e32 v1, vcc, 0, v1, vcc
	v_add_co_u32_e32 v2, vcc, s21, v134
	s_nop 1
	v_addc_co_u32_e32 v3, vcc, 0, v135, vcc
	v_mov_b32_e32 v0, 0
	v_mov_b32_e32 v1, v0
	v_mov_b32_e32 v2, v0
	v_mov_b32_e32 v3, v0
	v_mov_b32_e32 v4, v0
	v_mov_b32_e32 v5, v0
	v_mov_b32_e32 v6, v0
	v_mov_b32_e32 v7, v0
	v_mov_b32_e32 v8, v0
	v_mov_b32_e32 v9, v0
	v_mov_b32_e32 v10, v0
	v_mov_b32_e32 v11, v0
	v_mov_b32_e32 v12, v0
	v_mov_b32_e32 v13, v0
	v_mov_b32_e32 v14, v0
	v_mov_b32_e32 v15, v0
	v_mov_b32_e32 v16, v0
	v_mov_b32_e32 v17, v0
	v_mov_b32_e32 v18, v0
	v_mov_b32_e32 v19, v0
	v_mov_b32_e32 v20, v0
	v_mov_b32_e32 v21, v0
	v_mov_b32_e32 v22, v0
	v_mov_b32_e32 v23, v0
	v_mov_b32_e32 v24, v0
	v_mov_b32_e32 v25, v0
	v_mov_b32_e32 v26, v0
	v_mov_b32_e32 v27, v0
	v_mov_b32_e32 v28, v0
	v_mov_b32_e32 v29, v0
	v_mov_b32_e32 v30, v0
	v_mov_b32_e32 v31, v0
	v_mov_b32_e32 v64, v0
	v_mov_b32_e32 v65, v0
	v_mov_b32_e32 v66, v0
	v_mov_b32_e32 v67, v0
	v_mov_b32_e32 v68, v0
	v_mov_b32_e32 v69, v0
	v_mov_b32_e32 v70, v0
	v_mov_b32_e32 v71, v0
	v_mov_b32_e32 v72, v0
	v_mov_b32_e32 v73, v0
	v_mov_b32_e32 v74, v0
	v_mov_b32_e32 v75, v0
	v_mov_b32_e32 v76, v0
	v_mov_b32_e32 v77, v0
	v_mov_b32_e32 v78, v0
	v_mov_b32_e32 v79, v0
	v_mov_b32_e32 v80, v0
	v_mov_b32_e32 v81, v0
	v_mov_b32_e32 v82, v0
	v_mov_b32_e32 v83, v0
	v_mov_b32_e32 v84, v0
	v_mov_b32_e32 v85, v0
	v_mov_b32_e32 v32, v0
	v_mov_b32_e32 v33, v0
	v_mov_b32_e32 v34, v0
	v_mov_b32_e32 v35, v0
	v_mov_b32_e32 v36, v0
	v_mov_b32_e32 v37, v0
	v_mov_b32_e32 v38, v0
	v_mov_b32_e32 v39, v0
	v_mov_b32_e32 v40, v0
	v_mov_b32_e32 v41, v0
	v_mov_b32_e32 v42, v0
	v_mov_b32_e32 v43, v0
	v_mov_b32_e32 v44, v0
	v_mov_b32_e32 v45, v0
	v_mov_b32_e32 v46, v0
	v_mov_b32_e32 v47, v0
	v_mov_b32_e32 v48, v0
	v_mov_b32_e32 v49, v0
	v_mov_b32_e32 v50, v0
	v_mov_b32_e32 v51, v0
	v_mov_b32_e32 v52, v0
	v_mov_b32_e32 v53, v0
	v_mov_b32_e32 v54, v0
	v_mov_b32_e32 v55, v0
	v_mov_b32_e32 v56, v0
	v_mov_b32_e32 v57, v0
	v_mov_b32_e32 v58, v0
	v_mov_b32_e32 v59, v0
	v_mov_b32_e32 v60, v0
	v_mov_b32_e32 v61, v0
	v_mov_b32_e32 v62, v0
	v_mov_b32_e32 v63, v0
	v_mov_b32_e32 v86, v0
	v_mov_b32_e32 v87, v0
	v_mov_b32_e32 v88, v0
	v_mov_b32_e32 v89, v0
	v_mov_b32_e32 v90, v0
	v_mov_b32_e32 v91, v0
	v_mov_b32_e32 v92, v0
	v_mov_b32_e32 v93, v0
	v_mov_b32_e32 v94, v0
	v_mov_b32_e32 v95, v0
	v_mov_b32_e32 v96, v0
	v_mov_b32_e32 v97, v0
	v_mov_b32_e32 v98, v0
	v_mov_b32_e32 v99, v0
	v_mov_b32_e32 v100, v0
	v_mov_b32_e32 v101, v0
	v_mov_b32_e32 v102, v0
	v_mov_b32_e32 v103, v0
	v_mov_b32_e32 v104, v0
	v_mov_b32_e32 v105, v0
	v_mov_b32_e32 v106, v0
	v_mov_b32_e32 v107, v0
	v_mov_b32_e32 v108, v0
	v_mov_b32_e32 v109, v0
	v_mov_b32_e32 v110, v0
	v_mov_b32_e32 v111, v0
	v_mov_b32_e32 v112, v0
	v_mov_b32_e32 v113, v0
	v_mov_b32_e32 v114, v0
	v_mov_b32_e32 v115, v0
	v_mov_b32_e32 v116, v0
	v_mov_b32_e32 v117, v0
	v_mov_b32_e32 v118, v0
	v_mov_b32_e32 v119, v0
	v_mov_b32_e32 v120, v0
	v_mov_b32_e32 v121, v0
	v_mov_b32_e32 v122, v0
	v_mov_b32_e32 v123, v0
	v_mov_b32_e32 v124, v0
	v_mov_b32_e32 v125, v0
	v_mov_b32_e32 v126, v0
	v_mov_b32_e32 v127, v0
	v_and_b32_e32 v229, 63, v174
	v_lshrrev_b32_e32 v230, 3, v229
	v_mov_b32_e32 v233, 0x800
	v_mul_u32_u24_e32 v224, v230, v233
	v_bfe_u32 v231, v174, 4, 2
	v_bfe_u32 v232, v174, 6, 1
	v_lshl_or_b32 v232, v232, 2, v231
	v_and_b32_e32 v233, 7, v174
	v_xor_b32_e32 v232, v232, v233
	v_lshl_add_u32 v224, v232, 4, v224
	v_and_b32_e32 v229, 15, v174
	v_bfe_u32 v230, v174, 1, 3
	v_xor_b32_e32 v230, v230, v231
	v_lshlrev_b32_e32 v230, 4, v230
	v_lshl_or_b32 v230, v229, 7, v230
	v_lshrrev_b32_e32 v229, 8, v174
	v_lshl_or_b32 v225, v229, 14, v230
	v_bfe_u32 v229, v174, 6, 2
	v_lshl_or_b32 v227, v229, 13, v230
	v_or_b32_e32 v227, 0x10000, v227
	v_xor_b32_e32 v226, 64, v225
	v_xor_b32_e32 v228, 64, v227
	v_readfirstlane_b32 s97, v174
	s_lshl_b32 s97, s97, 4
	s_mov_b32 s28, 14
	s_add_u32 m0, s97, 0x0
	s_add_u32 s12, s98, 0x0
	s_addc_u32 s13, s99, 0
	global_load_lds_dwordx4 v224, s[12:13]
	s_add_u32 m0, s97, 0x10000
	s_add_u32 s12, s100, 0x0
	s_addc_u32 s13, s101, 0
	global_load_lds_dwordx4 v224, s[12:13]
	s_add_u32 m0, s97, 0x2000
	s_add_u32 s12, s98, 0x20000
	s_addc_u32 s13, s99, 0
	global_load_lds_dwordx4 v224, s[12:13]
	s_add_u32 m0, s97, 0x12000
	s_add_u32 s12, s100, 0x20000
	s_addc_u32 s13, s101, 0
	global_load_lds_dwordx4 v224, s[12:13]
	s_add_u32 m0, s97, 0x4000
	s_add_u32 s12, s98, 0x40000
	s_addc_u32 s13, s99, 0
	global_load_lds_dwordx4 v224, s[12:13]
	s_add_u32 m0, s97, 0x14000
	s_add_u32 s12, s100, 0x40000
	s_addc_u32 s13, s101, 0
	global_load_lds_dwordx4 v224, s[12:13]
	s_add_u32 m0, s97, 0x6000
	s_add_u32 s12, s98, 0x60000
	s_addc_u32 s13, s99, 0
	global_load_lds_dwordx4 v224, s[12:13]
	s_add_u32 m0, s97, 0x16000
	s_add_u32 s12, s100, 0x60000
	s_addc_u32 s13, s101, 0
	global_load_lds_dwordx4 v224, s[12:13]
	s_add_u32 m0, s97, 0x8000
	s_add_u32 s12, s98, 0x80
	s_addc_u32 s13, s99, 0
	global_load_lds_dwordx4 v224, s[12:13]
	s_add_u32 m0, s97, 0x18000
	s_add_u32 s12, s100, 0x80
	s_addc_u32 s13, s101, 0
	global_load_lds_dwordx4 v224, s[12:13]
	s_add_u32 m0, s97, 0xa000
	s_add_u32 s12, s98, 0x20080
	s_addc_u32 s13, s99, 0
	global_load_lds_dwordx4 v224, s[12:13]
	s_add_u32 m0, s97, 0x1a000
	s_add_u32 s12, s100, 0x20080
	s_addc_u32 s13, s101, 0
	global_load_lds_dwordx4 v224, s[12:13]
	s_add_u32 m0, s97, 0xc000
	s_add_u32 s12, s98, 0x40080
	s_addc_u32 s13, s99, 0
	global_load_lds_dwordx4 v224, s[12:13]
	s_add_u32 m0, s97, 0x1c000
	s_add_u32 s12, s100, 0x40080
	s_addc_u32 s13, s101, 0
	global_load_lds_dwordx4 v224, s[12:13]
	s_add_u32 m0, s97, 0xe000
	s_add_u32 s12, s98, 0x60080
	s_addc_u32 s13, s99, 0
	global_load_lds_dwordx4 v224, s[12:13]
	s_add_u32 m0, s97, 0x1e000
	s_add_u32 s12, s100, 0x60080
	s_addc_u32 s13, s101, 0
	global_load_lds_dwordx4 v224, s[12:13]
	s_add_u32 s98, s98, 0x100
	s_addc_u32 s99, s99, 0
	s_add_u32 s100, s100, 0x100
	s_addc_u32 s101, s101, 0
	s_waitcnt vmcnt(8)
	s_barrier
; #define G_LOAD(KT) do { _Pragma("unroll") for (int i = 0; i < 4; ++i) { ra[i] = *(const u32x4*)(Ag + (size_t)i * 64 * lda + (KT) * 64); rb[i] = *(const u32x4*)(Bg + (size_t)i * 64 * K + (KT) * 64); } } while (0)
; #define G_STORE(BUF) do { u16* ad = As + (BUF) * 256 * 64 + sto; u16* bd = Bs + (BUF) * 256 * 64 + sto; _Pragma("unroll") for (int i = 0; i < 4; ++i) { *(u32x4*)(ad + i * 64 * 64) = ra[i]; *(u32x4*)(bd + i * 64 * 64) = rb[i]; } } while (0)
; template <int EPI>
; DI void gemm_phase(const u16* __restrict__ A, int lda, const u16* __restrict__ Bt, int K, int N, u16* outb, int ldo,
;                    const float* r0, const float* r1, float* outf, char* lds, int bid, int nb) {
;     ...
;     G_LOAD(0);
;     G_STORE(0);
;     __syncthreads();
;     for (int kt = 0; kt < nk; ++kt) {
;       const int cur = kt & 1;
;       if (kt + 1 < nk) G_LOAD(kt + 1);
;       G_MMA(cur, fo0);
;       G_MMA(cur, fo1);
;       if (kt + 1 < nk) G_STORE(cur ^ 1);
;       __syncthreads();
;     }
	ds_read_b128 v[152:155], v227 offset:0
	ds_read_b128 v[156:159], v227 offset:2048
	ds_read_b128 v[160:163], v227 offset:4096
	ds_read_b128 v[164:167], v227 offset:6144
	ds_read_b128 v[188:191], v225 offset:0
	ds_read_b128 v[192:195], v225 offset:2048
	ds_read_b128 v[196:199], v225 offset:4096
	ds_read_b128 v[200:203], v225 offset:6144
	ds_read_b128 v[204:207], v225 offset:8192
	ds_read_b128 v[208:211], v225 offset:10240
	ds_read_b128 v[212:215], v225 offset:12288
	ds_read_b128 v[216:219], v225 offset:14336
	v_xor_b32_e32 v225, 0x8000, v225
	v_xor_b32_e32 v227, 0x8000, v227
	s_waitcnt lgkmcnt(0)
	s_bitcmp1_b32 s97, 12
	s_cbranch_scc0 .Lgm0_noprio
	s_setprio 1
.Lgm0_noprio:
.Lgm0_loop:
	s_waitcnt lgkmcnt(4)
	v_mfma_f32_16x16x32_bf16 v[124:127], v[152:155], v[188:191], v[124:127]
	v_mfma_f32_16x16x32_bf16 v[120:123], v[156:159], v[188:191], v[120:123]
	v_mfma_f32_16x16x32_bf16 v[116:119], v[160:163], v[188:191], v[116:119]
	v_mfma_f32_16x16x32_bf16 v[112:115], v[164:167], v[188:191], v[112:115]
	ds_read_b128 v[188:191], v226 offset:0
	ds_read_b128 v[168:171], v228 offset:0
	v_mfma_f32_16x16x32_bf16 v[108:111], v[152:155], v[192:195], v[108:111]
	v_mfma_f32_16x16x32_bf16 v[104:107], v[156:159], v[192:195], v[104:107]
	v_mfma_f32_16x16x32_bf16 v[100:103], v[160:163], v[192:195], v[100:103]
	v_mfma_f32_16x16x32_bf16 v[96:99], v[164:167], v[192:195], v[96:99]
	ds_read_b128 v[192:195], v226 offset:2048
	ds_read_b128 v[176:179], v228 offset:2048
	v_mfma_f32_16x16x32_bf16 v[92:95], v[152:155], v[196:199], v[92:95]
	v_mfma_f32_16x16x32_bf16 v[88:91], v[156:159], v[196:199], v[88:91]
	v_mfma_f32_16x16x32_bf16 v[84:87], v[160:163], v[196:199], v[84:87]
	v_mfma_f32_16x16x32_bf16 v[80:83], v[164:167], v[196:199], v[80:83]
	ds_read_b128 v[196:199], v226 offset:4096
	ds_read_b128 v[180:183], v228 offset:4096
	v_mfma_f32_16x16x32_bf16 v[76:79], v[152:155], v[200:203], v[76:79]
	v_mfma_f32_16x16x32_bf16 v[72:75], v[156:159], v[200:203], v[72:75]
	v_mfma_f32_16x16x32_bf16 v[68:71], v[160:163], v[200:203], v[68:71]
	v_mfma_f32_16x16x32_bf16 v[64:67], v[164:167], v[200:203], v[64:67]
	ds_read_b128 v[200:203], v226 offset:6144
	ds_read_b128 v[184:187], v228 offset:6144
	s_waitcnt lgkmcnt(11)
	v_mfma_f32_16x16x32_bf16 v[60:63], v[152:155], v[204:207], v[60:63]
	v_mfma_f32_16x16x32_bf16 v[56:59], v[156:159], v[204:207], v[56:59]
	v_mfma_f32_16x16x32_bf16 v[52:55], v[160:163], v[204:207], v[52:55]
	v_mfma_f32_16x16x32_bf16 v[48:51], v[164:167], v[204:207], v[48:51]
	ds_read_b128 v[204:207], v226 offset:8192
	ds_read_b128 v[220:223], v226 offset:14336
	s_waitcnt lgkmcnt(11)
	v_mfma_f32_16x16x32_bf16 v[44:47], v[152:155], v[208:211], v[44:47]
	v_mfma_f32_16x16x32_bf16 v[40:43], v[156:159], v[208:211], v[40:43]
	v_mfma_f32_16x16x32_bf16 v[36:39], v[160:163], v[208:211], v[36:39]
	v_mfma_f32_16x16x32_bf16 v[32:35], v[164:167], v[208:211], v[32:35]
	ds_read_b128 v[208:211], v226 offset:10240
	s_waitcnt lgkmcnt(11)
	v_mfma_f32_16x16x32_bf16 v[28:31], v[152:155], v[212:215], v[28:31]
	v_mfma_f32_16x16x32_bf16 v[24:27], v[156:159], v[212:215], v[24:27]
	v_mfma_f32_16x16x32_bf16 v[20:23], v[160:163], v[212:215], v[20:23]
	v_mfma_f32_16x16x32_bf16 v[16:19], v[164:167], v[212:215], v[16:19]
	ds_read_b128 v[212:215], v226 offset:12288
	v_mfma_f32_16x16x32_bf16 v[12:15], v[152:155], v[216:219], v[12:15]
	v_mfma_f32_16x16x32_bf16 v[8:11], v[156:159], v[216:219], v[8:11]
	v_mfma_f32_16x16x32_bf16 v[4:7], v[160:163], v[216:219], v[4:7]
	v_mfma_f32_16x16x32_bf16 v[0:3], v[164:167], v[216:219], v[0:3]
	s_waitcnt vmcnt(0) lgkmcnt(0)
	s_barrier
	v_mfma_f32_16x16x32_bf16 v[124:127], v[168:171], v[188:191], v[124:127]
	v_mfma_f32_16x16x32_bf16 v[120:123], v[176:179], v[188:191], v[120:123]
	v_mfma_f32_16x16x32_bf16 v[116:119], v[180:183], v[188:191], v[116:119]
	v_mfma_f32_16x16x32_bf16 v[112:115], v[184:187], v[188:191], v[112:115]
	ds_read_b128 v[188:191], v225 offset:0
	ds_read_b128 v[152:155], v227 offset:0
	s_add_u32 m0, s97, 0x0
	s_add_u32 s12, s98, 0x0
	s_addc_u32 s13, s99, 0
	global_load_lds_dwordx4 v224, s[12:13]
	v_mfma_f32_16x16x32_bf16 v[108:111], v[168:171], v[192:195], v[108:111]
	v_mfma_f32_16x16x32_bf16 v[104:107], v[176:179], v[192:195], v[104:107]
	v_mfma_f32_16x16x32_bf16 v[100:103], v[180:183], v[192:195], v[100:103]
	v_mfma_f32_16x16x32_bf16 v[96:99], v[184:187], v[192:195], v[96:99]
	ds_read_b128 v[192:195], v225 offset:2048
	ds_read_b128 v[156:159], v227 offset:2048
	s_add_u32 m0, s97, 0x10000
	s_add_u32 s12, s100, 0x0
	s_addc_u32 s13, s101, 0
	global_load_lds_dwordx4 v224, s[12:13]
	v_mfma_f32_16x16x32_bf16 v[92:95], v[168:171], v[196:199], v[92:95]
	v_mfma_f32_16x16x32_bf16 v[88:91], v[176:179], v[196:199], v[88:91]
	v_mfma_f32_16x16x32_bf16 v[84:87], v[180:183], v[196:199], v[84:87]
	v_mfma_f32_16x16x32_bf16 v[80:83], v[184:187], v[196:199], v[80:83]
	ds_read_b128 v[196:199], v225 offset:4096
	ds_read_b128 v[160:163], v227 offset:4096
	s_add_u32 m0, s97, 0x2000
	s_add_u32 s12, s98, 0x20000
	s_addc_u32 s13, s99, 0
	global_load_lds_dwordx4 v224, s[12:13]
	v_mfma_f32_16x16x32_bf16 v[76:79], v[168:171], v[200:203], v[76:79]
	v_mfma_f32_16x16x32_bf16 v[72:75], v[176:179], v[200:203], v[72:75]
	v_mfma_f32_16x16x32_bf16 v[68:71], v[180:183], v[200:203], v[68:71]
	v_mfma_f32_16x16x32_bf16 v[64:67], v[184:187], v[200:203], v[64:67]
	ds_read_b128 v[200:203], v225 offset:6144
	ds_read_b128 v[164:167], v227 offset:6144
	s_add_u32 m0, s97, 0x12000
	s_add_u32 s12, s100, 0x20000
	s_addc_u32 s13, s101, 0
	global_load_lds_dwordx4 v224, s[12:13]
	v_mfma_f32_16x16x32_bf16 v[60:63], v[168:171], v[204:207], v[60:63]
	v_mfma_f32_16x16x32_bf16 v[56:59], v[176:179], v[204:207], v[56:59]
; #define G_LOAD(KT) do { _Pragma("unroll") for (int i = 0; i < 4; ++i) { ra[i] = *(const u32x4*)(Ag + (size_t)i * 64 * lda + (KT) * 64); rb[i] = *(const u32x4*)(Bg + (size_t)i * 64 * K + (KT) * 64); } } while (0)
; #define G_STORE(BUF) do { u16* ad = As + (BUF) * 256 * 64 + sto; u16* bd = Bs + (BUF) * 256 * 64 + sto; _Pragma("unroll") for (int i = 0; i < 4; ++i) { *(u32x4*)(ad + i * 64 * 64) = ra[i]; *(u32x4*)(bd + i * 64 * 64) = rb[i]; } } while (0)
; template <int EPI>
; DI void gemm_phase(const u16* __restrict__ A, int lda, const u16* __restrict__ Bt, int K, int N, u16* outb, int ldo,
;                    const float* r0, const float* r1, float* outf, char* lds, int bid, int nb) {
;     ...
;     for (int kt = 0; kt < nk; ++kt) {
;       const int cur = kt & 1;
;       if (kt + 1 < nk) G_LOAD(kt + 1);
;       G_MMA(cur, fo0);
;       G_MMA(cur, fo1);
;       if (kt + 1 < nk) G_STORE(cur ^ 1);
;       __syncthreads();
;     }
	v_mfma_f32_16x16x32_bf16 v[52:55], v[180:183], v[204:207], v[52:55]
	v_mfma_f32_16x16x32_bf16 v[48:51], v[184:187], v[204:207], v[48:51]
	ds_read_b128 v[204:207], v225 offset:8192
	ds_read_b128 v[216:219], v225 offset:14336
	s_add_u32 m0, s97, 0x4000
	s_add_u32 s12, s98, 0x40000
	s_addc_u32 s13, s99, 0
	global_load_lds_dwordx4 v224, s[12:13]
	v_mfma_f32_16x16x32_bf16 v[44:47], v[168:171], v[208:211], v[44:47]
	v_mfma_f32_16x16x32_bf16 v[40:43], v[176:179], v[208:211], v[40:43]
	v_mfma_f32_16x16x32_bf16 v[36:39], v[180:183], v[208:211], v[36:39]
	v_mfma_f32_16x16x32_bf16 v[32:35], v[184:187], v[208:211], v[32:35]
	ds_read_b128 v[208:211], v225 offset:10240
	s_add_u32 m0, s97, 0x14000
	s_add_u32 s12, s100, 0x40000
	s_addc_u32 s13, s101, 0
	global_load_lds_dwordx4 v224, s[12:13]
	v_mfma_f32_16x16x32_bf16 v[28:31], v[168:171], v[212:215], v[28:31]
	v_mfma_f32_16x16x32_bf16 v[24:27], v[176:179], v[212:215], v[24:27]
	v_mfma_f32_16x16x32_bf16 v[20:23], v[180:183], v[212:215], v[20:23]
	v_mfma_f32_16x16x32_bf16 v[16:19], v[184:187], v[212:215], v[16:19]
	ds_read_b128 v[212:215], v225 offset:12288
	s_add_u32 m0, s97, 0x6000
	s_add_u32 s12, s98, 0x60000
	s_addc_u32 s13, s99, 0
	global_load_lds_dwordx4 v224, s[12:13]
	v_mfma_f32_16x16x32_bf16 v[12:15], v[168:171], v[220:223], v[12:15]
	v_mfma_f32_16x16x32_bf16 v[8:11], v[176:179], v[220:223], v[8:11]
	v_mfma_f32_16x16x32_bf16 v[4:7], v[180:183], v[220:223], v[4:7]
	v_mfma_f32_16x16x32_bf16 v[0:3], v[184:187], v[220:223], v[0:3]
	s_add_u32 m0, s97, 0x16000
	s_add_u32 s12, s100, 0x60000
	s_addc_u32 s13, s101, 0
	global_load_lds_dwordx4 v224, s[12:13]
	v_xor_b32_e32 v225, 0x8000, v225
	v_xor_b32_e32 v227, 0x8000, v227
	v_xor_b32_e32 v226, 0x8000, v226
	v_xor_b32_e32 v228, 0x8000, v228
	s_xor_b32 s97, s97, 0x8000
	s_add_u32 s98, s98, 0x80
	s_addc_u32 s99, s99, 0
	s_add_u32 s100, s100, 0x80
	s_addc_u32 s101, s101, 0
	s_sub_u32 s28, s28, 1
	s_cmp_lg_u32 s28, 0
	s_cbranch_scc1 .Lgm0_loop
	s_waitcnt lgkmcnt(4)
	v_mfma_f32_16x16x32_bf16 v[124:127], v[152:155], v[188:191], v[124:127]
	v_mfma_f32_16x16x32_bf16 v[120:123], v[156:159], v[188:191], v[120:123]
	v_mfma_f32_16x16x32_bf16 v[116:119], v[160:163], v[188:191], v[116:119]
	v_mfma_f32_16x16x32_bf16 v[112:115], v[164:167], v[188:191], v[112:115]
	ds_read_b128 v[188:191], v226 offset:0
	ds_read_b128 v[168:171], v228 offset:0
	v_mfma_f32_16x16x32_bf16 v[108:111], v[152:155], v[192:195], v[108:111]
	v_mfma_f32_16x16x32_bf16 v[104:107], v[156:159], v[192:195], v[104:107]
	v_mfma_f32_16x16x32_bf16 v[100:103], v[160:163], v[192:195], v[100:103]
	v_mfma_f32_16x16x32_bf16 v[96:99], v[164:167], v[192:195], v[96:99]
	ds_read_b128 v[192:195], v226 offset:2048
	ds_read_b128 v[176:179], v228 offset:2048
	v_mfma_f32_16x16x32_bf16 v[92:95], v[152:155], v[196:199], v[92:95]
	v_mfma_f32_16x16x32_bf16 v[88:91], v[156:159], v[196:199], v[88:91]
	v_mfma_f32_16x16x32_bf16 v[84:87], v[160:163], v[196:199], v[84:87]
	v_mfma_f32_16x16x32_bf16 v[80:83], v[164:167], v[196:199], v[80:83]
	ds_read_b128 v[196:199], v226 offset:4096
	ds_read_b128 v[180:183], v228 offset:4096
	v_mfma_f32_16x16x32_bf16 v[76:79], v[152:155], v[200:203], v[76:79]
	v_mfma_f32_16x16x32_bf16 v[72:75], v[156:159], v[200:203], v[72:75]
	v_mfma_f32_16x16x32_bf16 v[68:71], v[160:163], v[200:203], v[68:71]
	v_mfma_f32_16x16x32_bf16 v[64:67], v[164:167], v[200:203], v[64:67]
	ds_read_b128 v[200:203], v226 offset:6144
	ds_read_b128 v[184:187], v228 offset:6144
	s_waitcnt lgkmcnt(11)
	v_mfma_f32_16x16x32_bf16 v[60:63], v[152:155], v[204:207], v[60:63]
	v_mfma_f32_16x16x32_bf16 v[56:59], v[156:159], v[204:207], v[56:59]
	v_mfma_f32_16x16x32_bf16 v[52:55], v[160:163], v[204:207], v[52:55]
	v_mfma_f32_16x16x32_bf16 v[48:51], v[164:167], v[204:207], v[48:51]
	ds_read_b128 v[204:207], v226 offset:8192
	ds_read_b128 v[220:223], v226 offset:14336
	s_waitcnt lgkmcnt(11)
	v_mfma_f32_16x16x32_bf16 v[44:47], v[152:155], v[208:211], v[44:47]
	v_mfma_f32_16x16x32_bf16 v[40:43], v[156:159], v[208:211], v[40:43]
	v_mfma_f32_16x16x32_bf16 v[36:39], v[160:163], v[208:211], v[36:39]
	v_mfma_f32_16x16x32_bf16 v[32:35], v[164:167], v[208:211], v[32:35]
	ds_read_b128 v[208:211], v226 offset:10240
	s_waitcnt lgkmcnt(11)
	v_mfma_f32_16x16x32_bf16 v[28:31], v[152:155], v[212:215], v[28:31]
	v_mfma_f32_16x16x32_bf16 v[24:27], v[156:159], v[212:215], v[24:27]
	v_mfma_f32_16x16x32_bf16 v[20:23], v[160:163], v[212:215], v[20:23]
	v_mfma_f32_16x16x32_bf16 v[16:19], v[164:167], v[212:215], v[16:19]
	ds_read_b128 v[212:215], v226 offset:12288
	v_mfma_f32_16x16x32_bf16 v[12:15], v[152:155], v[216:219], v[12:15]
	v_mfma_f32_16x16x32_bf16 v[8:11], v[156:159], v[216:219], v[8:11]
	v_mfma_f32_16x16x32_bf16 v[4:7], v[160:163], v[216:219], v[4:7]
	v_mfma_f32_16x16x32_bf16 v[0:3], v[164:167], v[216:219], v[0:3]
	s_waitcnt vmcnt(0) lgkmcnt(0)
	s_barrier
; #define G_LOAD(KT) do { _Pragma("unroll") for (int i = 0; i < 4; ++i) { ra[i] = *(const u32x4*)(Ag + (size_t)i * 64 * lda + (KT) * 64); rb[i] = *(const u32x4*)(Bg + (size_t)i * 64 * K + (KT) * 64); } } while (0)
; #define G_STORE(BUF) do { u16* ad = As + (BUF) * 256 * 64 + sto; u16* bd = Bs + (BUF) * 256 * 64 + sto; _Pragma("unroll") for (int i = 0; i < 4; ++i) { *(u32x4*)(ad + i * 64 * 64) = ra[i]; *(u32x4*)(bd + i * 64 * 64) = rb[i]; } } while (0)
; template <int EPI>
; DI void gemm_phase(const u16* __restrict__ A, int lda, const u16* __restrict__ Bt, int K, int N, u16* outb, int ldo,
;                    const float* r0, const float* r1, float* outf, char* lds, int bid, int nb) {
;     ...
;     for (int kt = 0; kt < nk; ++kt) {
;       const int cur = kt & 1;
;       if (kt + 1 < nk) G_LOAD(kt + 1);
;       G_MMA(cur, fo0);
;       G_MMA(cur, fo1);
;       if (kt + 1 < nk) G_STORE(cur ^ 1);
;       __syncthreads();
;     }
	v_mfma_f32_16x16x32_bf16 v[124:127], v[168:171], v[188:191], v[124:127]
	v_mfma_f32_16x16x32_bf16 v[120:123], v[176:179], v[188:191], v[120:123]
	v_mfma_f32_16x16x32_bf16 v[116:119], v[180:183], v[188:191], v[116:119]
	v_mfma_f32_16x16x32_bf16 v[112:115], v[184:187], v[188:191], v[112:115]
	ds_read_b128 v[188:191], v225 offset:0
	ds_read_b128 v[152:155], v227 offset:0
	v_mfma_f32_16x16x32_bf16 v[108:111], v[168:171], v[192:195], v[108:111]
	v_mfma_f32_16x16x32_bf16 v[104:107], v[176:179], v[192:195], v[104:107]
	v_mfma_f32_16x16x32_bf16 v[100:103], v[180:183], v[192:195], v[100:103]
	v_mfma_f32_16x16x32_bf16 v[96:99], v[184:187], v[192:195], v[96:99]
	ds_read_b128 v[192:195], v225 offset:2048
	ds_read_b128 v[156:159], v227 offset:2048
	v_mfma_f32_16x16x32_bf16 v[92:95], v[168:171], v[196:199], v[92:95]
	v_mfma_f32_16x16x32_bf16 v[88:91], v[176:179], v[196:199], v[88:91]
	v_mfma_f32_16x16x32_bf16 v[84:87], v[180:183], v[196:199], v[84:87]
	v_mfma_f32_16x16x32_bf16 v[80:83], v[184:187], v[196:199], v[80:83]
	ds_read_b128 v[196:199], v225 offset:4096
	ds_read_b128 v[160:163], v227 offset:4096
	v_mfma_f32_16x16x32_bf16 v[76:79], v[168:171], v[200:203], v[76:79]
	v_mfma_f32_16x16x32_bf16 v[72:75], v[176:179], v[200:203], v[72:75]
	v_mfma_f32_16x16x32_bf16 v[68:71], v[180:183], v[200:203], v[68:71]
	v_mfma_f32_16x16x32_bf16 v[64:67], v[184:187], v[200:203], v[64:67]
	ds_read_b128 v[200:203], v225 offset:6144
	ds_read_b128 v[164:167], v227 offset:6144
	v_mfma_f32_16x16x32_bf16 v[60:63], v[168:171], v[204:207], v[60:63]
	v_mfma_f32_16x16x32_bf16 v[56:59], v[176:179], v[204:207], v[56:59]
	v_mfma_f32_16x16x32_bf16 v[52:55], v[180:183], v[204:207], v[52:55]
	v_mfma_f32_16x16x32_bf16 v[48:51], v[184:187], v[204:207], v[48:51]
	ds_read_b128 v[204:207], v225 offset:8192
	ds_read_b128 v[216:219], v225 offset:14336
	v_mfma_f32_16x16x32_bf16 v[44:47], v[168:171], v[208:211], v[44:47]
	v_mfma_f32_16x16x32_bf16 v[40:43], v[176:179], v[208:211], v[40:43]
	v_mfma_f32_16x16x32_bf16 v[36:39], v[180:183], v[208:211], v[36:39]
	v_mfma_f32_16x16x32_bf16 v[32:35], v[184:187], v[208:211], v[32:35]
	ds_read_b128 v[208:211], v225 offset:10240
	v_mfma_f32_16x16x32_bf16 v[28:31], v[168:171], v[212:215], v[28:31]
	v_mfma_f32_16x16x32_bf16 v[24:27], v[176:179], v[212:215], v[24:27]
	v_mfma_f32_16x16x32_bf16 v[20:23], v[180:183], v[212:215], v[20:23]
	v_mfma_f32_16x16x32_bf16 v[16:19], v[184:187], v[212:215], v[16:19]
	ds_read_b128 v[212:215], v225 offset:12288
	v_mfma_f32_16x16x32_bf16 v[12:15], v[168:171], v[220:223], v[12:15]
	v_mfma_f32_16x16x32_bf16 v[8:11], v[176:179], v[220:223], v[8:11]
	v_mfma_f32_16x16x32_bf16 v[4:7], v[180:183], v[220:223], v[4:7]
	v_mfma_f32_16x16x32_bf16 v[0:3], v[184:187], v[220:223], v[0:3]
	v_xor_b32_e32 v226, 0x8000, v226
	v_xor_b32_e32 v228, 0x8000, v228
	s_waitcnt lgkmcnt(4)
	v_mfma_f32_16x16x32_bf16 v[124:127], v[152:155], v[188:191], v[124:127]
	v_mfma_f32_16x16x32_bf16 v[120:123], v[156:159], v[188:191], v[120:123]
	v_mfma_f32_16x16x32_bf16 v[116:119], v[160:163], v[188:191], v[116:119]
	v_mfma_f32_16x16x32_bf16 v[112:115], v[164:167], v[188:191], v[112:115]
	ds_read_b128 v[188:191], v226 offset:0
	ds_read_b128 v[168:171], v228 offset:0
	v_mfma_f32_16x16x32_bf16 v[108:111], v[152:155], v[192:195], v[108:111]
	v_mfma_f32_16x16x32_bf16 v[104:107], v[156:159], v[192:195], v[104:107]
	v_mfma_f32_16x16x32_bf16 v[100:103], v[160:163], v[192:195], v[100:103]
	v_mfma_f32_16x16x32_bf16 v[96:99], v[164:167], v[192:195], v[96:99]
	ds_read_b128 v[192:195], v226 offset:2048
	ds_read_b128 v[176:179], v228 offset:2048
	v_mfma_f32_16x16x32_bf16 v[92:95], v[152:155], v[196:199], v[92:95]
	v_mfma_f32_16x16x32_bf16 v[88:91], v[156:159], v[196:199], v[88:91]
	v_mfma_f32_16x16x32_bf16 v[84:87], v[160:163], v[196:199], v[84:87]
	v_mfma_f32_16x16x32_bf16 v[80:83], v[164:167], v[196:199], v[80:83]
	ds_read_b128 v[196:199], v226 offset:4096
	ds_read_b128 v[180:183], v228 offset:4096
	v_mfma_f32_16x16x32_bf16 v[76:79], v[152:155], v[200:203], v[76:79]
	v_mfma_f32_16x16x32_bf16 v[72:75], v[156:159], v[200:203], v[72:75]
	v_mfma_f32_16x16x32_bf16 v[68:71], v[160:163], v[200:203], v[68:71]
	v_mfma_f32_16x16x32_bf16 v[64:67], v[164:167], v[200:203], v[64:67]
	ds_read_b128 v[200:203], v226 offset:6144
	ds_read_b128 v[184:187], v228 offset:6144
	s_waitcnt lgkmcnt(11)
	v_mfma_f32_16x16x32_bf16 v[60:63], v[152:155], v[204:207], v[60:63]
	v_mfma_f32_16x16x32_bf16 v[56:59], v[156:159], v[204:207], v[56:59]
	v_mfma_f32_16x16x32_bf16 v[52:55], v[160:163], v[204:207], v[52:55]
	v_mfma_f32_16x16x32_bf16 v[48:51], v[164:167], v[204:207], v[48:51]
	ds_read_b128 v[204:207], v226 offset:8192
	ds_read_b128 v[220:223], v226 offset:14336
	s_waitcnt lgkmcnt(11)
	v_mfma_f32_16x16x32_bf16 v[44:47], v[152:155], v[208:211], v[44:47]
	v_mfma_f32_16x16x32_bf16 v[40:43], v[156:159], v[208:211], v[40:43]
	v_mfma_f32_16x16x32_bf16 v[36:39], v[160:163], v[208:211], v[36:39]
	v_mfma_f32_16x16x32_bf16 v[32:35], v[164:167], v[208:211], v[32:35]
	ds_read_b128 v[208:211], v226 offset:10240
	s_waitcnt lgkmcnt(11)
	v_mfma_f32_16x16x32_bf16 v[28:31], v[152:155], v[212:215], v[28:31]
	v_mfma_f32_16x16x32_bf16 v[24:27], v[156:159], v[212:215], v[24:27]
	v_mfma_f32_16x16x32_bf16 v[20:23], v[160:163], v[212:215], v[20:23]
	v_mfma_f32_16x16x32_bf16 v[16:19], v[164:167], v[212:215], v[16:19]
	ds_read_b128 v[212:215], v226 offset:12288
	v_mfma_f32_16x16x32_bf16 v[12:15], v[152:155], v[216:219], v[12:15]
	v_mfma_f32_16x16x32_bf16 v[8:11], v[156:159], v[216:219], v[8:11]
	v_mfma_f32_16x16x32_bf16 v[4:7], v[160:163], v[216:219], v[4:7]
	v_mfma_f32_16x16x32_bf16 v[0:3], v[164:167], v[216:219], v[0:3]
	s_waitcnt vmcnt(0) lgkmcnt(0)
	s_barrier
; DI u16 f2bf(float a) { return (u16)(pk2(a, 0.f) & 0xffffu); }
; template <int EPI>
; DI void gemm_phase(const u16* __restrict__ A, int lda, const u16* __restrict__ Bt, int K, int N, u16* outb, int ldo,
;                    const float* r0, const float* r1, float* outf, char* lds, int bid, int nb) {
;     ...
;     const int mrow = tm * 256 + wr * 128 + quad * 4;
;     if constexpr (EPI == EPI_BF16) {
;       const int col = tn * 256 + wc * 64 + l15;
; #pragma unroll
;       for (int i = 0; i < 8; ++i)
; #pragma unroll
;         for (int r = 0; r < 4; ++r) {
;           u16* o0 = outb + (size_t)(mrow + i * 16 + r) * ldo + col;
;           o0[0] = f2bf(acc[i][0][r]); o0[16] = f2bf(acc[i][1][r]); o0[32] = f2bf(acc[i][2][r]); o0[48] = f2bf(acc[i][3][r]);
;         }
	v_mfma_f32_16x16x32_bf16 v[124:127], v[168:171], v[188:191], v[124:127]
	v_mfma_f32_16x16x32_bf16 v[120:123], v[176:179], v[188:191], v[120:123]
	v_mfma_f32_16x16x32_bf16 v[116:119], v[180:183], v[188:191], v[116:119]
	v_mfma_f32_16x16x32_bf16 v[112:115], v[184:187], v[188:191], v[112:115]
	v_mfma_f32_16x16x32_bf16 v[108:111], v[168:171], v[192:195], v[108:111]
	v_mfma_f32_16x16x32_bf16 v[104:107], v[176:179], v[192:195], v[104:107]
	v_mfma_f32_16x16x32_bf16 v[100:103], v[180:183], v[192:195], v[100:103]
	v_mfma_f32_16x16x32_bf16 v[96:99], v[184:187], v[192:195], v[96:99]
	v_mfma_f32_16x16x32_bf16 v[92:95], v[168:171], v[196:199], v[92:95]
	v_mfma_f32_16x16x32_bf16 v[88:91], v[176:179], v[196:199], v[88:91]
	v_mfma_f32_16x16x32_bf16 v[84:87], v[180:183], v[196:199], v[84:87]
	v_mfma_f32_16x16x32_bf16 v[80:83], v[184:187], v[196:199], v[80:83]
	v_mfma_f32_16x16x32_bf16 v[76:79], v[168:171], v[200:203], v[76:79]
	v_mfma_f32_16x16x32_bf16 v[72:75], v[176:179], v[200:203], v[72:75]
	v_mfma_f32_16x16x32_bf16 v[68:71], v[180:183], v[200:203], v[68:71]
	v_mfma_f32_16x16x32_bf16 v[64:67], v[184:187], v[200:203], v[64:67]
	v_mfma_f32_16x16x32_bf16 v[60:63], v[168:171], v[204:207], v[60:63]
	v_mfma_f32_16x16x32_bf16 v[56:59], v[176:179], v[204:207], v[56:59]
	v_mfma_f32_16x16x32_bf16 v[52:55], v[180:183], v[204:207], v[52:55]
	v_mfma_f32_16x16x32_bf16 v[48:51], v[184:187], v[204:207], v[48:51]
	v_mfma_f32_16x16x32_bf16 v[44:47], v[168:171], v[208:211], v[44:47]
	v_mfma_f32_16x16x32_bf16 v[40:43], v[176:179], v[208:211], v[40:43]
	v_mfma_f32_16x16x32_bf16 v[36:39], v[180:183], v[208:211], v[36:39]
	v_mfma_f32_16x16x32_bf16 v[32:35], v[184:187], v[208:211], v[32:35]
	v_mfma_f32_16x16x32_bf16 v[28:31], v[168:171], v[212:215], v[28:31]
	v_mfma_f32_16x16x32_bf16 v[24:27], v[176:179], v[212:215], v[24:27]
	v_mfma_f32_16x16x32_bf16 v[20:23], v[180:183], v[212:215], v[20:23]
	v_mfma_f32_16x16x32_bf16 v[16:19], v[184:187], v[212:215], v[16:19]
	v_mfma_f32_16x16x32_bf16 v[12:15], v[168:171], v[220:223], v[12:15]
	v_mfma_f32_16x16x32_bf16 v[8:11], v[176:179], v[220:223], v[8:11]
	v_mfma_f32_16x16x32_bf16 v[4:7], v[180:183], v[220:223], v[4:7]
	v_mfma_f32_16x16x32_bf16 v[0:3], v[184:187], v[220:223], v[0:3]
	s_setprio 0
	s_nop 7
	s_nop 3
	v_and_b32_e32 v225, 15, v174
	v_lshrrev_b32_e32 v226, 8, v174
	v_lshl_or_b32 v225, v226, 7, v225
	v_bfe_u32 v226, v174, 6, 2
	v_bfe_u32 v227, v174, 4, 2
	v_lshlrev_b32_e32 v227, 2, v227
	v_add_u32_e32 v225, s56, v225
	v_lshl_add_u32 v226, v226, 6, v227
	v_add_u32_e32 v226, s57, v226
	v_lshlrev_b32_e32 v226, 1, v226
	v_mov_b32_e32 v227, 0x1400
	v_mad_u32_u24 v224, v225, v227, v226
	v_cvt_pk_bf16_f32 v188, v124, v125
	v_cvt_pk_bf16_f32 v189, v126, v127
	global_store_dwordx2 v224, v[188:189], s[8:9] offset:0
	v_cvt_pk_bf16_f32 v190, v120, v121
	v_cvt_pk_bf16_f32 v191, v122, v123
	global_store_dwordx2 v224, v[190:191], s[8:9] offset:32
	v_cvt_pk_bf16_f32 v192, v116, v117
	v_cvt_pk_bf16_f32 v193, v118, v119
	global_store_dwordx2 v224, v[192:193], s[8:9] offset:64
	v_cvt_pk_bf16_f32 v194, v112, v113
	v_cvt_pk_bf16_f32 v195, v114, v115
	global_store_dwordx2 v224, v[194:195], s[8:9] offset:96
	v_add_u32_e32 v224, 0x14000, v224
	v_cvt_pk_bf16_f32 v196, v108, v109
	v_cvt_pk_bf16_f32 v197, v110, v111
	global_store_dwordx2 v224, v[196:197], s[8:9] offset:0
	v_cvt_pk_bf16_f32 v198, v104, v105
	v_cvt_pk_bf16_f32 v199, v106, v107
	global_store_dwordx2 v224, v[198:199], s[8:9] offset:32
	v_cvt_pk_bf16_f32 v200, v100, v101
	v_cvt_pk_bf16_f32 v201, v102, v103
	global_store_dwordx2 v224, v[200:201], s[8:9] offset:64
	v_cvt_pk_bf16_f32 v202, v96, v97
	v_cvt_pk_bf16_f32 v203, v98, v99
	global_store_dwordx2 v224, v[202:203], s[8:9] offset:96
	v_add_u32_e32 v224, 0x14000, v224
	v_cvt_pk_bf16_f32 v204, v92, v93
	v_cvt_pk_bf16_f32 v205, v94, v95
	global_store_dwordx2 v224, v[204:205], s[8:9] offset:0
	v_cvt_pk_bf16_f32 v206, v88, v89
	v_cvt_pk_bf16_f32 v207, v90, v91
	global_store_dwordx2 v224, v[206:207], s[8:9] offset:32
	v_cvt_pk_bf16_f32 v208, v84, v85
	v_cvt_pk_bf16_f32 v209, v86, v87
	global_store_dwordx2 v224, v[208:209], s[8:9] offset:64
	v_cvt_pk_bf16_f32 v210, v80, v81
	v_cvt_pk_bf16_f32 v211, v82, v83
	global_store_dwordx2 v224, v[210:211], s[8:9] offset:96
	v_add_u32_e32 v224, 0x14000, v224
	v_cvt_pk_bf16_f32 v212, v76, v77
	v_cvt_pk_bf16_f32 v213, v78, v79
	global_store_dwordx2 v224, v[212:213], s[8:9] offset:0
	v_cvt_pk_bf16_f32 v214, v72, v73
	v_cvt_pk_bf16_f32 v215, v74, v75
	global_store_dwordx2 v224, v[214:215], s[8:9] offset:32
	v_cvt_pk_bf16_f32 v216, v68, v69
	v_cvt_pk_bf16_f32 v217, v70, v71
	global_store_dwordx2 v224, v[216:217], s[8:9] offset:64
	v_cvt_pk_bf16_f32 v218, v64, v65
	v_cvt_pk_bf16_f32 v219, v66, v67
	global_store_dwordx2 v224, v[218:219], s[8:9] offset:96
	v_add_u32_e32 v224, 0x14000, v224
	v_cvt_pk_bf16_f32 v188, v60, v61
	v_cvt_pk_bf16_f32 v189, v62, v63
	global_store_dwordx2 v224, v[188:189], s[8:9] offset:0
	v_cvt_pk_bf16_f32 v190, v56, v57
	v_cvt_pk_bf16_f32 v191, v58, v59
	global_store_dwordx2 v224, v[190:191], s[8:9] offset:32
	v_cvt_pk_bf16_f32 v192, v52, v53
	v_cvt_pk_bf16_f32 v193, v54, v55
	global_store_dwordx2 v224, v[192:193], s[8:9] offset:64
	v_cvt_pk_bf16_f32 v194, v48, v49
	v_cvt_pk_bf16_f32 v195, v50, v51
	global_store_dwordx2 v224, v[194:195], s[8:9] offset:96
	v_add_u32_e32 v224, 0x14000, v224
	v_cvt_pk_bf16_f32 v196, v44, v45
	v_cvt_pk_bf16_f32 v197, v46, v47
	global_store_dwordx2 v224, v[196:197], s[8:9] offset:0
	v_cvt_pk_bf16_f32 v198, v40, v41
	v_cvt_pk_bf16_f32 v199, v42, v43
	global_store_dwordx2 v224, v[198:199], s[8:9] offset:32
	v_cvt_pk_bf16_f32 v200, v36, v37
	v_cvt_pk_bf16_f32 v201, v38, v39
	global_store_dwordx2 v224, v[200:201], s[8:9] offset:64
	v_cvt_pk_bf16_f32 v202, v32, v33
	v_cvt_pk_bf16_f32 v203, v34, v35
	global_store_dwordx2 v224, v[202:203], s[8:9] offset:96
	v_add_u32_e32 v224, 0x14000, v224
	v_cvt_pk_bf16_f32 v204, v28, v29
	v_cvt_pk_bf16_f32 v205, v30, v31
	global_store_dwordx2 v224, v[204:205], s[8:9] offset:0
	v_cvt_pk_bf16_f32 v206, v24, v25
	v_cvt_pk_bf16_f32 v207, v26, v27
	global_store_dwordx2 v224, v[206:207], s[8:9] offset:32
	v_cvt_pk_bf16_f32 v208, v20, v21
	v_cvt_pk_bf16_f32 v209, v22, v23
	global_store_dwordx2 v224, v[208:209], s[8:9] offset:64
	v_cvt_pk_bf16_f32 v210, v16, v17
	v_cvt_pk_bf16_f32 v211, v18, v19
	global_store_dwordx2 v224, v[210:211], s[8:9] offset:96
	v_add_u32_e32 v224, 0x14000, v224
	v_cvt_pk_bf16_f32 v212, v12, v13
	v_cvt_pk_bf16_f32 v213, v14, v15
	global_store_dwordx2 v224, v[212:213], s[8:9] offset:0
	v_cvt_pk_bf16_f32 v214, v8, v9
	v_cvt_pk_bf16_f32 v215, v10, v11
	global_store_dwordx2 v224, v[214:215], s[8:9] offset:32
	v_cvt_pk_bf16_f32 v216, v4, v5
	v_cvt_pk_bf16_f32 v217, v6, v7
	global_store_dwordx2 v224, v[216:217], s[8:9] offset:64
	v_cvt_pk_bf16_f32 v218, v0, v1
	v_cvt_pk_bf16_f32 v219, v2, v3
	global_store_dwordx2 v224, v[218:219], s[8:9] offset:96
	s_add_i32 s18, s18, 1
	s_cmp_eq_u32 s18, s14
	s_cbranch_scc0 .LBB0_283

; #define G_LOAD(KT) do { _Pragma("unroll") for (int i = 0; i < 4; ++i) { ra[i] = *(const u32x4*)(Ag + (size_t)i * 64 * lda + (KT) * 64); rb[i] = *(const u32x4*)(Bg + (size_t)i * 64 * K + (KT) * 64); } } while (0)
; #define G_STORE(BUF) do { u16* ad = As + (BUF) * 256 * 64 + sto; u16* bd = Bs + (BUF) * 256 * 64 + sto; _Pragma("unroll") for (int i = 0; i < 4; ++i) { *(u32x4*)(ad + i * 64 * 64) = ra[i]; *(u32x4*)(bd + i * 64 * 64) = rb[i]; } } while (0)
; template <int EPI>
; DI void gemm_phase(const u16* __restrict__ A, int lda, const u16* __restrict__ Bt, int K, int N, u16* outb, int ldo,
;                    const float* r0, const float* r1, float* outf, char* lds, int bid, int nb) {
;     ...
;   for (int it = 0; it < nIter; ++it) {
;     int tm, tn;
;     if (swz) { const int st = xcd + 8 * it, sm = st / nSN, sn = st - sm * nSN; tm = sm * GM + jb / GN; tn = sn * GN + (jb % GN); }
;     else { const int t = bid + it * nb; tm = t / nN; tn = t - tm * nN; }
;     const u16* Ag = A + (size_t)(tm * 256 + lrow) * lda + lch * 8;
;     const u16* Bg = Bt + (size_t)(tn * 256 + lrow) * K + lch * 8;
;     f32x4 acc[8][4];
; #pragma unroll
;     for (int i = 0; i < 8; ++i)
; #pragma unroll
;       for (int j = 0; j < 4; ++j) acc[i][j] = (f32x4){0.f, 0.f, 0.f, 0.f};
;     u32x4 ra[4], rb[4];
;     ...
;     G_LOAD(0);
;     G_STORE(0);
;     __syncthreads();
.LBB0_581:
	s_lshl_b32 s52, s51, 8
	v_or_b32_e32 v0, s52, v138
	v_ashrrev_i32_e32 v1, 31, v0
	s_lshl_b32 s53, s53, 8
	v_or_b32_e32 v2, s53, v138
	v_lshlrev_b64 v[62:63], 11, v[0:1]
	v_ashrrev_i32_e32 v3, 31, v2
	v_lshl_add_u64 v[0:1], v[128:129], 0, v[62:63]
	v_lshlrev_b64 v[64:65], 11, v[2:3]
	v_add_co_u32_e32 v4, vcc, s19, v0
	v_lshl_add_u64 v[2:3], v[130:131], 0, v[64:65]
	s_nop 0
	v_addc_co_u32_e32 v5, vcc, 0, v1, vcc
	v_add_co_u32_e32 v6, vcc, s19, v2
	s_nop 1
	v_readfirstlane_b32 s98, v0
	v_readfirstlane_b32 s99, v1
	s_nop 1
	v_readfirstlane_b32 s100, v2
	v_readfirstlane_b32 s101, v3
	v_addc_co_u32_e32 v7, vcc, 0, v3, vcc
	v_add_co_u32_e32 v4, vcc, s20, v0
	s_mov_b32 s54, 0
	s_nop 0
	v_addc_co_u32_e32 v5, vcc, 0, v1, vcc
	v_add_co_u32_e32 v6, vcc, s20, v2
	s_mov_b64 s[8:9], 0
	s_nop 0
	v_addc_co_u32_e32 v7, vcc, 0, v3, vcc
	v_add_co_u32_e32 v0, vcc, s21, v0
	v_addc_co_u32_e32 v1, vcc, 0, v1, vcc
	v_add_co_u32_e32 v2, vcc, s21, v2
	v_lshl_add_u64 v[134:135], v[132:133], 0, v[62:63]
	s_nop 0
	v_addc_co_u32_e32 v3, vcc, 0, v3, vcc
	v_mov_b32_e32 v0, 0
	v_mov_b32_e32 v1, v0
	v_mov_b32_e32 v2, v0
	v_mov_b32_e32 v3, v0
	v_mov_b32_e32 v4, v0
	v_mov_b32_e32 v5, v0
	v_mov_b32_e32 v6, v0
	v_mov_b32_e32 v7, v0
	v_mov_b32_e32 v8, v0
	v_mov_b32_e32 v9, v0
	v_mov_b32_e32 v10, v0
	v_mov_b32_e32 v11, v0
	v_mov_b32_e32 v12, v0
	v_mov_b32_e32 v13, v0
	v_mov_b32_e32 v14, v0
	v_mov_b32_e32 v15, v0
	v_mov_b32_e32 v16, v0
	v_mov_b32_e32 v17, v0
	v_mov_b32_e32 v18, v0
	v_mov_b32_e32 v19, v0
	v_mov_b32_e32 v20, v0
	v_mov_b32_e32 v21, v0
	v_mov_b32_e32 v22, v0
	v_mov_b32_e32 v23, v0
	v_mov_b32_e32 v24, v0
	v_mov_b32_e32 v25, v0
	v_mov_b32_e32 v26, v0
	v_mov_b32_e32 v27, v0
	v_mov_b32_e32 v28, v0
	v_mov_b32_e32 v29, v0
	v_lshl_add_u64 v[136:137], v[132:133], 0, v[64:65]
	v_mov_b32_e32 v62, v0
	v_mov_b32_e32 v63, v0
	v_mov_b32_e32 v64, v0
	v_mov_b32_e32 v65, v0
	v_mov_b32_e32 v66, v0
	v_mov_b32_e32 v67, v0
	v_mov_b32_e32 v68, v0
	v_mov_b32_e32 v69, v0
	v_mov_b32_e32 v70, v0
	v_mov_b32_e32 v71, v0
	v_mov_b32_e32 v72, v0
	v_mov_b32_e32 v73, v0
	v_mov_b32_e32 v74, v0
	v_mov_b32_e32 v75, v0
	v_mov_b32_e32 v76, v0
	v_mov_b32_e32 v77, v0
	v_mov_b32_e32 v78, v0
	v_mov_b32_e32 v79, v0
	v_mov_b32_e32 v80, v0
	v_mov_b32_e32 v81, v0
	v_mov_b32_e32 v82, v0
	v_mov_b32_e32 v83, v0
	v_mov_b32_e32 v84, v0
	v_mov_b32_e32 v85, v0
	v_mov_b32_e32 v30, v0
	v_mov_b32_e32 v31, v0
	v_mov_b32_e32 v32, v0
	v_mov_b32_e32 v33, v0
	v_mov_b32_e32 v34, v0
	v_mov_b32_e32 v35, v0
	v_mov_b32_e32 v36, v0
	v_mov_b32_e32 v37, v0
	v_mov_b32_e32 v38, v0
	v_mov_b32_e32 v39, v0
	v_mov_b32_e32 v40, v0
	v_mov_b32_e32 v41, v0
	v_mov_b32_e32 v42, v0
	v_mov_b32_e32 v43, v0
	v_mov_b32_e32 v44, v0
	v_mov_b32_e32 v45, v0
	v_mov_b32_e32 v46, v0
	v_mov_b32_e32 v47, v0
	v_mov_b32_e32 v48, v0
	v_mov_b32_e32 v49, v0
	v_mov_b32_e32 v50, v0
	v_mov_b32_e32 v51, v0
	v_mov_b32_e32 v52, v0
	v_mov_b32_e32 v53, v0
	v_mov_b32_e32 v54, v0
	v_mov_b32_e32 v55, v0
	v_mov_b32_e32 v56, v0
	v_mov_b32_e32 v57, v0
	v_mov_b32_e32 v58, v0
	v_mov_b32_e32 v59, v0
	v_mov_b32_e32 v60, v0
	v_mov_b32_e32 v61, v0
	v_mov_b32_e32 v86, v0
	v_mov_b32_e32 v87, v0
	v_mov_b32_e32 v88, v0
	v_mov_b32_e32 v89, v0
	v_mov_b32_e32 v90, v0
	v_mov_b32_e32 v91, v0
	v_mov_b32_e32 v92, v0
	v_mov_b32_e32 v93, v0
	v_mov_b32_e32 v94, v0
	v_mov_b32_e32 v95, v0
	v_mov_b32_e32 v96, v0
	v_mov_b32_e32 v97, v0
	v_mov_b32_e32 v98, v0
	v_mov_b32_e32 v99, v0
	v_mov_b32_e32 v100, v0
	v_mov_b32_e32 v101, v0
	v_mov_b32_e32 v102, v0
	v_mov_b32_e32 v103, v0
	v_mov_b32_e32 v104, v0
	v_mov_b32_e32 v105, v0
	v_mov_b32_e32 v106, v0
	v_mov_b32_e32 v107, v0
	v_mov_b32_e32 v108, v0
	v_mov_b32_e32 v109, v0
	v_mov_b32_e32 v110, v0
	v_mov_b32_e32 v111, v0
	v_mov_b32_e32 v112, v0
	v_mov_b32_e32 v113, v0
	v_mov_b32_e32 v114, v0
	v_mov_b32_e32 v115, v0
	v_mov_b32_e32 v116, v0
	v_mov_b32_e32 v117, v0
	v_mov_b32_e32 v118, v0
	v_mov_b32_e32 v119, v0
	v_mov_b32_e32 v120, v0
	v_mov_b32_e32 v121, v0
	v_mov_b32_e32 v122, v0
	v_mov_b32_e32 v123, v0
	v_mov_b32_e32 v124, v0
	v_mov_b32_e32 v125, v0
	v_mov_b32_e32 v126, v0
	v_mov_b32_e32 v127, v0
	v_and_b32_e32 v229, 63, v174
	v_lshrrev_b32_e32 v230, 3, v229
	v_mov_b32_e32 v233, 0x800
	v_mul_u32_u24_e32 v224, v230, v233
	v_bfe_u32 v231, v174, 4, 2
	v_bfe_u32 v232, v174, 6, 1
	v_lshl_or_b32 v232, v232, 2, v231
	v_and_b32_e32 v233, 7, v174
	v_xor_b32_e32 v232, v232, v233
	v_lshl_add_u32 v224, v232, 4, v224
	v_and_b32_e32 v229, 15, v174
	v_bfe_u32 v230, v174, 1, 3
	v_xor_b32_e32 v230, v230, v231
	v_lshlrev_b32_e32 v230, 4, v230
	v_lshl_or_b32 v230, v229, 7, v230
	v_lshrrev_b32_e32 v229, 8, v174
	v_lshl_or_b32 v225, v229, 14, v230
	v_bfe_u32 v229, v174, 6, 2
	v_lshl_or_b32 v227, v229, 13, v230
	v_or_b32_e32 v227, 0x10000, v227
	v_xor_b32_e32 v226, 64, v225
	v_xor_b32_e32 v228, 64, v227
	v_readfirstlane_b32 s97, v174
	s_lshl_b32 s97, s97, 4
	s_mov_b32 s28, 14
	s_add_u32 m0, s97, 0x0
	s_add_u32 s8, s98, 0x0
	s_addc_u32 s9, s99, 0
	global_load_lds_dwordx4 v224, s[8:9]
	s_add_u32 m0, s97, 0x10000
	s_add_u32 s8, s100, 0x0
	s_addc_u32 s9, s101, 0
	global_load_lds_dwordx4 v224, s[8:9]
	s_add_u32 m0, s97, 0x2000
	s_add_u32 s8, s98, 0x20000
	s_addc_u32 s9, s99, 0
	global_load_lds_dwordx4 v224, s[8:9]
	s_add_u32 m0, s97, 0x12000
	s_add_u32 s8, s100, 0x20000
	s_addc_u32 s9, s101, 0
	global_load_lds_dwordx4 v224, s[8:9]
	s_add_u32 m0, s97, 0x4000
	s_add_u32 s8, s98, 0x40000
	s_addc_u32 s9, s99, 0
	global_load_lds_dwordx4 v224, s[8:9]
	s_add_u32 m0, s97, 0x14000
	s_add_u32 s8, s100, 0x40000
	s_addc_u32 s9, s101, 0
	global_load_lds_dwordx4 v224, s[8:9]
	s_add_u32 m0, s97, 0x6000
	s_add_u32 s8, s98, 0x60000
	s_addc_u32 s9, s99, 0
	global_load_lds_dwordx4 v224, s[8:9]
	s_add_u32 m0, s97, 0x16000
	s_add_u32 s8, s100, 0x60000
	s_addc_u32 s9, s101, 0
	global_load_lds_dwordx4 v224, s[8:9]
	s_add_u32 m0, s97, 0x8000
	s_add_u32 s8, s98, 0x80
	s_addc_u32 s9, s99, 0
	global_load_lds_dwordx4 v224, s[8:9]
	s_add_u32 m0, s97, 0x18000
	s_add_u32 s8, s100, 0x80
	s_addc_u32 s9, s101, 0
	global_load_lds_dwordx4 v224, s[8:9]
	s_add_u32 m0, s97, 0xa000
	s_add_u32 s8, s98, 0x20080
	s_addc_u32 s9, s99, 0
	global_load_lds_dwordx4 v224, s[8:9]
	s_add_u32 m0, s97, 0x1a000
	s_add_u32 s8, s100, 0x20080
	s_addc_u32 s9, s101, 0
	global_load_lds_dwordx4 v224, s[8:9]
	s_add_u32 m0, s97, 0xc000
	s_add_u32 s8, s98, 0x40080
	s_addc_u32 s9, s99, 0
	global_load_lds_dwordx4 v224, s[8:9]
	s_add_u32 m0, s97, 0x1c000
	s_add_u32 s8, s100, 0x40080
	s_addc_u32 s9, s101, 0
	global_load_lds_dwordx4 v224, s[8:9]
	s_add_u32 m0, s97, 0xe000
	s_add_u32 s8, s98, 0x60080
	s_addc_u32 s9, s99, 0
	global_load_lds_dwordx4 v224, s[8:9]
	s_add_u32 m0, s97, 0x1e000
	s_add_u32 s8, s100, 0x60080
	s_addc_u32 s9, s101, 0
	global_load_lds_dwordx4 v224, s[8:9]
	s_add_u32 s98, s98, 0x100
	s_addc_u32 s99, s99, 0
	s_add_u32 s100, s100, 0x100
	s_addc_u32 s101, s101, 0
	s_waitcnt vmcnt(8)
	s_barrier
; #define G_LOAD(KT) do { _Pragma("unroll") for (int i = 0; i < 4; ++i) { ra[i] = *(const u32x4*)(Ag + (size_t)i * 64 * lda + (KT) * 64); rb[i] = *(const u32x4*)(Bg + (size_t)i * 64 * K + (KT) * 64); } } while (0)
; #define G_STORE(BUF) do { u16* ad = As + (BUF) * 256 * 64 + sto; u16* bd = Bs + (BUF) * 256 * 64 + sto; _Pragma("unroll") for (int i = 0; i < 4; ++i) { *(u32x4*)(ad + i * 64 * 64) = ra[i]; *(u32x4*)(bd + i * 64 * 64) = rb[i]; } } while (0)
; template <int EPI>
; DI void gemm_phase(const u16* __restrict__ A, int lda, const u16* __restrict__ Bt, int K, int N, u16* outb, int ldo,
;                    const float* r0, const float* r1, float* outf, char* lds, int bid, int nb) {
;     ...
;     G_LOAD(0);
;     G_STORE(0);
;     __syncthreads();
;     for (int kt = 0; kt < nk; ++kt) {
;       const int cur = kt & 1;
;       if (kt + 1 < nk) G_LOAD(kt + 1);
;       G_MMA(cur, fo0);
;       G_MMA(cur, fo1);
;       if (kt + 1 < nk) G_STORE(cur ^ 1);
	ds_read_b128 v[152:155], v227 offset:0
	ds_read_b128 v[156:159], v227 offset:2048
	ds_read_b128 v[160:163], v227 offset:4096
	ds_read_b128 v[164:167], v227 offset:6144
	ds_read_b128 v[188:191], v225 offset:0
	ds_read_b128 v[192:195], v225 offset:2048
	ds_read_b128 v[196:199], v225 offset:4096
	ds_read_b128 v[200:203], v225 offset:6144
	ds_read_b128 v[204:207], v225 offset:8192
	ds_read_b128 v[208:211], v225 offset:10240
	ds_read_b128 v[212:215], v225 offset:12288
	ds_read_b128 v[216:219], v225 offset:14336
	v_xor_b32_e32 v225, 0x8000, v225
	v_xor_b32_e32 v227, 0x8000, v227
	s_waitcnt lgkmcnt(0)
	s_bitcmp1_b32 s97, 12
	s_cbranch_scc0 .Lgm1_noprio
	s_setprio 1
.Lgm1_noprio:
.Lgm1_loop:
	s_waitcnt lgkmcnt(4)
	v_mfma_f32_16x16x32_bf16 v[124:127], v[152:155], v[188:191], v[124:127]
	v_mfma_f32_16x16x32_bf16 v[120:123], v[156:159], v[188:191], v[120:123]
	v_mfma_f32_16x16x32_bf16 v[116:119], v[160:163], v[188:191], v[116:119]
	v_mfma_f32_16x16x32_bf16 v[112:115], v[164:167], v[188:191], v[112:115]
	ds_read_b128 v[188:191], v226 offset:0
	ds_read_b128 v[168:171], v228 offset:0
	v_mfma_f32_16x16x32_bf16 v[108:111], v[152:155], v[192:195], v[108:111]
	v_mfma_f32_16x16x32_bf16 v[104:107], v[156:159], v[192:195], v[104:107]
	v_mfma_f32_16x16x32_bf16 v[100:103], v[160:163], v[192:195], v[100:103]
	v_mfma_f32_16x16x32_bf16 v[96:99], v[164:167], v[192:195], v[96:99]
	ds_read_b128 v[192:195], v226 offset:2048
	ds_read_b128 v[176:179], v228 offset:2048
	v_mfma_f32_16x16x32_bf16 v[92:95], v[152:155], v[196:199], v[92:95]
	v_mfma_f32_16x16x32_bf16 v[88:91], v[156:159], v[196:199], v[88:91]
	v_mfma_f32_16x16x32_bf16 v[84:87], v[160:163], v[196:199], v[84:87]
	v_mfma_f32_16x16x32_bf16 v[80:83], v[164:167], v[196:199], v[80:83]
	ds_read_b128 v[196:199], v226 offset:4096
	ds_read_b128 v[180:183], v228 offset:4096
	v_mfma_f32_16x16x32_bf16 v[76:79], v[152:155], v[200:203], v[76:79]
	v_mfma_f32_16x16x32_bf16 v[72:75], v[156:159], v[200:203], v[72:75]
	v_mfma_f32_16x16x32_bf16 v[68:71], v[160:163], v[200:203], v[68:71]
	v_mfma_f32_16x16x32_bf16 v[64:67], v[164:167], v[200:203], v[64:67]
	ds_read_b128 v[200:203], v226 offset:6144
	ds_read_b128 v[184:187], v228 offset:6144
	s_waitcnt lgkmcnt(11)
	v_mfma_f32_16x16x32_bf16 v[60:63], v[152:155], v[204:207], v[60:63]
	v_mfma_f32_16x16x32_bf16 v[56:59], v[156:159], v[204:207], v[56:59]
	v_mfma_f32_16x16x32_bf16 v[52:55], v[160:163], v[204:207], v[52:55]
	v_mfma_f32_16x16x32_bf16 v[48:51], v[164:167], v[204:207], v[48:51]
	ds_read_b128 v[204:207], v226 offset:8192
	ds_read_b128 v[220:223], v226 offset:14336
	s_waitcnt lgkmcnt(11)
	v_mfma_f32_16x16x32_bf16 v[44:47], v[152:155], v[208:211], v[44:47]
	v_mfma_f32_16x16x32_bf16 v[40:43], v[156:159], v[208:211], v[40:43]
	v_mfma_f32_16x16x32_bf16 v[36:39], v[160:163], v[208:211], v[36:39]
	v_mfma_f32_16x16x32_bf16 v[32:35], v[164:167], v[208:211], v[32:35]
	ds_read_b128 v[208:211], v226 offset:10240
	s_waitcnt lgkmcnt(11)
	v_mfma_f32_16x16x32_bf16 v[28:31], v[152:155], v[212:215], v[28:31]
	v_mfma_f32_16x16x32_bf16 v[24:27], v[156:159], v[212:215], v[24:27]
	v_mfma_f32_16x16x32_bf16 v[20:23], v[160:163], v[212:215], v[20:23]
	v_mfma_f32_16x16x32_bf16 v[16:19], v[164:167], v[212:215], v[16:19]
	ds_read_b128 v[212:215], v226 offset:12288
	v_mfma_f32_16x16x32_bf16 v[12:15], v[152:155], v[216:219], v[12:15]
	v_mfma_f32_16x16x32_bf16 v[8:11], v[156:159], v[216:219], v[8:11]
	v_mfma_f32_16x16x32_bf16 v[4:7], v[160:163], v[216:219], v[4:7]
	v_mfma_f32_16x16x32_bf16 v[0:3], v[164:167], v[216:219], v[0:3]
	s_waitcnt vmcnt(0) lgkmcnt(0)
	s_barrier
	v_mfma_f32_16x16x32_bf16 v[124:127], v[168:171], v[188:191], v[124:127]
	v_mfma_f32_16x16x32_bf16 v[120:123], v[176:179], v[188:191], v[120:123]
	v_mfma_f32_16x16x32_bf16 v[116:119], v[180:183], v[188:191], v[116:119]
	v_mfma_f32_16x16x32_bf16 v[112:115], v[184:187], v[188:191], v[112:115]
	ds_read_b128 v[188:191], v225 offset:0
	ds_read_b128 v[152:155], v227 offset:0
	s_add_u32 m0, s97, 0x0
	s_add_u32 s8, s98, 0x0
	s_addc_u32 s9, s99, 0
	global_load_lds_dwordx4 v224, s[8:9]
	v_mfma_f32_16x16x32_bf16 v[108:111], v[168:171], v[192:195], v[108:111]
	v_mfma_f32_16x16x32_bf16 v[104:107], v[176:179], v[192:195], v[104:107]
	v_mfma_f32_16x16x32_bf16 v[100:103], v[180:183], v[192:195], v[100:103]
	v_mfma_f32_16x16x32_bf16 v[96:99], v[184:187], v[192:195], v[96:99]
	ds_read_b128 v[192:195], v225 offset:2048
	ds_read_b128 v[156:159], v227 offset:2048
	s_add_u32 m0, s97, 0x10000
	s_add_u32 s8, s100, 0x0
	s_addc_u32 s9, s101, 0
	global_load_lds_dwordx4 v224, s[8:9]
	v_mfma_f32_16x16x32_bf16 v[92:95], v[168:171], v[196:199], v[92:95]
	v_mfma_f32_16x16x32_bf16 v[88:91], v[176:179], v[196:199], v[88:91]
	v_mfma_f32_16x16x32_bf16 v[84:87], v[180:183], v[196:199], v[84:87]
	v_mfma_f32_16x16x32_bf16 v[80:83], v[184:187], v[196:199], v[80:83]
	ds_read_b128 v[196:199], v225 offset:4096
	ds_read_b128 v[160:163], v227 offset:4096
	s_add_u32 m0, s97, 0x2000
	s_add_u32 s8, s98, 0x20000
	s_addc_u32 s9, s99, 0
	global_load_lds_dwordx4 v224, s[8:9]
	v_mfma_f32_16x16x32_bf16 v[76:79], v[168:171], v[200:203], v[76:79]
	v_mfma_f32_16x16x32_bf16 v[72:75], v[176:179], v[200:203], v[72:75]
	v_mfma_f32_16x16x32_bf16 v[68:71], v[180:183], v[200:203], v[68:71]
	v_mfma_f32_16x16x32_bf16 v[64:67], v[184:187], v[200:203], v[64:67]
	ds_read_b128 v[200:203], v225 offset:6144
	ds_read_b128 v[164:167], v227 offset:6144
	s_add_u32 m0, s97, 0x12000
	s_add_u32 s8, s100, 0x20000
	s_addc_u32 s9, s101, 0
	global_load_lds_dwordx4 v224, s[8:9]
	v_mfma_f32_16x16x32_bf16 v[60:63], v[168:171], v[204:207], v[60:63]
	v_mfma_f32_16x16x32_bf16 v[56:59], v[176:179], v[204:207], v[56:59]
; #define G_LOAD(KT) do { _Pragma("unroll") for (int i = 0; i < 4; ++i) { ra[i] = *(const u32x4*)(Ag + (size_t)i * 64 * lda + (KT) * 64); rb[i] = *(const u32x4*)(Bg + (size_t)i * 64 * K + (KT) * 64); } } while (0)
; #define G_STORE(BUF) do { u16* ad = As + (BUF) * 256 * 64 + sto; u16* bd = Bs + (BUF) * 256 * 64 + sto; _Pragma("unroll") for (int i = 0; i < 4; ++i) { *(u32x4*)(ad + i * 64 * 64) = ra[i]; *(u32x4*)(bd + i * 64 * 64) = rb[i]; } } while (0)
; template <int EPI>
; DI void gemm_phase(const u16* __restrict__ A, int lda, const u16* __restrict__ Bt, int K, int N, u16* outb, int ldo,
;                    const float* r0, const float* r1, float* outf, char* lds, int bid, int nb) {
;     ...
;     for (int kt = 0; kt < nk; ++kt) {
;       const int cur = kt & 1;
;       if (kt + 1 < nk) G_LOAD(kt + 1);
;       G_MMA(cur, fo0);
;       G_MMA(cur, fo1);
;       if (kt + 1 < nk) G_STORE(cur ^ 1);
;       __syncthreads();
;     }
	v_mfma_f32_16x16x32_bf16 v[52:55], v[180:183], v[204:207], v[52:55]
	v_mfma_f32_16x16x32_bf16 v[48:51], v[184:187], v[204:207], v[48:51]
	ds_read_b128 v[204:207], v225 offset:8192
	ds_read_b128 v[216:219], v225 offset:14336
	s_add_u32 m0, s97, 0x4000
	s_add_u32 s8, s98, 0x40000
	s_addc_u32 s9, s99, 0
	global_load_lds_dwordx4 v224, s[8:9]
	v_mfma_f32_16x16x32_bf16 v[44:47], v[168:171], v[208:211], v[44:47]
	v_mfma_f32_16x16x32_bf16 v[40:43], v[176:179], v[208:211], v[40:43]
	v_mfma_f32_16x16x32_bf16 v[36:39], v[180:183], v[208:211], v[36:39]
	v_mfma_f32_16x16x32_bf16 v[32:35], v[184:187], v[208:211], v[32:35]
	ds_read_b128 v[208:211], v225 offset:10240
	s_add_u32 m0, s97, 0x14000
	s_add_u32 s8, s100, 0x40000
	s_addc_u32 s9, s101, 0
	global_load_lds_dwordx4 v224, s[8:9]
	v_mfma_f32_16x16x32_bf16 v[28:31], v[168:171], v[212:215], v[28:31]
	v_mfma_f32_16x16x32_bf16 v[24:27], v[176:179], v[212:215], v[24:27]
	v_mfma_f32_16x16x32_bf16 v[20:23], v[180:183], v[212:215], v[20:23]
	v_mfma_f32_16x16x32_bf16 v[16:19], v[184:187], v[212:215], v[16:19]
	ds_read_b128 v[212:215], v225 offset:12288
	s_add_u32 m0, s97, 0x6000
	s_add_u32 s8, s98, 0x60000
	s_addc_u32 s9, s99, 0
	global_load_lds_dwordx4 v224, s[8:9]
	v_mfma_f32_16x16x32_bf16 v[12:15], v[168:171], v[220:223], v[12:15]
	v_mfma_f32_16x16x32_bf16 v[8:11], v[176:179], v[220:223], v[8:11]
	v_mfma_f32_16x16x32_bf16 v[4:7], v[180:183], v[220:223], v[4:7]
	v_mfma_f32_16x16x32_bf16 v[0:3], v[184:187], v[220:223], v[0:3]
	s_add_u32 m0, s97, 0x16000
	s_add_u32 s8, s100, 0x60000
	s_addc_u32 s9, s101, 0
	global_load_lds_dwordx4 v224, s[8:9]
	v_xor_b32_e32 v225, 0x8000, v225
	v_xor_b32_e32 v227, 0x8000, v227
	v_xor_b32_e32 v226, 0x8000, v226
	v_xor_b32_e32 v228, 0x8000, v228
	s_xor_b32 s97, s97, 0x8000
	s_add_u32 s98, s98, 0x80
	s_addc_u32 s99, s99, 0
	s_add_u32 s100, s100, 0x80
	s_addc_u32 s101, s101, 0
	s_sub_u32 s28, s28, 1
	s_cmp_lg_u32 s28, 0
	s_cbranch_scc1 .Lgm1_loop
	s_waitcnt lgkmcnt(4)
	v_mfma_f32_16x16x32_bf16 v[124:127], v[152:155], v[188:191], v[124:127]
	v_mfma_f32_16x16x32_bf16 v[120:123], v[156:159], v[188:191], v[120:123]
	v_mfma_f32_16x16x32_bf16 v[116:119], v[160:163], v[188:191], v[116:119]
	v_mfma_f32_16x16x32_bf16 v[112:115], v[164:167], v[188:191], v[112:115]
	ds_read_b128 v[188:191], v226 offset:0
	ds_read_b128 v[168:171], v228 offset:0
	v_mfma_f32_16x16x32_bf16 v[108:111], v[152:155], v[192:195], v[108:111]
	v_mfma_f32_16x16x32_bf16 v[104:107], v[156:159], v[192:195], v[104:107]
	v_mfma_f32_16x16x32_bf16 v[100:103], v[160:163], v[192:195], v[100:103]
	v_mfma_f32_16x16x32_bf16 v[96:99], v[164:167], v[192:195], v[96:99]
	ds_read_b128 v[192:195], v226 offset:2048
	ds_read_b128 v[176:179], v228 offset:2048
	v_mfma_f32_16x16x32_bf16 v[92:95], v[152:155], v[196:199], v[92:95]
	v_mfma_f32_16x16x32_bf16 v[88:91], v[156:159], v[196:199], v[88:91]
	v_mfma_f32_16x16x32_bf16 v[84:87], v[160:163], v[196:199], v[84:87]
	v_mfma_f32_16x16x32_bf16 v[80:83], v[164:167], v[196:199], v[80:83]
	ds_read_b128 v[196:199], v226 offset:4096
	ds_read_b128 v[180:183], v228 offset:4096
	v_mfma_f32_16x16x32_bf16 v[76:79], v[152:155], v[200:203], v[76:79]
	v_mfma_f32_16x16x32_bf16 v[72:75], v[156:159], v[200:203], v[72:75]
	v_mfma_f32_16x16x32_bf16 v[68:71], v[160:163], v[200:203], v[68:71]
	v_mfma_f32_16x16x32_bf16 v[64:67], v[164:167], v[200:203], v[64:67]
	ds_read_b128 v[200:203], v226 offset:6144
	ds_read_b128 v[184:187], v228 offset:6144
	s_waitcnt lgkmcnt(11)
	v_mfma_f32_16x16x32_bf16 v[60:63], v[152:155], v[204:207], v[60:63]
	v_mfma_f32_16x16x32_bf16 v[56:59], v[156:159], v[204:207], v[56:59]
	v_mfma_f32_16x16x32_bf16 v[52:55], v[160:163], v[204:207], v[52:55]
	v_mfma_f32_16x16x32_bf16 v[48:51], v[164:167], v[204:207], v[48:51]
	ds_read_b128 v[204:207], v226 offset:8192
	ds_read_b128 v[220:223], v226 offset:14336
	s_waitcnt lgkmcnt(11)
	v_mfma_f32_16x16x32_bf16 v[44:47], v[152:155], v[208:211], v[44:47]
	v_mfma_f32_16x16x32_bf16 v[40:43], v[156:159], v[208:211], v[40:43]
	v_mfma_f32_16x16x32_bf16 v[36:39], v[160:163], v[208:211], v[36:39]
	v_mfma_f32_16x16x32_bf16 v[32:35], v[164:167], v[208:211], v[32:35]
	ds_read_b128 v[208:211], v226 offset:10240
	s_waitcnt lgkmcnt(11)
	v_mfma_f32_16x16x32_bf16 v[28:31], v[152:155], v[212:215], v[28:31]
	v_mfma_f32_16x16x32_bf16 v[24:27], v[156:159], v[212:215], v[24:27]
	v_mfma_f32_16x16x32_bf16 v[20:23], v[160:163], v[212:215], v[20:23]
	v_mfma_f32_16x16x32_bf16 v[16:19], v[164:167], v[212:215], v[16:19]
	ds_read_b128 v[212:215], v226 offset:12288
	v_mfma_f32_16x16x32_bf16 v[12:15], v[152:155], v[216:219], v[12:15]
	v_mfma_f32_16x16x32_bf16 v[8:11], v[156:159], v[216:219], v[8:11]
	v_mfma_f32_16x16x32_bf16 v[4:7], v[160:163], v[216:219], v[4:7]
	v_mfma_f32_16x16x32_bf16 v[0:3], v[164:167], v[216:219], v[0:3]
	s_waitcnt vmcnt(0) lgkmcnt(0)
	s_barrier
; #define G_LOAD(KT) do { _Pragma("unroll") for (int i = 0; i < 4; ++i) { ra[i] = *(const u32x4*)(Ag + (size_t)i * 64 * lda + (KT) * 64); rb[i] = *(const u32x4*)(Bg + (size_t)i * 64 * K + (KT) * 64); } } while (0)
; #define G_STORE(BUF) do { u16* ad = As + (BUF) * 256 * 64 + sto; u16* bd = Bs + (BUF) * 256 * 64 + sto; _Pragma("unroll") for (int i = 0; i < 4; ++i) { *(u32x4*)(ad + i * 64 * 64) = ra[i]; *(u32x4*)(bd + i * 64 * 64) = rb[i]; } } while (0)
; template <int EPI>
; DI void gemm_phase(const u16* __restrict__ A, int lda, const u16* __restrict__ Bt, int K, int N, u16* outb, int ldo,
;                    const float* r0, const float* r1, float* outf, char* lds, int bid, int nb) {
;     ...
;     G_LOAD(0);
;     G_STORE(0);
;     __syncthreads();
;     for (int kt = 0; kt < nk; ++kt) {
;       const int cur = kt & 1;
;       if (kt + 1 < nk) G_LOAD(kt + 1);
;       G_MMA(cur, fo0);
;       G_MMA(cur, fo1);
;       if (kt + 1 < nk) G_STORE(cur ^ 1);
;       __syncthreads();
	v_mfma_f32_16x16x32_bf16 v[124:127], v[168:171], v[188:191], v[124:127]
	v_mfma_f32_16x16x32_bf16 v[120:123], v[176:179], v[188:191], v[120:123]
	v_mfma_f32_16x16x32_bf16 v[116:119], v[180:183], v[188:191], v[116:119]
	v_mfma_f32_16x16x32_bf16 v[112:115], v[184:187], v[188:191], v[112:115]
	ds_read_b128 v[188:191], v225 offset:0
	ds_read_b128 v[152:155], v227 offset:0
	v_mfma_f32_16x16x32_bf16 v[108:111], v[168:171], v[192:195], v[108:111]
	v_mfma_f32_16x16x32_bf16 v[104:107], v[176:179], v[192:195], v[104:107]
	v_mfma_f32_16x16x32_bf16 v[100:103], v[180:183], v[192:195], v[100:103]
	v_mfma_f32_16x16x32_bf16 v[96:99], v[184:187], v[192:195], v[96:99]
	ds_read_b128 v[192:195], v225 offset:2048
	ds_read_b128 v[156:159], v227 offset:2048
	v_mfma_f32_16x16x32_bf16 v[92:95], v[168:171], v[196:199], v[92:95]
	v_mfma_f32_16x16x32_bf16 v[88:91], v[176:179], v[196:199], v[88:91]
	v_mfma_f32_16x16x32_bf16 v[84:87], v[180:183], v[196:199], v[84:87]
	v_mfma_f32_16x16x32_bf16 v[80:83], v[184:187], v[196:199], v[80:83]
	ds_read_b128 v[196:199], v225 offset:4096
	ds_read_b128 v[160:163], v227 offset:4096
	v_mfma_f32_16x16x32_bf16 v[76:79], v[168:171], v[200:203], v[76:79]
	v_mfma_f32_16x16x32_bf16 v[72:75], v[176:179], v[200:203], v[72:75]
	v_mfma_f32_16x16x32_bf16 v[68:71], v[180:183], v[200:203], v[68:71]
	v_mfma_f32_16x16x32_bf16 v[64:67], v[184:187], v[200:203], v[64:67]
	ds_read_b128 v[200:203], v225 offset:6144
	ds_read_b128 v[164:167], v227 offset:6144
	v_mfma_f32_16x16x32_bf16 v[60:63], v[168:171], v[204:207], v[60:63]
	v_mfma_f32_16x16x32_bf16 v[56:59], v[176:179], v[204:207], v[56:59]
	v_mfma_f32_16x16x32_bf16 v[52:55], v[180:183], v[204:207], v[52:55]
	v_mfma_f32_16x16x32_bf16 v[48:51], v[184:187], v[204:207], v[48:51]
	ds_read_b128 v[204:207], v225 offset:8192
	ds_read_b128 v[216:219], v225 offset:14336
	v_mfma_f32_16x16x32_bf16 v[44:47], v[168:171], v[208:211], v[44:47]
	v_mfma_f32_16x16x32_bf16 v[40:43], v[176:179], v[208:211], v[40:43]
	v_mfma_f32_16x16x32_bf16 v[36:39], v[180:183], v[208:211], v[36:39]
	v_mfma_f32_16x16x32_bf16 v[32:35], v[184:187], v[208:211], v[32:35]
	ds_read_b128 v[208:211], v225 offset:10240
	v_mfma_f32_16x16x32_bf16 v[28:31], v[168:171], v[212:215], v[28:31]
	v_mfma_f32_16x16x32_bf16 v[24:27], v[176:179], v[212:215], v[24:27]
	v_mfma_f32_16x16x32_bf16 v[20:23], v[180:183], v[212:215], v[20:23]
	v_mfma_f32_16x16x32_bf16 v[16:19], v[184:187], v[212:215], v[16:19]
	ds_read_b128 v[212:215], v225 offset:12288
	v_mfma_f32_16x16x32_bf16 v[12:15], v[168:171], v[220:223], v[12:15]
	v_mfma_f32_16x16x32_bf16 v[8:11], v[176:179], v[220:223], v[8:11]
	v_mfma_f32_16x16x32_bf16 v[4:7], v[180:183], v[220:223], v[4:7]
	v_mfma_f32_16x16x32_bf16 v[0:3], v[184:187], v[220:223], v[0:3]
	v_xor_b32_e32 v226, 0x8000, v226
	v_xor_b32_e32 v228, 0x8000, v228
	s_waitcnt lgkmcnt(4)
	v_mfma_f32_16x16x32_bf16 v[124:127], v[152:155], v[188:191], v[124:127]
	v_mfma_f32_16x16x32_bf16 v[120:123], v[156:159], v[188:191], v[120:123]
	v_mfma_f32_16x16x32_bf16 v[116:119], v[160:163], v[188:191], v[116:119]
	v_mfma_f32_16x16x32_bf16 v[112:115], v[164:167], v[188:191], v[112:115]
	ds_read_b128 v[188:191], v226 offset:0
	ds_read_b128 v[168:171], v228 offset:0
	v_mfma_f32_16x16x32_bf16 v[108:111], v[152:155], v[192:195], v[108:111]
	v_mfma_f32_16x16x32_bf16 v[104:107], v[156:159], v[192:195], v[104:107]
	v_mfma_f32_16x16x32_bf16 v[100:103], v[160:163], v[192:195], v[100:103]
	v_mfma_f32_16x16x32_bf16 v[96:99], v[164:167], v[192:195], v[96:99]
	ds_read_b128 v[192:195], v226 offset:2048
	ds_read_b128 v[176:179], v228 offset:2048
	v_mfma_f32_16x16x32_bf16 v[92:95], v[152:155], v[196:199], v[92:95]
	v_mfma_f32_16x16x32_bf16 v[88:91], v[156:159], v[196:199], v[88:91]
	v_mfma_f32_16x16x32_bf16 v[84:87], v[160:163], v[196:199], v[84:87]
	v_mfma_f32_16x16x32_bf16 v[80:83], v[164:167], v[196:199], v[80:83]
	ds_read_b128 v[196:199], v226 offset:4096
	ds_read_b128 v[180:183], v228 offset:4096
	v_mfma_f32_16x16x32_bf16 v[76:79], v[152:155], v[200:203], v[76:79]
	v_mfma_f32_16x16x32_bf16 v[72:75], v[156:159], v[200:203], v[72:75]
	v_mfma_f32_16x16x32_bf16 v[68:71], v[160:163], v[200:203], v[68:71]
	v_mfma_f32_16x16x32_bf16 v[64:67], v[164:167], v[200:203], v[64:67]
	ds_read_b128 v[200:203], v226 offset:6144
	ds_read_b128 v[184:187], v228 offset:6144
	s_waitcnt lgkmcnt(11)
	v_mfma_f32_16x16x32_bf16 v[60:63], v[152:155], v[204:207], v[60:63]
	v_mfma_f32_16x16x32_bf16 v[56:59], v[156:159], v[204:207], v[56:59]
	v_mfma_f32_16x16x32_bf16 v[52:55], v[160:163], v[204:207], v[52:55]
	v_mfma_f32_16x16x32_bf16 v[48:51], v[164:167], v[204:207], v[48:51]
	ds_read_b128 v[204:207], v226 offset:8192
	ds_read_b128 v[220:223], v226 offset:14336
	s_waitcnt lgkmcnt(11)
	v_mfma_f32_16x16x32_bf16 v[44:47], v[152:155], v[208:211], v[44:47]
	v_mfma_f32_16x16x32_bf16 v[40:43], v[156:159], v[208:211], v[40:43]
	v_mfma_f32_16x16x32_bf16 v[36:39], v[160:163], v[208:211], v[36:39]
	v_mfma_f32_16x16x32_bf16 v[32:35], v[164:167], v[208:211], v[32:35]
	ds_read_b128 v[208:211], v226 offset:10240
	s_waitcnt lgkmcnt(11)
	v_mfma_f32_16x16x32_bf16 v[28:31], v[152:155], v[212:215], v[28:31]
	v_mfma_f32_16x16x32_bf16 v[24:27], v[156:159], v[212:215], v[24:27]
	v_mfma_f32_16x16x32_bf16 v[20:23], v[160:163], v[212:215], v[20:23]
	v_mfma_f32_16x16x32_bf16 v[16:19], v[164:167], v[212:215], v[16:19]
	ds_read_b128 v[212:215], v226 offset:12288
	v_mfma_f32_16x16x32_bf16 v[12:15], v[152:155], v[216:219], v[12:15]
	v_mfma_f32_16x16x32_bf16 v[8:11], v[156:159], v[216:219], v[8:11]
	v_mfma_f32_16x16x32_bf16 v[4:7], v[160:163], v[216:219], v[4:7]
	v_mfma_f32_16x16x32_bf16 v[0:3], v[164:167], v[216:219], v[0:3]
	s_waitcnt vmcnt(0) lgkmcnt(0)
	s_barrier
; template <int EPI>
; DI void gemm_phase(const u16* __restrict__ A, int lda, const u16* __restrict__ Bt, int K, int N, u16* outb, int ldo,
;                    const float* r0, const float* r1, float* outf, char* lds, int bid, int nb) {
;     ...
;     } else if constexpr (EPI == EPI_RESID) {
;       const int col = tn * 256 + wc * 64 + l15;
;       const float* rb_ = (tm * 256 < M_P) ? r0 : (r1 - (size_t)M_P * DM);
; #pragma unroll
;       for (int i = 0; i < 8; ++i)
; #pragma unroll
;         for (int r = 0; r < 4; ++r) {
;           const size_t i0 = (size_t)(mrow + i * 16 + r) * DM + col;
;           const float x0 = rb_[i0], x1 = rb_[i0 + 16], x2 = rb_[i0 + 32], x3 = rb_[i0 + 48];
;           outf[i0] = x0 + acc[i][0][r]; outf[i0 + 16] = x1 + acc[i][1][r]; outf[i0 + 32] = x2 + acc[i][2][r]; outf[i0 + 48] = x3 + acc[i][3][r];
;         }
	v_mfma_f32_16x16x32_bf16 v[124:127], v[168:171], v[188:191], v[124:127]
	v_mfma_f32_16x16x32_bf16 v[120:123], v[176:179], v[188:191], v[120:123]
	v_mfma_f32_16x16x32_bf16 v[116:119], v[180:183], v[188:191], v[116:119]
	v_mfma_f32_16x16x32_bf16 v[112:115], v[184:187], v[188:191], v[112:115]
	v_mfma_f32_16x16x32_bf16 v[108:111], v[168:171], v[192:195], v[108:111]
	v_mfma_f32_16x16x32_bf16 v[104:107], v[176:179], v[192:195], v[104:107]
	v_mfma_f32_16x16x32_bf16 v[100:103], v[180:183], v[192:195], v[100:103]
	v_mfma_f32_16x16x32_bf16 v[96:99], v[184:187], v[192:195], v[96:99]
	v_mfma_f32_16x16x32_bf16 v[92:95], v[168:171], v[196:199], v[92:95]
	v_mfma_f32_16x16x32_bf16 v[88:91], v[176:179], v[196:199], v[88:91]
	v_mfma_f32_16x16x32_bf16 v[84:87], v[180:183], v[196:199], v[84:87]
	v_mfma_f32_16x16x32_bf16 v[80:83], v[184:187], v[196:199], v[80:83]
	v_mfma_f32_16x16x32_bf16 v[76:79], v[168:171], v[200:203], v[76:79]
	v_mfma_f32_16x16x32_bf16 v[72:75], v[176:179], v[200:203], v[72:75]
	v_mfma_f32_16x16x32_bf16 v[68:71], v[180:183], v[200:203], v[68:71]
	v_mfma_f32_16x16x32_bf16 v[64:67], v[184:187], v[200:203], v[64:67]
	v_mfma_f32_16x16x32_bf16 v[60:63], v[168:171], v[204:207], v[60:63]
	v_mfma_f32_16x16x32_bf16 v[56:59], v[176:179], v[204:207], v[56:59]
	v_mfma_f32_16x16x32_bf16 v[52:55], v[180:183], v[204:207], v[52:55]
	v_mfma_f32_16x16x32_bf16 v[48:51], v[184:187], v[204:207], v[48:51]
	v_mfma_f32_16x16x32_bf16 v[44:47], v[168:171], v[208:211], v[44:47]
	v_mfma_f32_16x16x32_bf16 v[40:43], v[176:179], v[208:211], v[40:43]
	v_mfma_f32_16x16x32_bf16 v[36:39], v[180:183], v[208:211], v[36:39]
	v_mfma_f32_16x16x32_bf16 v[32:35], v[184:187], v[208:211], v[32:35]
	v_mfma_f32_16x16x32_bf16 v[28:31], v[168:171], v[212:215], v[28:31]
	v_mfma_f32_16x16x32_bf16 v[24:27], v[176:179], v[212:215], v[24:27]
	v_mfma_f32_16x16x32_bf16 v[20:23], v[180:183], v[212:215], v[20:23]
	v_mfma_f32_16x16x32_bf16 v[16:19], v[184:187], v[212:215], v[16:19]
	v_mfma_f32_16x16x32_bf16 v[12:15], v[168:171], v[220:223], v[12:15]
	v_mfma_f32_16x16x32_bf16 v[8:11], v[176:179], v[220:223], v[8:11]
	v_mfma_f32_16x16x32_bf16 v[4:7], v[180:183], v[220:223], v[4:7]
	v_mfma_f32_16x16x32_bf16 v[0:3], v[184:187], v[220:223], v[0:3]
	s_setprio 0
	s_nop 7
	s_nop 3
	s_cmpk_lt_i32 s51, 0x80
	s_cselect_b32 s9, s37, s17
	s_cselect_b32 s8, s36, s16
	v_and_b32_e32 v225, 15, v174
	v_lshrrev_b32_e32 v226, 8, v174
	v_lshl_or_b32 v225, v226, 7, v225
	v_bfe_u32 v226, v174, 6, 2
	v_bfe_u32 v227, v174, 4, 2
	v_lshlrev_b32_e32 v227, 2, v227
	v_add_u32_e32 v225, s52, v225
	v_lshl_add_u32 v226, v226, 6, v227
	v_add_u32_e32 v226, s53, v226
	v_lshlrev_b32_e32 v226, 2, v226
	v_lshl_add_u32 v224, v225, 12, v226
	v_mov_b32_e32 v229, v224
	v_add_u32_e32 v224, 0x0, v229
	global_load_dwordx4 v[152:155], v224, s[8:9] offset:0
	global_load_dwordx4 v[156:159], v224, s[8:9] offset:64
	global_load_dwordx4 v[160:163], v224, s[8:9] offset:128
	global_load_dwordx4 v[164:167], v224, s[8:9] offset:192
	v_add_u32_e32 v228, 0x10000, v229
	global_load_dwordx4 v[168:171], v228, s[8:9] offset:0
	global_load_dwordx4 v[176:179], v228, s[8:9] offset:64
	global_load_dwordx4 v[180:183], v228, s[8:9] offset:128
	global_load_dwordx4 v[184:187], v228, s[8:9] offset:192
	s_waitcnt vmcnt(4)
	v_add_f32_e32 v152, v124, v152
	v_add_f32_e32 v153, v125, v153
	v_add_f32_e32 v154, v126, v154
	v_add_f32_e32 v155, v127, v155
	v_add_f32_e32 v156, v120, v156
	v_add_f32_e32 v157, v121, v157
	v_add_f32_e32 v158, v122, v158
	v_add_f32_e32 v159, v123, v159
	v_add_f32_e32 v160, v116, v160
	v_add_f32_e32 v161, v117, v161
	v_add_f32_e32 v162, v118, v162
	v_add_f32_e32 v163, v119, v163
	v_add_f32_e32 v164, v112, v164
	v_add_f32_e32 v165, v113, v165
	v_add_f32_e32 v166, v114, v166
	v_add_f32_e32 v167, v115, v167
	global_store_dwordx4 v224, v[152:155], s[22:23] offset:0
	global_store_dwordx4 v224, v[156:159], s[22:23] offset:64
	global_store_dwordx4 v224, v[160:163], s[22:23] offset:128
	global_store_dwordx4 v224, v[164:167], s[22:23] offset:192
	s_nop 1
	v_add_u32_e32 v224, 0x20000, v229
	global_load_dwordx4 v[152:155], v224, s[8:9] offset:0
	global_load_dwordx4 v[156:159], v224, s[8:9] offset:64
	global_load_dwordx4 v[160:163], v224, s[8:9] offset:128
	global_load_dwordx4 v[164:167], v224, s[8:9] offset:192
	s_waitcnt vmcnt(8)
	v_add_f32_e32 v168, v108, v168
	v_add_f32_e32 v169, v109, v169
	v_add_f32_e32 v170, v110, v170
	v_add_f32_e32 v171, v111, v171
	v_add_f32_e32 v176, v104, v176
	v_add_f32_e32 v177, v105, v177
	v_add_f32_e32 v178, v106, v178
	v_add_f32_e32 v179, v107, v179
	v_add_f32_e32 v180, v100, v180
	v_add_f32_e32 v181, v101, v181
	v_add_f32_e32 v182, v102, v182
	v_add_f32_e32 v183, v103, v183
	v_add_f32_e32 v184, v96, v184
	v_add_f32_e32 v185, v97, v185
	v_add_f32_e32 v186, v98, v186
	v_add_f32_e32 v187, v99, v187
	global_store_dwordx4 v228, v[168:171], s[22:23] offset:0
	global_store_dwordx4 v228, v[176:179], s[22:23] offset:64
	global_store_dwordx4 v228, v[180:183], s[22:23] offset:128
	global_store_dwordx4 v228, v[184:187], s[22:23] offset:192
	s_nop 1
	v_add_u32_e32 v228, 0x30000, v229
	global_load_dwordx4 v[168:171], v228, s[8:9] offset:0
	global_load_dwordx4 v[176:179], v228, s[8:9] offset:64
	global_load_dwordx4 v[180:183], v228, s[8:9] offset:128
	global_load_dwordx4 v[184:187], v228, s[8:9] offset:192
	s_waitcnt vmcnt(8)
; template <int EPI>
; DI void gemm_phase(const u16* __restrict__ A, int lda, const u16* __restrict__ Bt, int K, int N, u16* outb, int ldo,
;                    const float* r0, const float* r1, float* outf, char* lds, int bid, int nb) {
;     ...
;       for (int i = 0; i < 8; ++i)
; #pragma unroll
;         for (int r = 0; r < 4; ++r) {
;           const size_t i0 = (size_t)(mrow + i * 16 + r) * DM + col;
;           const float x0 = rb_[i0], x1 = rb_[i0 + 16], x2 = rb_[i0 + 32], x3 = rb_[i0 + 48];
;           outf[i0] = x0 + acc[i][0][r]; outf[i0 + 16] = x1 + acc[i][1][r]; outf[i0 + 32] = x2 + acc[i][2][r]; outf[i0 + 48] = x3 + acc[i][3][r];
;         }
	v_add_f32_e32 v152, v92, v152
	v_add_f32_e32 v153, v93, v153
	v_add_f32_e32 v154, v94, v154
	v_add_f32_e32 v155, v95, v155
	v_add_f32_e32 v156, v88, v156
	v_add_f32_e32 v157, v89, v157
	v_add_f32_e32 v158, v90, v158
	v_add_f32_e32 v159, v91, v159
	v_add_f32_e32 v160, v84, v160
	v_add_f32_e32 v161, v85, v161
	v_add_f32_e32 v162, v86, v162
	v_add_f32_e32 v163, v87, v163
	v_add_f32_e32 v164, v80, v164
	v_add_f32_e32 v165, v81, v165
	v_add_f32_e32 v166, v82, v166
	v_add_f32_e32 v167, v83, v167
	global_store_dwordx4 v224, v[152:155], s[22:23] offset:0
	global_store_dwordx4 v224, v[156:159], s[22:23] offset:64
	global_store_dwordx4 v224, v[160:163], s[22:23] offset:128
	global_store_dwordx4 v224, v[164:167], s[22:23] offset:192
	s_nop 1
	v_add_u32_e32 v224, 0x40000, v229
	global_load_dwordx4 v[152:155], v224, s[8:9] offset:0
	global_load_dwordx4 v[156:159], v224, s[8:9] offset:64
	global_load_dwordx4 v[160:163], v224, s[8:9] offset:128
	global_load_dwordx4 v[164:167], v224, s[8:9] offset:192
	s_waitcnt vmcnt(8)
	v_add_f32_e32 v168, v76, v168
	v_add_f32_e32 v169, v77, v169
	v_add_f32_e32 v170, v78, v170
	v_add_f32_e32 v171, v79, v171
	v_add_f32_e32 v176, v72, v176
	v_add_f32_e32 v177, v73, v177
	v_add_f32_e32 v178, v74, v178
	v_add_f32_e32 v179, v75, v179
	v_add_f32_e32 v180, v68, v180
	v_add_f32_e32 v181, v69, v181
	v_add_f32_e32 v182, v70, v182
	v_add_f32_e32 v183, v71, v183
	v_add_f32_e32 v184, v64, v184
	v_add_f32_e32 v185, v65, v185
	v_add_f32_e32 v186, v66, v186
	v_add_f32_e32 v187, v67, v187
	global_store_dwordx4 v228, v[168:171], s[22:23] offset:0
	global_store_dwordx4 v228, v[176:179], s[22:23] offset:64
	global_store_dwordx4 v228, v[180:183], s[22:23] offset:128
	global_store_dwordx4 v228, v[184:187], s[22:23] offset:192
	s_nop 1
	v_add_u32_e32 v228, 0x50000, v229
	global_load_dwordx4 v[168:171], v228, s[8:9] offset:0
	global_load_dwordx4 v[176:179], v228, s[8:9] offset:64
	global_load_dwordx4 v[180:183], v228, s[8:9] offset:128
	global_load_dwordx4 v[184:187], v228, s[8:9] offset:192
	s_waitcnt vmcnt(8)
	v_add_f32_e32 v152, v60, v152
	v_add_f32_e32 v153, v61, v153
	v_add_f32_e32 v154, v62, v154
	v_add_f32_e32 v155, v63, v155
	v_add_f32_e32 v156, v56, v156
	v_add_f32_e32 v157, v57, v157
	v_add_f32_e32 v158, v58, v158
	v_add_f32_e32 v159, v59, v159
	v_add_f32_e32 v160, v52, v160
	v_add_f32_e32 v161, v53, v161
	v_add_f32_e32 v162, v54, v162
	v_add_f32_e32 v163, v55, v163
	v_add_f32_e32 v164, v48, v164
	v_add_f32_e32 v165, v49, v165
	v_add_f32_e32 v166, v50, v166
	v_add_f32_e32 v167, v51, v167
	global_store_dwordx4 v224, v[152:155], s[22:23] offset:0
	global_store_dwordx4 v224, v[156:159], s[22:23] offset:64
	global_store_dwordx4 v224, v[160:163], s[22:23] offset:128
	global_store_dwordx4 v224, v[164:167], s[22:23] offset:192
	s_nop 1
	v_add_u32_e32 v224, 0x60000, v229
	global_load_dwordx4 v[152:155], v224, s[8:9] offset:0
	global_load_dwordx4 v[156:159], v224, s[8:9] offset:64
	global_load_dwordx4 v[160:163], v224, s[8:9] offset:128
	global_load_dwordx4 v[164:167], v224, s[8:9] offset:192
	s_waitcnt vmcnt(8)
	v_add_f32_e32 v168, v44, v168
	v_add_f32_e32 v169, v45, v169
	v_add_f32_e32 v170, v46, v170
	v_add_f32_e32 v171, v47, v171
	v_add_f32_e32 v176, v40, v176
	v_add_f32_e32 v177, v41, v177
	v_add_f32_e32 v178, v42, v178
	v_add_f32_e32 v179, v43, v179
	v_add_f32_e32 v180, v36, v180
	v_add_f32_e32 v181, v37, v181
	v_add_f32_e32 v182, v38, v182
	v_add_f32_e32 v183, v39, v183
	v_add_f32_e32 v184, v32, v184
	v_add_f32_e32 v185, v33, v185
	v_add_f32_e32 v186, v34, v186
	v_add_f32_e32 v187, v35, v187
	global_store_dwordx4 v228, v[168:171], s[22:23] offset:0
	global_store_dwordx4 v228, v[176:179], s[22:23] offset:64
	global_store_dwordx4 v228, v[180:183], s[22:23] offset:128
	global_store_dwordx4 v228, v[184:187], s[22:23] offset:192
	s_nop 1
	v_add_u32_e32 v228, 0x70000, v229
	global_load_dwordx4 v[168:171], v228, s[8:9] offset:0
	global_load_dwordx4 v[176:179], v228, s[8:9] offset:64
	global_load_dwordx4 v[180:183], v228, s[8:9] offset:128
	global_load_dwordx4 v[184:187], v228, s[8:9] offset:192
	s_waitcnt vmcnt(8)
	v_add_f32_e32 v152, v28, v152
	v_add_f32_e32 v153, v29, v153
	v_add_f32_e32 v154, v30, v154
	v_add_f32_e32 v155, v31, v155
	v_add_f32_e32 v156, v24, v156
	v_add_f32_e32 v157, v25, v157
	v_add_f32_e32 v158, v26, v158
	v_add_f32_e32 v159, v27, v159
	v_add_f32_e32 v160, v20, v160
	v_add_f32_e32 v161, v21, v161
	v_add_f32_e32 v162, v22, v162
	v_add_f32_e32 v163, v23, v163
	v_add_f32_e32 v164, v16, v164
	v_add_f32_e32 v165, v17, v165
	v_add_f32_e32 v166, v18, v166
	v_add_f32_e32 v167, v19, v167
	global_store_dwordx4 v224, v[152:155], s[22:23] offset:0
	global_store_dwordx4 v224, v[156:159], s[22:23] offset:64
	global_store_dwordx4 v224, v[160:163], s[22:23] offset:128
	global_store_dwordx4 v224, v[164:167], s[22:23] offset:192
	s_waitcnt vmcnt(4)
	v_add_f32_e32 v168, v12, v168
	v_add_f32_e32 v169, v13, v169
	v_add_f32_e32 v170, v14, v170
	v_add_f32_e32 v171, v15, v171
	v_add_f32_e32 v176, v8, v176
	v_add_f32_e32 v177, v9, v177
	v_add_f32_e32 v178, v10, v178
	v_add_f32_e32 v179, v11, v179
	v_add_f32_e32 v180, v4, v180
	v_add_f32_e32 v181, v5, v181
	v_add_f32_e32 v182, v6, v182
	v_add_f32_e32 v183, v7, v183
	v_add_f32_e32 v184, v0, v184
	v_add_f32_e32 v185, v1, v185
	v_add_f32_e32 v186, v2, v186
	v_add_f32_e32 v187, v3, v187
	global_store_dwordx4 v228, v[168:171], s[22:23] offset:0
	global_store_dwordx4 v228, v[176:179], s[22:23] offset:64
	global_store_dwordx4 v228, v[180:183], s[22:23] offset:128
	global_store_dwordx4 v228, v[184:187], s[22:23] offset:192
	s_add_i32 s18, s18, 1
	s_cmp_eq_u32 s18, s3
	s_cbranch_scc0 .LBB0_577

; #define G_LOAD(KT) do { _Pragma("unroll") for (int i = 0; i < 4; ++i) { ra[i] = *(const u32x4*)(Ag + (size_t)i * 64 * lda + (KT) * 64); rb[i] = *(const u32x4*)(Bg + (size_t)i * 64 * K + (KT) * 64); } } while (0)
; #define G_STORE(BUF) do { u16* ad = As + (BUF) * 256 * 64 + sto; u16* bd = Bs + (BUF) * 256 * 64 + sto; _Pragma("unroll") for (int i = 0; i < 4; ++i) { *(u32x4*)(ad + i * 64 * 64) = ra[i]; *(u32x4*)(bd + i * 64 * 64) = rb[i]; } } while (0)
; template <int EPI>
; DI void gemm_phase(const u16* __restrict__ A, int lda, const u16* __restrict__ Bt, int K, int N, u16* outb, int ldo,
;                    const float* r0, const float* r1, float* outf, char* lds, int bid, int nb) {
;     ...
;   for (int it = 0; it < nIter; ++it) {
;     int tm, tn;
;     if (swz) { const int st = xcd + 8 * it, sm = st / nSN, sn = st - sm * nSN; tm = sm * GM + jb / GN; tn = sn * GN + (jb % GN); }
;     else { const int t = bid + it * nb; tm = t / nN; tn = t - tm * nN; }
;     const u16* Ag = A + (size_t)(tm * 256 + lrow) * lda + lch * 8;
;     const u16* Bg = Bt + (size_t)(tn * 256 + lrow) * K + lch * 8;
;     f32x4 acc[8][4];
; #pragma unroll
;     for (int i = 0; i < 8; ++i)
; #pragma unroll
;       for (int j = 0; j < 4; ++j) acc[i][j] = (f32x4){0.f, 0.f, 0.f, 0.f};
;     u32x4 ra[4], rb[4];
;     ...
;     G_LOAD(0);
;     G_STORE(0);
;     __syncthreads();
.LBB0_701:
	s_lshl_b32 s49, s49, 8
	v_or_b32_e32 v0, s49, v138
	v_ashrrev_i32_e32 v1, 31, v0
	v_lshlrev_b64 v[64:65], 11, v[0:1]
	v_lshl_or_b32 v0, s48, 8, v138
	v_ashrrev_i32_e32 v1, 31, v0
	v_lshlrev_b64 v[66:67], 11, v[0:1]
	v_lshl_add_u64 v[0:1], v[128:129], 0, v[64:65]
	v_add_co_u32_e32 v4, vcc, 0x20000, v0
	v_lshl_add_u64 v[2:3], v[130:131], 0, v[66:67]
	s_nop 0
	v_addc_co_u32_e32 v5, vcc, 0, v1, vcc
	v_add_co_u32_e32 v6, vcc, 0x20000, v2
	s_nop 1
	v_readfirstlane_b32 s98, v0
	v_readfirstlane_b32 s99, v1
	s_nop 1
	v_readfirstlane_b32 s100, v2
	v_readfirstlane_b32 s101, v3
	v_addc_co_u32_e32 v7, vcc, 0, v3, vcc
	v_add_co_u32_e32 v4, vcc, 0x40000, v0
	s_mov_b32 s50, 0
	s_nop 0
	v_addc_co_u32_e32 v5, vcc, 0, v1, vcc
	v_add_co_u32_e32 v6, vcc, 0x40000, v2
	s_mov_b64 s[14:15], 0
	s_nop 0
	v_addc_co_u32_e32 v7, vcc, 0, v3, vcc
	v_add_co_u32_e32 v0, vcc, 0x60000, v0
	v_addc_co_u32_e32 v1, vcc, 0, v1, vcc
	v_add_co_u32_e32 v2, vcc, 0x60000, v2
	v_lshl_add_u64 v[134:135], v[132:133], 0, v[66:67]
	s_nop 0
	v_addc_co_u32_e32 v3, vcc, 0, v3, vcc
	v_mov_b32_e32 v0, 0
	v_mov_b32_e32 v1, v0
	v_mov_b32_e32 v2, v0
	v_mov_b32_e32 v3, v0
	v_mov_b32_e32 v4, v0
	v_mov_b32_e32 v5, v0
	v_mov_b32_e32 v6, v0
	v_mov_b32_e32 v7, v0
	v_mov_b32_e32 v8, v0
	v_mov_b32_e32 v9, v0
	v_mov_b32_e32 v10, v0
	v_mov_b32_e32 v11, v0
	v_mov_b32_e32 v12, v0
	v_mov_b32_e32 v13, v0
	v_mov_b32_e32 v14, v0
	v_mov_b32_e32 v15, v0
	v_mov_b32_e32 v16, v0
	v_mov_b32_e32 v17, v0
	v_mov_b32_e32 v18, v0
	v_mov_b32_e32 v19, v0
	v_mov_b32_e32 v20, v0
	v_mov_b32_e32 v21, v0
	v_mov_b32_e32 v22, v0
	v_mov_b32_e32 v23, v0
	v_mov_b32_e32 v24, v0
	v_mov_b32_e32 v25, v0
	v_mov_b32_e32 v26, v0
	v_mov_b32_e32 v27, v0
	v_mov_b32_e32 v28, v0
	v_mov_b32_e32 v29, v0
	v_mov_b32_e32 v30, v0
	v_lshl_add_u64 v[136:137], v[132:133], 0, v[64:65]
	v_mov_b32_e32 v31, v0
	v_mov_b32_e32 v64, v0
	v_mov_b32_e32 v65, v0
	v_mov_b32_e32 v66, v0
	v_mov_b32_e32 v67, v0
	v_mov_b32_e32 v68, v0
	v_mov_b32_e32 v69, v0
	v_mov_b32_e32 v70, v0
	v_mov_b32_e32 v71, v0
	v_mov_b32_e32 v72, v0
	v_mov_b32_e32 v73, v0
	v_mov_b32_e32 v74, v0
	v_mov_b32_e32 v75, v0
	v_mov_b32_e32 v76, v0
	v_mov_b32_e32 v77, v0
	v_mov_b32_e32 v78, v0
	v_mov_b32_e32 v79, v0
	v_mov_b32_e32 v80, v0
	v_mov_b32_e32 v81, v0
	v_mov_b32_e32 v82, v0
	v_mov_b32_e32 v83, v0
	v_mov_b32_e32 v84, v0
	v_mov_b32_e32 v85, v0
	v_mov_b32_e32 v86, v0
	v_mov_b32_e32 v87, v0
	v_mov_b32_e32 v32, v0
	v_mov_b32_e32 v33, v0
	v_mov_b32_e32 v34, v0
	v_mov_b32_e32 v35, v0
	v_mov_b32_e32 v36, v0
	v_mov_b32_e32 v37, v0
	v_mov_b32_e32 v38, v0
	v_mov_b32_e32 v39, v0
	v_mov_b32_e32 v40, v0
	v_mov_b32_e32 v41, v0
	v_mov_b32_e32 v42, v0
	v_mov_b32_e32 v43, v0
	v_mov_b32_e32 v44, v0
	v_mov_b32_e32 v45, v0
	v_mov_b32_e32 v46, v0
	v_mov_b32_e32 v47, v0
	v_mov_b32_e32 v48, v0
	v_mov_b32_e32 v49, v0
	v_mov_b32_e32 v50, v0
	v_mov_b32_e32 v51, v0
	v_mov_b32_e32 v52, v0
	v_mov_b32_e32 v53, v0
	v_mov_b32_e32 v54, v0
	v_mov_b32_e32 v55, v0
	v_mov_b32_e32 v56, v0
	v_mov_b32_e32 v57, v0
	v_mov_b32_e32 v58, v0
	v_mov_b32_e32 v59, v0
	v_mov_b32_e32 v60, v0
	v_mov_b32_e32 v61, v0
	v_mov_b32_e32 v62, v0
	v_mov_b32_e32 v63, v0
	v_mov_b32_e32 v88, v0
	v_mov_b32_e32 v89, v0
	v_mov_b32_e32 v90, v0
	v_mov_b32_e32 v91, v0
	v_mov_b32_e32 v92, v0
	v_mov_b32_e32 v93, v0
	v_mov_b32_e32 v94, v0
	v_mov_b32_e32 v95, v0
	v_mov_b32_e32 v96, v0
	v_mov_b32_e32 v97, v0
	v_mov_b32_e32 v98, v0
	v_mov_b32_e32 v99, v0
	v_mov_b32_e32 v100, v0
	v_mov_b32_e32 v101, v0
	v_mov_b32_e32 v102, v0
	v_mov_b32_e32 v103, v0
	v_mov_b32_e32 v104, v0
	v_mov_b32_e32 v105, v0
	v_mov_b32_e32 v106, v0
	v_mov_b32_e32 v107, v0
	v_mov_b32_e32 v108, v0
	v_mov_b32_e32 v109, v0
	v_mov_b32_e32 v110, v0
	v_mov_b32_e32 v111, v0
	v_mov_b32_e32 v112, v0
	v_mov_b32_e32 v113, v0
	v_mov_b32_e32 v114, v0
	v_mov_b32_e32 v115, v0
	v_mov_b32_e32 v116, v0
	v_mov_b32_e32 v117, v0
	v_mov_b32_e32 v118, v0
	v_mov_b32_e32 v119, v0
	v_mov_b32_e32 v120, v0
	v_mov_b32_e32 v121, v0
	v_mov_b32_e32 v122, v0
	v_mov_b32_e32 v123, v0
	v_mov_b32_e32 v124, v0
	v_mov_b32_e32 v125, v0
	v_mov_b32_e32 v126, v0
	v_mov_b32_e32 v127, v0
	v_and_b32_e32 v229, 63, v174
	v_lshrrev_b32_e32 v230, 3, v229
	v_mov_b32_e32 v233, 0x800
	v_mul_u32_u24_e32 v224, v230, v233
	v_bfe_u32 v231, v174, 4, 2
	v_bfe_u32 v232, v174, 6, 1
	v_lshl_or_b32 v232, v232, 2, v231
	v_and_b32_e32 v233, 7, v174
	v_xor_b32_e32 v232, v232, v233
	v_lshl_add_u32 v224, v232, 4, v224
	v_and_b32_e32 v229, 15, v174
	v_bfe_u32 v230, v174, 1, 3
	v_xor_b32_e32 v230, v230, v231
	v_lshlrev_b32_e32 v230, 4, v230
	v_lshl_or_b32 v230, v229, 7, v230
	v_lshrrev_b32_e32 v229, 8, v174
	v_lshl_or_b32 v225, v229, 14, v230
	v_bfe_u32 v229, v174, 6, 2
	v_lshl_or_b32 v227, v229, 13, v230
	v_or_b32_e32 v227, 0x10000, v227
	v_xor_b32_e32 v226, 64, v225
	v_xor_b32_e32 v228, 64, v227
	v_readfirstlane_b32 s97, v174
	s_lshl_b32 s97, s97, 4
	s_mov_b32 s28, 14
	s_add_u32 m0, s97, 0x0
	s_add_u32 s14, s98, 0x0
	s_addc_u32 s15, s99, 0
	global_load_lds_dwordx4 v224, s[14:15]
	s_add_u32 m0, s97, 0x10000
	s_add_u32 s14, s100, 0x0
	s_addc_u32 s15, s101, 0
	global_load_lds_dwordx4 v224, s[14:15]
	s_add_u32 m0, s97, 0x2000
	s_add_u32 s14, s98, 0x20000
	s_addc_u32 s15, s99, 0
	global_load_lds_dwordx4 v224, s[14:15]
	s_add_u32 m0, s97, 0x12000
	s_add_u32 s14, s100, 0x20000
	s_addc_u32 s15, s101, 0
	global_load_lds_dwordx4 v224, s[14:15]
	s_add_u32 m0, s97, 0x4000
	s_add_u32 s14, s98, 0x40000
	s_addc_u32 s15, s99, 0
	global_load_lds_dwordx4 v224, s[14:15]
	s_add_u32 m0, s97, 0x14000
	s_add_u32 s14, s100, 0x40000
	s_addc_u32 s15, s101, 0
	global_load_lds_dwordx4 v224, s[14:15]
	s_add_u32 m0, s97, 0x6000
	s_add_u32 s14, s98, 0x60000
	s_addc_u32 s15, s99, 0
	global_load_lds_dwordx4 v224, s[14:15]
	s_add_u32 m0, s97, 0x16000
	s_add_u32 s14, s100, 0x60000
	s_addc_u32 s15, s101, 0
	global_load_lds_dwordx4 v224, s[14:15]
	s_add_u32 m0, s97, 0x8000
	s_add_u32 s14, s98, 0x80
	s_addc_u32 s15, s99, 0
	global_load_lds_dwordx4 v224, s[14:15]
	s_add_u32 m0, s97, 0x18000
	s_add_u32 s14, s100, 0x80
	s_addc_u32 s15, s101, 0
	global_load_lds_dwordx4 v224, s[14:15]
	s_add_u32 m0, s97, 0xa000
	s_add_u32 s14, s98, 0x20080
	s_addc_u32 s15, s99, 0
	global_load_lds_dwordx4 v224, s[14:15]
	s_add_u32 m0, s97, 0x1a000
	s_add_u32 s14, s100, 0x20080
	s_addc_u32 s15, s101, 0
	global_load_lds_dwordx4 v224, s[14:15]
	s_add_u32 m0, s97, 0xc000
	s_add_u32 s14, s98, 0x40080
	s_addc_u32 s15, s99, 0
	global_load_lds_dwordx4 v224, s[14:15]
	s_add_u32 m0, s97, 0x1c000
	s_add_u32 s14, s100, 0x40080
	s_addc_u32 s15, s101, 0
	global_load_lds_dwordx4 v224, s[14:15]
	s_add_u32 m0, s97, 0xe000
	s_add_u32 s14, s98, 0x60080
	s_addc_u32 s15, s99, 0
	global_load_lds_dwordx4 v224, s[14:15]
	s_add_u32 m0, s97, 0x1e000
	s_add_u32 s14, s100, 0x60080
	s_addc_u32 s15, s101, 0
	global_load_lds_dwordx4 v224, s[14:15]
	s_add_u32 s98, s98, 0x100
	s_addc_u32 s99, s99, 0
	s_add_u32 s100, s100, 0x100
	s_addc_u32 s101, s101, 0
	s_waitcnt vmcnt(8)
	s_barrier
; #define G_LOAD(KT) do { _Pragma("unroll") for (int i = 0; i < 4; ++i) { ra[i] = *(const u32x4*)(Ag + (size_t)i * 64 * lda + (KT) * 64); rb[i] = *(const u32x4*)(Bg + (size_t)i * 64 * K + (KT) * 64); } } while (0)
; #define G_STORE(BUF) do { u16* ad = As + (BUF) * 256 * 64 + sto; u16* bd = Bs + (BUF) * 256 * 64 + sto; _Pragma("unroll") for (int i = 0; i < 4; ++i) { *(u32x4*)(ad + i * 64 * 64) = ra[i]; *(u32x4*)(bd + i * 64 * 64) = rb[i]; } } while (0)
; template <int EPI>
; DI void gemm_phase(const u16* __restrict__ A, int lda, const u16* __restrict__ Bt, int K, int N, u16* outb, int ldo,
;                    const float* r0, const float* r1, float* outf, char* lds, int bid, int nb) {
;     ...
;     G_LOAD(0);
;     G_STORE(0);
;     __syncthreads();
;     for (int kt = 0; kt < nk; ++kt) {
;       const int cur = kt & 1;
;       if (kt + 1 < nk) G_LOAD(kt + 1);
;       G_MMA(cur, fo0);
;       G_MMA(cur, fo1);
;       if (kt + 1 < nk) G_STORE(cur ^ 1);
	ds_read_b128 v[152:155], v227 offset:0
	ds_read_b128 v[156:159], v227 offset:2048
	ds_read_b128 v[160:163], v227 offset:4096
	ds_read_b128 v[164:167], v227 offset:6144
	ds_read_b128 v[188:191], v225 offset:0
	ds_read_b128 v[192:195], v225 offset:2048
	ds_read_b128 v[196:199], v225 offset:4096
	ds_read_b128 v[200:203], v225 offset:6144
	ds_read_b128 v[204:207], v225 offset:8192
	ds_read_b128 v[208:211], v225 offset:10240
	ds_read_b128 v[212:215], v225 offset:12288
	ds_read_b128 v[216:219], v225 offset:14336
	v_xor_b32_e32 v225, 0x8000, v225
	v_xor_b32_e32 v227, 0x8000, v227
	s_waitcnt lgkmcnt(0)
	s_bitcmp1_b32 s97, 12
	s_cbranch_scc0 .Lgm2_noprio
	s_setprio 1
.Lgm2_noprio:
.Lgm2_loop:
	s_waitcnt lgkmcnt(4)
	v_mfma_f32_16x16x32_bf16 v[124:127], v[152:155], v[188:191], v[124:127]
	v_mfma_f32_16x16x32_bf16 v[120:123], v[156:159], v[188:191], v[120:123]
	v_mfma_f32_16x16x32_bf16 v[116:119], v[160:163], v[188:191], v[116:119]
	v_mfma_f32_16x16x32_bf16 v[112:115], v[164:167], v[188:191], v[112:115]
	ds_read_b128 v[188:191], v226 offset:0
	ds_read_b128 v[168:171], v228 offset:0
	v_mfma_f32_16x16x32_bf16 v[108:111], v[152:155], v[192:195], v[108:111]
	v_mfma_f32_16x16x32_bf16 v[104:107], v[156:159], v[192:195], v[104:107]
	v_mfma_f32_16x16x32_bf16 v[100:103], v[160:163], v[192:195], v[100:103]
	v_mfma_f32_16x16x32_bf16 v[96:99], v[164:167], v[192:195], v[96:99]
	ds_read_b128 v[192:195], v226 offset:2048
	ds_read_b128 v[176:179], v228 offset:2048
	v_mfma_f32_16x16x32_bf16 v[92:95], v[152:155], v[196:199], v[92:95]
	v_mfma_f32_16x16x32_bf16 v[88:91], v[156:159], v[196:199], v[88:91]
	v_mfma_f32_16x16x32_bf16 v[84:87], v[160:163], v[196:199], v[84:87]
	v_mfma_f32_16x16x32_bf16 v[80:83], v[164:167], v[196:199], v[80:83]
	ds_read_b128 v[196:199], v226 offset:4096
	ds_read_b128 v[180:183], v228 offset:4096
	v_mfma_f32_16x16x32_bf16 v[76:79], v[152:155], v[200:203], v[76:79]
	v_mfma_f32_16x16x32_bf16 v[72:75], v[156:159], v[200:203], v[72:75]
	v_mfma_f32_16x16x32_bf16 v[68:71], v[160:163], v[200:203], v[68:71]
	v_mfma_f32_16x16x32_bf16 v[64:67], v[164:167], v[200:203], v[64:67]
	ds_read_b128 v[200:203], v226 offset:6144
	ds_read_b128 v[184:187], v228 offset:6144
	s_waitcnt lgkmcnt(11)
	v_mfma_f32_16x16x32_bf16 v[60:63], v[152:155], v[204:207], v[60:63]
	v_mfma_f32_16x16x32_bf16 v[56:59], v[156:159], v[204:207], v[56:59]
	v_mfma_f32_16x16x32_bf16 v[52:55], v[160:163], v[204:207], v[52:55]
	v_mfma_f32_16x16x32_bf16 v[48:51], v[164:167], v[204:207], v[48:51]
	ds_read_b128 v[204:207], v226 offset:8192
	ds_read_b128 v[220:223], v226 offset:14336
	s_waitcnt lgkmcnt(11)
	v_mfma_f32_16x16x32_bf16 v[44:47], v[152:155], v[208:211], v[44:47]
	v_mfma_f32_16x16x32_bf16 v[40:43], v[156:159], v[208:211], v[40:43]
	v_mfma_f32_16x16x32_bf16 v[36:39], v[160:163], v[208:211], v[36:39]
	v_mfma_f32_16x16x32_bf16 v[32:35], v[164:167], v[208:211], v[32:35]
	ds_read_b128 v[208:211], v226 offset:10240
	s_waitcnt lgkmcnt(11)
	v_mfma_f32_16x16x32_bf16 v[28:31], v[152:155], v[212:215], v[28:31]
	v_mfma_f32_16x16x32_bf16 v[24:27], v[156:159], v[212:215], v[24:27]
	v_mfma_f32_16x16x32_bf16 v[20:23], v[160:163], v[212:215], v[20:23]
	v_mfma_f32_16x16x32_bf16 v[16:19], v[164:167], v[212:215], v[16:19]
	ds_read_b128 v[212:215], v226 offset:12288
	v_mfma_f32_16x16x32_bf16 v[12:15], v[152:155], v[216:219], v[12:15]
	v_mfma_f32_16x16x32_bf16 v[8:11], v[156:159], v[216:219], v[8:11]
	v_mfma_f32_16x16x32_bf16 v[4:7], v[160:163], v[216:219], v[4:7]
	v_mfma_f32_16x16x32_bf16 v[0:3], v[164:167], v[216:219], v[0:3]
	s_waitcnt vmcnt(0) lgkmcnt(0)
	s_barrier
	v_mfma_f32_16x16x32_bf16 v[124:127], v[168:171], v[188:191], v[124:127]
	v_mfma_f32_16x16x32_bf16 v[120:123], v[176:179], v[188:191], v[120:123]
	v_mfma_f32_16x16x32_bf16 v[116:119], v[180:183], v[188:191], v[116:119]
	v_mfma_f32_16x16x32_bf16 v[112:115], v[184:187], v[188:191], v[112:115]
	ds_read_b128 v[188:191], v225 offset:0
	ds_read_b128 v[152:155], v227 offset:0
	s_add_u32 m0, s97, 0x0
	s_add_u32 s14, s98, 0x0
	s_addc_u32 s15, s99, 0
	global_load_lds_dwordx4 v224, s[14:15]
	v_mfma_f32_16x16x32_bf16 v[108:111], v[168:171], v[192:195], v[108:111]
	v_mfma_f32_16x16x32_bf16 v[104:107], v[176:179], v[192:195], v[104:107]
	v_mfma_f32_16x16x32_bf16 v[100:103], v[180:183], v[192:195], v[100:103]
	v_mfma_f32_16x16x32_bf16 v[96:99], v[184:187], v[192:195], v[96:99]
	ds_read_b128 v[192:195], v225 offset:2048
	ds_read_b128 v[156:159], v227 offset:2048
	s_add_u32 m0, s97, 0x10000
	s_add_u32 s14, s100, 0x0
	s_addc_u32 s15, s101, 0
	global_load_lds_dwordx4 v224, s[14:15]
	v_mfma_f32_16x16x32_bf16 v[92:95], v[168:171], v[196:199], v[92:95]
	v_mfma_f32_16x16x32_bf16 v[88:91], v[176:179], v[196:199], v[88:91]
	v_mfma_f32_16x16x32_bf16 v[84:87], v[180:183], v[196:199], v[84:87]
	v_mfma_f32_16x16x32_bf16 v[80:83], v[184:187], v[196:199], v[80:83]
	ds_read_b128 v[196:199], v225 offset:4096
	ds_read_b128 v[160:163], v227 offset:4096
	s_add_u32 m0, s97, 0x2000
	s_add_u32 s14, s98, 0x20000
	s_addc_u32 s15, s99, 0
	global_load_lds_dwordx4 v224, s[14:15]
	v_mfma_f32_16x16x32_bf16 v[76:79], v[168:171], v[200:203], v[76:79]
	v_mfma_f32_16x16x32_bf16 v[72:75], v[176:179], v[200:203], v[72:75]
	v_mfma_f32_16x16x32_bf16 v[68:71], v[180:183], v[200:203], v[68:71]
	v_mfma_f32_16x16x32_bf16 v[64:67], v[184:187], v[200:203], v[64:67]
	ds_read_b128 v[200:203], v225 offset:6144
	ds_read_b128 v[164:167], v227 offset:6144
	s_add_u32 m0, s97, 0x12000
	s_add_u32 s14, s100, 0x20000
	s_addc_u32 s15, s101, 0
	global_load_lds_dwordx4 v224, s[14:15]
	v_mfma_f32_16x16x32_bf16 v[60:63], v[168:171], v[204:207], v[60:63]
	v_mfma_f32_16x16x32_bf16 v[56:59], v[176:179], v[204:207], v[56:59]
; #define G_LOAD(KT) do { _Pragma("unroll") for (int i = 0; i < 4; ++i) { ra[i] = *(const u32x4*)(Ag + (size_t)i * 64 * lda + (KT) * 64); rb[i] = *(const u32x4*)(Bg + (size_t)i * 64 * K + (KT) * 64); } } while (0)
; #define G_STORE(BUF) do { u16* ad = As + (BUF) * 256 * 64 + sto; u16* bd = Bs + (BUF) * 256 * 64 + sto; _Pragma("unroll") for (int i = 0; i < 4; ++i) { *(u32x4*)(ad + i * 64 * 64) = ra[i]; *(u32x4*)(bd + i * 64 * 64) = rb[i]; } } while (0)
; template <int EPI>
; DI void gemm_phase(const u16* __restrict__ A, int lda, const u16* __restrict__ Bt, int K, int N, u16* outb, int ldo,
;                    const float* r0, const float* r1, float* outf, char* lds, int bid, int nb) {
;     ...
;     for (int kt = 0; kt < nk; ++kt) {
;       const int cur = kt & 1;
;       if (kt + 1 < nk) G_LOAD(kt + 1);
;       G_MMA(cur, fo0);
;       G_MMA(cur, fo1);
;       if (kt + 1 < nk) G_STORE(cur ^ 1);
;       __syncthreads();
;     }
	v_mfma_f32_16x16x32_bf16 v[52:55], v[180:183], v[204:207], v[52:55]
	v_mfma_f32_16x16x32_bf16 v[48:51], v[184:187], v[204:207], v[48:51]
	ds_read_b128 v[204:207], v225 offset:8192
	ds_read_b128 v[216:219], v225 offset:14336
	s_add_u32 m0, s97, 0x4000
	s_add_u32 s14, s98, 0x40000
	s_addc_u32 s15, s99, 0
	global_load_lds_dwordx4 v224, s[14:15]
	v_mfma_f32_16x16x32_bf16 v[44:47], v[168:171], v[208:211], v[44:47]
	v_mfma_f32_16x16x32_bf16 v[40:43], v[176:179], v[208:211], v[40:43]
	v_mfma_f32_16x16x32_bf16 v[36:39], v[180:183], v[208:211], v[36:39]
	v_mfma_f32_16x16x32_bf16 v[32:35], v[184:187], v[208:211], v[32:35]
	ds_read_b128 v[208:211], v225 offset:10240
	s_add_u32 m0, s97, 0x14000
	s_add_u32 s14, s100, 0x40000
	s_addc_u32 s15, s101, 0
	global_load_lds_dwordx4 v224, s[14:15]
	v_mfma_f32_16x16x32_bf16 v[28:31], v[168:171], v[212:215], v[28:31]
	v_mfma_f32_16x16x32_bf16 v[24:27], v[176:179], v[212:215], v[24:27]
	v_mfma_f32_16x16x32_bf16 v[20:23], v[180:183], v[212:215], v[20:23]
	v_mfma_f32_16x16x32_bf16 v[16:19], v[184:187], v[212:215], v[16:19]
	ds_read_b128 v[212:215], v225 offset:12288
	s_add_u32 m0, s97, 0x6000
	s_add_u32 s14, s98, 0x60000
	s_addc_u32 s15, s99, 0
	global_load_lds_dwordx4 v224, s[14:15]
	v_mfma_f32_16x16x32_bf16 v[12:15], v[168:171], v[220:223], v[12:15]
	v_mfma_f32_16x16x32_bf16 v[8:11], v[176:179], v[220:223], v[8:11]
	v_mfma_f32_16x16x32_bf16 v[4:7], v[180:183], v[220:223], v[4:7]
	v_mfma_f32_16x16x32_bf16 v[0:3], v[184:187], v[220:223], v[0:3]
	s_add_u32 m0, s97, 0x16000
	s_add_u32 s14, s100, 0x60000
	s_addc_u32 s15, s101, 0
	global_load_lds_dwordx4 v224, s[14:15]
	v_xor_b32_e32 v225, 0x8000, v225
	v_xor_b32_e32 v227, 0x8000, v227
	v_xor_b32_e32 v226, 0x8000, v226
	v_xor_b32_e32 v228, 0x8000, v228
	s_xor_b32 s97, s97, 0x8000
	s_add_u32 s98, s98, 0x80
	s_addc_u32 s99, s99, 0
	s_add_u32 s100, s100, 0x80
	s_addc_u32 s101, s101, 0
	s_sub_u32 s28, s28, 1
	s_cmp_lg_u32 s28, 0
	s_cbranch_scc1 .Lgm2_loop
	s_waitcnt lgkmcnt(4)
	v_mfma_f32_16x16x32_bf16 v[124:127], v[152:155], v[188:191], v[124:127]
	v_mfma_f32_16x16x32_bf16 v[120:123], v[156:159], v[188:191], v[120:123]
	v_mfma_f32_16x16x32_bf16 v[116:119], v[160:163], v[188:191], v[116:119]
	v_mfma_f32_16x16x32_bf16 v[112:115], v[164:167], v[188:191], v[112:115]
	ds_read_b128 v[188:191], v226 offset:0
	ds_read_b128 v[168:171], v228 offset:0
	v_mfma_f32_16x16x32_bf16 v[108:111], v[152:155], v[192:195], v[108:111]
	v_mfma_f32_16x16x32_bf16 v[104:107], v[156:159], v[192:195], v[104:107]
	v_mfma_f32_16x16x32_bf16 v[100:103], v[160:163], v[192:195], v[100:103]
	v_mfma_f32_16x16x32_bf16 v[96:99], v[164:167], v[192:195], v[96:99]
	ds_read_b128 v[192:195], v226 offset:2048
	ds_read_b128 v[176:179], v228 offset:2048
	v_mfma_f32_16x16x32_bf16 v[92:95], v[152:155], v[196:199], v[92:95]
	v_mfma_f32_16x16x32_bf16 v[88:91], v[156:159], v[196:199], v[88:91]
	v_mfma_f32_16x16x32_bf16 v[84:87], v[160:163], v[196:199], v[84:87]
	v_mfma_f32_16x16x32_bf16 v[80:83], v[164:167], v[196:199], v[80:83]
	ds_read_b128 v[196:199], v226 offset:4096
	ds_read_b128 v[180:183], v228 offset:4096
	v_mfma_f32_16x16x32_bf16 v[76:79], v[152:155], v[200:203], v[76:79]
	v_mfma_f32_16x16x32_bf16 v[72:75], v[156:159], v[200:203], v[72:75]
	v_mfma_f32_16x16x32_bf16 v[68:71], v[160:163], v[200:203], v[68:71]
	v_mfma_f32_16x16x32_bf16 v[64:67], v[164:167], v[200:203], v[64:67]
	ds_read_b128 v[200:203], v226 offset:6144
	ds_read_b128 v[184:187], v228 offset:6144
	s_waitcnt lgkmcnt(11)
	v_mfma_f32_16x16x32_bf16 v[60:63], v[152:155], v[204:207], v[60:63]
	v_mfma_f32_16x16x32_bf16 v[56:59], v[156:159], v[204:207], v[56:59]
	v_mfma_f32_16x16x32_bf16 v[52:55], v[160:163], v[204:207], v[52:55]
	v_mfma_f32_16x16x32_bf16 v[48:51], v[164:167], v[204:207], v[48:51]
	ds_read_b128 v[204:207], v226 offset:8192
	ds_read_b128 v[220:223], v226 offset:14336
	s_waitcnt lgkmcnt(11)
	v_mfma_f32_16x16x32_bf16 v[44:47], v[152:155], v[208:211], v[44:47]
	v_mfma_f32_16x16x32_bf16 v[40:43], v[156:159], v[208:211], v[40:43]
	v_mfma_f32_16x16x32_bf16 v[36:39], v[160:163], v[208:211], v[36:39]
	v_mfma_f32_16x16x32_bf16 v[32:35], v[164:167], v[208:211], v[32:35]
	ds_read_b128 v[208:211], v226 offset:10240
	s_waitcnt lgkmcnt(11)
	v_mfma_f32_16x16x32_bf16 v[28:31], v[152:155], v[212:215], v[28:31]
	v_mfma_f32_16x16x32_bf16 v[24:27], v[156:159], v[212:215], v[24:27]
	v_mfma_f32_16x16x32_bf16 v[20:23], v[160:163], v[212:215], v[20:23]
	v_mfma_f32_16x16x32_bf16 v[16:19], v[164:167], v[212:215], v[16:19]
	ds_read_b128 v[212:215], v226 offset:12288
	v_mfma_f32_16x16x32_bf16 v[12:15], v[152:155], v[216:219], v[12:15]
	v_mfma_f32_16x16x32_bf16 v[8:11], v[156:159], v[216:219], v[8:11]
	v_mfma_f32_16x16x32_bf16 v[4:7], v[160:163], v[216:219], v[4:7]
	v_mfma_f32_16x16x32_bf16 v[0:3], v[164:167], v[216:219], v[0:3]
	s_waitcnt vmcnt(0) lgkmcnt(0)
	s_barrier
; #define G_LOAD(KT) do { _Pragma("unroll") for (int i = 0; i < 4; ++i) { ra[i] = *(const u32x4*)(Ag + (size_t)i * 64 * lda + (KT) * 64); rb[i] = *(const u32x4*)(Bg + (size_t)i * 64 * K + (KT) * 64); } } while (0)
; #define G_STORE(BUF) do { u16* ad = As + (BUF) * 256 * 64 + sto; u16* bd = Bs + (BUF) * 256 * 64 + sto; _Pragma("unroll") for (int i = 0; i < 4; ++i) { *(u32x4*)(ad + i * 64 * 64) = ra[i]; *(u32x4*)(bd + i * 64 * 64) = rb[i]; } } while (0)
; template <int EPI>
; DI void gemm_phase(const u16* __restrict__ A, int lda, const u16* __restrict__ Bt, int K, int N, u16* outb, int ldo,
;                    const float* r0, const float* r1, float* outf, char* lds, int bid, int nb) {
;     ...
;     G_LOAD(0);
;     G_STORE(0);
;     __syncthreads();
;     for (int kt = 0; kt < nk; ++kt) {
;       const int cur = kt & 1;
;       if (kt + 1 < nk) G_LOAD(kt + 1);
;       G_MMA(cur, fo0);
;       G_MMA(cur, fo1);
;       if (kt + 1 < nk) G_STORE(cur ^ 1);
;       __syncthreads();
	v_mfma_f32_16x16x32_bf16 v[124:127], v[168:171], v[188:191], v[124:127]
	v_mfma_f32_16x16x32_bf16 v[120:123], v[176:179], v[188:191], v[120:123]
	v_mfma_f32_16x16x32_bf16 v[116:119], v[180:183], v[188:191], v[116:119]
	v_mfma_f32_16x16x32_bf16 v[112:115], v[184:187], v[188:191], v[112:115]
	ds_read_b128 v[188:191], v225 offset:0
	ds_read_b128 v[152:155], v227 offset:0
	v_mfma_f32_16x16x32_bf16 v[108:111], v[168:171], v[192:195], v[108:111]
	v_mfma_f32_16x16x32_bf16 v[104:107], v[176:179], v[192:195], v[104:107]
	v_mfma_f32_16x16x32_bf16 v[100:103], v[180:183], v[192:195], v[100:103]
	v_mfma_f32_16x16x32_bf16 v[96:99], v[184:187], v[192:195], v[96:99]
	ds_read_b128 v[192:195], v225 offset:2048
	ds_read_b128 v[156:159], v227 offset:2048
	v_mfma_f32_16x16x32_bf16 v[92:95], v[168:171], v[196:199], v[92:95]
	v_mfma_f32_16x16x32_bf16 v[88:91], v[176:179], v[196:199], v[88:91]
	v_mfma_f32_16x16x32_bf16 v[84:87], v[180:183], v[196:199], v[84:87]
	v_mfma_f32_16x16x32_bf16 v[80:83], v[184:187], v[196:199], v[80:83]
	ds_read_b128 v[196:199], v225 offset:4096
	ds_read_b128 v[160:163], v227 offset:4096
	v_mfma_f32_16x16x32_bf16 v[76:79], v[168:171], v[200:203], v[76:79]
	v_mfma_f32_16x16x32_bf16 v[72:75], v[176:179], v[200:203], v[72:75]
	v_mfma_f32_16x16x32_bf16 v[68:71], v[180:183], v[200:203], v[68:71]
	v_mfma_f32_16x16x32_bf16 v[64:67], v[184:187], v[200:203], v[64:67]
	ds_read_b128 v[200:203], v225 offset:6144
	ds_read_b128 v[164:167], v227 offset:6144
	v_mfma_f32_16x16x32_bf16 v[60:63], v[168:171], v[204:207], v[60:63]
	v_mfma_f32_16x16x32_bf16 v[56:59], v[176:179], v[204:207], v[56:59]
	v_mfma_f32_16x16x32_bf16 v[52:55], v[180:183], v[204:207], v[52:55]
	v_mfma_f32_16x16x32_bf16 v[48:51], v[184:187], v[204:207], v[48:51]
	ds_read_b128 v[204:207], v225 offset:8192
	ds_read_b128 v[216:219], v225 offset:14336
	v_mfma_f32_16x16x32_bf16 v[44:47], v[168:171], v[208:211], v[44:47]
	v_mfma_f32_16x16x32_bf16 v[40:43], v[176:179], v[208:211], v[40:43]
	v_mfma_f32_16x16x32_bf16 v[36:39], v[180:183], v[208:211], v[36:39]
	v_mfma_f32_16x16x32_bf16 v[32:35], v[184:187], v[208:211], v[32:35]
	ds_read_b128 v[208:211], v225 offset:10240
	v_mfma_f32_16x16x32_bf16 v[28:31], v[168:171], v[212:215], v[28:31]
	v_mfma_f32_16x16x32_bf16 v[24:27], v[176:179], v[212:215], v[24:27]
	v_mfma_f32_16x16x32_bf16 v[20:23], v[180:183], v[212:215], v[20:23]
	v_mfma_f32_16x16x32_bf16 v[16:19], v[184:187], v[212:215], v[16:19]
	ds_read_b128 v[212:215], v225 offset:12288
	v_mfma_f32_16x16x32_bf16 v[12:15], v[168:171], v[220:223], v[12:15]
	v_mfma_f32_16x16x32_bf16 v[8:11], v[176:179], v[220:223], v[8:11]
	v_mfma_f32_16x16x32_bf16 v[4:7], v[180:183], v[220:223], v[4:7]
	v_mfma_f32_16x16x32_bf16 v[0:3], v[184:187], v[220:223], v[0:3]
	v_xor_b32_e32 v226, 0x8000, v226
	v_xor_b32_e32 v228, 0x8000, v228
	s_waitcnt lgkmcnt(4)
	v_mfma_f32_16x16x32_bf16 v[124:127], v[152:155], v[188:191], v[124:127]
	v_mfma_f32_16x16x32_bf16 v[120:123], v[156:159], v[188:191], v[120:123]
	v_mfma_f32_16x16x32_bf16 v[116:119], v[160:163], v[188:191], v[116:119]
	v_mfma_f32_16x16x32_bf16 v[112:115], v[164:167], v[188:191], v[112:115]
	ds_read_b128 v[188:191], v226 offset:0
	ds_read_b128 v[168:171], v228 offset:0
	v_mfma_f32_16x16x32_bf16 v[108:111], v[152:155], v[192:195], v[108:111]
	v_mfma_f32_16x16x32_bf16 v[104:107], v[156:159], v[192:195], v[104:107]
	v_mfma_f32_16x16x32_bf16 v[100:103], v[160:163], v[192:195], v[100:103]
	v_mfma_f32_16x16x32_bf16 v[96:99], v[164:167], v[192:195], v[96:99]
	ds_read_b128 v[192:195], v226 offset:2048
	ds_read_b128 v[176:179], v228 offset:2048
	v_mfma_f32_16x16x32_bf16 v[92:95], v[152:155], v[196:199], v[92:95]
	v_mfma_f32_16x16x32_bf16 v[88:91], v[156:159], v[196:199], v[88:91]
	v_mfma_f32_16x16x32_bf16 v[84:87], v[160:163], v[196:199], v[84:87]
	v_mfma_f32_16x16x32_bf16 v[80:83], v[164:167], v[196:199], v[80:83]
	ds_read_b128 v[196:199], v226 offset:4096
	ds_read_b128 v[180:183], v228 offset:4096
	v_mfma_f32_16x16x32_bf16 v[76:79], v[152:155], v[200:203], v[76:79]
	v_mfma_f32_16x16x32_bf16 v[72:75], v[156:159], v[200:203], v[72:75]
	v_mfma_f32_16x16x32_bf16 v[68:71], v[160:163], v[200:203], v[68:71]
	v_mfma_f32_16x16x32_bf16 v[64:67], v[164:167], v[200:203], v[64:67]
	ds_read_b128 v[200:203], v226 offset:6144
	ds_read_b128 v[184:187], v228 offset:6144
	s_waitcnt lgkmcnt(11)
	v_mfma_f32_16x16x32_bf16 v[60:63], v[152:155], v[204:207], v[60:63]
	v_mfma_f32_16x16x32_bf16 v[56:59], v[156:159], v[204:207], v[56:59]
	v_mfma_f32_16x16x32_bf16 v[52:55], v[160:163], v[204:207], v[52:55]
	v_mfma_f32_16x16x32_bf16 v[48:51], v[164:167], v[204:207], v[48:51]
	ds_read_b128 v[204:207], v226 offset:8192
	ds_read_b128 v[220:223], v226 offset:14336
	s_waitcnt lgkmcnt(11)
	v_mfma_f32_16x16x32_bf16 v[44:47], v[152:155], v[208:211], v[44:47]
	v_mfma_f32_16x16x32_bf16 v[40:43], v[156:159], v[208:211], v[40:43]
	v_mfma_f32_16x16x32_bf16 v[36:39], v[160:163], v[208:211], v[36:39]
	v_mfma_f32_16x16x32_bf16 v[32:35], v[164:167], v[208:211], v[32:35]
	ds_read_b128 v[208:211], v226 offset:10240
	s_waitcnt lgkmcnt(11)
	v_mfma_f32_16x16x32_bf16 v[28:31], v[152:155], v[212:215], v[28:31]
	v_mfma_f32_16x16x32_bf16 v[24:27], v[156:159], v[212:215], v[24:27]
	v_mfma_f32_16x16x32_bf16 v[20:23], v[160:163], v[212:215], v[20:23]
	v_mfma_f32_16x16x32_bf16 v[16:19], v[164:167], v[212:215], v[16:19]
	ds_read_b128 v[212:215], v226 offset:12288
	v_mfma_f32_16x16x32_bf16 v[12:15], v[152:155], v[216:219], v[12:15]
	v_mfma_f32_16x16x32_bf16 v[8:11], v[156:159], v[216:219], v[8:11]
	v_mfma_f32_16x16x32_bf16 v[4:7], v[160:163], v[216:219], v[4:7]
	v_mfma_f32_16x16x32_bf16 v[0:3], v[164:167], v[216:219], v[0:3]
	s_waitcnt vmcnt(0) lgkmcnt(0)
	s_barrier
; DI u16 f2bf(float a) { return (u16)(pk2(a, 0.f) & 0xffffu); }
; DI float sigmoidf_(float x) { return __builtin_amdgcn_rcpf(1.f + __builtin_amdgcn_exp2f(-1.4426950408889634f * x)); }
; template <int EPI>
; DI void gemm_phase(const u16* __restrict__ A, int lda, const u16* __restrict__ Bt, int K, int N, u16* outb, int ldo,
;                    const float* r0, const float* r1, float* outf, char* lds, int bid, int nb) {
;     ...
;     } else {
;       const int col = (tn * 4 + wc) * 32 + l15;
; #pragma unroll
;       for (int i = 0; i < 8; ++i)
; #pragma unroll
;         for (int r = 0; r < 4; ++r) {
;           const float g0 = acc[i][0][r], u0 = acc[i][2][r], g1 = acc[i][1][r], u1 = acc[i][3][r];
;           u16* o0 = outb + (size_t)(mrow + i * 16 + r) * ldo + col;
;           o0[0] = f2bf(g0 * sigmoidf_(g0) * u0); o0[16] = f2bf(g1 * sigmoidf_(g1) * u1);
;         }
	v_mfma_f32_16x16x32_bf16 v[124:127], v[168:171], v[188:191], v[124:127]
	v_mfma_f32_16x16x32_bf16 v[120:123], v[176:179], v[188:191], v[120:123]
	v_mfma_f32_16x16x32_bf16 v[116:119], v[180:183], v[188:191], v[116:119]
	v_mfma_f32_16x16x32_bf16 v[112:115], v[184:187], v[188:191], v[112:115]
	v_mfma_f32_16x16x32_bf16 v[108:111], v[168:171], v[192:195], v[108:111]
	v_mfma_f32_16x16x32_bf16 v[104:107], v[176:179], v[192:195], v[104:107]
	v_mfma_f32_16x16x32_bf16 v[100:103], v[180:183], v[192:195], v[100:103]
	v_mfma_f32_16x16x32_bf16 v[96:99], v[184:187], v[192:195], v[96:99]
	v_mfma_f32_16x16x32_bf16 v[92:95], v[168:171], v[196:199], v[92:95]
	v_mfma_f32_16x16x32_bf16 v[88:91], v[176:179], v[196:199], v[88:91]
	v_mfma_f32_16x16x32_bf16 v[84:87], v[180:183], v[196:199], v[84:87]
	v_mfma_f32_16x16x32_bf16 v[80:83], v[184:187], v[196:199], v[80:83]
	v_mfma_f32_16x16x32_bf16 v[76:79], v[168:171], v[200:203], v[76:79]
	v_mfma_f32_16x16x32_bf16 v[72:75], v[176:179], v[200:203], v[72:75]
	v_mfma_f32_16x16x32_bf16 v[68:71], v[180:183], v[200:203], v[68:71]
	v_mfma_f32_16x16x32_bf16 v[64:67], v[184:187], v[200:203], v[64:67]
	v_mfma_f32_16x16x32_bf16 v[60:63], v[168:171], v[204:207], v[60:63]
	v_mfma_f32_16x16x32_bf16 v[56:59], v[176:179], v[204:207], v[56:59]
	v_mfma_f32_16x16x32_bf16 v[52:55], v[180:183], v[204:207], v[52:55]
	v_mfma_f32_16x16x32_bf16 v[48:51], v[184:187], v[204:207], v[48:51]
	v_mfma_f32_16x16x32_bf16 v[44:47], v[168:171], v[208:211], v[44:47]
	v_mfma_f32_16x16x32_bf16 v[40:43], v[176:179], v[208:211], v[40:43]
	v_mfma_f32_16x16x32_bf16 v[36:39], v[180:183], v[208:211], v[36:39]
	v_mfma_f32_16x16x32_bf16 v[32:35], v[184:187], v[208:211], v[32:35]
	v_mfma_f32_16x16x32_bf16 v[28:31], v[168:171], v[212:215], v[28:31]
	v_mfma_f32_16x16x32_bf16 v[24:27], v[176:179], v[212:215], v[24:27]
	v_mfma_f32_16x16x32_bf16 v[20:23], v[180:183], v[212:215], v[20:23]
	v_mfma_f32_16x16x32_bf16 v[16:19], v[184:187], v[212:215], v[16:19]
	v_mfma_f32_16x16x32_bf16 v[12:15], v[168:171], v[220:223], v[12:15]
	v_mfma_f32_16x16x32_bf16 v[8:11], v[176:179], v[220:223], v[8:11]
	v_mfma_f32_16x16x32_bf16 v[4:7], v[180:183], v[220:223], v[4:7]
	v_mfma_f32_16x16x32_bf16 v[0:3], v[184:187], v[220:223], v[0:3]
	s_setprio 0
	s_nop 7
	s_nop 3
	v_and_b32_e32 v225, 15, v174
	v_lshrrev_b32_e32 v226, 8, v174
	v_lshl_or_b32 v225, v226, 7, v225
	v_bfe_u32 v226, v174, 6, 2
	v_bfe_u32 v227, v174, 4, 2
	v_lshlrev_b32_e32 v227, 2, v227
	v_add_u32_e32 v225, s49, v225
	v_lshl_add_u32 v226, v226, 5, v227
	v_lshl_or_b32 v226, s48, 7, v226
	v_lshlrev_b32_e32 v226, 1, v226
	v_mov_b32_e32 v227, 0x1600
	v_mad_u32_u24 v224, v225, v227, v226
	v_mul_f32_e32 v188, 0xbfb8aa3b, v124
	v_mul_f32_e32 v189, 0xbfb8aa3b, v125
	v_mul_f32_e32 v190, 0xbfb8aa3b, v126
	v_mul_f32_e32 v191, 0xbfb8aa3b, v127
	v_exp_f32_e32 v188, v188
	v_exp_f32_e32 v189, v189
	v_exp_f32_e32 v190, v190
	v_exp_f32_e32 v191, v191
	v_add_f32_e32 v188, 1.0, v188
	v_add_f32_e32 v189, 1.0, v189
	v_add_f32_e32 v190, 1.0, v190
	v_add_f32_e32 v191, 1.0, v191
	v_rcp_f32_e32 v188, v188
	v_rcp_f32_e32 v189, v189
	v_rcp_f32_e32 v190, v190
	v_rcp_f32_e32 v191, v191
	v_mul_f32_e32 v188, v124, v188
	v_mul_f32_e32 v189, v125, v189
	v_mul_f32_e32 v190, v126, v190
	v_mul_f32_e32 v191, v127, v191
	v_mul_f32_e32 v188, v116, v188
	v_mul_f32_e32 v189, v117, v189
	v_mul_f32_e32 v190, v118, v190
	v_mul_f32_e32 v191, v119, v191
	v_cvt_pk_bf16_f32 v200, v188, v189
	v_cvt_pk_bf16_f32 v201, v190, v191
	global_store_dwordx2 v224, v[200:201], s[8:9] offset:0
	v_mul_f32_e32 v188, 0xbfb8aa3b, v120
	v_mul_f32_e32 v189, 0xbfb8aa3b, v121
	v_mul_f32_e32 v190, 0xbfb8aa3b, v122
	v_mul_f32_e32 v191, 0xbfb8aa3b, v123
	v_exp_f32_e32 v188, v188
	v_exp_f32_e32 v189, v189
	v_exp_f32_e32 v190, v190
	v_exp_f32_e32 v191, v191
	v_add_f32_e32 v188, 1.0, v188
	v_add_f32_e32 v189, 1.0, v189
	v_add_f32_e32 v190, 1.0, v190
	v_add_f32_e32 v191, 1.0, v191
	v_rcp_f32_e32 v188, v188
	v_rcp_f32_e32 v189, v189
	v_rcp_f32_e32 v190, v190
	v_rcp_f32_e32 v191, v191
	v_mul_f32_e32 v188, v120, v188
	v_mul_f32_e32 v189, v121, v189
	v_mul_f32_e32 v190, v122, v190
	v_mul_f32_e32 v191, v123, v191
	v_mul_f32_e32 v188, v112, v188
	v_mul_f32_e32 v189, v113, v189
	v_mul_f32_e32 v190, v114, v190
	v_mul_f32_e32 v191, v115, v191
	v_cvt_pk_bf16_f32 v202, v188, v189
	v_cvt_pk_bf16_f32 v203, v190, v191
	global_store_dwordx2 v224, v[202:203], s[8:9] offset:32
	v_add_u32_e32 v224, 0x16000, v224
	v_mul_f32_e32 v188, 0xbfb8aa3b, v108
	v_mul_f32_e32 v189, 0xbfb8aa3b, v109
	v_mul_f32_e32 v190, 0xbfb8aa3b, v110
	v_mul_f32_e32 v191, 0xbfb8aa3b, v111
	v_exp_f32_e32 v188, v188
	v_exp_f32_e32 v189, v189
	v_exp_f32_e32 v190, v190
	v_exp_f32_e32 v191, v191
	v_add_f32_e32 v188, 1.0, v188
	v_add_f32_e32 v189, 1.0, v189
	v_add_f32_e32 v190, 1.0, v190
	v_add_f32_e32 v191, 1.0, v191
	v_rcp_f32_e32 v188, v188
	v_rcp_f32_e32 v189, v189
	v_rcp_f32_e32 v190, v190
	v_rcp_f32_e32 v191, v191
	v_mul_f32_e32 v188, v108, v188
	v_mul_f32_e32 v189, v109, v189
	v_mul_f32_e32 v190, v110, v190
	v_mul_f32_e32 v191, v111, v191
	v_mul_f32_e32 v188, v100, v188
	v_mul_f32_e32 v189, v101, v189
	v_mul_f32_e32 v190, v102, v190
	v_mul_f32_e32 v191, v103, v191
	v_cvt_pk_bf16_f32 v204, v188, v189
	v_cvt_pk_bf16_f32 v205, v190, v191
	global_store_dwordx2 v224, v[204:205], s[8:9] offset:0
	v_mul_f32_e32 v188, 0xbfb8aa3b, v104
	v_mul_f32_e32 v189, 0xbfb8aa3b, v105
	v_mul_f32_e32 v190, 0xbfb8aa3b, v106
	v_mul_f32_e32 v191, 0xbfb8aa3b, v107
	v_exp_f32_e32 v188, v188
	v_exp_f32_e32 v189, v189
	v_exp_f32_e32 v190, v190
	v_exp_f32_e32 v191, v191
	v_add_f32_e32 v188, 1.0, v188
	v_add_f32_e32 v189, 1.0, v189
	v_add_f32_e32 v190, 1.0, v190
; DI u16 f2bf(float a) { return (u16)(pk2(a, 0.f) & 0xffffu); }
; DI float sigmoidf_(float x) { return __builtin_amdgcn_rcpf(1.f + __builtin_amdgcn_exp2f(-1.4426950408889634f * x)); }
; template <int EPI>
; DI void gemm_phase(const u16* __restrict__ A, int lda, const u16* __restrict__ Bt, int K, int N, u16* outb, int ldo,
;                    const float* r0, const float* r1, float* outf, char* lds, int bid, int nb) {
;     ...
;       for (int i = 0; i < 8; ++i)
; #pragma unroll
;         for (int r = 0; r < 4; ++r) {
;           const float g0 = acc[i][0][r], u0 = acc[i][2][r], g1 = acc[i][1][r], u1 = acc[i][3][r];
;           u16* o0 = outb + (size_t)(mrow + i * 16 + r) * ldo + col;
;           o0[0] = f2bf(g0 * sigmoidf_(g0) * u0); o0[16] = f2bf(g1 * sigmoidf_(g1) * u1);
;         }
	v_add_f32_e32 v191, 1.0, v191
	v_rcp_f32_e32 v188, v188
	v_rcp_f32_e32 v189, v189
	v_rcp_f32_e32 v190, v190
	v_rcp_f32_e32 v191, v191
	v_mul_f32_e32 v188, v104, v188
	v_mul_f32_e32 v189, v105, v189
	v_mul_f32_e32 v190, v106, v190
	v_mul_f32_e32 v191, v107, v191
	v_mul_f32_e32 v188, v96, v188
	v_mul_f32_e32 v189, v97, v189
	v_mul_f32_e32 v190, v98, v190
	v_mul_f32_e32 v191, v99, v191
	v_cvt_pk_bf16_f32 v206, v188, v189
	v_cvt_pk_bf16_f32 v207, v190, v191
	global_store_dwordx2 v224, v[206:207], s[8:9] offset:32
	v_add_u32_e32 v224, 0x16000, v224
	v_mul_f32_e32 v188, 0xbfb8aa3b, v92
	v_mul_f32_e32 v189, 0xbfb8aa3b, v93
	v_mul_f32_e32 v190, 0xbfb8aa3b, v94
	v_mul_f32_e32 v191, 0xbfb8aa3b, v95
	v_exp_f32_e32 v188, v188
	v_exp_f32_e32 v189, v189
	v_exp_f32_e32 v190, v190
	v_exp_f32_e32 v191, v191
	v_add_f32_e32 v188, 1.0, v188
	v_add_f32_e32 v189, 1.0, v189
	v_add_f32_e32 v190, 1.0, v190
	v_add_f32_e32 v191, 1.0, v191
	v_rcp_f32_e32 v188, v188
	v_rcp_f32_e32 v189, v189
	v_rcp_f32_e32 v190, v190
	v_rcp_f32_e32 v191, v191
	v_mul_f32_e32 v188, v92, v188
	v_mul_f32_e32 v189, v93, v189
	v_mul_f32_e32 v190, v94, v190
	v_mul_f32_e32 v191, v95, v191
	v_mul_f32_e32 v188, v84, v188
	v_mul_f32_e32 v189, v85, v189
	v_mul_f32_e32 v190, v86, v190
	v_mul_f32_e32 v191, v87, v191
	v_cvt_pk_bf16_f32 v208, v188, v189
	v_cvt_pk_bf16_f32 v209, v190, v191
	global_store_dwordx2 v224, v[208:209], s[8:9] offset:0
	v_mul_f32_e32 v188, 0xbfb8aa3b, v88
	v_mul_f32_e32 v189, 0xbfb8aa3b, v89
	v_mul_f32_e32 v190, 0xbfb8aa3b, v90
	v_mul_f32_e32 v191, 0xbfb8aa3b, v91
	v_exp_f32_e32 v188, v188
	v_exp_f32_e32 v189, v189
	v_exp_f32_e32 v190, v190
	v_exp_f32_e32 v191, v191
	v_add_f32_e32 v188, 1.0, v188
	v_add_f32_e32 v189, 1.0, v189
	v_add_f32_e32 v190, 1.0, v190
	v_add_f32_e32 v191, 1.0, v191
	v_rcp_f32_e32 v188, v188
	v_rcp_f32_e32 v189, v189
	v_rcp_f32_e32 v190, v190
	v_rcp_f32_e32 v191, v191
	v_mul_f32_e32 v188, v88, v188
	v_mul_f32_e32 v189, v89, v189
	v_mul_f32_e32 v190, v90, v190
	v_mul_f32_e32 v191, v91, v191
	v_mul_f32_e32 v188, v80, v188
	v_mul_f32_e32 v189, v81, v189
	v_mul_f32_e32 v190, v82, v190
	v_mul_f32_e32 v191, v83, v191
	v_cvt_pk_bf16_f32 v210, v188, v189
	v_cvt_pk_bf16_f32 v211, v190, v191
	global_store_dwordx2 v224, v[210:211], s[8:9] offset:32
	v_add_u32_e32 v224, 0x16000, v224
	v_mul_f32_e32 v188, 0xbfb8aa3b, v76
	v_mul_f32_e32 v189, 0xbfb8aa3b, v77
	v_mul_f32_e32 v190, 0xbfb8aa3b, v78
	v_mul_f32_e32 v191, 0xbfb8aa3b, v79
	v_exp_f32_e32 v188, v188
	v_exp_f32_e32 v189, v189
	v_exp_f32_e32 v190, v190
	v_exp_f32_e32 v191, v191
	v_add_f32_e32 v188, 1.0, v188
	v_add_f32_e32 v189, 1.0, v189
	v_add_f32_e32 v190, 1.0, v190
	v_add_f32_e32 v191, 1.0, v191
	v_rcp_f32_e32 v188, v188
	v_rcp_f32_e32 v189, v189
	v_rcp_f32_e32 v190, v190
	v_rcp_f32_e32 v191, v191
	v_mul_f32_e32 v188, v76, v188
	v_mul_f32_e32 v189, v77, v189
	v_mul_f32_e32 v190, v78, v190
	v_mul_f32_e32 v191, v79, v191
	v_mul_f32_e32 v188, v68, v188
	v_mul_f32_e32 v189, v69, v189
	v_mul_f32_e32 v190, v70, v190
	v_mul_f32_e32 v191, v71, v191
	v_cvt_pk_bf16_f32 v212, v188, v189
	v_cvt_pk_bf16_f32 v213, v190, v191
	global_store_dwordx2 v224, v[212:213], s[8:9] offset:0
	v_mul_f32_e32 v188, 0xbfb8aa3b, v72
	v_mul_f32_e32 v189, 0xbfb8aa3b, v73
	v_mul_f32_e32 v190, 0xbfb8aa3b, v74
	v_mul_f32_e32 v191, 0xbfb8aa3b, v75
	v_exp_f32_e32 v188, v188
	v_exp_f32_e32 v189, v189
	v_exp_f32_e32 v190, v190
	v_exp_f32_e32 v191, v191
	v_add_f32_e32 v188, 1.0, v188
	v_add_f32_e32 v189, 1.0, v189
	v_add_f32_e32 v190, 1.0, v190
	v_add_f32_e32 v191, 1.0, v191
	v_rcp_f32_e32 v188, v188
	v_rcp_f32_e32 v189, v189
	v_rcp_f32_e32 v190, v190
	v_rcp_f32_e32 v191, v191
	v_mul_f32_e32 v188, v72, v188
	v_mul_f32_e32 v189, v73, v189
	v_mul_f32_e32 v190, v74, v190
	v_mul_f32_e32 v191, v75, v191
	v_mul_f32_e32 v188, v64, v188
	v_mul_f32_e32 v189, v65, v189
	v_mul_f32_e32 v190, v66, v190
	v_mul_f32_e32 v191, v67, v191
	v_cvt_pk_bf16_f32 v214, v188, v189
	v_cvt_pk_bf16_f32 v215, v190, v191
	global_store_dwordx2 v224, v[214:215], s[8:9] offset:32
	v_add_u32_e32 v224, 0x16000, v224
	v_mul_f32_e32 v188, 0xbfb8aa3b, v60
	v_mul_f32_e32 v189, 0xbfb8aa3b, v61
	v_mul_f32_e32 v190, 0xbfb8aa3b, v62
	v_mul_f32_e32 v191, 0xbfb8aa3b, v63
	v_exp_f32_e32 v188, v188
	v_exp_f32_e32 v189, v189
	v_exp_f32_e32 v190, v190
	v_exp_f32_e32 v191, v191
	v_add_f32_e32 v188, 1.0, v188
	v_add_f32_e32 v189, 1.0, v189
	v_add_f32_e32 v190, 1.0, v190
	v_add_f32_e32 v191, 1.0, v191
	v_rcp_f32_e32 v188, v188
	v_rcp_f32_e32 v189, v189
	v_rcp_f32_e32 v190, v190
	v_rcp_f32_e32 v191, v191
	v_mul_f32_e32 v188, v60, v188
	v_mul_f32_e32 v189, v61, v189
	v_mul_f32_e32 v190, v62, v190
	v_mul_f32_e32 v191, v63, v191
	v_mul_f32_e32 v188, v52, v188
	v_mul_f32_e32 v189, v53, v189
	v_mul_f32_e32 v190, v54, v190
	v_mul_f32_e32 v191, v55, v191
	v_cvt_pk_bf16_f32 v200, v188, v189
	v_cvt_pk_bf16_f32 v201, v190, v191
	global_store_dwordx2 v224, v[200:201], s[8:9] offset:0
	v_mul_f32_e32 v188, 0xbfb8aa3b, v56
	v_mul_f32_e32 v189, 0xbfb8aa3b, v57
	v_mul_f32_e32 v190, 0xbfb8aa3b, v58
	v_mul_f32_e32 v191, 0xbfb8aa3b, v59
	v_exp_f32_e32 v188, v188
	v_exp_f32_e32 v189, v189
	v_exp_f32_e32 v190, v190
	v_exp_f32_e32 v191, v191
	v_add_f32_e32 v188, 1.0, v188
	v_add_f32_e32 v189, 1.0, v189
	v_add_f32_e32 v190, 1.0, v190
	v_add_f32_e32 v191, 1.0, v191
	v_rcp_f32_e32 v188, v188
	v_rcp_f32_e32 v189, v189
	v_rcp_f32_e32 v190, v190
	v_rcp_f32_e32 v191, v191
	v_mul_f32_e32 v188, v56, v188
	v_mul_f32_e32 v189, v57, v189
	v_mul_f32_e32 v190, v58, v190
	v_mul_f32_e32 v191, v59, v191
	v_mul_f32_e32 v188, v48, v188
; DI u16 f2bf(float a) { return (u16)(pk2(a, 0.f) & 0xffffu); }
; DI float sigmoidf_(float x) { return __builtin_amdgcn_rcpf(1.f + __builtin_amdgcn_exp2f(-1.4426950408889634f * x)); }
; template <int EPI>
; DI void gemm_phase(const u16* __restrict__ A, int lda, const u16* __restrict__ Bt, int K, int N, u16* outb, int ldo,
;                    const float* r0, const float* r1, float* outf, char* lds, int bid, int nb) {
;     ...
;       for (int i = 0; i < 8; ++i)
; #pragma unroll
;         for (int r = 0; r < 4; ++r) {
;           const float g0 = acc[i][0][r], u0 = acc[i][2][r], g1 = acc[i][1][r], u1 = acc[i][3][r];
;           u16* o0 = outb + (size_t)(mrow + i * 16 + r) * ldo + col;
;           o0[0] = f2bf(g0 * sigmoidf_(g0) * u0); o0[16] = f2bf(g1 * sigmoidf_(g1) * u1);
;         }
	v_mul_f32_e32 v189, v49, v189
	v_mul_f32_e32 v190, v50, v190
	v_mul_f32_e32 v191, v51, v191
	v_cvt_pk_bf16_f32 v202, v188, v189
	v_cvt_pk_bf16_f32 v203, v190, v191
	global_store_dwordx2 v224, v[202:203], s[8:9] offset:32
	v_add_u32_e32 v224, 0x16000, v224
	v_mul_f32_e32 v188, 0xbfb8aa3b, v44
	v_mul_f32_e32 v189, 0xbfb8aa3b, v45
	v_mul_f32_e32 v190, 0xbfb8aa3b, v46
	v_mul_f32_e32 v191, 0xbfb8aa3b, v47
	v_exp_f32_e32 v188, v188
	v_exp_f32_e32 v189, v189
	v_exp_f32_e32 v190, v190
	v_exp_f32_e32 v191, v191
	v_add_f32_e32 v188, 1.0, v188
	v_add_f32_e32 v189, 1.0, v189
	v_add_f32_e32 v190, 1.0, v190
	v_add_f32_e32 v191, 1.0, v191
	v_rcp_f32_e32 v188, v188
	v_rcp_f32_e32 v189, v189
	v_rcp_f32_e32 v190, v190
	v_rcp_f32_e32 v191, v191
	v_mul_f32_e32 v188, v44, v188
	v_mul_f32_e32 v189, v45, v189
	v_mul_f32_e32 v190, v46, v190
	v_mul_f32_e32 v191, v47, v191
	v_mul_f32_e32 v188, v36, v188
	v_mul_f32_e32 v189, v37, v189
	v_mul_f32_e32 v190, v38, v190
	v_mul_f32_e32 v191, v39, v191
	v_cvt_pk_bf16_f32 v204, v188, v189
	v_cvt_pk_bf16_f32 v205, v190, v191
	global_store_dwordx2 v224, v[204:205], s[8:9] offset:0
	v_mul_f32_e32 v188, 0xbfb8aa3b, v40
	v_mul_f32_e32 v189, 0xbfb8aa3b, v41
	v_mul_f32_e32 v190, 0xbfb8aa3b, v42
	v_mul_f32_e32 v191, 0xbfb8aa3b, v43
	v_exp_f32_e32 v188, v188
	v_exp_f32_e32 v189, v189
	v_exp_f32_e32 v190, v190
	v_exp_f32_e32 v191, v191
	v_add_f32_e32 v188, 1.0, v188
	v_add_f32_e32 v189, 1.0, v189
	v_add_f32_e32 v190, 1.0, v190
	v_add_f32_e32 v191, 1.0, v191
	v_rcp_f32_e32 v188, v188
	v_rcp_f32_e32 v189, v189
	v_rcp_f32_e32 v190, v190
	v_rcp_f32_e32 v191, v191
	v_mul_f32_e32 v188, v40, v188
	v_mul_f32_e32 v189, v41, v189
	v_mul_f32_e32 v190, v42, v190
	v_mul_f32_e32 v191, v43, v191
	v_mul_f32_e32 v188, v32, v188
	v_mul_f32_e32 v189, v33, v189
	v_mul_f32_e32 v190, v34, v190
	v_mul_f32_e32 v191, v35, v191
	v_cvt_pk_bf16_f32 v206, v188, v189
	v_cvt_pk_bf16_f32 v207, v190, v191
	global_store_dwordx2 v224, v[206:207], s[8:9] offset:32
	v_add_u32_e32 v224, 0x16000, v224
	v_mul_f32_e32 v188, 0xbfb8aa3b, v28
	v_mul_f32_e32 v189, 0xbfb8aa3b, v29
	v_mul_f32_e32 v190, 0xbfb8aa3b, v30
	v_mul_f32_e32 v191, 0xbfb8aa3b, v31
	v_exp_f32_e32 v188, v188
	v_exp_f32_e32 v189, v189
	v_exp_f32_e32 v190, v190
	v_exp_f32_e32 v191, v191
	v_add_f32_e32 v188, 1.0, v188
	v_add_f32_e32 v189, 1.0, v189
	v_add_f32_e32 v190, 1.0, v190
	v_add_f32_e32 v191, 1.0, v191
	v_rcp_f32_e32 v188, v188
	v_rcp_f32_e32 v189, v189
	v_rcp_f32_e32 v190, v190
	v_rcp_f32_e32 v191, v191
	v_mul_f32_e32 v188, v28, v188
	v_mul_f32_e32 v189, v29, v189
	v_mul_f32_e32 v190, v30, v190
	v_mul_f32_e32 v191, v31, v191
	v_mul_f32_e32 v188, v20, v188
	v_mul_f32_e32 v189, v21, v189
	v_mul_f32_e32 v190, v22, v190
	v_mul_f32_e32 v191, v23, v191
	v_cvt_pk_bf16_f32 v208, v188, v189
	v_cvt_pk_bf16_f32 v209, v190, v191
	global_store_dwordx2 v224, v[208:209], s[8:9] offset:0
	v_mul_f32_e32 v188, 0xbfb8aa3b, v24
	v_mul_f32_e32 v189, 0xbfb8aa3b, v25
	v_mul_f32_e32 v190, 0xbfb8aa3b, v26
	v_mul_f32_e32 v191, 0xbfb8aa3b, v27
	v_exp_f32_e32 v188, v188
	v_exp_f32_e32 v189, v189
	v_exp_f32_e32 v190, v190
	v_exp_f32_e32 v191, v191
	v_add_f32_e32 v188, 1.0, v188
	v_add_f32_e32 v189, 1.0, v189
	v_add_f32_e32 v190, 1.0, v190
	v_add_f32_e32 v191, 1.0, v191
	v_rcp_f32_e32 v188, v188
	v_rcp_f32_e32 v189, v189
	v_rcp_f32_e32 v190, v190
	v_rcp_f32_e32 v191, v191
	v_mul_f32_e32 v188, v24, v188
	v_mul_f32_e32 v189, v25, v189
	v_mul_f32_e32 v190, v26, v190
	v_mul_f32_e32 v191, v27, v191
	v_mul_f32_e32 v188, v16, v188
	v_mul_f32_e32 v189, v17, v189
	v_mul_f32_e32 v190, v18, v190
	v_mul_f32_e32 v191, v19, v191
	v_cvt_pk_bf16_f32 v210, v188, v189
	v_cvt_pk_bf16_f32 v211, v190, v191
	global_store_dwordx2 v224, v[210:211], s[8:9] offset:32
	v_add_u32_e32 v224, 0x16000, v224
	v_mul_f32_e32 v188, 0xbfb8aa3b, v12
	v_mul_f32_e32 v189, 0xbfb8aa3b, v13
	v_mul_f32_e32 v190, 0xbfb8aa3b, v14
	v_mul_f32_e32 v191, 0xbfb8aa3b, v15
	v_exp_f32_e32 v188, v188
	v_exp_f32_e32 v189, v189
	v_exp_f32_e32 v190, v190
	v_exp_f32_e32 v191, v191
	v_add_f32_e32 v188, 1.0, v188
	v_add_f32_e32 v189, 1.0, v189
	v_add_f32_e32 v190, 1.0, v190
	v_add_f32_e32 v191, 1.0, v191
	v_rcp_f32_e32 v188, v188
	v_rcp_f32_e32 v189, v189
	v_rcp_f32_e32 v190, v190
	v_rcp_f32_e32 v191, v191
	v_mul_f32_e32 v188, v12, v188
	v_mul_f32_e32 v189, v13, v189
	v_mul_f32_e32 v190, v14, v190
	v_mul_f32_e32 v191, v15, v191
	v_mul_f32_e32 v188, v4, v188
	v_mul_f32_e32 v189, v5, v189
	v_mul_f32_e32 v190, v6, v190
	v_mul_f32_e32 v191, v7, v191
	v_cvt_pk_bf16_f32 v212, v188, v189
	v_cvt_pk_bf16_f32 v213, v190, v191
	global_store_dwordx2 v224, v[212:213], s[8:9] offset:0
	v_mul_f32_e32 v188, 0xbfb8aa3b, v8
	v_mul_f32_e32 v189, 0xbfb8aa3b, v9
	v_mul_f32_e32 v190, 0xbfb8aa3b, v10
	v_mul_f32_e32 v191, 0xbfb8aa3b, v11
	v_exp_f32_e32 v188, v188
	v_exp_f32_e32 v189, v189
	v_exp_f32_e32 v190, v190
	v_exp_f32_e32 v191, v191
	v_add_f32_e32 v188, 1.0, v188
	v_add_f32_e32 v189, 1.0, v189
	v_add_f32_e32 v190, 1.0, v190
	v_add_f32_e32 v191, 1.0, v191
	v_rcp_f32_e32 v188, v188
	v_rcp_f32_e32 v189, v189
	v_rcp_f32_e32 v190, v190
	v_rcp_f32_e32 v191, v191
	v_mul_f32_e32 v188, v8, v188
	v_mul_f32_e32 v189, v9, v189
	v_mul_f32_e32 v190, v10, v190
	v_mul_f32_e32 v191, v11, v191
	v_mul_f32_e32 v188, v0, v188
	v_mul_f32_e32 v189, v1, v189
	v_mul_f32_e32 v190, v2, v190
	v_mul_f32_e32 v191, v3, v191
	v_cvt_pk_bf16_f32 v214, v188, v189
	v_cvt_pk_bf16_f32 v215, v190, v191
	global_store_dwordx2 v224, v[214:215], s[8:9] offset:32
	s_add_i32 s19, s19, 1
	s_cmp_eq_u32 s19, s3
	s_cbranch_scc0 .LBB0_697

; #define G_LOAD(KT) do { _Pragma("unroll") for (int i = 0; i < 4; ++i) { ra[i] = *(const u32x4*)(Ag + (size_t)i * 64 * lda + (KT) * 64); rb[i] = *(const u32x4*)(Bg + (size_t)i * 64 * K + (KT) * 64); } } while (0)
; #define G_STORE(BUF) do { u16* ad = As + (BUF) * 256 * 64 + sto; u16* bd = Bs + (BUF) * 256 * 64 + sto; _Pragma("unroll") for (int i = 0; i < 4; ++i) { *(u32x4*)(ad + i * 64 * 64) = ra[i]; *(u32x4*)(bd + i * 64 * 64) = rb[i]; } } while (0)
; template <int EPI>
; DI void gemm_phase(const u16* __restrict__ A, int lda, const u16* __restrict__ Bt, int K, int N, u16* outb, int ldo,
;                    const float* r0, const float* r1, float* outf, char* lds, int bid, int nb) {
;     ...
;   for (int it = 0; it < nIter; ++it) {
;     int tm, tn;
;     if (swz) { const int st = xcd + 8 * it, sm = st / nSN, sn = st - sm * nSN; tm = sm * GM + jb / GN; tn = sn * GN + (jb % GN); }
;     else { const int t = bid + it * nb; tm = t / nN; tn = t - tm * nN; }
;     const u16* Ag = A + (size_t)(tm * 256 + lrow) * lda + lch * 8;
;     const u16* Bg = Bt + (size_t)(tn * 256 + lrow) * K + lch * 8;
;     f32x4 acc[8][4];
; #pragma unroll
;     for (int i = 0; i < 8; ++i)
; #pragma unroll
;       for (int j = 0; j < 4; ++j) acc[i][j] = (f32x4){0.f, 0.f, 0.f, 0.f};
;     u32x4 ra[4], rb[4];
;     ...
;     G_LOAD(0);
;     G_STORE(0);
;     __syncthreads();
.LBB0_763:
	s_lshl_b32 s39, s39, 8
	v_or_b32_e32 v60, s39, v138
	s_lshl_b32 s46, s46, 8
	v_mad_i64_i32 v[0:1], s[8:9], v60, s17, v[128:129]
	v_or_b32_e32 v61, s46, v138
	v_add_co_u32_e32 v4, vcc, 0x58000, v0
	v_mad_i64_i32 v[2:3], s[8:9], v61, s17, v[130:131]
	s_nop 0
	v_addc_co_u32_e32 v5, vcc, 0, v1, vcc
	v_add_co_u32_e32 v6, vcc, 0x58000, v2
	s_nop 1
	v_readfirstlane_b32 s98, v0
	v_readfirstlane_b32 s99, v1
	s_nop 1
	v_readfirstlane_b32 s100, v2
	v_readfirstlane_b32 s101, v3
	v_addc_co_u32_e32 v7, vcc, 0, v3, vcc
	v_add_co_u32_e32 v4, vcc, 0xb0000, v0
	s_mov_b32 s47, 0
	s_nop 0
	v_addc_co_u32_e32 v5, vcc, 0, v1, vcc
	v_add_co_u32_e32 v6, vcc, 0xb0000, v2
	s_mov_b64 s[8:9], 0
	s_nop 0
	v_addc_co_u32_e32 v7, vcc, 0, v3, vcc
	v_add_co_u32_e32 v0, vcc, 0x108000, v0
	v_addc_co_u32_e32 v1, vcc, 0, v1, vcc
	v_add_co_u32_e32 v2, vcc, 0x108000, v2
	v_mad_i64_i32 v[134:135], s[28:29], v60, s17, v[132:133]
	s_nop 0
	v_addc_co_u32_e32 v3, vcc, 0, v3, vcc
	v_mov_b32_e32 v0, 0
	v_mov_b32_e32 v1, v0
	v_mov_b32_e32 v2, v0
	v_mov_b32_e32 v3, v0
	v_mov_b32_e32 v4, v0
	v_mov_b32_e32 v5, v0
	v_mov_b32_e32 v6, v0
	v_mov_b32_e32 v7, v0
	v_mov_b32_e32 v8, v0
	v_mov_b32_e32 v9, v0
	v_mov_b32_e32 v10, v0
	v_mov_b32_e32 v11, v0
	v_mov_b32_e32 v12, v0
	v_mov_b32_e32 v13, v0
	v_mov_b32_e32 v14, v0
	v_mov_b32_e32 v15, v0
	v_mov_b32_e32 v16, v0
	v_mov_b32_e32 v17, v0
	v_mov_b32_e32 v18, v0
	v_mov_b32_e32 v19, v0
	v_mov_b32_e32 v20, v0
	v_mov_b32_e32 v21, v0
	v_mov_b32_e32 v22, v0
	v_mov_b32_e32 v23, v0
	v_mov_b32_e32 v24, v0
	v_mov_b32_e32 v25, v0
	v_mov_b32_e32 v26, v0
	v_mov_b32_e32 v27, v0
	v_mad_i64_i32 v[136:137], s[28:29], v61, s17, v[132:133]
	v_mov_b32_e32 v60, v0
	v_mov_b32_e32 v61, v0
	v_mov_b32_e32 v62, v0
	v_mov_b32_e32 v63, v0
	v_mov_b32_e32 v64, v0
	v_mov_b32_e32 v65, v0
	v_mov_b32_e32 v66, v0
	v_mov_b32_e32 v67, v0
	v_mov_b32_e32 v68, v0
	v_mov_b32_e32 v69, v0
	v_mov_b32_e32 v70, v0
	v_mov_b32_e32 v71, v0
	v_mov_b32_e32 v72, v0
	v_mov_b32_e32 v73, v0
	v_mov_b32_e32 v74, v0
	v_mov_b32_e32 v75, v0
	v_mov_b32_e32 v76, v0
	v_mov_b32_e32 v77, v0
	v_mov_b32_e32 v78, v0
	v_mov_b32_e32 v79, v0
	v_mov_b32_e32 v80, v0
	v_mov_b32_e32 v81, v0
	v_mov_b32_e32 v82, v0
	v_mov_b32_e32 v83, v0
	v_mov_b32_e32 v28, v0
	v_mov_b32_e32 v29, v0
	v_mov_b32_e32 v30, v0
	v_mov_b32_e32 v31, v0
	v_mov_b32_e32 v32, v0
	v_mov_b32_e32 v33, v0
	v_mov_b32_e32 v34, v0
	v_mov_b32_e32 v35, v0
	v_mov_b32_e32 v36, v0
	v_mov_b32_e32 v37, v0
	v_mov_b32_e32 v38, v0
	v_mov_b32_e32 v39, v0
	v_mov_b32_e32 v40, v0
	v_mov_b32_e32 v41, v0
	v_mov_b32_e32 v42, v0
	v_mov_b32_e32 v43, v0
	v_mov_b32_e32 v44, v0
	v_mov_b32_e32 v45, v0
	v_mov_b32_e32 v46, v0
	v_mov_b32_e32 v47, v0
	v_mov_b32_e32 v48, v0
	v_mov_b32_e32 v49, v0
	v_mov_b32_e32 v50, v0
	v_mov_b32_e32 v51, v0
	v_mov_b32_e32 v52, v0
	v_mov_b32_e32 v53, v0
	v_mov_b32_e32 v54, v0
	v_mov_b32_e32 v55, v0
	v_mov_b32_e32 v56, v0
	v_mov_b32_e32 v57, v0
	v_mov_b32_e32 v58, v0
	v_mov_b32_e32 v59, v0
	v_mov_b32_e32 v84, v0
	v_mov_b32_e32 v85, v0
	v_mov_b32_e32 v86, v0
	v_mov_b32_e32 v87, v0
	v_mov_b32_e32 v88, v0
	v_mov_b32_e32 v89, v0
	v_mov_b32_e32 v90, v0
	v_mov_b32_e32 v91, v0
	v_mov_b32_e32 v92, v0
	v_mov_b32_e32 v93, v0
	v_mov_b32_e32 v94, v0
	v_mov_b32_e32 v95, v0
	v_mov_b32_e32 v96, v0
	v_mov_b32_e32 v97, v0
	v_mov_b32_e32 v98, v0
	v_mov_b32_e32 v99, v0
	v_mov_b32_e32 v100, v0
	v_mov_b32_e32 v101, v0
	v_mov_b32_e32 v102, v0
	v_mov_b32_e32 v103, v0
	v_mov_b32_e32 v104, v0
	v_mov_b32_e32 v105, v0
	v_mov_b32_e32 v106, v0
	v_mov_b32_e32 v107, v0
	v_mov_b32_e32 v108, v0
	v_mov_b32_e32 v109, v0
	v_mov_b32_e32 v110, v0
	v_mov_b32_e32 v111, v0
	v_mov_b32_e32 v112, v0
	v_mov_b32_e32 v113, v0
	v_mov_b32_e32 v114, v0
	v_mov_b32_e32 v115, v0
	v_mov_b32_e32 v116, v0
	v_mov_b32_e32 v117, v0
	v_mov_b32_e32 v118, v0
	v_mov_b32_e32 v119, v0
	v_mov_b32_e32 v120, v0
	v_mov_b32_e32 v121, v0
	v_mov_b32_e32 v122, v0
	v_mov_b32_e32 v123, v0
	v_mov_b32_e32 v124, v0
	v_mov_b32_e32 v125, v0
	v_mov_b32_e32 v126, v0
	v_mov_b32_e32 v127, v0
	v_and_b32_e32 v229, 63, v174
	v_lshrrev_b32_e32 v230, 3, v229
	v_mov_b32_e32 v233, 0x1600
	v_mul_u32_u24_e32 v224, v230, v233
	v_bfe_u32 v231, v174, 4, 2
	v_bfe_u32 v232, v174, 6, 1
	v_lshl_or_b32 v232, v232, 2, v231
	v_and_b32_e32 v233, 7, v174
	v_xor_b32_e32 v232, v232, v233
	v_lshl_add_u32 v224, v232, 4, v224
	v_and_b32_e32 v229, 15, v174
	v_bfe_u32 v230, v174, 1, 3
	v_xor_b32_e32 v230, v230, v231
	v_lshlrev_b32_e32 v230, 4, v230
	v_lshl_or_b32 v230, v229, 7, v230
	v_lshrrev_b32_e32 v229, 8, v174
	v_lshl_or_b32 v225, v229, 14, v230
	v_bfe_u32 v229, v174, 6, 2
	v_lshl_or_b32 v227, v229, 13, v230
	v_or_b32_e32 v227, 0x10000, v227
	v_xor_b32_e32 v226, 64, v225
	v_xor_b32_e32 v228, 64, v227
	v_readfirstlane_b32 s97, v174
	s_lshl_b32 s97, s97, 4
	s_mov_b32 s28, 42
	s_add_u32 m0, s97, 0x0
	s_add_u32 s8, s98, 0x0
	s_addc_u32 s9, s99, 0
	global_load_lds_dwordx4 v224, s[8:9]
	s_add_u32 m0, s97, 0x10000
	s_add_u32 s8, s100, 0x0
	s_addc_u32 s9, s101, 0
	global_load_lds_dwordx4 v224, s[8:9]
	s_add_u32 m0, s97, 0x2000
	s_add_u32 s8, s98, 0x58000
	s_addc_u32 s9, s99, 0
	global_load_lds_dwordx4 v224, s[8:9]
	s_add_u32 m0, s97, 0x12000
	s_add_u32 s8, s100, 0x58000
	s_addc_u32 s9, s101, 0
	global_load_lds_dwordx4 v224, s[8:9]
	s_add_u32 m0, s97, 0x4000
	s_add_u32 s8, s98, 0xb0000
	s_addc_u32 s9, s99, 0
	global_load_lds_dwordx4 v224, s[8:9]
	s_add_u32 m0, s97, 0x14000
	s_add_u32 s8, s100, 0xb0000
	s_addc_u32 s9, s101, 0
	global_load_lds_dwordx4 v224, s[8:9]
	s_add_u32 m0, s97, 0x6000
	s_add_u32 s8, s98, 0x108000
	s_addc_u32 s9, s99, 0
	global_load_lds_dwordx4 v224, s[8:9]
	s_add_u32 m0, s97, 0x16000
	s_add_u32 s8, s100, 0x108000
	s_addc_u32 s9, s101, 0
	global_load_lds_dwordx4 v224, s[8:9]
	s_add_u32 m0, s97, 0x8000
	s_add_u32 s8, s98, 0x80
	s_addc_u32 s9, s99, 0
	global_load_lds_dwordx4 v224, s[8:9]
	s_add_u32 m0, s97, 0x18000
	s_add_u32 s8, s100, 0x80
	s_addc_u32 s9, s101, 0
	global_load_lds_dwordx4 v224, s[8:9]
	s_add_u32 m0, s97, 0xa000
	s_add_u32 s8, s98, 0x58080
	s_addc_u32 s9, s99, 0
	global_load_lds_dwordx4 v224, s[8:9]
	s_add_u32 m0, s97, 0x1a000
	s_add_u32 s8, s100, 0x58080
	s_addc_u32 s9, s101, 0
	global_load_lds_dwordx4 v224, s[8:9]
	s_add_u32 m0, s97, 0xc000
	s_add_u32 s8, s98, 0xb0080
	s_addc_u32 s9, s99, 0
	global_load_lds_dwordx4 v224, s[8:9]
	s_add_u32 m0, s97, 0x1c000
	s_add_u32 s8, s100, 0xb0080
	s_addc_u32 s9, s101, 0
	global_load_lds_dwordx4 v224, s[8:9]
	s_add_u32 m0, s97, 0xe000
	s_add_u32 s8, s98, 0x108080
	s_addc_u32 s9, s99, 0
	global_load_lds_dwordx4 v224, s[8:9]
	s_add_u32 m0, s97, 0x1e000
	s_add_u32 s8, s100, 0x108080
	s_addc_u32 s9, s101, 0
	global_load_lds_dwordx4 v224, s[8:9]
	s_add_u32 s98, s98, 0x100
	s_addc_u32 s99, s99, 0
	s_add_u32 s100, s100, 0x100
	s_addc_u32 s101, s101, 0
	s_waitcnt vmcnt(8)
	s_barrier
; #define G_LOAD(KT) do { _Pragma("unroll") for (int i = 0; i < 4; ++i) { ra[i] = *(const u32x4*)(Ag + (size_t)i * 64 * lda + (KT) * 64); rb[i] = *(const u32x4*)(Bg + (size_t)i * 64 * K + (KT) * 64); } } while (0)
; #define G_STORE(BUF) do { u16* ad = As + (BUF) * 256 * 64 + sto; u16* bd = Bs + (BUF) * 256 * 64 + sto; _Pragma("unroll") for (int i = 0; i < 4; ++i) { *(u32x4*)(ad + i * 64 * 64) = ra[i]; *(u32x4*)(bd + i * 64 * 64) = rb[i]; } } while (0)
; template <int EPI>
; DI void gemm_phase(const u16* __restrict__ A, int lda, const u16* __restrict__ Bt, int K, int N, u16* outb, int ldo,
;                    const float* r0, const float* r1, float* outf, char* lds, int bid, int nb) {
;     ...
;     G_LOAD(0);
;     G_STORE(0);
;     __syncthreads();
;     for (int kt = 0; kt < nk; ++kt) {
;       const int cur = kt & 1;
;       if (kt + 1 < nk) G_LOAD(kt + 1);
;       G_MMA(cur, fo0);
;       G_MMA(cur, fo1);
;       if (kt + 1 < nk) G_STORE(cur ^ 1);
	ds_read_b128 v[152:155], v227 offset:0
	ds_read_b128 v[156:159], v227 offset:2048
	ds_read_b128 v[160:163], v227 offset:4096
	ds_read_b128 v[164:167], v227 offset:6144
	ds_read_b128 v[188:191], v225 offset:0
	ds_read_b128 v[192:195], v225 offset:2048
	ds_read_b128 v[196:199], v225 offset:4096
	ds_read_b128 v[200:203], v225 offset:6144
	ds_read_b128 v[204:207], v225 offset:8192
	ds_read_b128 v[208:211], v225 offset:10240
	ds_read_b128 v[212:215], v225 offset:12288
	ds_read_b128 v[216:219], v225 offset:14336
	v_xor_b32_e32 v225, 0x8000, v225
	v_xor_b32_e32 v227, 0x8000, v227
	s_waitcnt lgkmcnt(0)
	s_bitcmp1_b32 s97, 12
	s_cbranch_scc0 .Lgm3_noprio
	s_setprio 1
.Lgm3_noprio:
.Lgm3_loop:
	s_waitcnt lgkmcnt(4)
	v_mfma_f32_16x16x32_bf16 v[124:127], v[152:155], v[188:191], v[124:127]
	v_mfma_f32_16x16x32_bf16 v[120:123], v[156:159], v[188:191], v[120:123]
	v_mfma_f32_16x16x32_bf16 v[116:119], v[160:163], v[188:191], v[116:119]
	v_mfma_f32_16x16x32_bf16 v[112:115], v[164:167], v[188:191], v[112:115]
	ds_read_b128 v[188:191], v226 offset:0
	ds_read_b128 v[168:171], v228 offset:0
	v_mfma_f32_16x16x32_bf16 v[108:111], v[152:155], v[192:195], v[108:111]
	v_mfma_f32_16x16x32_bf16 v[104:107], v[156:159], v[192:195], v[104:107]
	v_mfma_f32_16x16x32_bf16 v[100:103], v[160:163], v[192:195], v[100:103]
	v_mfma_f32_16x16x32_bf16 v[96:99], v[164:167], v[192:195], v[96:99]
	ds_read_b128 v[192:195], v226 offset:2048
	ds_read_b128 v[176:179], v228 offset:2048
	v_mfma_f32_16x16x32_bf16 v[92:95], v[152:155], v[196:199], v[92:95]
	v_mfma_f32_16x16x32_bf16 v[88:91], v[156:159], v[196:199], v[88:91]
	v_mfma_f32_16x16x32_bf16 v[84:87], v[160:163], v[196:199], v[84:87]
	v_mfma_f32_16x16x32_bf16 v[80:83], v[164:167], v[196:199], v[80:83]
	ds_read_b128 v[196:199], v226 offset:4096
	ds_read_b128 v[180:183], v228 offset:4096
	v_mfma_f32_16x16x32_bf16 v[76:79], v[152:155], v[200:203], v[76:79]
	v_mfma_f32_16x16x32_bf16 v[72:75], v[156:159], v[200:203], v[72:75]
	v_mfma_f32_16x16x32_bf16 v[68:71], v[160:163], v[200:203], v[68:71]
	v_mfma_f32_16x16x32_bf16 v[64:67], v[164:167], v[200:203], v[64:67]
	ds_read_b128 v[200:203], v226 offset:6144
	ds_read_b128 v[184:187], v228 offset:6144
	s_waitcnt lgkmcnt(11)
	v_mfma_f32_16x16x32_bf16 v[60:63], v[152:155], v[204:207], v[60:63]
	v_mfma_f32_16x16x32_bf16 v[56:59], v[156:159], v[204:207], v[56:59]
	v_mfma_f32_16x16x32_bf16 v[52:55], v[160:163], v[204:207], v[52:55]
	v_mfma_f32_16x16x32_bf16 v[48:51], v[164:167], v[204:207], v[48:51]
	ds_read_b128 v[204:207], v226 offset:8192
	ds_read_b128 v[220:223], v226 offset:14336
	s_waitcnt lgkmcnt(11)
	v_mfma_f32_16x16x32_bf16 v[44:47], v[152:155], v[208:211], v[44:47]
	v_mfma_f32_16x16x32_bf16 v[40:43], v[156:159], v[208:211], v[40:43]
	v_mfma_f32_16x16x32_bf16 v[36:39], v[160:163], v[208:211], v[36:39]
	v_mfma_f32_16x16x32_bf16 v[32:35], v[164:167], v[208:211], v[32:35]
	ds_read_b128 v[208:211], v226 offset:10240
	s_waitcnt lgkmcnt(11)
	v_mfma_f32_16x16x32_bf16 v[28:31], v[152:155], v[212:215], v[28:31]
	v_mfma_f32_16x16x32_bf16 v[24:27], v[156:159], v[212:215], v[24:27]
	v_mfma_f32_16x16x32_bf16 v[20:23], v[160:163], v[212:215], v[20:23]
	v_mfma_f32_16x16x32_bf16 v[16:19], v[164:167], v[212:215], v[16:19]
	ds_read_b128 v[212:215], v226 offset:12288
	v_mfma_f32_16x16x32_bf16 v[12:15], v[152:155], v[216:219], v[12:15]
	v_mfma_f32_16x16x32_bf16 v[8:11], v[156:159], v[216:219], v[8:11]
	v_mfma_f32_16x16x32_bf16 v[4:7], v[160:163], v[216:219], v[4:7]
	v_mfma_f32_16x16x32_bf16 v[0:3], v[164:167], v[216:219], v[0:3]
	s_waitcnt vmcnt(0) lgkmcnt(0)
	s_barrier
	v_mfma_f32_16x16x32_bf16 v[124:127], v[168:171], v[188:191], v[124:127]
	v_mfma_f32_16x16x32_bf16 v[120:123], v[176:179], v[188:191], v[120:123]
	v_mfma_f32_16x16x32_bf16 v[116:119], v[180:183], v[188:191], v[116:119]
	v_mfma_f32_16x16x32_bf16 v[112:115], v[184:187], v[188:191], v[112:115]
	ds_read_b128 v[188:191], v225 offset:0
	ds_read_b128 v[152:155], v227 offset:0
	s_add_u32 m0, s97, 0x0
	s_add_u32 s8, s98, 0x0
	s_addc_u32 s9, s99, 0
	global_load_lds_dwordx4 v224, s[8:9]
	v_mfma_f32_16x16x32_bf16 v[108:111], v[168:171], v[192:195], v[108:111]
	v_mfma_f32_16x16x32_bf16 v[104:107], v[176:179], v[192:195], v[104:107]
	v_mfma_f32_16x16x32_bf16 v[100:103], v[180:183], v[192:195], v[100:103]
	v_mfma_f32_16x16x32_bf16 v[96:99], v[184:187], v[192:195], v[96:99]
	ds_read_b128 v[192:195], v225 offset:2048
	ds_read_b128 v[156:159], v227 offset:2048
	s_add_u32 m0, s97, 0x10000
	s_add_u32 s8, s100, 0x0
	s_addc_u32 s9, s101, 0
	global_load_lds_dwordx4 v224, s[8:9]
	v_mfma_f32_16x16x32_bf16 v[92:95], v[168:171], v[196:199], v[92:95]
	v_mfma_f32_16x16x32_bf16 v[88:91], v[176:179], v[196:199], v[88:91]
	v_mfma_f32_16x16x32_bf16 v[84:87], v[180:183], v[196:199], v[84:87]
	v_mfma_f32_16x16x32_bf16 v[80:83], v[184:187], v[196:199], v[80:83]
	ds_read_b128 v[196:199], v225 offset:4096
	ds_read_b128 v[160:163], v227 offset:4096
	s_add_u32 m0, s97, 0x2000
	s_add_u32 s8, s98, 0x58000
	s_addc_u32 s9, s99, 0
	global_load_lds_dwordx4 v224, s[8:9]
	v_mfma_f32_16x16x32_bf16 v[76:79], v[168:171], v[200:203], v[76:79]
	v_mfma_f32_16x16x32_bf16 v[72:75], v[176:179], v[200:203], v[72:75]
	v_mfma_f32_16x16x32_bf16 v[68:71], v[180:183], v[200:203], v[68:71]
	v_mfma_f32_16x16x32_bf16 v[64:67], v[184:187], v[200:203], v[64:67]
	ds_read_b128 v[200:203], v225 offset:6144
	ds_read_b128 v[164:167], v227 offset:6144
	s_add_u32 m0, s97, 0x12000
	s_add_u32 s8, s100, 0x58000
	s_addc_u32 s9, s101, 0
	global_load_lds_dwordx4 v224, s[8:9]
	v_mfma_f32_16x16x32_bf16 v[60:63], v[168:171], v[204:207], v[60:63]
	v_mfma_f32_16x16x32_bf16 v[56:59], v[176:179], v[204:207], v[56:59]
; #define G_LOAD(KT) do { _Pragma("unroll") for (int i = 0; i < 4; ++i) { ra[i] = *(const u32x4*)(Ag + (size_t)i * 64 * lda + (KT) * 64); rb[i] = *(const u32x4*)(Bg + (size_t)i * 64 * K + (KT) * 64); } } while (0)
; #define G_STORE(BUF) do { u16* ad = As + (BUF) * 256 * 64 + sto; u16* bd = Bs + (BUF) * 256 * 64 + sto; _Pragma("unroll") for (int i = 0; i < 4; ++i) { *(u32x4*)(ad + i * 64 * 64) = ra[i]; *(u32x4*)(bd + i * 64 * 64) = rb[i]; } } while (0)
; template <int EPI>
; DI void gemm_phase(const u16* __restrict__ A, int lda, const u16* __restrict__ Bt, int K, int N, u16* outb, int ldo,
;                    const float* r0, const float* r1, float* outf, char* lds, int bid, int nb) {
;     ...
;     for (int kt = 0; kt < nk; ++kt) {
;       const int cur = kt & 1;
;       if (kt + 1 < nk) G_LOAD(kt + 1);
;       G_MMA(cur, fo0);
;       G_MMA(cur, fo1);
;       if (kt + 1 < nk) G_STORE(cur ^ 1);
;       __syncthreads();
;     }
	v_mfma_f32_16x16x32_bf16 v[52:55], v[180:183], v[204:207], v[52:55]
	v_mfma_f32_16x16x32_bf16 v[48:51], v[184:187], v[204:207], v[48:51]
	ds_read_b128 v[204:207], v225 offset:8192
	ds_read_b128 v[216:219], v225 offset:14336
	s_add_u32 m0, s97, 0x4000
	s_add_u32 s8, s98, 0xb0000
	s_addc_u32 s9, s99, 0
	global_load_lds_dwordx4 v224, s[8:9]
	v_mfma_f32_16x16x32_bf16 v[44:47], v[168:171], v[208:211], v[44:47]
	v_mfma_f32_16x16x32_bf16 v[40:43], v[176:179], v[208:211], v[40:43]
	v_mfma_f32_16x16x32_bf16 v[36:39], v[180:183], v[208:211], v[36:39]
	v_mfma_f32_16x16x32_bf16 v[32:35], v[184:187], v[208:211], v[32:35]
	ds_read_b128 v[208:211], v225 offset:10240
	s_add_u32 m0, s97, 0x14000
	s_add_u32 s8, s100, 0xb0000
	s_addc_u32 s9, s101, 0
	global_load_lds_dwordx4 v224, s[8:9]
	v_mfma_f32_16x16x32_bf16 v[28:31], v[168:171], v[212:215], v[28:31]
	v_mfma_f32_16x16x32_bf16 v[24:27], v[176:179], v[212:215], v[24:27]
	v_mfma_f32_16x16x32_bf16 v[20:23], v[180:183], v[212:215], v[20:23]
	v_mfma_f32_16x16x32_bf16 v[16:19], v[184:187], v[212:215], v[16:19]
	ds_read_b128 v[212:215], v225 offset:12288
	s_add_u32 m0, s97, 0x6000
	s_add_u32 s8, s98, 0x108000
	s_addc_u32 s9, s99, 0
	global_load_lds_dwordx4 v224, s[8:9]
	v_mfma_f32_16x16x32_bf16 v[12:15], v[168:171], v[220:223], v[12:15]
	v_mfma_f32_16x16x32_bf16 v[8:11], v[176:179], v[220:223], v[8:11]
	v_mfma_f32_16x16x32_bf16 v[4:7], v[180:183], v[220:223], v[4:7]
	v_mfma_f32_16x16x32_bf16 v[0:3], v[184:187], v[220:223], v[0:3]
	s_add_u32 m0, s97, 0x16000
	s_add_u32 s8, s100, 0x108000
	s_addc_u32 s9, s101, 0
	global_load_lds_dwordx4 v224, s[8:9]
	v_xor_b32_e32 v225, 0x8000, v225
	v_xor_b32_e32 v227, 0x8000, v227
	v_xor_b32_e32 v226, 0x8000, v226
	v_xor_b32_e32 v228, 0x8000, v228
	s_xor_b32 s97, s97, 0x8000
	s_add_u32 s98, s98, 0x80
	s_addc_u32 s99, s99, 0
	s_add_u32 s100, s100, 0x80
	s_addc_u32 s101, s101, 0
	s_sub_u32 s28, s28, 1
	s_cmp_lg_u32 s28, 0
	s_cbranch_scc1 .Lgm3_loop
	s_waitcnt lgkmcnt(4)
	v_mfma_f32_16x16x32_bf16 v[124:127], v[152:155], v[188:191], v[124:127]
	v_mfma_f32_16x16x32_bf16 v[120:123], v[156:159], v[188:191], v[120:123]
	v_mfma_f32_16x16x32_bf16 v[116:119], v[160:163], v[188:191], v[116:119]
	v_mfma_f32_16x16x32_bf16 v[112:115], v[164:167], v[188:191], v[112:115]
	ds_read_b128 v[188:191], v226 offset:0
	ds_read_b128 v[168:171], v228 offset:0
	v_mfma_f32_16x16x32_bf16 v[108:111], v[152:155], v[192:195], v[108:111]
	v_mfma_f32_16x16x32_bf16 v[104:107], v[156:159], v[192:195], v[104:107]
	v_mfma_f32_16x16x32_bf16 v[100:103], v[160:163], v[192:195], v[100:103]
	v_mfma_f32_16x16x32_bf16 v[96:99], v[164:167], v[192:195], v[96:99]
	ds_read_b128 v[192:195], v226 offset:2048
	ds_read_b128 v[176:179], v228 offset:2048
	v_mfma_f32_16x16x32_bf16 v[92:95], v[152:155], v[196:199], v[92:95]
	v_mfma_f32_16x16x32_bf16 v[88:91], v[156:159], v[196:199], v[88:91]
	v_mfma_f32_16x16x32_bf16 v[84:87], v[160:163], v[196:199], v[84:87]
	v_mfma_f32_16x16x32_bf16 v[80:83], v[164:167], v[196:199], v[80:83]
	ds_read_b128 v[196:199], v226 offset:4096
	ds_read_b128 v[180:183], v228 offset:4096
	v_mfma_f32_16x16x32_bf16 v[76:79], v[152:155], v[200:203], v[76:79]
	v_mfma_f32_16x16x32_bf16 v[72:75], v[156:159], v[200:203], v[72:75]
	v_mfma_f32_16x16x32_bf16 v[68:71], v[160:163], v[200:203], v[68:71]
	v_mfma_f32_16x16x32_bf16 v[64:67], v[164:167], v[200:203], v[64:67]
	ds_read_b128 v[200:203], v226 offset:6144
	ds_read_b128 v[184:187], v228 offset:6144
	s_waitcnt lgkmcnt(11)
	v_mfma_f32_16x16x32_bf16 v[60:63], v[152:155], v[204:207], v[60:63]
	v_mfma_f32_16x16x32_bf16 v[56:59], v[156:159], v[204:207], v[56:59]
	v_mfma_f32_16x16x32_bf16 v[52:55], v[160:163], v[204:207], v[52:55]
	v_mfma_f32_16x16x32_bf16 v[48:51], v[164:167], v[204:207], v[48:51]
	ds_read_b128 v[204:207], v226 offset:8192
	ds_read_b128 v[220:223], v226 offset:14336
	s_waitcnt lgkmcnt(11)
	v_mfma_f32_16x16x32_bf16 v[44:47], v[152:155], v[208:211], v[44:47]
	v_mfma_f32_16x16x32_bf16 v[40:43], v[156:159], v[208:211], v[40:43]
	v_mfma_f32_16x16x32_bf16 v[36:39], v[160:163], v[208:211], v[36:39]
	v_mfma_f32_16x16x32_bf16 v[32:35], v[164:167], v[208:211], v[32:35]
	ds_read_b128 v[208:211], v226 offset:10240
	s_waitcnt lgkmcnt(11)
	v_mfma_f32_16x16x32_bf16 v[28:31], v[152:155], v[212:215], v[28:31]
	v_mfma_f32_16x16x32_bf16 v[24:27], v[156:159], v[212:215], v[24:27]
	v_mfma_f32_16x16x32_bf16 v[20:23], v[160:163], v[212:215], v[20:23]
	v_mfma_f32_16x16x32_bf16 v[16:19], v[164:167], v[212:215], v[16:19]
	ds_read_b128 v[212:215], v226 offset:12288
	v_mfma_f32_16x16x32_bf16 v[12:15], v[152:155], v[216:219], v[12:15]
	v_mfma_f32_16x16x32_bf16 v[8:11], v[156:159], v[216:219], v[8:11]
	v_mfma_f32_16x16x32_bf16 v[4:7], v[160:163], v[216:219], v[4:7]
	v_mfma_f32_16x16x32_bf16 v[0:3], v[164:167], v[216:219], v[0:3]
	s_waitcnt vmcnt(0) lgkmcnt(0)
	s_barrier
; #define G_LOAD(KT) do { _Pragma("unroll") for (int i = 0; i < 4; ++i) { ra[i] = *(const u32x4*)(Ag + (size_t)i * 64 * lda + (KT) * 64); rb[i] = *(const u32x4*)(Bg + (size_t)i * 64 * K + (KT) * 64); } } while (0)
; #define G_STORE(BUF) do { u16* ad = As + (BUF) * 256 * 64 + sto; u16* bd = Bs + (BUF) * 256 * 64 + sto; _Pragma("unroll") for (int i = 0; i < 4; ++i) { *(u32x4*)(ad + i * 64 * 64) = ra[i]; *(u32x4*)(bd + i * 64 * 64) = rb[i]; } } while (0)
; template <int EPI>
; DI void gemm_phase(const u16* __restrict__ A, int lda, const u16* __restrict__ Bt, int K, int N, u16* outb, int ldo,
;                    const float* r0, const float* r1, float* outf, char* lds, int bid, int nb) {
;     ...
;     G_LOAD(0);
;     G_STORE(0);
;     __syncthreads();
;     for (int kt = 0; kt < nk; ++kt) {
;       const int cur = kt & 1;
;       if (kt + 1 < nk) G_LOAD(kt + 1);
;       G_MMA(cur, fo0);
;       G_MMA(cur, fo1);
;       if (kt + 1 < nk) G_STORE(cur ^ 1);
;       __syncthreads();
	v_mfma_f32_16x16x32_bf16 v[124:127], v[168:171], v[188:191], v[124:127]
	v_mfma_f32_16x16x32_bf16 v[120:123], v[176:179], v[188:191], v[120:123]
	v_mfma_f32_16x16x32_bf16 v[116:119], v[180:183], v[188:191], v[116:119]
	v_mfma_f32_16x16x32_bf16 v[112:115], v[184:187], v[188:191], v[112:115]
	ds_read_b128 v[188:191], v225 offset:0
	ds_read_b128 v[152:155], v227 offset:0
	v_mfma_f32_16x16x32_bf16 v[108:111], v[168:171], v[192:195], v[108:111]
	v_mfma_f32_16x16x32_bf16 v[104:107], v[176:179], v[192:195], v[104:107]
	v_mfma_f32_16x16x32_bf16 v[100:103], v[180:183], v[192:195], v[100:103]
	v_mfma_f32_16x16x32_bf16 v[96:99], v[184:187], v[192:195], v[96:99]
	ds_read_b128 v[192:195], v225 offset:2048
	ds_read_b128 v[156:159], v227 offset:2048
	v_mfma_f32_16x16x32_bf16 v[92:95], v[168:171], v[196:199], v[92:95]
	v_mfma_f32_16x16x32_bf16 v[88:91], v[176:179], v[196:199], v[88:91]
	v_mfma_f32_16x16x32_bf16 v[84:87], v[180:183], v[196:199], v[84:87]
	v_mfma_f32_16x16x32_bf16 v[80:83], v[184:187], v[196:199], v[80:83]
	ds_read_b128 v[196:199], v225 offset:4096
	ds_read_b128 v[160:163], v227 offset:4096
	v_mfma_f32_16x16x32_bf16 v[76:79], v[168:171], v[200:203], v[76:79]
	v_mfma_f32_16x16x32_bf16 v[72:75], v[176:179], v[200:203], v[72:75]
	v_mfma_f32_16x16x32_bf16 v[68:71], v[180:183], v[200:203], v[68:71]
	v_mfma_f32_16x16x32_bf16 v[64:67], v[184:187], v[200:203], v[64:67]
	ds_read_b128 v[200:203], v225 offset:6144
	ds_read_b128 v[164:167], v227 offset:6144
	v_mfma_f32_16x16x32_bf16 v[60:63], v[168:171], v[204:207], v[60:63]
	v_mfma_f32_16x16x32_bf16 v[56:59], v[176:179], v[204:207], v[56:59]
	v_mfma_f32_16x16x32_bf16 v[52:55], v[180:183], v[204:207], v[52:55]
	v_mfma_f32_16x16x32_bf16 v[48:51], v[184:187], v[204:207], v[48:51]
	ds_read_b128 v[204:207], v225 offset:8192
	ds_read_b128 v[216:219], v225 offset:14336
	v_mfma_f32_16x16x32_bf16 v[44:47], v[168:171], v[208:211], v[44:47]
	v_mfma_f32_16x16x32_bf16 v[40:43], v[176:179], v[208:211], v[40:43]
	v_mfma_f32_16x16x32_bf16 v[36:39], v[180:183], v[208:211], v[36:39]
	v_mfma_f32_16x16x32_bf16 v[32:35], v[184:187], v[208:211], v[32:35]
	ds_read_b128 v[208:211], v225 offset:10240
	v_mfma_f32_16x16x32_bf16 v[28:31], v[168:171], v[212:215], v[28:31]
	v_mfma_f32_16x16x32_bf16 v[24:27], v[176:179], v[212:215], v[24:27]
	v_mfma_f32_16x16x32_bf16 v[20:23], v[180:183], v[212:215], v[20:23]
	v_mfma_f32_16x16x32_bf16 v[16:19], v[184:187], v[212:215], v[16:19]
	ds_read_b128 v[212:215], v225 offset:12288
	v_mfma_f32_16x16x32_bf16 v[12:15], v[168:171], v[220:223], v[12:15]
	v_mfma_f32_16x16x32_bf16 v[8:11], v[176:179], v[220:223], v[8:11]
	v_mfma_f32_16x16x32_bf16 v[4:7], v[180:183], v[220:223], v[4:7]
	v_mfma_f32_16x16x32_bf16 v[0:3], v[184:187], v[220:223], v[0:3]
	v_xor_b32_e32 v226, 0x8000, v226
	v_xor_b32_e32 v228, 0x8000, v228
	s_waitcnt lgkmcnt(4)
	v_mfma_f32_16x16x32_bf16 v[124:127], v[152:155], v[188:191], v[124:127]
	v_mfma_f32_16x16x32_bf16 v[120:123], v[156:159], v[188:191], v[120:123]
	v_mfma_f32_16x16x32_bf16 v[116:119], v[160:163], v[188:191], v[116:119]
	v_mfma_f32_16x16x32_bf16 v[112:115], v[164:167], v[188:191], v[112:115]
	ds_read_b128 v[188:191], v226 offset:0
	ds_read_b128 v[168:171], v228 offset:0
	v_mfma_f32_16x16x32_bf16 v[108:111], v[152:155], v[192:195], v[108:111]
	v_mfma_f32_16x16x32_bf16 v[104:107], v[156:159], v[192:195], v[104:107]
	v_mfma_f32_16x16x32_bf16 v[100:103], v[160:163], v[192:195], v[100:103]
	v_mfma_f32_16x16x32_bf16 v[96:99], v[164:167], v[192:195], v[96:99]
	ds_read_b128 v[192:195], v226 offset:2048
	ds_read_b128 v[176:179], v228 offset:2048
	v_mfma_f32_16x16x32_bf16 v[92:95], v[152:155], v[196:199], v[92:95]
	v_mfma_f32_16x16x32_bf16 v[88:91], v[156:159], v[196:199], v[88:91]
	v_mfma_f32_16x16x32_bf16 v[84:87], v[160:163], v[196:199], v[84:87]
	v_mfma_f32_16x16x32_bf16 v[80:83], v[164:167], v[196:199], v[80:83]
	ds_read_b128 v[196:199], v226 offset:4096
	ds_read_b128 v[180:183], v228 offset:4096
	v_mfma_f32_16x16x32_bf16 v[76:79], v[152:155], v[200:203], v[76:79]
	v_mfma_f32_16x16x32_bf16 v[72:75], v[156:159], v[200:203], v[72:75]
	v_mfma_f32_16x16x32_bf16 v[68:71], v[160:163], v[200:203], v[68:71]
	v_mfma_f32_16x16x32_bf16 v[64:67], v[164:167], v[200:203], v[64:67]
	ds_read_b128 v[200:203], v226 offset:6144
	ds_read_b128 v[184:187], v228 offset:6144
	s_waitcnt lgkmcnt(11)
	v_mfma_f32_16x16x32_bf16 v[60:63], v[152:155], v[204:207], v[60:63]
	v_mfma_f32_16x16x32_bf16 v[56:59], v[156:159], v[204:207], v[56:59]
	v_mfma_f32_16x16x32_bf16 v[52:55], v[160:163], v[204:207], v[52:55]
	v_mfma_f32_16x16x32_bf16 v[48:51], v[164:167], v[204:207], v[48:51]
	ds_read_b128 v[204:207], v226 offset:8192
	ds_read_b128 v[220:223], v226 offset:14336
	s_waitcnt lgkmcnt(11)
	v_mfma_f32_16x16x32_bf16 v[44:47], v[152:155], v[208:211], v[44:47]
	v_mfma_f32_16x16x32_bf16 v[40:43], v[156:159], v[208:211], v[40:43]
	v_mfma_f32_16x16x32_bf16 v[36:39], v[160:163], v[208:211], v[36:39]
	v_mfma_f32_16x16x32_bf16 v[32:35], v[164:167], v[208:211], v[32:35]
	ds_read_b128 v[208:211], v226 offset:10240
	s_waitcnt lgkmcnt(11)
	v_mfma_f32_16x16x32_bf16 v[28:31], v[152:155], v[212:215], v[28:31]
	v_mfma_f32_16x16x32_bf16 v[24:27], v[156:159], v[212:215], v[24:27]
	v_mfma_f32_16x16x32_bf16 v[20:23], v[160:163], v[212:215], v[20:23]
	v_mfma_f32_16x16x32_bf16 v[16:19], v[164:167], v[212:215], v[16:19]
	ds_read_b128 v[212:215], v226 offset:12288
	v_mfma_f32_16x16x32_bf16 v[12:15], v[152:155], v[216:219], v[12:15]
	v_mfma_f32_16x16x32_bf16 v[8:11], v[156:159], v[216:219], v[8:11]
	v_mfma_f32_16x16x32_bf16 v[4:7], v[160:163], v[216:219], v[4:7]
	v_mfma_f32_16x16x32_bf16 v[0:3], v[164:167], v[216:219], v[0:3]
	s_waitcnt vmcnt(0) lgkmcnt(0)
	s_barrier
; template <int EPI>
; DI void gemm_phase(const u16* __restrict__ A, int lda, const u16* __restrict__ Bt, int K, int N, u16* outb, int ldo,
;                    const float* r0, const float* r1, float* outf, char* lds, int bid, int nb) {
;     ...
;     } else if constexpr (EPI == EPI_RESID) {
;       const int col = tn * 256 + wc * 64 + l15;
;       const float* rb_ = (tm * 256 < M_P) ? r0 : (r1 - (size_t)M_P * DM);
; #pragma unroll
;       for (int i = 0; i < 8; ++i)
; #pragma unroll
;         for (int r = 0; r < 4; ++r) {
;           const size_t i0 = (size_t)(mrow + i * 16 + r) * DM + col;
;           const float x0 = rb_[i0], x1 = rb_[i0 + 16], x2 = rb_[i0 + 32], x3 = rb_[i0 + 48];
;           outf[i0] = x0 + acc[i][0][r]; outf[i0 + 16] = x1 + acc[i][1][r]; outf[i0 + 32] = x2 + acc[i][2][r]; outf[i0 + 48] = x3 + acc[i][3][r];
;         }
	v_mfma_f32_16x16x32_bf16 v[124:127], v[168:171], v[188:191], v[124:127]
	v_mfma_f32_16x16x32_bf16 v[120:123], v[176:179], v[188:191], v[120:123]
	v_mfma_f32_16x16x32_bf16 v[116:119], v[180:183], v[188:191], v[116:119]
	v_mfma_f32_16x16x32_bf16 v[112:115], v[184:187], v[188:191], v[112:115]
	v_mfma_f32_16x16x32_bf16 v[108:111], v[168:171], v[192:195], v[108:111]
	v_mfma_f32_16x16x32_bf16 v[104:107], v[176:179], v[192:195], v[104:107]
	v_mfma_f32_16x16x32_bf16 v[100:103], v[180:183], v[192:195], v[100:103]
	v_mfma_f32_16x16x32_bf16 v[96:99], v[184:187], v[192:195], v[96:99]
	v_mfma_f32_16x16x32_bf16 v[92:95], v[168:171], v[196:199], v[92:95]
	v_mfma_f32_16x16x32_bf16 v[88:91], v[176:179], v[196:199], v[88:91]
	v_mfma_f32_16x16x32_bf16 v[84:87], v[180:183], v[196:199], v[84:87]
	v_mfma_f32_16x16x32_bf16 v[80:83], v[184:187], v[196:199], v[80:83]
	v_mfma_f32_16x16x32_bf16 v[76:79], v[168:171], v[200:203], v[76:79]
	v_mfma_f32_16x16x32_bf16 v[72:75], v[176:179], v[200:203], v[72:75]
	v_mfma_f32_16x16x32_bf16 v[68:71], v[180:183], v[200:203], v[68:71]
	v_mfma_f32_16x16x32_bf16 v[64:67], v[184:187], v[200:203], v[64:67]
	v_mfma_f32_16x16x32_bf16 v[60:63], v[168:171], v[204:207], v[60:63]
	v_mfma_f32_16x16x32_bf16 v[56:59], v[176:179], v[204:207], v[56:59]
	v_mfma_f32_16x16x32_bf16 v[52:55], v[180:183], v[204:207], v[52:55]
	v_mfma_f32_16x16x32_bf16 v[48:51], v[184:187], v[204:207], v[48:51]
	v_mfma_f32_16x16x32_bf16 v[44:47], v[168:171], v[208:211], v[44:47]
	v_mfma_f32_16x16x32_bf16 v[40:43], v[176:179], v[208:211], v[40:43]
	v_mfma_f32_16x16x32_bf16 v[36:39], v[180:183], v[208:211], v[36:39]
	v_mfma_f32_16x16x32_bf16 v[32:35], v[184:187], v[208:211], v[32:35]
	v_mfma_f32_16x16x32_bf16 v[28:31], v[168:171], v[212:215], v[28:31]
	v_mfma_f32_16x16x32_bf16 v[24:27], v[176:179], v[212:215], v[24:27]
	v_mfma_f32_16x16x32_bf16 v[20:23], v[180:183], v[212:215], v[20:23]
	v_mfma_f32_16x16x32_bf16 v[16:19], v[184:187], v[212:215], v[16:19]
	v_mfma_f32_16x16x32_bf16 v[12:15], v[168:171], v[220:223], v[12:15]
	v_mfma_f32_16x16x32_bf16 v[8:11], v[176:179], v[220:223], v[8:11]
	v_mfma_f32_16x16x32_bf16 v[4:7], v[180:183], v[220:223], v[4:7]
	v_mfma_f32_16x16x32_bf16 v[0:3], v[184:187], v[220:223], v[0:3]
	s_setprio 0
	s_nop 7
	s_nop 3
	v_and_b32_e32 v225, 15, v174
	v_lshrrev_b32_e32 v226, 8, v174
	v_lshl_or_b32 v225, v226, 7, v225
	v_bfe_u32 v226, v174, 6, 2
	v_bfe_u32 v227, v174, 4, 2
	v_lshlrev_b32_e32 v227, 2, v227
	v_add_u32_e32 v225, s39, v225
	v_lshl_add_u32 v226, v226, 6, v227
	v_add_u32_e32 v226, s46, v226
	v_lshlrev_b32_e32 v226, 2, v226
	v_lshl_add_u32 v224, v225, 12, v226
	v_mov_b32_e32 v229, v224
	v_add_u32_e32 v224, 0x0, v229
	global_load_dwordx4 v[152:155], v224, s[22:23] offset:0
	global_load_dwordx4 v[156:159], v224, s[22:23] offset:64
	global_load_dwordx4 v[160:163], v224, s[22:23] offset:128
	global_load_dwordx4 v[164:167], v224, s[22:23] offset:192
	v_add_u32_e32 v228, 0x10000, v229
	global_load_dwordx4 v[168:171], v228, s[22:23] offset:0
	global_load_dwordx4 v[176:179], v228, s[22:23] offset:64
	global_load_dwordx4 v[180:183], v228, s[22:23] offset:128
	global_load_dwordx4 v[184:187], v228, s[22:23] offset:192
	s_waitcnt vmcnt(4)
	v_add_f32_e32 v152, v124, v152
	v_add_f32_e32 v153, v125, v153
	v_add_f32_e32 v154, v126, v154
	v_add_f32_e32 v155, v127, v155
	v_add_f32_e32 v156, v120, v156
	v_add_f32_e32 v157, v121, v157
	v_add_f32_e32 v158, v122, v158
	v_add_f32_e32 v159, v123, v159
	v_add_f32_e32 v160, v116, v160
	v_add_f32_e32 v161, v117, v161
	v_add_f32_e32 v162, v118, v162
	v_add_f32_e32 v163, v119, v163
	v_add_f32_e32 v164, v112, v164
	v_add_f32_e32 v165, v113, v165
	v_add_f32_e32 v166, v114, v166
	v_add_f32_e32 v167, v115, v167
	global_store_dwordx4 v224, v[152:155], s[22:23] offset:0
	global_store_dwordx4 v224, v[156:159], s[22:23] offset:64
	global_store_dwordx4 v224, v[160:163], s[22:23] offset:128
	global_store_dwordx4 v224, v[164:167], s[22:23] offset:192
	s_nop 1
	v_add_u32_e32 v224, 0x20000, v229
	global_load_dwordx4 v[152:155], v224, s[22:23] offset:0
	global_load_dwordx4 v[156:159], v224, s[22:23] offset:64
	global_load_dwordx4 v[160:163], v224, s[22:23] offset:128
	global_load_dwordx4 v[164:167], v224, s[22:23] offset:192
	s_waitcnt vmcnt(8)
	v_add_f32_e32 v168, v108, v168
	v_add_f32_e32 v169, v109, v169
	v_add_f32_e32 v170, v110, v170
	v_add_f32_e32 v171, v111, v171
	v_add_f32_e32 v176, v104, v176
	v_add_f32_e32 v177, v105, v177
	v_add_f32_e32 v178, v106, v178
	v_add_f32_e32 v179, v107, v179
	v_add_f32_e32 v180, v100, v180
	v_add_f32_e32 v181, v101, v181
	v_add_f32_e32 v182, v102, v182
	v_add_f32_e32 v183, v103, v183
	v_add_f32_e32 v184, v96, v184
	v_add_f32_e32 v185, v97, v185
	v_add_f32_e32 v186, v98, v186
	v_add_f32_e32 v187, v99, v187
	global_store_dwordx4 v228, v[168:171], s[22:23] offset:0
	global_store_dwordx4 v228, v[176:179], s[22:23] offset:64
	global_store_dwordx4 v228, v[180:183], s[22:23] offset:128
	global_store_dwordx4 v228, v[184:187], s[22:23] offset:192
	s_nop 1
	v_add_u32_e32 v228, 0x30000, v229
	global_load_dwordx4 v[168:171], v228, s[22:23] offset:0
	global_load_dwordx4 v[176:179], v228, s[22:23] offset:64
	global_load_dwordx4 v[180:183], v228, s[22:23] offset:128
	global_load_dwordx4 v[184:187], v228, s[22:23] offset:192
	s_waitcnt vmcnt(8)
; template <int EPI>
; DI void gemm_phase(const u16* __restrict__ A, int lda, const u16* __restrict__ Bt, int K, int N, u16* outb, int ldo,
;                    const float* r0, const float* r1, float* outf, char* lds, int bid, int nb) {
;     ...
;       for (int i = 0; i < 8; ++i)
; #pragma unroll
;         for (int r = 0; r < 4; ++r) {
;           const size_t i0 = (size_t)(mrow + i * 16 + r) * DM + col;
;           const float x0 = rb_[i0], x1 = rb_[i0 + 16], x2 = rb_[i0 + 32], x3 = rb_[i0 + 48];
;           outf[i0] = x0 + acc[i][0][r]; outf[i0 + 16] = x1 + acc[i][1][r]; outf[i0 + 32] = x2 + acc[i][2][r]; outf[i0 + 48] = x3 + acc[i][3][r];
;         }
	v_add_f32_e32 v152, v92, v152
	v_add_f32_e32 v153, v93, v153
	v_add_f32_e32 v154, v94, v154
	v_add_f32_e32 v155, v95, v155
	v_add_f32_e32 v156, v88, v156
	v_add_f32_e32 v157, v89, v157
	v_add_f32_e32 v158, v90, v158
	v_add_f32_e32 v159, v91, v159
	v_add_f32_e32 v160, v84, v160
	v_add_f32_e32 v161, v85, v161
	v_add_f32_e32 v162, v86, v162
	v_add_f32_e32 v163, v87, v163
	v_add_f32_e32 v164, v80, v164
	v_add_f32_e32 v165, v81, v165
	v_add_f32_e32 v166, v82, v166
	v_add_f32_e32 v167, v83, v167
	global_store_dwordx4 v224, v[152:155], s[22:23] offset:0
	global_store_dwordx4 v224, v[156:159], s[22:23] offset:64
	global_store_dwordx4 v224, v[160:163], s[22:23] offset:128
	global_store_dwordx4 v224, v[164:167], s[22:23] offset:192
	s_nop 1
	v_add_u32_e32 v224, 0x40000, v229
	global_load_dwordx4 v[152:155], v224, s[22:23] offset:0
	global_load_dwordx4 v[156:159], v224, s[22:23] offset:64
	global_load_dwordx4 v[160:163], v224, s[22:23] offset:128
	global_load_dwordx4 v[164:167], v224, s[22:23] offset:192
	s_waitcnt vmcnt(8)
	v_add_f32_e32 v168, v76, v168
	v_add_f32_e32 v169, v77, v169
	v_add_f32_e32 v170, v78, v170
	v_add_f32_e32 v171, v79, v171
	v_add_f32_e32 v176, v72, v176
	v_add_f32_e32 v177, v73, v177
	v_add_f32_e32 v178, v74, v178
	v_add_f32_e32 v179, v75, v179
	v_add_f32_e32 v180, v68, v180
	v_add_f32_e32 v181, v69, v181
	v_add_f32_e32 v182, v70, v182
	v_add_f32_e32 v183, v71, v183
	v_add_f32_e32 v184, v64, v184
	v_add_f32_e32 v185, v65, v185
	v_add_f32_e32 v186, v66, v186
	v_add_f32_e32 v187, v67, v187
	global_store_dwordx4 v228, v[168:171], s[22:23] offset:0
	global_store_dwordx4 v228, v[176:179], s[22:23] offset:64
	global_store_dwordx4 v228, v[180:183], s[22:23] offset:128
	global_store_dwordx4 v228, v[184:187], s[22:23] offset:192
	s_nop 1
	v_add_u32_e32 v228, 0x50000, v229
	global_load_dwordx4 v[168:171], v228, s[22:23] offset:0
	global_load_dwordx4 v[176:179], v228, s[22:23] offset:64
	global_load_dwordx4 v[180:183], v228, s[22:23] offset:128
	global_load_dwordx4 v[184:187], v228, s[22:23] offset:192
	s_waitcnt vmcnt(8)
	v_add_f32_e32 v152, v60, v152
	v_add_f32_e32 v153, v61, v153
	v_add_f32_e32 v154, v62, v154
	v_add_f32_e32 v155, v63, v155
	v_add_f32_e32 v156, v56, v156
	v_add_f32_e32 v157, v57, v157
	v_add_f32_e32 v158, v58, v158
	v_add_f32_e32 v159, v59, v159
	v_add_f32_e32 v160, v52, v160
	v_add_f32_e32 v161, v53, v161
	v_add_f32_e32 v162, v54, v162
	v_add_f32_e32 v163, v55, v163
	v_add_f32_e32 v164, v48, v164
	v_add_f32_e32 v165, v49, v165
	v_add_f32_e32 v166, v50, v166
	v_add_f32_e32 v167, v51, v167
	global_store_dwordx4 v224, v[152:155], s[22:23] offset:0
	global_store_dwordx4 v224, v[156:159], s[22:23] offset:64
	global_store_dwordx4 v224, v[160:163], s[22:23] offset:128
	global_store_dwordx4 v224, v[164:167], s[22:23] offset:192
	s_nop 1
	v_add_u32_e32 v224, 0x60000, v229
	global_load_dwordx4 v[152:155], v224, s[22:23] offset:0
	global_load_dwordx4 v[156:159], v224, s[22:23] offset:64
	global_load_dwordx4 v[160:163], v224, s[22:23] offset:128
	global_load_dwordx4 v[164:167], v224, s[22:23] offset:192
	s_waitcnt vmcnt(8)
	v_add_f32_e32 v168, v44, v168
	v_add_f32_e32 v169, v45, v169
	v_add_f32_e32 v170, v46, v170
	v_add_f32_e32 v171, v47, v171
	v_add_f32_e32 v176, v40, v176
	v_add_f32_e32 v177, v41, v177
	v_add_f32_e32 v178, v42, v178
	v_add_f32_e32 v179, v43, v179
	v_add_f32_e32 v180, v36, v180
	v_add_f32_e32 v181, v37, v181
	v_add_f32_e32 v182, v38, v182
	v_add_f32_e32 v183, v39, v183
	v_add_f32_e32 v184, v32, v184
	v_add_f32_e32 v185, v33, v185
	v_add_f32_e32 v186, v34, v186
	v_add_f32_e32 v187, v35, v187
	global_store_dwordx4 v228, v[168:171], s[22:23] offset:0
	global_store_dwordx4 v228, v[176:179], s[22:23] offset:64
	global_store_dwordx4 v228, v[180:183], s[22:23] offset:128
	global_store_dwordx4 v228, v[184:187], s[22:23] offset:192
	s_nop 1
	v_add_u32_e32 v228, 0x70000, v229
	global_load_dwordx4 v[168:171], v228, s[22:23] offset:0
	global_load_dwordx4 v[176:179], v228, s[22:23] offset:64
	global_load_dwordx4 v[180:183], v228, s[22:23] offset:128
	global_load_dwordx4 v[184:187], v228, s[22:23] offset:192
	s_waitcnt vmcnt(8)
	v_add_f32_e32 v152, v28, v152
	v_add_f32_e32 v153, v29, v153
	v_add_f32_e32 v154, v30, v154
	v_add_f32_e32 v155, v31, v155
	v_add_f32_e32 v156, v24, v156
	v_add_f32_e32 v157, v25, v157
	v_add_f32_e32 v158, v26, v158
	v_add_f32_e32 v159, v27, v159
	v_add_f32_e32 v160, v20, v160
	v_add_f32_e32 v161, v21, v161
	v_add_f32_e32 v162, v22, v162
	v_add_f32_e32 v163, v23, v163
	v_add_f32_e32 v164, v16, v164
	v_add_f32_e32 v165, v17, v165
	v_add_f32_e32 v166, v18, v166
	v_add_f32_e32 v167, v19, v167
	global_store_dwordx4 v224, v[152:155], s[22:23] offset:0
	global_store_dwordx4 v224, v[156:159], s[22:23] offset:64
	global_store_dwordx4 v224, v[160:163], s[22:23] offset:128
	global_store_dwordx4 v224, v[164:167], s[22:23] offset:192
	s_waitcnt vmcnt(4)
	v_add_f32_e32 v168, v12, v168
	v_add_f32_e32 v169, v13, v169
	v_add_f32_e32 v170, v14, v170
	v_add_f32_e32 v171, v15, v171
	v_add_f32_e32 v176, v8, v176
	v_add_f32_e32 v177, v9, v177
	v_add_f32_e32 v178, v10, v178
	v_add_f32_e32 v179, v11, v179
	v_add_f32_e32 v180, v4, v180
	v_add_f32_e32 v181, v5, v181
	v_add_f32_e32 v182, v6, v182
	v_add_f32_e32 v183, v7, v183
	v_add_f32_e32 v184, v0, v184
	v_add_f32_e32 v185, v1, v185
	v_add_f32_e32 v186, v2, v186
	v_add_f32_e32 v187, v3, v187
	global_store_dwordx4 v228, v[168:171], s[22:23] offset:0
	global_store_dwordx4 v228, v[176:179], s[22:23] offset:64
	global_store_dwordx4 v228, v[180:183], s[22:23] offset:128
	global_store_dwordx4 v228, v[184:187], s[22:23] offset:192
	s_add_i32 s16, s16, 1
	s_cmp_eq_u32 s16, s3
	s_cbranch_scc0 .LBB0_759

; #define G_LOAD(KT) do { _Pragma("unroll") for (int i = 0; i < 4; ++i) { ra[i] = *(const u32x4*)(Ag + (size_t)i * 64 * lda + (KT) * 64); rb[i] = *(const u32x4*)(Bg + (size_t)i * 64 * K + (KT) * 64); } } while (0)
; #define G_STORE(BUF) do { u16* ad = As + (BUF) * 256 * 64 + sto; u16* bd = Bs + (BUF) * 256 * 64 + sto; _Pragma("unroll") for (int i = 0; i < 4; ++i) { *(u32x4*)(ad + i * 64 * 64) = ra[i]; *(u32x4*)(bd + i * 64 * 64) = rb[i]; } } while (0)
; template <int EPI>
; DI void gemm_phase(const u16* __restrict__ A, int lda, const u16* __restrict__ Bt, int K, int N, u16* outb, int ldo,
;                    const float* r0, const float* r1, float* outf, char* lds, int bid, int nb) {
;     ...
;   for (int it = 0; it < nIter; ++it) {
;     int tm, tn;
;     if (swz) { const int st = xcd + 8 * it, sm = st / nSN, sn = st - sm * nSN; tm = sm * GM + jb / GN; tn = sn * GN + (jb % GN); }
;     else { const int t = bid + it * nb; tm = t / nN; tn = t - tm * nN; }
;     const u16* Ag = A + (size_t)(tm * 256 + lrow) * lda + lch * 8;
;     const u16* Bg = Bt + (size_t)(tn * 256 + lrow) * K + lch * 8;
;     f32x4 acc[8][4];
; #pragma unroll
;     for (int i = 0; i < 8; ++i)
; #pragma unroll
;       for (int j = 0; j < 4; ++j) acc[i][j] = (f32x4){0.f, 0.f, 0.f, 0.f};
;     u32x4 ra[4], rb[4];
;     ...
;     G_LOAD(0);
;     G_STORE(0);
;     __syncthreads();
.LBB0_883:
	s_lshl_b32 s48, s48, 8
	v_or_b32_e32 v0, s48, v138
	v_ashrrev_i32_e32 v1, 31, v0
	s_lshl_b32 s49, s49, 8
	v_or_b32_e32 v2, s49, v138
	v_lshlrev_b64 v[62:63], 11, v[0:1]
	v_ashrrev_i32_e32 v3, 31, v2
	v_lshl_add_u64 v[0:1], v[128:129], 0, v[62:63]
	v_lshlrev_b64 v[64:65], 11, v[2:3]
	v_add_co_u32_e32 v4, vcc, s19, v0
	v_lshl_add_u64 v[2:3], v[130:131], 0, v[64:65]
	s_nop 0
	v_addc_co_u32_e32 v5, vcc, 0, v1, vcc
	v_add_co_u32_e32 v6, vcc, s19, v2
	s_nop 1
	v_readfirstlane_b32 s98, v0
	v_readfirstlane_b32 s99, v1
	s_nop 1
	v_readfirstlane_b32 s100, v2
	v_readfirstlane_b32 s101, v3
	v_addc_co_u32_e32 v7, vcc, 0, v3, vcc
	v_add_co_u32_e32 v4, vcc, s20, v0
	s_mov_b32 s50, 0
	s_nop 0
	v_addc_co_u32_e32 v5, vcc, 0, v1, vcc
	v_add_co_u32_e32 v6, vcc, s20, v2
	s_mov_b64 s[14:15], 0
	s_nop 0
	v_addc_co_u32_e32 v7, vcc, 0, v3, vcc
	v_add_co_u32_e32 v0, vcc, s21, v0
	v_addc_co_u32_e32 v1, vcc, 0, v1, vcc
	v_add_co_u32_e32 v2, vcc, s21, v2
	v_lshl_add_u64 v[134:135], v[132:133], 0, v[62:63]
	s_nop 0
	v_addc_co_u32_e32 v3, vcc, 0, v3, vcc
	v_mov_b32_e32 v0, 0
	v_mov_b32_e32 v1, v0
	v_mov_b32_e32 v2, v0
	v_mov_b32_e32 v3, v0
	v_mov_b32_e32 v4, v0
	v_mov_b32_e32 v5, v0
	v_mov_b32_e32 v6, v0
	v_mov_b32_e32 v7, v0
	v_mov_b32_e32 v8, v0
	v_mov_b32_e32 v9, v0
	v_mov_b32_e32 v10, v0
	v_mov_b32_e32 v11, v0
	v_mov_b32_e32 v12, v0
	v_mov_b32_e32 v13, v0
	v_mov_b32_e32 v14, v0
	v_mov_b32_e32 v15, v0
	v_mov_b32_e32 v16, v0
	v_mov_b32_e32 v17, v0
	v_mov_b32_e32 v18, v0
	v_mov_b32_e32 v19, v0
	v_mov_b32_e32 v20, v0
	v_mov_b32_e32 v21, v0
	v_mov_b32_e32 v22, v0
	v_mov_b32_e32 v23, v0
	v_mov_b32_e32 v24, v0
	v_mov_b32_e32 v25, v0
	v_mov_b32_e32 v26, v0
	v_mov_b32_e32 v27, v0
	v_mov_b32_e32 v28, v0
	v_mov_b32_e32 v29, v0
	v_lshl_add_u64 v[136:137], v[132:133], 0, v[64:65]
	v_mov_b32_e32 v62, v0
	v_mov_b32_e32 v63, v0
	v_mov_b32_e32 v64, v0
	v_mov_b32_e32 v65, v0
	v_mov_b32_e32 v66, v0
	v_mov_b32_e32 v67, v0
	v_mov_b32_e32 v68, v0
	v_mov_b32_e32 v69, v0
	v_mov_b32_e32 v70, v0
	v_mov_b32_e32 v71, v0
	v_mov_b32_e32 v72, v0
	v_mov_b32_e32 v73, v0
	v_mov_b32_e32 v74, v0
	v_mov_b32_e32 v75, v0
	v_mov_b32_e32 v76, v0
	v_mov_b32_e32 v77, v0
	v_mov_b32_e32 v78, v0
	v_mov_b32_e32 v79, v0
	v_mov_b32_e32 v80, v0
	v_mov_b32_e32 v81, v0
	v_mov_b32_e32 v82, v0
	v_mov_b32_e32 v83, v0
	v_mov_b32_e32 v84, v0
	v_mov_b32_e32 v85, v0
	v_mov_b32_e32 v30, v0
	v_mov_b32_e32 v31, v0
	v_mov_b32_e32 v32, v0
	v_mov_b32_e32 v33, v0
	v_mov_b32_e32 v34, v0
	v_mov_b32_e32 v35, v0
	v_mov_b32_e32 v36, v0
	v_mov_b32_e32 v37, v0
	v_mov_b32_e32 v38, v0
	v_mov_b32_e32 v39, v0
	v_mov_b32_e32 v40, v0
	v_mov_b32_e32 v41, v0
	v_mov_b32_e32 v42, v0
	v_mov_b32_e32 v43, v0
	v_mov_b32_e32 v44, v0
	v_mov_b32_e32 v45, v0
	v_mov_b32_e32 v46, v0
	v_mov_b32_e32 v47, v0
	v_mov_b32_e32 v48, v0
	v_mov_b32_e32 v49, v0
	v_mov_b32_e32 v50, v0
	v_mov_b32_e32 v51, v0
	v_mov_b32_e32 v52, v0
	v_mov_b32_e32 v53, v0
	v_mov_b32_e32 v54, v0
	v_mov_b32_e32 v55, v0
	v_mov_b32_e32 v56, v0
	v_mov_b32_e32 v57, v0
	v_mov_b32_e32 v58, v0
	v_mov_b32_e32 v59, v0
	v_mov_b32_e32 v60, v0
	v_mov_b32_e32 v61, v0
	v_mov_b32_e32 v86, v0
	v_mov_b32_e32 v87, v0
	v_mov_b32_e32 v88, v0
	v_mov_b32_e32 v89, v0
	v_mov_b32_e32 v90, v0
	v_mov_b32_e32 v91, v0
	v_mov_b32_e32 v92, v0
	v_mov_b32_e32 v93, v0
	v_mov_b32_e32 v94, v0
	v_mov_b32_e32 v95, v0
	v_mov_b32_e32 v96, v0
	v_mov_b32_e32 v97, v0
	v_mov_b32_e32 v98, v0
	v_mov_b32_e32 v99, v0
	v_mov_b32_e32 v100, v0
	v_mov_b32_e32 v101, v0
	v_mov_b32_e32 v102, v0
	v_mov_b32_e32 v103, v0
	v_mov_b32_e32 v104, v0
	v_mov_b32_e32 v105, v0
	v_mov_b32_e32 v106, v0
	v_mov_b32_e32 v107, v0
	v_mov_b32_e32 v108, v0
	v_mov_b32_e32 v109, v0
	v_mov_b32_e32 v110, v0
	v_mov_b32_e32 v111, v0
	v_mov_b32_e32 v112, v0
	v_mov_b32_e32 v113, v0
	v_mov_b32_e32 v114, v0
	v_mov_b32_e32 v115, v0
	v_mov_b32_e32 v116, v0
	v_mov_b32_e32 v117, v0
	v_mov_b32_e32 v118, v0
	v_mov_b32_e32 v119, v0
	v_mov_b32_e32 v120, v0
	v_mov_b32_e32 v121, v0
	v_mov_b32_e32 v122, v0
	v_mov_b32_e32 v123, v0
	v_mov_b32_e32 v124, v0
	v_mov_b32_e32 v125, v0
	v_mov_b32_e32 v126, v0
	v_mov_b32_e32 v127, v0
	v_and_b32_e32 v229, 63, v174
	v_lshrrev_b32_e32 v230, 3, v229
	v_mov_b32_e32 v233, 0x800
	v_mul_u32_u24_e32 v224, v230, v233
	v_bfe_u32 v231, v174, 4, 2
	v_bfe_u32 v232, v174, 6, 1
	v_lshl_or_b32 v232, v232, 2, v231
	v_and_b32_e32 v233, 7, v174
	v_xor_b32_e32 v232, v232, v233
	v_lshl_add_u32 v224, v232, 4, v224
	v_and_b32_e32 v229, 15, v174
	v_bfe_u32 v230, v174, 1, 3
	v_xor_b32_e32 v230, v230, v231
	v_lshlrev_b32_e32 v230, 4, v230
	v_lshl_or_b32 v230, v229, 7, v230
	v_lshrrev_b32_e32 v229, 8, v174
	v_lshl_or_b32 v225, v229, 14, v230
	v_bfe_u32 v229, v174, 6, 2
	v_lshl_or_b32 v227, v229, 13, v230
	v_or_b32_e32 v227, 0x10000, v227
	v_xor_b32_e32 v226, 64, v225
	v_xor_b32_e32 v228, 64, v227
	v_readfirstlane_b32 s97, v174
	s_lshl_b32 s97, s97, 4
	s_mov_b32 s28, 14
	s_add_u32 m0, s97, 0x0
	s_add_u32 s14, s98, 0x0
	s_addc_u32 s15, s99, 0
	global_load_lds_dwordx4 v224, s[14:15]
	s_add_u32 m0, s97, 0x10000
	s_add_u32 s14, s100, 0x0
	s_addc_u32 s15, s101, 0
	global_load_lds_dwordx4 v224, s[14:15]
	s_add_u32 m0, s97, 0x2000
	s_add_u32 s14, s98, 0x20000
	s_addc_u32 s15, s99, 0
	global_load_lds_dwordx4 v224, s[14:15]
	s_add_u32 m0, s97, 0x12000
	s_add_u32 s14, s100, 0x20000
	s_addc_u32 s15, s101, 0
	global_load_lds_dwordx4 v224, s[14:15]
	s_add_u32 m0, s97, 0x4000
	s_add_u32 s14, s98, 0x40000
	s_addc_u32 s15, s99, 0
	global_load_lds_dwordx4 v224, s[14:15]
	s_add_u32 m0, s97, 0x14000
	s_add_u32 s14, s100, 0x40000
	s_addc_u32 s15, s101, 0
	global_load_lds_dwordx4 v224, s[14:15]
	s_add_u32 m0, s97, 0x6000
	s_add_u32 s14, s98, 0x60000
	s_addc_u32 s15, s99, 0
	global_load_lds_dwordx4 v224, s[14:15]
	s_add_u32 m0, s97, 0x16000
	s_add_u32 s14, s100, 0x60000
	s_addc_u32 s15, s101, 0
	global_load_lds_dwordx4 v224, s[14:15]
	s_add_u32 m0, s97, 0x8000
	s_add_u32 s14, s98, 0x80
	s_addc_u32 s15, s99, 0
	global_load_lds_dwordx4 v224, s[14:15]
	s_add_u32 m0, s97, 0x18000
	s_add_u32 s14, s100, 0x80
	s_addc_u32 s15, s101, 0
	global_load_lds_dwordx4 v224, s[14:15]
	s_add_u32 m0, s97, 0xa000
	s_add_u32 s14, s98, 0x20080
	s_addc_u32 s15, s99, 0
	global_load_lds_dwordx4 v224, s[14:15]
	s_add_u32 m0, s97, 0x1a000
	s_add_u32 s14, s100, 0x20080
	s_addc_u32 s15, s101, 0
	global_load_lds_dwordx4 v224, s[14:15]
	s_add_u32 m0, s97, 0xc000
	s_add_u32 s14, s98, 0x40080
	s_addc_u32 s15, s99, 0
	global_load_lds_dwordx4 v224, s[14:15]
	s_add_u32 m0, s97, 0x1c000
	s_add_u32 s14, s100, 0x40080
	s_addc_u32 s15, s101, 0
	global_load_lds_dwordx4 v224, s[14:15]
	s_add_u32 m0, s97, 0xe000
	s_add_u32 s14, s98, 0x60080
	s_addc_u32 s15, s99, 0
	global_load_lds_dwordx4 v224, s[14:15]
	s_add_u32 m0, s97, 0x1e000
	s_add_u32 s14, s100, 0x60080
	s_addc_u32 s15, s101, 0
	global_load_lds_dwordx4 v224, s[14:15]
	s_add_u32 s98, s98, 0x100
	s_addc_u32 s99, s99, 0
	s_add_u32 s100, s100, 0x100
	s_addc_u32 s101, s101, 0
	s_waitcnt vmcnt(8)
	s_barrier
; #define G_LOAD(KT) do { _Pragma("unroll") for (int i = 0; i < 4; ++i) { ra[i] = *(const u32x4*)(Ag + (size_t)i * 64 * lda + (KT) * 64); rb[i] = *(const u32x4*)(Bg + (size_t)i * 64 * K + (KT) * 64); } } while (0)
; #define G_STORE(BUF) do { u16* ad = As + (BUF) * 256 * 64 + sto; u16* bd = Bs + (BUF) * 256 * 64 + sto; _Pragma("unroll") for (int i = 0; i < 4; ++i) { *(u32x4*)(ad + i * 64 * 64) = ra[i]; *(u32x4*)(bd + i * 64 * 64) = rb[i]; } } while (0)
; template <int EPI>
; DI void gemm_phase(const u16* __restrict__ A, int lda, const u16* __restrict__ Bt, int K, int N, u16* outb, int ldo,
;                    const float* r0, const float* r1, float* outf, char* lds, int bid, int nb) {
;     ...
;     G_LOAD(0);
;     G_STORE(0);
;     __syncthreads();
;     for (int kt = 0; kt < nk; ++kt) {
;       const int cur = kt & 1;
;       if (kt + 1 < nk) G_LOAD(kt + 1);
;       G_MMA(cur, fo0);
;       G_MMA(cur, fo1);
;       if (kt + 1 < nk) G_STORE(cur ^ 1);
;       __syncthreads();
;     }
	ds_read_b128 v[152:155], v227 offset:0
	ds_read_b128 v[156:159], v227 offset:2048
	ds_read_b128 v[160:163], v227 offset:4096
	ds_read_b128 v[164:167], v227 offset:6144
	ds_read_b128 v[188:191], v225 offset:0
	ds_read_b128 v[192:195], v225 offset:2048
	ds_read_b128 v[196:199], v225 offset:4096
	ds_read_b128 v[200:203], v225 offset:6144
	ds_read_b128 v[204:207], v225 offset:8192
	ds_read_b128 v[208:211], v225 offset:10240
	ds_read_b128 v[212:215], v225 offset:12288
	ds_read_b128 v[216:219], v225 offset:14336
	v_xor_b32_e32 v225, 0x8000, v225
	v_xor_b32_e32 v227, 0x8000, v227
	s_waitcnt lgkmcnt(0)
	s_bitcmp1_b32 s97, 12
	s_cbranch_scc0 .Lgm4_noprio
	s_setprio 1
.Lgm4_noprio:
.Lgm4_loop:
	s_waitcnt lgkmcnt(4)
	v_mfma_f32_16x16x32_bf16 v[124:127], v[152:155], v[188:191], v[124:127]
	v_mfma_f32_16x16x32_bf16 v[120:123], v[156:159], v[188:191], v[120:123]
	v_mfma_f32_16x16x32_bf16 v[116:119], v[160:163], v[188:191], v[116:119]
	v_mfma_f32_16x16x32_bf16 v[112:115], v[164:167], v[188:191], v[112:115]
	ds_read_b128 v[188:191], v226 offset:0
	ds_read_b128 v[168:171], v228 offset:0
	v_mfma_f32_16x16x32_bf16 v[108:111], v[152:155], v[192:195], v[108:111]
	v_mfma_f32_16x16x32_bf16 v[104:107], v[156:159], v[192:195], v[104:107]
	v_mfma_f32_16x16x32_bf16 v[100:103], v[160:163], v[192:195], v[100:103]
	v_mfma_f32_16x16x32_bf16 v[96:99], v[164:167], v[192:195], v[96:99]
	ds_read_b128 v[192:195], v226 offset:2048
	ds_read_b128 v[176:179], v228 offset:2048
	v_mfma_f32_16x16x32_bf16 v[92:95], v[152:155], v[196:199], v[92:95]
	v_mfma_f32_16x16x32_bf16 v[88:91], v[156:159], v[196:199], v[88:91]
	v_mfma_f32_16x16x32_bf16 v[84:87], v[160:163], v[196:199], v[84:87]
	v_mfma_f32_16x16x32_bf16 v[80:83], v[164:167], v[196:199], v[80:83]
	ds_read_b128 v[196:199], v226 offset:4096
	ds_read_b128 v[180:183], v228 offset:4096
	v_mfma_f32_16x16x32_bf16 v[76:79], v[152:155], v[200:203], v[76:79]
	v_mfma_f32_16x16x32_bf16 v[72:75], v[156:159], v[200:203], v[72:75]
	v_mfma_f32_16x16x32_bf16 v[68:71], v[160:163], v[200:203], v[68:71]
	v_mfma_f32_16x16x32_bf16 v[64:67], v[164:167], v[200:203], v[64:67]
	ds_read_b128 v[200:203], v226 offset:6144
	ds_read_b128 v[184:187], v228 offset:6144
	s_waitcnt lgkmcnt(11)
	v_mfma_f32_16x16x32_bf16 v[60:63], v[152:155], v[204:207], v[60:63]
	v_mfma_f32_16x16x32_bf16 v[56:59], v[156:159], v[204:207], v[56:59]
	v_mfma_f32_16x16x32_bf16 v[52:55], v[160:163], v[204:207], v[52:55]
	v_mfma_f32_16x16x32_bf16 v[48:51], v[164:167], v[204:207], v[48:51]
	ds_read_b128 v[204:207], v226 offset:8192
	ds_read_b128 v[220:223], v226 offset:14336
	s_waitcnt lgkmcnt(11)
	v_mfma_f32_16x16x32_bf16 v[44:47], v[152:155], v[208:211], v[44:47]
	v_mfma_f32_16x16x32_bf16 v[40:43], v[156:159], v[208:211], v[40:43]
	v_mfma_f32_16x16x32_bf16 v[36:39], v[160:163], v[208:211], v[36:39]
	v_mfma_f32_16x16x32_bf16 v[32:35], v[164:167], v[208:211], v[32:35]
	ds_read_b128 v[208:211], v226 offset:10240
	s_waitcnt lgkmcnt(11)
	v_mfma_f32_16x16x32_bf16 v[28:31], v[152:155], v[212:215], v[28:31]
	v_mfma_f32_16x16x32_bf16 v[24:27], v[156:159], v[212:215], v[24:27]
	v_mfma_f32_16x16x32_bf16 v[20:23], v[160:163], v[212:215], v[20:23]
	v_mfma_f32_16x16x32_bf16 v[16:19], v[164:167], v[212:215], v[16:19]
	ds_read_b128 v[212:215], v226 offset:12288
	v_mfma_f32_16x16x32_bf16 v[12:15], v[152:155], v[216:219], v[12:15]
	v_mfma_f32_16x16x32_bf16 v[8:11], v[156:159], v[216:219], v[8:11]
	v_mfma_f32_16x16x32_bf16 v[4:7], v[160:163], v[216:219], v[4:7]
	v_mfma_f32_16x16x32_bf16 v[0:3], v[164:167], v[216:219], v[0:3]
	s_waitcnt vmcnt(0) lgkmcnt(0)
	s_barrier
	v_mfma_f32_16x16x32_bf16 v[124:127], v[168:171], v[188:191], v[124:127]
	v_mfma_f32_16x16x32_bf16 v[120:123], v[176:179], v[188:191], v[120:123]
	v_mfma_f32_16x16x32_bf16 v[116:119], v[180:183], v[188:191], v[116:119]
	v_mfma_f32_16x16x32_bf16 v[112:115], v[184:187], v[188:191], v[112:115]
	ds_read_b128 v[188:191], v225 offset:0
	ds_read_b128 v[152:155], v227 offset:0
	s_add_u32 m0, s97, 0x0
	s_add_u32 s14, s98, 0x0
	s_addc_u32 s15, s99, 0
	global_load_lds_dwordx4 v224, s[14:15]
	v_mfma_f32_16x16x32_bf16 v[108:111], v[168:171], v[192:195], v[108:111]
	v_mfma_f32_16x16x32_bf16 v[104:107], v[176:179], v[192:195], v[104:107]
	v_mfma_f32_16x16x32_bf16 v[100:103], v[180:183], v[192:195], v[100:103]
	v_mfma_f32_16x16x32_bf16 v[96:99], v[184:187], v[192:195], v[96:99]
	ds_read_b128 v[192:195], v225 offset:2048
	ds_read_b128 v[156:159], v227 offset:2048
	s_add_u32 m0, s97, 0x10000
	s_add_u32 s14, s100, 0x0
	s_addc_u32 s15, s101, 0
	global_load_lds_dwordx4 v224, s[14:15]
	v_mfma_f32_16x16x32_bf16 v[92:95], v[168:171], v[196:199], v[92:95]
	v_mfma_f32_16x16x32_bf16 v[88:91], v[176:179], v[196:199], v[88:91]
	v_mfma_f32_16x16x32_bf16 v[84:87], v[180:183], v[196:199], v[84:87]
	v_mfma_f32_16x16x32_bf16 v[80:83], v[184:187], v[196:199], v[80:83]
	ds_read_b128 v[196:199], v225 offset:4096
	ds_read_b128 v[160:163], v227 offset:4096
	s_add_u32 m0, s97, 0x2000
	s_add_u32 s14, s98, 0x20000
	s_addc_u32 s15, s99, 0
	global_load_lds_dwordx4 v224, s[14:15]
	v_mfma_f32_16x16x32_bf16 v[76:79], v[168:171], v[200:203], v[76:79]
	v_mfma_f32_16x16x32_bf16 v[72:75], v[176:179], v[200:203], v[72:75]
	v_mfma_f32_16x16x32_bf16 v[68:71], v[180:183], v[200:203], v[68:71]
	v_mfma_f32_16x16x32_bf16 v[64:67], v[184:187], v[200:203], v[64:67]
	ds_read_b128 v[200:203], v225 offset:6144
	ds_read_b128 v[164:167], v227 offset:6144
	s_add_u32 m0, s97, 0x12000
	s_add_u32 s14, s100, 0x20000
	s_addc_u32 s15, s101, 0
	global_load_lds_dwordx4 v224, s[14:15]
	v_mfma_f32_16x16x32_bf16 v[60:63], v[168:171], v[204:207], v[60:63]
	v_mfma_f32_16x16x32_bf16 v[56:59], v[176:179], v[204:207], v[56:59]
; #define G_LOAD(KT) do { _Pragma("unroll") for (int i = 0; i < 4; ++i) { ra[i] = *(const u32x4*)(Ag + (size_t)i * 64 * lda + (KT) * 64); rb[i] = *(const u32x4*)(Bg + (size_t)i * 64 * K + (KT) * 64); } } while (0)
; #define G_STORE(BUF) do { u16* ad = As + (BUF) * 256 * 64 + sto; u16* bd = Bs + (BUF) * 256 * 64 + sto; _Pragma("unroll") for (int i = 0; i < 4; ++i) { *(u32x4*)(ad + i * 64 * 64) = ra[i]; *(u32x4*)(bd + i * 64 * 64) = rb[i]; } } while (0)
; template <int EPI>
; DI void gemm_phase(const u16* __restrict__ A, int lda, const u16* __restrict__ Bt, int K, int N, u16* outb, int ldo,
;                    const float* r0, const float* r1, float* outf, char* lds, int bid, int nb) {
;     ...
;     G_LOAD(0);
;     G_STORE(0);
;     __syncthreads();
;     for (int kt = 0; kt < nk; ++kt) {
;       const int cur = kt & 1;
;       if (kt + 1 < nk) G_LOAD(kt + 1);
;       G_MMA(cur, fo0);
;       G_MMA(cur, fo1);
;       if (kt + 1 < nk) G_STORE(cur ^ 1);
;       __syncthreads();
;     }
	v_mfma_f32_16x16x32_bf16 v[52:55], v[180:183], v[204:207], v[52:55]
	v_mfma_f32_16x16x32_bf16 v[48:51], v[184:187], v[204:207], v[48:51]
	ds_read_b128 v[204:207], v225 offset:8192
	ds_read_b128 v[216:219], v225 offset:14336
	s_add_u32 m0, s97, 0x4000
	s_add_u32 s14, s98, 0x40000
	s_addc_u32 s15, s99, 0
	global_load_lds_dwordx4 v224, s[14:15]
	v_mfma_f32_16x16x32_bf16 v[44:47], v[168:171], v[208:211], v[44:47]
	v_mfma_f32_16x16x32_bf16 v[40:43], v[176:179], v[208:211], v[40:43]
	v_mfma_f32_16x16x32_bf16 v[36:39], v[180:183], v[208:211], v[36:39]
	v_mfma_f32_16x16x32_bf16 v[32:35], v[184:187], v[208:211], v[32:35]
	ds_read_b128 v[208:211], v225 offset:10240
	s_add_u32 m0, s97, 0x14000
	s_add_u32 s14, s100, 0x40000
	s_addc_u32 s15, s101, 0
	global_load_lds_dwordx4 v224, s[14:15]
	v_mfma_f32_16x16x32_bf16 v[28:31], v[168:171], v[212:215], v[28:31]
	v_mfma_f32_16x16x32_bf16 v[24:27], v[176:179], v[212:215], v[24:27]
	v_mfma_f32_16x16x32_bf16 v[20:23], v[180:183], v[212:215], v[20:23]
	v_mfma_f32_16x16x32_bf16 v[16:19], v[184:187], v[212:215], v[16:19]
	ds_read_b128 v[212:215], v225 offset:12288
	s_add_u32 m0, s97, 0x6000
	s_add_u32 s14, s98, 0x60000
	s_addc_u32 s15, s99, 0
	global_load_lds_dwordx4 v224, s[14:15]
	v_mfma_f32_16x16x32_bf16 v[12:15], v[168:171], v[220:223], v[12:15]
	v_mfma_f32_16x16x32_bf16 v[8:11], v[176:179], v[220:223], v[8:11]
	v_mfma_f32_16x16x32_bf16 v[4:7], v[180:183], v[220:223], v[4:7]
	v_mfma_f32_16x16x32_bf16 v[0:3], v[184:187], v[220:223], v[0:3]
	s_add_u32 m0, s97, 0x16000
	s_add_u32 s14, s100, 0x60000
	s_addc_u32 s15, s101, 0
	global_load_lds_dwordx4 v224, s[14:15]
	v_xor_b32_e32 v225, 0x8000, v225
	v_xor_b32_e32 v227, 0x8000, v227
	v_xor_b32_e32 v226, 0x8000, v226
	v_xor_b32_e32 v228, 0x8000, v228
	s_xor_b32 s97, s97, 0x8000
	s_add_u32 s98, s98, 0x80
	s_addc_u32 s99, s99, 0
	s_add_u32 s100, s100, 0x80
	s_addc_u32 s101, s101, 0
	s_sub_u32 s28, s28, 1
	s_cmp_lg_u32 s28, 0
	s_cbranch_scc1 .Lgm4_loop
	s_waitcnt lgkmcnt(4)
	v_mfma_f32_16x16x32_bf16 v[124:127], v[152:155], v[188:191], v[124:127]
	v_mfma_f32_16x16x32_bf16 v[120:123], v[156:159], v[188:191], v[120:123]
	v_mfma_f32_16x16x32_bf16 v[116:119], v[160:163], v[188:191], v[116:119]
	v_mfma_f32_16x16x32_bf16 v[112:115], v[164:167], v[188:191], v[112:115]
	ds_read_b128 v[188:191], v226 offset:0
	ds_read_b128 v[168:171], v228 offset:0
	v_mfma_f32_16x16x32_bf16 v[108:111], v[152:155], v[192:195], v[108:111]
	v_mfma_f32_16x16x32_bf16 v[104:107], v[156:159], v[192:195], v[104:107]
	v_mfma_f32_16x16x32_bf16 v[100:103], v[160:163], v[192:195], v[100:103]
	v_mfma_f32_16x16x32_bf16 v[96:99], v[164:167], v[192:195], v[96:99]
	ds_read_b128 v[192:195], v226 offset:2048
	ds_read_b128 v[176:179], v228 offset:2048
	v_mfma_f32_16x16x32_bf16 v[92:95], v[152:155], v[196:199], v[92:95]
	v_mfma_f32_16x16x32_bf16 v[88:91], v[156:159], v[196:199], v[88:91]
	v_mfma_f32_16x16x32_bf16 v[84:87], v[160:163], v[196:199], v[84:87]
	v_mfma_f32_16x16x32_bf16 v[80:83], v[164:167], v[196:199], v[80:83]
	ds_read_b128 v[196:199], v226 offset:4096
	ds_read_b128 v[180:183], v228 offset:4096
	v_mfma_f32_16x16x32_bf16 v[76:79], v[152:155], v[200:203], v[76:79]
	v_mfma_f32_16x16x32_bf16 v[72:75], v[156:159], v[200:203], v[72:75]
	v_mfma_f32_16x16x32_bf16 v[68:71], v[160:163], v[200:203], v[68:71]
	v_mfma_f32_16x16x32_bf16 v[64:67], v[164:167], v[200:203], v[64:67]
	ds_read_b128 v[200:203], v226 offset:6144
	ds_read_b128 v[184:187], v228 offset:6144
	s_waitcnt lgkmcnt(11)
	v_mfma_f32_16x16x32_bf16 v[60:63], v[152:155], v[204:207], v[60:63]
	v_mfma_f32_16x16x32_bf16 v[56:59], v[156:159], v[204:207], v[56:59]
	v_mfma_f32_16x16x32_bf16 v[52:55], v[160:163], v[204:207], v[52:55]
	v_mfma_f32_16x16x32_bf16 v[48:51], v[164:167], v[204:207], v[48:51]
	ds_read_b128 v[204:207], v226 offset:8192
	ds_read_b128 v[220:223], v226 offset:14336
	s_waitcnt lgkmcnt(11)
	v_mfma_f32_16x16x32_bf16 v[44:47], v[152:155], v[208:211], v[44:47]
	v_mfma_f32_16x16x32_bf16 v[40:43], v[156:159], v[208:211], v[40:43]
	v_mfma_f32_16x16x32_bf16 v[36:39], v[160:163], v[208:211], v[36:39]
	v_mfma_f32_16x16x32_bf16 v[32:35], v[164:167], v[208:211], v[32:35]
	ds_read_b128 v[208:211], v226 offset:10240
	s_waitcnt lgkmcnt(11)
	v_mfma_f32_16x16x32_bf16 v[28:31], v[152:155], v[212:215], v[28:31]
	v_mfma_f32_16x16x32_bf16 v[24:27], v[156:159], v[212:215], v[24:27]
	v_mfma_f32_16x16x32_bf16 v[20:23], v[160:163], v[212:215], v[20:23]
	v_mfma_f32_16x16x32_bf16 v[16:19], v[164:167], v[212:215], v[16:19]
	ds_read_b128 v[212:215], v226 offset:12288
	v_mfma_f32_16x16x32_bf16 v[12:15], v[152:155], v[216:219], v[12:15]
	v_mfma_f32_16x16x32_bf16 v[8:11], v[156:159], v[216:219], v[8:11]
	v_mfma_f32_16x16x32_bf16 v[4:7], v[160:163], v[216:219], v[4:7]
	v_mfma_f32_16x16x32_bf16 v[0:3], v[164:167], v[216:219], v[0:3]
	s_waitcnt vmcnt(0) lgkmcnt(0)
	s_barrier
; #define G_LOAD(KT) do { _Pragma("unroll") for (int i = 0; i < 4; ++i) { ra[i] = *(const u32x4*)(Ag + (size_t)i * 64 * lda + (KT) * 64); rb[i] = *(const u32x4*)(Bg + (size_t)i * 64 * K + (KT) * 64); } } while (0)
; #define G_STORE(BUF) do { u16* ad = As + (BUF) * 256 * 64 + sto; u16* bd = Bs + (BUF) * 256 * 64 + sto; _Pragma("unroll") for (int i = 0; i < 4; ++i) { *(u32x4*)(ad + i * 64 * 64) = ra[i]; *(u32x4*)(bd + i * 64 * 64) = rb[i]; } } while (0)
; template <int EPI>
; DI void gemm_phase(const u16* __restrict__ A, int lda, const u16* __restrict__ Bt, int K, int N, u16* outb, int ldo,
;                    const float* r0, const float* r1, float* outf, char* lds, int bid, int nb) {
;     ...
;     for (int kt = 0; kt < nk; ++kt) {
;       const int cur = kt & 1;
;       if (kt + 1 < nk) G_LOAD(kt + 1);
;       G_MMA(cur, fo0);
;       G_MMA(cur, fo1);
;       if (kt + 1 < nk) G_STORE(cur ^ 1);
;       __syncthreads();
;     }
	v_mfma_f32_16x16x32_bf16 v[124:127], v[168:171], v[188:191], v[124:127]
	v_mfma_f32_16x16x32_bf16 v[120:123], v[176:179], v[188:191], v[120:123]
	v_mfma_f32_16x16x32_bf16 v[116:119], v[180:183], v[188:191], v[116:119]
	v_mfma_f32_16x16x32_bf16 v[112:115], v[184:187], v[188:191], v[112:115]
	ds_read_b128 v[188:191], v225 offset:0
	ds_read_b128 v[152:155], v227 offset:0
	v_mfma_f32_16x16x32_bf16 v[108:111], v[168:171], v[192:195], v[108:111]
	v_mfma_f32_16x16x32_bf16 v[104:107], v[176:179], v[192:195], v[104:107]
	v_mfma_f32_16x16x32_bf16 v[100:103], v[180:183], v[192:195], v[100:103]
	v_mfma_f32_16x16x32_bf16 v[96:99], v[184:187], v[192:195], v[96:99]
	ds_read_b128 v[192:195], v225 offset:2048
	ds_read_b128 v[156:159], v227 offset:2048
	v_mfma_f32_16x16x32_bf16 v[92:95], v[168:171], v[196:199], v[92:95]
	v_mfma_f32_16x16x32_bf16 v[88:91], v[176:179], v[196:199], v[88:91]
	v_mfma_f32_16x16x32_bf16 v[84:87], v[180:183], v[196:199], v[84:87]
	v_mfma_f32_16x16x32_bf16 v[80:83], v[184:187], v[196:199], v[80:83]
	ds_read_b128 v[196:199], v225 offset:4096
	ds_read_b128 v[160:163], v227 offset:4096
	v_mfma_f32_16x16x32_bf16 v[76:79], v[168:171], v[200:203], v[76:79]
	v_mfma_f32_16x16x32_bf16 v[72:75], v[176:179], v[200:203], v[72:75]
	v_mfma_f32_16x16x32_bf16 v[68:71], v[180:183], v[200:203], v[68:71]
	v_mfma_f32_16x16x32_bf16 v[64:67], v[184:187], v[200:203], v[64:67]
	ds_read_b128 v[200:203], v225 offset:6144
	ds_read_b128 v[164:167], v227 offset:6144
	v_mfma_f32_16x16x32_bf16 v[60:63], v[168:171], v[204:207], v[60:63]
	v_mfma_f32_16x16x32_bf16 v[56:59], v[176:179], v[204:207], v[56:59]
	v_mfma_f32_16x16x32_bf16 v[52:55], v[180:183], v[204:207], v[52:55]
	v_mfma_f32_16x16x32_bf16 v[48:51], v[184:187], v[204:207], v[48:51]
	ds_read_b128 v[204:207], v225 offset:8192
	ds_read_b128 v[216:219], v225 offset:14336
	v_mfma_f32_16x16x32_bf16 v[44:47], v[168:171], v[208:211], v[44:47]
	v_mfma_f32_16x16x32_bf16 v[40:43], v[176:179], v[208:211], v[40:43]
	v_mfma_f32_16x16x32_bf16 v[36:39], v[180:183], v[208:211], v[36:39]
	v_mfma_f32_16x16x32_bf16 v[32:35], v[184:187], v[208:211], v[32:35]
	ds_read_b128 v[208:211], v225 offset:10240
	v_mfma_f32_16x16x32_bf16 v[28:31], v[168:171], v[212:215], v[28:31]
	v_mfma_f32_16x16x32_bf16 v[24:27], v[176:179], v[212:215], v[24:27]
	v_mfma_f32_16x16x32_bf16 v[20:23], v[180:183], v[212:215], v[20:23]
	v_mfma_f32_16x16x32_bf16 v[16:19], v[184:187], v[212:215], v[16:19]
	ds_read_b128 v[212:215], v225 offset:12288
	v_mfma_f32_16x16x32_bf16 v[12:15], v[168:171], v[220:223], v[12:15]
	v_mfma_f32_16x16x32_bf16 v[8:11], v[176:179], v[220:223], v[8:11]
	v_mfma_f32_16x16x32_bf16 v[4:7], v[180:183], v[220:223], v[4:7]
	v_mfma_f32_16x16x32_bf16 v[0:3], v[184:187], v[220:223], v[0:3]
	v_xor_b32_e32 v226, 0x8000, v226
	v_xor_b32_e32 v228, 0x8000, v228
	s_waitcnt lgkmcnt(4)
	v_mfma_f32_16x16x32_bf16 v[124:127], v[152:155], v[188:191], v[124:127]
	v_mfma_f32_16x16x32_bf16 v[120:123], v[156:159], v[188:191], v[120:123]
	v_mfma_f32_16x16x32_bf16 v[116:119], v[160:163], v[188:191], v[116:119]
	v_mfma_f32_16x16x32_bf16 v[112:115], v[164:167], v[188:191], v[112:115]
	ds_read_b128 v[188:191], v226 offset:0
	ds_read_b128 v[168:171], v228 offset:0
	v_mfma_f32_16x16x32_bf16 v[108:111], v[152:155], v[192:195], v[108:111]
	v_mfma_f32_16x16x32_bf16 v[104:107], v[156:159], v[192:195], v[104:107]
	v_mfma_f32_16x16x32_bf16 v[100:103], v[160:163], v[192:195], v[100:103]
	v_mfma_f32_16x16x32_bf16 v[96:99], v[164:167], v[192:195], v[96:99]
	ds_read_b128 v[192:195], v226 offset:2048
	ds_read_b128 v[176:179], v228 offset:2048
	v_mfma_f32_16x16x32_bf16 v[92:95], v[152:155], v[196:199], v[92:95]
	v_mfma_f32_16x16x32_bf16 v[88:91], v[156:159], v[196:199], v[88:91]
	v_mfma_f32_16x16x32_bf16 v[84:87], v[160:163], v[196:199], v[84:87]
	v_mfma_f32_16x16x32_bf16 v[80:83], v[164:167], v[196:199], v[80:83]
	ds_read_b128 v[196:199], v226 offset:4096
	ds_read_b128 v[180:183], v228 offset:4096
	v_mfma_f32_16x16x32_bf16 v[76:79], v[152:155], v[200:203], v[76:79]
	v_mfma_f32_16x16x32_bf16 v[72:75], v[156:159], v[200:203], v[72:75]
	v_mfma_f32_16x16x32_bf16 v[68:71], v[160:163], v[200:203], v[68:71]
	v_mfma_f32_16x16x32_bf16 v[64:67], v[164:167], v[200:203], v[64:67]
	ds_read_b128 v[200:203], v226 offset:6144
	ds_read_b128 v[184:187], v228 offset:6144
	s_waitcnt lgkmcnt(11)
	v_mfma_f32_16x16x32_bf16 v[60:63], v[152:155], v[204:207], v[60:63]
	v_mfma_f32_16x16x32_bf16 v[56:59], v[156:159], v[204:207], v[56:59]
	v_mfma_f32_16x16x32_bf16 v[52:55], v[160:163], v[204:207], v[52:55]
	v_mfma_f32_16x16x32_bf16 v[48:51], v[164:167], v[204:207], v[48:51]
	ds_read_b128 v[204:207], v226 offset:8192
	ds_read_b128 v[220:223], v226 offset:14336
	s_waitcnt lgkmcnt(11)
	v_mfma_f32_16x16x32_bf16 v[44:47], v[152:155], v[208:211], v[44:47]
	v_mfma_f32_16x16x32_bf16 v[40:43], v[156:159], v[208:211], v[40:43]
	v_mfma_f32_16x16x32_bf16 v[36:39], v[160:163], v[208:211], v[36:39]
	v_mfma_f32_16x16x32_bf16 v[32:35], v[164:167], v[208:211], v[32:35]
	ds_read_b128 v[208:211], v226 offset:10240
	s_waitcnt lgkmcnt(11)
	v_mfma_f32_16x16x32_bf16 v[28:31], v[152:155], v[212:215], v[28:31]
	v_mfma_f32_16x16x32_bf16 v[24:27], v[156:159], v[212:215], v[24:27]
	v_mfma_f32_16x16x32_bf16 v[20:23], v[160:163], v[212:215], v[20:23]
	v_mfma_f32_16x16x32_bf16 v[16:19], v[164:167], v[212:215], v[16:19]
	ds_read_b128 v[212:215], v226 offset:12288
	v_mfma_f32_16x16x32_bf16 v[12:15], v[152:155], v[216:219], v[12:15]
	v_mfma_f32_16x16x32_bf16 v[8:11], v[156:159], v[216:219], v[8:11]
	v_mfma_f32_16x16x32_bf16 v[4:7], v[160:163], v[216:219], v[4:7]
	v_mfma_f32_16x16x32_bf16 v[0:3], v[164:167], v[216:219], v[0:3]
	s_waitcnt vmcnt(0) lgkmcnt(0)
	s_barrier
; DI u16 f2bf(float a) { return (u16)(pk2(a, 0.f) & 0xffffu); }
; #define G_STORE(BUF) do { u16* ad = As + (BUF) * 256 * 64 + sto; u16* bd = Bs + (BUF) * 256 * 64 + sto; _Pragma("unroll") for (int i = 0; i < 4; ++i) { *(u32x4*)(ad + i * 64 * 64) = ra[i]; *(u32x4*)(bd + i * 64 * 64) = rb[i]; } } while (0)
; template <int EPI>
; DI void gemm_phase(const u16* __restrict__ A, int lda, const u16* __restrict__ Bt, int K, int N, u16* outb, int ldo,
;                    const float* r0, const float* r1, float* outf, char* lds, int bid, int nb) {
;     ...
;       G_MMA(cur, fo0);
;       G_MMA(cur, fo1);
;       if (kt + 1 < nk) G_STORE(cur ^ 1);
;       __syncthreads();
;     }
;     ...
;     const int mrow = tm * 256 + wr * 128 + quad * 4;
;     if constexpr (EPI == EPI_BF16) {
;       const int col = tn * 256 + wc * 64 + l15;
; #pragma unroll
;       for (int i = 0; i < 8; ++i)
; #pragma unroll
;         for (int r = 0; r < 4; ++r) {
;           u16* o0 = outb + (size_t)(mrow + i * 16 + r) * ldo + col;
;           o0[0] = f2bf(acc[i][0][r]); o0[16] = f2bf(acc[i][1][r]); o0[32] = f2bf(acc[i][2][r]); o0[48] = f2bf(acc[i][3][r]);
;         }
	v_mfma_f32_16x16x32_bf16 v[124:127], v[168:171], v[188:191], v[124:127]
	v_mfma_f32_16x16x32_bf16 v[120:123], v[176:179], v[188:191], v[120:123]
	v_mfma_f32_16x16x32_bf16 v[116:119], v[180:183], v[188:191], v[116:119]
	v_mfma_f32_16x16x32_bf16 v[112:115], v[184:187], v[188:191], v[112:115]
	v_mfma_f32_16x16x32_bf16 v[108:111], v[168:171], v[192:195], v[108:111]
	v_mfma_f32_16x16x32_bf16 v[104:107], v[176:179], v[192:195], v[104:107]
	v_mfma_f32_16x16x32_bf16 v[100:103], v[180:183], v[192:195], v[100:103]
	v_mfma_f32_16x16x32_bf16 v[96:99], v[184:187], v[192:195], v[96:99]
	v_mfma_f32_16x16x32_bf16 v[92:95], v[168:171], v[196:199], v[92:95]
	v_mfma_f32_16x16x32_bf16 v[88:91], v[176:179], v[196:199], v[88:91]
	v_mfma_f32_16x16x32_bf16 v[84:87], v[180:183], v[196:199], v[84:87]
	v_mfma_f32_16x16x32_bf16 v[80:83], v[184:187], v[196:199], v[80:83]
	v_mfma_f32_16x16x32_bf16 v[76:79], v[168:171], v[200:203], v[76:79]
	v_mfma_f32_16x16x32_bf16 v[72:75], v[176:179], v[200:203], v[72:75]
	v_mfma_f32_16x16x32_bf16 v[68:71], v[180:183], v[200:203], v[68:71]
	v_mfma_f32_16x16x32_bf16 v[64:67], v[184:187], v[200:203], v[64:67]
	v_mfma_f32_16x16x32_bf16 v[60:63], v[168:171], v[204:207], v[60:63]
	v_mfma_f32_16x16x32_bf16 v[56:59], v[176:179], v[204:207], v[56:59]
	v_mfma_f32_16x16x32_bf16 v[52:55], v[180:183], v[204:207], v[52:55]
	v_mfma_f32_16x16x32_bf16 v[48:51], v[184:187], v[204:207], v[48:51]
	v_mfma_f32_16x16x32_bf16 v[44:47], v[168:171], v[208:211], v[44:47]
	v_mfma_f32_16x16x32_bf16 v[40:43], v[176:179], v[208:211], v[40:43]
	v_mfma_f32_16x16x32_bf16 v[36:39], v[180:183], v[208:211], v[36:39]
	v_mfma_f32_16x16x32_bf16 v[32:35], v[184:187], v[208:211], v[32:35]
	v_mfma_f32_16x16x32_bf16 v[28:31], v[168:171], v[212:215], v[28:31]
	v_mfma_f32_16x16x32_bf16 v[24:27], v[176:179], v[212:215], v[24:27]
	v_mfma_f32_16x16x32_bf16 v[20:23], v[180:183], v[212:215], v[20:23]
	v_mfma_f32_16x16x32_bf16 v[16:19], v[184:187], v[212:215], v[16:19]
	v_mfma_f32_16x16x32_bf16 v[12:15], v[168:171], v[220:223], v[12:15]
	v_mfma_f32_16x16x32_bf16 v[8:11], v[176:179], v[220:223], v[8:11]
	v_mfma_f32_16x16x32_bf16 v[4:7], v[180:183], v[220:223], v[4:7]
	v_mfma_f32_16x16x32_bf16 v[0:3], v[184:187], v[220:223], v[0:3]
	s_setprio 0
	s_nop 7
	s_nop 3
	v_and_b32_e32 v225, 15, v174
	v_lshrrev_b32_e32 v226, 8, v174
	v_lshl_or_b32 v225, v226, 7, v225
	v_bfe_u32 v226, v174, 6, 2
	v_bfe_u32 v227, v174, 4, 2
	v_lshlrev_b32_e32 v227, 2, v227
	v_add_u32_e32 v225, s48, v225
	v_lshl_add_u32 v226, v226, 6, v227
	v_add_u32_e32 v226, s49, v226
	v_lshlrev_b32_e32 v226, 1, v226
	v_mov_b32_e32 v227, 0x600
	v_mad_u32_u24 v224, v225, v227, v226
	v_cvt_pk_bf16_f32 v188, v124, v125
	v_cvt_pk_bf16_f32 v189, v126, v127
	global_store_dwordx2 v224, v[188:189], s[8:9] offset:0
	v_cvt_pk_bf16_f32 v190, v120, v121
	v_cvt_pk_bf16_f32 v191, v122, v123
	global_store_dwordx2 v224, v[190:191], s[8:9] offset:32
	v_cvt_pk_bf16_f32 v192, v116, v117
	v_cvt_pk_bf16_f32 v193, v118, v119
	global_store_dwordx2 v224, v[192:193], s[8:9] offset:64
	v_cvt_pk_bf16_f32 v194, v112, v113
	v_cvt_pk_bf16_f32 v195, v114, v115
	global_store_dwordx2 v224, v[194:195], s[8:9] offset:96
	v_add_u32_e32 v224, 0x6000, v224
	v_cvt_pk_bf16_f32 v196, v108, v109
	v_cvt_pk_bf16_f32 v197, v110, v111
	global_store_dwordx2 v224, v[196:197], s[8:9] offset:0
	v_cvt_pk_bf16_f32 v198, v104, v105
	v_cvt_pk_bf16_f32 v199, v106, v107
	global_store_dwordx2 v224, v[198:199], s[8:9] offset:32
	v_cvt_pk_bf16_f32 v200, v100, v101
	v_cvt_pk_bf16_f32 v201, v102, v103
	global_store_dwordx2 v224, v[200:201], s[8:9] offset:64
	v_cvt_pk_bf16_f32 v202, v96, v97
	v_cvt_pk_bf16_f32 v203, v98, v99
	global_store_dwordx2 v224, v[202:203], s[8:9] offset:96
	v_add_u32_e32 v224, 0x6000, v224
	v_cvt_pk_bf16_f32 v204, v92, v93
	v_cvt_pk_bf16_f32 v205, v94, v95
	global_store_dwordx2 v224, v[204:205], s[8:9] offset:0
	v_cvt_pk_bf16_f32 v206, v88, v89
	v_cvt_pk_bf16_f32 v207, v90, v91
	global_store_dwordx2 v224, v[206:207], s[8:9] offset:32
	v_cvt_pk_bf16_f32 v208, v84, v85
	v_cvt_pk_bf16_f32 v209, v86, v87
	global_store_dwordx2 v224, v[208:209], s[8:9] offset:64
	v_cvt_pk_bf16_f32 v210, v80, v81
	v_cvt_pk_bf16_f32 v211, v82, v83
	global_store_dwordx2 v224, v[210:211], s[8:9] offset:96
	v_add_u32_e32 v224, 0x6000, v224
	v_cvt_pk_bf16_f32 v212, v76, v77
	v_cvt_pk_bf16_f32 v213, v78, v79
	global_store_dwordx2 v224, v[212:213], s[8:9] offset:0
	v_cvt_pk_bf16_f32 v214, v72, v73
	v_cvt_pk_bf16_f32 v215, v74, v75
	global_store_dwordx2 v224, v[214:215], s[8:9] offset:32
	v_cvt_pk_bf16_f32 v216, v68, v69
	v_cvt_pk_bf16_f32 v217, v70, v71
	global_store_dwordx2 v224, v[216:217], s[8:9] offset:64
	v_cvt_pk_bf16_f32 v218, v64, v65
	v_cvt_pk_bf16_f32 v219, v66, v67
	global_store_dwordx2 v224, v[218:219], s[8:9] offset:96
	v_add_u32_e32 v224, 0x6000, v224
	v_cvt_pk_bf16_f32 v188, v60, v61
	v_cvt_pk_bf16_f32 v189, v62, v63
	global_store_dwordx2 v224, v[188:189], s[8:9] offset:0
	v_cvt_pk_bf16_f32 v190, v56, v57
	v_cvt_pk_bf16_f32 v191, v58, v59
	global_store_dwordx2 v224, v[190:191], s[8:9] offset:32
	v_cvt_pk_bf16_f32 v192, v52, v53
	v_cvt_pk_bf16_f32 v193, v54, v55
	global_store_dwordx2 v224, v[192:193], s[8:9] offset:64
	v_cvt_pk_bf16_f32 v194, v48, v49
	v_cvt_pk_bf16_f32 v195, v50, v51
	global_store_dwordx2 v224, v[194:195], s[8:9] offset:96
	v_add_u32_e32 v224, 0x6000, v224
	v_cvt_pk_bf16_f32 v196, v44, v45
	v_cvt_pk_bf16_f32 v197, v46, v47
	global_store_dwordx2 v224, v[196:197], s[8:9] offset:0
	v_cvt_pk_bf16_f32 v198, v40, v41
	v_cvt_pk_bf16_f32 v199, v42, v43
	global_store_dwordx2 v224, v[198:199], s[8:9] offset:32
	v_cvt_pk_bf16_f32 v200, v36, v37
	v_cvt_pk_bf16_f32 v201, v38, v39
	global_store_dwordx2 v224, v[200:201], s[8:9] offset:64
	v_cvt_pk_bf16_f32 v202, v32, v33
	v_cvt_pk_bf16_f32 v203, v34, v35
	global_store_dwordx2 v224, v[202:203], s[8:9] offset:96
	v_add_u32_e32 v224, 0x6000, v224
	v_cvt_pk_bf16_f32 v204, v28, v29
	v_cvt_pk_bf16_f32 v205, v30, v31
	global_store_dwordx2 v224, v[204:205], s[8:9] offset:0
	v_cvt_pk_bf16_f32 v206, v24, v25
	v_cvt_pk_bf16_f32 v207, v26, v27
	global_store_dwordx2 v224, v[206:207], s[8:9] offset:32
	v_cvt_pk_bf16_f32 v208, v20, v21
	v_cvt_pk_bf16_f32 v209, v22, v23
	global_store_dwordx2 v224, v[208:209], s[8:9] offset:64
	v_cvt_pk_bf16_f32 v210, v16, v17
	v_cvt_pk_bf16_f32 v211, v18, v19
	global_store_dwordx2 v224, v[210:211], s[8:9] offset:96
	v_add_u32_e32 v224, 0x6000, v224
	v_cvt_pk_bf16_f32 v212, v12, v13
	v_cvt_pk_bf16_f32 v213, v14, v15
	global_store_dwordx2 v224, v[212:213], s[8:9] offset:0
	v_cvt_pk_bf16_f32 v214, v8, v9
	v_cvt_pk_bf16_f32 v215, v10, v11
	global_store_dwordx2 v224, v[214:215], s[8:9] offset:32
	v_cvt_pk_bf16_f32 v216, v4, v5
	v_cvt_pk_bf16_f32 v217, v6, v7
	global_store_dwordx2 v224, v[216:217], s[8:9] offset:64
	v_cvt_pk_bf16_f32 v218, v0, v1
	v_cvt_pk_bf16_f32 v219, v2, v3
	global_store_dwordx2 v224, v[218:219], s[8:9] offset:96
	s_add_i32 s18, s18, 1
	s_cmp_eq_u32 s18, s3
	s_cbranch_scc0 .LBB0_879

; #define G_LOAD(KT) do { _Pragma("unroll") for (int i = 0; i < 4; ++i) { ra[i] = *(const u32x4*)(Ag + (size_t)i * 64 * lda + (KT) * 64); rb[i] = *(const u32x4*)(Bg + (size_t)i * 64 * K + (KT) * 64); } } while (0)
; #define G_STORE(BUF) do { u16* ad = As + (BUF) * 256 * 64 + sto; u16* bd = Bs + (BUF) * 256 * 64 + sto; _Pragma("unroll") for (int i = 0; i < 4; ++i) { *(u32x4*)(ad + i * 64 * 64) = ra[i]; *(u32x4*)(bd + i * 64 * 64) = rb[i]; } } while (0)
; template <int EPI>
; DI void gemm_phase(const u16* __restrict__ A, int lda, const u16* __restrict__ Bt, int K, int N, u16* outb, int ldo,
;                    const float* r0, const float* r1, float* outf, char* lds, int bid, int nb) {
;     ...
;   for (int it = 0; it < nIter; ++it) {
;     int tm, tn;
;     if (swz) { const int st = xcd + 8 * it, sm = st / nSN, sn = st - sm * nSN; tm = sm * GM + jb / GN; tn = sn * GN + (jb % GN); }
;     else { const int t = bid + it * nb; tm = t / nN; tn = t - tm * nN; }
;     const u16* Ag = A + (size_t)(tm * 256 + lrow) * lda + lch * 8;
;     const u16* Bg = Bt + (size_t)(tn * 256 + lrow) * K + lch * 8;
;     f32x4 acc[8][4];
; #pragma unroll
;     for (int i = 0; i < 8; ++i)
; #pragma unroll
;       for (int j = 0; j < 4; ++j) acc[i][j] = (f32x4){0.f, 0.f, 0.f, 0.f};
;     u32x4 ra[4], rb[4];
;     ...
;     G_LOAD(0);
;     G_STORE(0);
;     __syncthreads();
.LBB0_1181:
	s_lshl_b32 s39, s39, 8
	v_or_b32_e32 v0, s39, v138
	v_ashrrev_i32_e32 v1, 31, v0
	s_lshl_b32 s40, s40, 8
	v_or_b32_e32 v2, s40, v138
	v_lshlrev_b64 v[62:63], 11, v[0:1]
	v_ashrrev_i32_e32 v3, 31, v2
	v_lshl_add_u64 v[0:1], v[128:129], 0, v[62:63]
	v_lshlrev_b64 v[64:65], 11, v[2:3]
	v_add_co_u32_e32 v4, vcc, s15, v0
	v_lshl_add_u64 v[2:3], v[130:131], 0, v[64:65]
	s_nop 0
	v_addc_co_u32_e32 v5, vcc, 0, v1, vcc
	v_add_co_u32_e32 v6, vcc, s15, v2
	s_nop 1
	v_readfirstlane_b32 s98, v0
	v_readfirstlane_b32 s99, v1
	s_nop 1
	v_readfirstlane_b32 s100, v2
	v_readfirstlane_b32 s101, v3
	v_addc_co_u32_e32 v7, vcc, 0, v3, vcc
	v_add_co_u32_e32 v4, vcc, s16, v0
	s_mov_b32 s41, 0
	s_nop 0
	v_addc_co_u32_e32 v5, vcc, 0, v1, vcc
	v_add_co_u32_e32 v6, vcc, s16, v2
	s_mov_b64 s[8:9], 0
	s_nop 0
	v_addc_co_u32_e32 v7, vcc, 0, v3, vcc
	v_add_co_u32_e32 v0, vcc, s17, v0
	v_addc_co_u32_e32 v1, vcc, 0, v1, vcc
	v_add_co_u32_e32 v2, vcc, s17, v2
	v_lshl_add_u64 v[134:135], v[132:133], 0, v[62:63]
	s_nop 0
	v_addc_co_u32_e32 v3, vcc, 0, v3, vcc
	v_mov_b32_e32 v0, 0
	v_mov_b32_e32 v1, v0
	v_mov_b32_e32 v2, v0
	v_mov_b32_e32 v3, v0
	v_mov_b32_e32 v4, v0
	v_mov_b32_e32 v5, v0
	v_mov_b32_e32 v6, v0
	v_mov_b32_e32 v7, v0
	v_mov_b32_e32 v8, v0
	v_mov_b32_e32 v9, v0
	v_mov_b32_e32 v10, v0
	v_mov_b32_e32 v11, v0
	v_mov_b32_e32 v12, v0
	v_mov_b32_e32 v13, v0
	v_mov_b32_e32 v14, v0
	v_mov_b32_e32 v15, v0
	v_mov_b32_e32 v16, v0
	v_mov_b32_e32 v17, v0
	v_mov_b32_e32 v18, v0
	v_mov_b32_e32 v19, v0
	v_mov_b32_e32 v20, v0
	v_mov_b32_e32 v21, v0
	v_mov_b32_e32 v22, v0
	v_mov_b32_e32 v23, v0
	v_mov_b32_e32 v24, v0
	v_mov_b32_e32 v25, v0
	v_mov_b32_e32 v26, v0
	v_mov_b32_e32 v27, v0
	v_mov_b32_e32 v28, v0
	v_mov_b32_e32 v29, v0
	v_lshl_add_u64 v[136:137], v[132:133], 0, v[64:65]
	v_mov_b32_e32 v62, v0
	v_mov_b32_e32 v63, v0
	v_mov_b32_e32 v64, v0
	v_mov_b32_e32 v65, v0
	v_mov_b32_e32 v66, v0
	v_mov_b32_e32 v67, v0
	v_mov_b32_e32 v68, v0
	v_mov_b32_e32 v69, v0
	v_mov_b32_e32 v70, v0
	v_mov_b32_e32 v71, v0
	v_mov_b32_e32 v72, v0
	v_mov_b32_e32 v73, v0
	v_mov_b32_e32 v74, v0
	v_mov_b32_e32 v75, v0
	v_mov_b32_e32 v76, v0
	v_mov_b32_e32 v77, v0
	v_mov_b32_e32 v78, v0
	v_mov_b32_e32 v79, v0
	v_mov_b32_e32 v80, v0
	v_mov_b32_e32 v81, v0
	v_mov_b32_e32 v82, v0
	v_mov_b32_e32 v83, v0
	v_mov_b32_e32 v84, v0
	v_mov_b32_e32 v85, v0
	v_mov_b32_e32 v30, v0
	v_mov_b32_e32 v31, v0
	v_mov_b32_e32 v32, v0
	v_mov_b32_e32 v33, v0
	v_mov_b32_e32 v34, v0
	v_mov_b32_e32 v35, v0
	v_mov_b32_e32 v36, v0
	v_mov_b32_e32 v37, v0
	v_mov_b32_e32 v38, v0
	v_mov_b32_e32 v39, v0
	v_mov_b32_e32 v40, v0
	v_mov_b32_e32 v41, v0
	v_mov_b32_e32 v42, v0
	v_mov_b32_e32 v43, v0
	v_mov_b32_e32 v44, v0
	v_mov_b32_e32 v45, v0
	v_mov_b32_e32 v46, v0
	v_mov_b32_e32 v47, v0
	v_mov_b32_e32 v48, v0
	v_mov_b32_e32 v49, v0
	v_mov_b32_e32 v50, v0
	v_mov_b32_e32 v51, v0
	v_mov_b32_e32 v52, v0
	v_mov_b32_e32 v53, v0
	v_mov_b32_e32 v54, v0
	v_mov_b32_e32 v55, v0
	v_mov_b32_e32 v56, v0
	v_mov_b32_e32 v57, v0
	v_mov_b32_e32 v58, v0
	v_mov_b32_e32 v59, v0
	v_mov_b32_e32 v60, v0
	v_mov_b32_e32 v61, v0
	v_mov_b32_e32 v86, v0
	v_mov_b32_e32 v87, v0
	v_mov_b32_e32 v88, v0
	v_mov_b32_e32 v89, v0
	v_mov_b32_e32 v90, v0
	v_mov_b32_e32 v91, v0
	v_mov_b32_e32 v92, v0
	v_mov_b32_e32 v93, v0
	v_mov_b32_e32 v94, v0
	v_mov_b32_e32 v95, v0
	v_mov_b32_e32 v96, v0
	v_mov_b32_e32 v97, v0
	v_mov_b32_e32 v98, v0
	v_mov_b32_e32 v99, v0
	v_mov_b32_e32 v100, v0
	v_mov_b32_e32 v101, v0
	v_mov_b32_e32 v102, v0
	v_mov_b32_e32 v103, v0
	v_mov_b32_e32 v104, v0
	v_mov_b32_e32 v105, v0
	v_mov_b32_e32 v106, v0
	v_mov_b32_e32 v107, v0
	v_mov_b32_e32 v108, v0
	v_mov_b32_e32 v109, v0
	v_mov_b32_e32 v110, v0
	v_mov_b32_e32 v111, v0
	v_mov_b32_e32 v112, v0
	v_mov_b32_e32 v113, v0
	v_mov_b32_e32 v114, v0
	v_mov_b32_e32 v115, v0
	v_mov_b32_e32 v116, v0
	v_mov_b32_e32 v117, v0
	v_mov_b32_e32 v118, v0
	v_mov_b32_e32 v119, v0
	v_mov_b32_e32 v120, v0
	v_mov_b32_e32 v121, v0
	v_mov_b32_e32 v122, v0
	v_mov_b32_e32 v123, v0
	v_mov_b32_e32 v124, v0
	v_mov_b32_e32 v125, v0
	v_mov_b32_e32 v126, v0
	v_mov_b32_e32 v127, v0
	v_and_b32_e32 v229, 63, v174
	v_lshrrev_b32_e32 v230, 3, v229
	v_mov_b32_e32 v233, 0x800
	v_mul_u32_u24_e32 v224, v230, v233
	v_bfe_u32 v231, v174, 4, 2
	v_bfe_u32 v232, v174, 6, 1
	v_lshl_or_b32 v232, v232, 2, v231
	v_and_b32_e32 v233, 7, v174
	v_xor_b32_e32 v232, v232, v233
	v_lshl_add_u32 v224, v232, 4, v224
	v_and_b32_e32 v229, 15, v174
	v_bfe_u32 v230, v174, 1, 3
	v_xor_b32_e32 v230, v230, v231
	v_lshlrev_b32_e32 v230, 4, v230
	v_lshl_or_b32 v230, v229, 7, v230
	v_lshrrev_b32_e32 v229, 8, v174
	v_lshl_or_b32 v225, v229, 14, v230
	v_bfe_u32 v229, v174, 6, 2
	v_lshl_or_b32 v227, v229, 13, v230
	v_or_b32_e32 v227, 0x10000, v227
	v_xor_b32_e32 v226, 64, v225
	v_xor_b32_e32 v228, 64, v227
	v_readfirstlane_b32 s97, v174
	s_lshl_b32 s97, s97, 4
	s_mov_b32 s28, 14
	s_add_u32 m0, s97, 0x0
	s_add_u32 s8, s98, 0x0
	s_addc_u32 s9, s99, 0
	global_load_lds_dwordx4 v224, s[8:9]
	s_add_u32 m0, s97, 0x10000
	s_add_u32 s8, s100, 0x0
	s_addc_u32 s9, s101, 0
	global_load_lds_dwordx4 v224, s[8:9]
	s_add_u32 m0, s97, 0x2000
	s_add_u32 s8, s98, 0x20000
	s_addc_u32 s9, s99, 0
	global_load_lds_dwordx4 v224, s[8:9]
	s_add_u32 m0, s97, 0x12000
	s_add_u32 s8, s100, 0x20000
	s_addc_u32 s9, s101, 0
	global_load_lds_dwordx4 v224, s[8:9]
	s_add_u32 m0, s97, 0x4000
	s_add_u32 s8, s98, 0x40000
	s_addc_u32 s9, s99, 0
	global_load_lds_dwordx4 v224, s[8:9]
	s_add_u32 m0, s97, 0x14000
	s_add_u32 s8, s100, 0x40000
	s_addc_u32 s9, s101, 0
	global_load_lds_dwordx4 v224, s[8:9]
	s_add_u32 m0, s97, 0x6000
	s_add_u32 s8, s98, 0x60000
	s_addc_u32 s9, s99, 0
	global_load_lds_dwordx4 v224, s[8:9]
	s_add_u32 m0, s97, 0x16000
	s_add_u32 s8, s100, 0x60000
	s_addc_u32 s9, s101, 0
	global_load_lds_dwordx4 v224, s[8:9]
	s_add_u32 m0, s97, 0x8000
	s_add_u32 s8, s98, 0x80
	s_addc_u32 s9, s99, 0
	global_load_lds_dwordx4 v224, s[8:9]
	s_add_u32 m0, s97, 0x18000
	s_add_u32 s8, s100, 0x80
	s_addc_u32 s9, s101, 0
	global_load_lds_dwordx4 v224, s[8:9]
	s_add_u32 m0, s97, 0xa000
	s_add_u32 s8, s98, 0x20080
	s_addc_u32 s9, s99, 0
	global_load_lds_dwordx4 v224, s[8:9]
	s_add_u32 m0, s97, 0x1a000
	s_add_u32 s8, s100, 0x20080
	s_addc_u32 s9, s101, 0
	global_load_lds_dwordx4 v224, s[8:9]
	s_add_u32 m0, s97, 0xc000
	s_add_u32 s8, s98, 0x40080
	s_addc_u32 s9, s99, 0
	global_load_lds_dwordx4 v224, s[8:9]
	s_add_u32 m0, s97, 0x1c000
	s_add_u32 s8, s100, 0x40080
	s_addc_u32 s9, s101, 0
	global_load_lds_dwordx4 v224, s[8:9]
	s_add_u32 m0, s97, 0xe000
	s_add_u32 s8, s98, 0x60080
	s_addc_u32 s9, s99, 0
	global_load_lds_dwordx4 v224, s[8:9]
	s_add_u32 m0, s97, 0x1e000
	s_add_u32 s8, s100, 0x60080
	s_addc_u32 s9, s101, 0
	global_load_lds_dwordx4 v224, s[8:9]
	s_add_u32 s98, s98, 0x100
	s_addc_u32 s99, s99, 0
	s_add_u32 s100, s100, 0x100
	s_addc_u32 s101, s101, 0
	s_waitcnt vmcnt(8)
	s_barrier
; #define G_LOAD(KT) do { _Pragma("unroll") for (int i = 0; i < 4; ++i) { ra[i] = *(const u32x4*)(Ag + (size_t)i * 64 * lda + (KT) * 64); rb[i] = *(const u32x4*)(Bg + (size_t)i * 64 * K + (KT) * 64); } } while (0)
; #define G_STORE(BUF) do { u16* ad = As + (BUF) * 256 * 64 + sto; u16* bd = Bs + (BUF) * 256 * 64 + sto; _Pragma("unroll") for (int i = 0; i < 4; ++i) { *(u32x4*)(ad + i * 64 * 64) = ra[i]; *(u32x4*)(bd + i * 64 * 64) = rb[i]; } } while (0)
; template <int EPI>
; DI void gemm_phase(const u16* __restrict__ A, int lda, const u16* __restrict__ Bt, int K, int N, u16* outb, int ldo,
;                    const float* r0, const float* r1, float* outf, char* lds, int bid, int nb) {
;     ...
;     G_LOAD(0);
;     G_STORE(0);
;     __syncthreads();
;     for (int kt = 0; kt < nk; ++kt) {
;       const int cur = kt & 1;
;       if (kt + 1 < nk) G_LOAD(kt + 1);
;       G_MMA(cur, fo0);
;       G_MMA(cur, fo1);
;       if (kt + 1 < nk) G_STORE(cur ^ 1);
;       __syncthreads();
;     }
	ds_read_b128 v[152:155], v227 offset:0
	ds_read_b128 v[156:159], v227 offset:2048
	ds_read_b128 v[160:163], v227 offset:4096
	ds_read_b128 v[164:167], v227 offset:6144
	ds_read_b128 v[188:191], v225 offset:0
	ds_read_b128 v[192:195], v225 offset:2048
	ds_read_b128 v[196:199], v225 offset:4096
	ds_read_b128 v[200:203], v225 offset:6144
	ds_read_b128 v[204:207], v225 offset:8192
	ds_read_b128 v[208:211], v225 offset:10240
	ds_read_b128 v[212:215], v225 offset:12288
	ds_read_b128 v[216:219], v225 offset:14336
	v_xor_b32_e32 v225, 0x8000, v225
	v_xor_b32_e32 v227, 0x8000, v227
	s_waitcnt lgkmcnt(0)
	s_bitcmp1_b32 s97, 12
	s_cbranch_scc0 .Lgm5_noprio
	s_setprio 1
.Lgm5_noprio:
.Lgm5_loop:
	s_waitcnt lgkmcnt(4)
	v_mfma_f32_16x16x32_bf16 v[124:127], v[152:155], v[188:191], v[124:127]
	v_mfma_f32_16x16x32_bf16 v[120:123], v[156:159], v[188:191], v[120:123]
	v_mfma_f32_16x16x32_bf16 v[116:119], v[160:163], v[188:191], v[116:119]
	v_mfma_f32_16x16x32_bf16 v[112:115], v[164:167], v[188:191], v[112:115]
	ds_read_b128 v[188:191], v226 offset:0
	ds_read_b128 v[168:171], v228 offset:0
	v_mfma_f32_16x16x32_bf16 v[108:111], v[152:155], v[192:195], v[108:111]
	v_mfma_f32_16x16x32_bf16 v[104:107], v[156:159], v[192:195], v[104:107]
	v_mfma_f32_16x16x32_bf16 v[100:103], v[160:163], v[192:195], v[100:103]
	v_mfma_f32_16x16x32_bf16 v[96:99], v[164:167], v[192:195], v[96:99]
	ds_read_b128 v[192:195], v226 offset:2048
	ds_read_b128 v[176:179], v228 offset:2048
	v_mfma_f32_16x16x32_bf16 v[92:95], v[152:155], v[196:199], v[92:95]
	v_mfma_f32_16x16x32_bf16 v[88:91], v[156:159], v[196:199], v[88:91]
	v_mfma_f32_16x16x32_bf16 v[84:87], v[160:163], v[196:199], v[84:87]
	v_mfma_f32_16x16x32_bf16 v[80:83], v[164:167], v[196:199], v[80:83]
	ds_read_b128 v[196:199], v226 offset:4096
	ds_read_b128 v[180:183], v228 offset:4096
	v_mfma_f32_16x16x32_bf16 v[76:79], v[152:155], v[200:203], v[76:79]
	v_mfma_f32_16x16x32_bf16 v[72:75], v[156:159], v[200:203], v[72:75]
	v_mfma_f32_16x16x32_bf16 v[68:71], v[160:163], v[200:203], v[68:71]
	v_mfma_f32_16x16x32_bf16 v[64:67], v[164:167], v[200:203], v[64:67]
	ds_read_b128 v[200:203], v226 offset:6144
	ds_read_b128 v[184:187], v228 offset:6144
	s_waitcnt lgkmcnt(11)
	v_mfma_f32_16x16x32_bf16 v[60:63], v[152:155], v[204:207], v[60:63]
	v_mfma_f32_16x16x32_bf16 v[56:59], v[156:159], v[204:207], v[56:59]
	v_mfma_f32_16x16x32_bf16 v[52:55], v[160:163], v[204:207], v[52:55]
	v_mfma_f32_16x16x32_bf16 v[48:51], v[164:167], v[204:207], v[48:51]
	ds_read_b128 v[204:207], v226 offset:8192
	ds_read_b128 v[220:223], v226 offset:14336
	s_waitcnt lgkmcnt(11)
	v_mfma_f32_16x16x32_bf16 v[44:47], v[152:155], v[208:211], v[44:47]
	v_mfma_f32_16x16x32_bf16 v[40:43], v[156:159], v[208:211], v[40:43]
	v_mfma_f32_16x16x32_bf16 v[36:39], v[160:163], v[208:211], v[36:39]
	v_mfma_f32_16x16x32_bf16 v[32:35], v[164:167], v[208:211], v[32:35]
	ds_read_b128 v[208:211], v226 offset:10240
	s_waitcnt lgkmcnt(11)
	v_mfma_f32_16x16x32_bf16 v[28:31], v[152:155], v[212:215], v[28:31]
	v_mfma_f32_16x16x32_bf16 v[24:27], v[156:159], v[212:215], v[24:27]
	v_mfma_f32_16x16x32_bf16 v[20:23], v[160:163], v[212:215], v[20:23]
	v_mfma_f32_16x16x32_bf16 v[16:19], v[164:167], v[212:215], v[16:19]
	ds_read_b128 v[212:215], v226 offset:12288
	v_mfma_f32_16x16x32_bf16 v[12:15], v[152:155], v[216:219], v[12:15]
	v_mfma_f32_16x16x32_bf16 v[8:11], v[156:159], v[216:219], v[8:11]
	v_mfma_f32_16x16x32_bf16 v[4:7], v[160:163], v[216:219], v[4:7]
	v_mfma_f32_16x16x32_bf16 v[0:3], v[164:167], v[216:219], v[0:3]
	s_waitcnt vmcnt(0) lgkmcnt(0)
	s_barrier
	v_mfma_f32_16x16x32_bf16 v[124:127], v[168:171], v[188:191], v[124:127]
	v_mfma_f32_16x16x32_bf16 v[120:123], v[176:179], v[188:191], v[120:123]
	v_mfma_f32_16x16x32_bf16 v[116:119], v[180:183], v[188:191], v[116:119]
	v_mfma_f32_16x16x32_bf16 v[112:115], v[184:187], v[188:191], v[112:115]
	ds_read_b128 v[188:191], v225 offset:0
	ds_read_b128 v[152:155], v227 offset:0
	s_add_u32 m0, s97, 0x0
	s_add_u32 s8, s98, 0x0
	s_addc_u32 s9, s99, 0
	global_load_lds_dwordx4 v224, s[8:9]
	v_mfma_f32_16x16x32_bf16 v[108:111], v[168:171], v[192:195], v[108:111]
	v_mfma_f32_16x16x32_bf16 v[104:107], v[176:179], v[192:195], v[104:107]
	v_mfma_f32_16x16x32_bf16 v[100:103], v[180:183], v[192:195], v[100:103]
	v_mfma_f32_16x16x32_bf16 v[96:99], v[184:187], v[192:195], v[96:99]
	ds_read_b128 v[192:195], v225 offset:2048
	ds_read_b128 v[156:159], v227 offset:2048
	s_add_u32 m0, s97, 0x10000
	s_add_u32 s8, s100, 0x0
	s_addc_u32 s9, s101, 0
	global_load_lds_dwordx4 v224, s[8:9]
	v_mfma_f32_16x16x32_bf16 v[92:95], v[168:171], v[196:199], v[92:95]
	v_mfma_f32_16x16x32_bf16 v[88:91], v[176:179], v[196:199], v[88:91]
	v_mfma_f32_16x16x32_bf16 v[84:87], v[180:183], v[196:199], v[84:87]
	v_mfma_f32_16x16x32_bf16 v[80:83], v[184:187], v[196:199], v[80:83]
	ds_read_b128 v[196:199], v225 offset:4096
	ds_read_b128 v[160:163], v227 offset:4096
	s_add_u32 m0, s97, 0x2000
	s_add_u32 s8, s98, 0x20000
	s_addc_u32 s9, s99, 0
	global_load_lds_dwordx4 v224, s[8:9]
	v_mfma_f32_16x16x32_bf16 v[76:79], v[168:171], v[200:203], v[76:79]
	v_mfma_f32_16x16x32_bf16 v[72:75], v[176:179], v[200:203], v[72:75]
	v_mfma_f32_16x16x32_bf16 v[68:71], v[180:183], v[200:203], v[68:71]
	v_mfma_f32_16x16x32_bf16 v[64:67], v[184:187], v[200:203], v[64:67]
	ds_read_b128 v[200:203], v225 offset:6144
	ds_read_b128 v[164:167], v227 offset:6144
	s_add_u32 m0, s97, 0x12000
	s_add_u32 s8, s100, 0x20000
	s_addc_u32 s9, s101, 0
	global_load_lds_dwordx4 v224, s[8:9]
	v_mfma_f32_16x16x32_bf16 v[60:63], v[168:171], v[204:207], v[60:63]
	v_mfma_f32_16x16x32_bf16 v[56:59], v[176:179], v[204:207], v[56:59]
; #define G_LOAD(KT) do { _Pragma("unroll") for (int i = 0; i < 4; ++i) { ra[i] = *(const u32x4*)(Ag + (size_t)i * 64 * lda + (KT) * 64); rb[i] = *(const u32x4*)(Bg + (size_t)i * 64 * K + (KT) * 64); } } while (0)
; #define G_STORE(BUF) do { u16* ad = As + (BUF) * 256 * 64 + sto; u16* bd = Bs + (BUF) * 256 * 64 + sto; _Pragma("unroll") for (int i = 0; i < 4; ++i) { *(u32x4*)(ad + i * 64 * 64) = ra[i]; *(u32x4*)(bd + i * 64 * 64) = rb[i]; } } while (0)
; template <int EPI>
; DI void gemm_phase(const u16* __restrict__ A, int lda, const u16* __restrict__ Bt, int K, int N, u16* outb, int ldo,
;                    const float* r0, const float* r1, float* outf, char* lds, int bid, int nb) {
;     ...
;     G_LOAD(0);
;     G_STORE(0);
;     __syncthreads();
;     for (int kt = 0; kt < nk; ++kt) {
;       const int cur = kt & 1;
;       if (kt + 1 < nk) G_LOAD(kt + 1);
;       G_MMA(cur, fo0);
;       G_MMA(cur, fo1);
;       if (kt + 1 < nk) G_STORE(cur ^ 1);
;       __syncthreads();
;     }
	v_mfma_f32_16x16x32_bf16 v[52:55], v[180:183], v[204:207], v[52:55]
	v_mfma_f32_16x16x32_bf16 v[48:51], v[184:187], v[204:207], v[48:51]
	ds_read_b128 v[204:207], v225 offset:8192
	ds_read_b128 v[216:219], v225 offset:14336
	s_add_u32 m0, s97, 0x4000
	s_add_u32 s8, s98, 0x40000
	s_addc_u32 s9, s99, 0
	global_load_lds_dwordx4 v224, s[8:9]
	v_mfma_f32_16x16x32_bf16 v[44:47], v[168:171], v[208:211], v[44:47]
	v_mfma_f32_16x16x32_bf16 v[40:43], v[176:179], v[208:211], v[40:43]
	v_mfma_f32_16x16x32_bf16 v[36:39], v[180:183], v[208:211], v[36:39]
	v_mfma_f32_16x16x32_bf16 v[32:35], v[184:187], v[208:211], v[32:35]
	ds_read_b128 v[208:211], v225 offset:10240
	s_add_u32 m0, s97, 0x14000
	s_add_u32 s8, s100, 0x40000
	s_addc_u32 s9, s101, 0
	global_load_lds_dwordx4 v224, s[8:9]
	v_mfma_f32_16x16x32_bf16 v[28:31], v[168:171], v[212:215], v[28:31]
	v_mfma_f32_16x16x32_bf16 v[24:27], v[176:179], v[212:215], v[24:27]
	v_mfma_f32_16x16x32_bf16 v[20:23], v[180:183], v[212:215], v[20:23]
	v_mfma_f32_16x16x32_bf16 v[16:19], v[184:187], v[212:215], v[16:19]
	ds_read_b128 v[212:215], v225 offset:12288
	s_add_u32 m0, s97, 0x6000
	s_add_u32 s8, s98, 0x60000
	s_addc_u32 s9, s99, 0
	global_load_lds_dwordx4 v224, s[8:9]
	v_mfma_f32_16x16x32_bf16 v[12:15], v[168:171], v[220:223], v[12:15]
	v_mfma_f32_16x16x32_bf16 v[8:11], v[176:179], v[220:223], v[8:11]
	v_mfma_f32_16x16x32_bf16 v[4:7], v[180:183], v[220:223], v[4:7]
	v_mfma_f32_16x16x32_bf16 v[0:3], v[184:187], v[220:223], v[0:3]
	s_add_u32 m0, s97, 0x16000
	s_add_u32 s8, s100, 0x60000
	s_addc_u32 s9, s101, 0
	global_load_lds_dwordx4 v224, s[8:9]
	v_xor_b32_e32 v225, 0x8000, v225
	v_xor_b32_e32 v227, 0x8000, v227
	v_xor_b32_e32 v226, 0x8000, v226
	v_xor_b32_e32 v228, 0x8000, v228
	s_xor_b32 s97, s97, 0x8000
	s_add_u32 s98, s98, 0x80
	s_addc_u32 s99, s99, 0
	s_add_u32 s100, s100, 0x80
	s_addc_u32 s101, s101, 0
	s_sub_u32 s28, s28, 1
	s_cmp_lg_u32 s28, 0
	s_cbranch_scc1 .Lgm5_loop
	s_waitcnt lgkmcnt(4)
	v_mfma_f32_16x16x32_bf16 v[124:127], v[152:155], v[188:191], v[124:127]
	v_mfma_f32_16x16x32_bf16 v[120:123], v[156:159], v[188:191], v[120:123]
	v_mfma_f32_16x16x32_bf16 v[116:119], v[160:163], v[188:191], v[116:119]
	v_mfma_f32_16x16x32_bf16 v[112:115], v[164:167], v[188:191], v[112:115]
	ds_read_b128 v[188:191], v226 offset:0
	ds_read_b128 v[168:171], v228 offset:0
	v_mfma_f32_16x16x32_bf16 v[108:111], v[152:155], v[192:195], v[108:111]
	v_mfma_f32_16x16x32_bf16 v[104:107], v[156:159], v[192:195], v[104:107]
	v_mfma_f32_16x16x32_bf16 v[100:103], v[160:163], v[192:195], v[100:103]
	v_mfma_f32_16x16x32_bf16 v[96:99], v[164:167], v[192:195], v[96:99]
	ds_read_b128 v[192:195], v226 offset:2048
	ds_read_b128 v[176:179], v228 offset:2048
	v_mfma_f32_16x16x32_bf16 v[92:95], v[152:155], v[196:199], v[92:95]
	v_mfma_f32_16x16x32_bf16 v[88:91], v[156:159], v[196:199], v[88:91]
	v_mfma_f32_16x16x32_bf16 v[84:87], v[160:163], v[196:199], v[84:87]
	v_mfma_f32_16x16x32_bf16 v[80:83], v[164:167], v[196:199], v[80:83]
	ds_read_b128 v[196:199], v226 offset:4096
	ds_read_b128 v[180:183], v228 offset:4096
	v_mfma_f32_16x16x32_bf16 v[76:79], v[152:155], v[200:203], v[76:79]
	v_mfma_f32_16x16x32_bf16 v[72:75], v[156:159], v[200:203], v[72:75]
	v_mfma_f32_16x16x32_bf16 v[68:71], v[160:163], v[200:203], v[68:71]
	v_mfma_f32_16x16x32_bf16 v[64:67], v[164:167], v[200:203], v[64:67]
	ds_read_b128 v[200:203], v226 offset:6144
	ds_read_b128 v[184:187], v228 offset:6144
	s_waitcnt lgkmcnt(11)
	v_mfma_f32_16x16x32_bf16 v[60:63], v[152:155], v[204:207], v[60:63]
	v_mfma_f32_16x16x32_bf16 v[56:59], v[156:159], v[204:207], v[56:59]
	v_mfma_f32_16x16x32_bf16 v[52:55], v[160:163], v[204:207], v[52:55]
	v_mfma_f32_16x16x32_bf16 v[48:51], v[164:167], v[204:207], v[48:51]
	ds_read_b128 v[204:207], v226 offset:8192
	ds_read_b128 v[220:223], v226 offset:14336
	s_waitcnt lgkmcnt(11)
	v_mfma_f32_16x16x32_bf16 v[44:47], v[152:155], v[208:211], v[44:47]
	v_mfma_f32_16x16x32_bf16 v[40:43], v[156:159], v[208:211], v[40:43]
	v_mfma_f32_16x16x32_bf16 v[36:39], v[160:163], v[208:211], v[36:39]
	v_mfma_f32_16x16x32_bf16 v[32:35], v[164:167], v[208:211], v[32:35]
	ds_read_b128 v[208:211], v226 offset:10240
	s_waitcnt lgkmcnt(11)
	v_mfma_f32_16x16x32_bf16 v[28:31], v[152:155], v[212:215], v[28:31]
	v_mfma_f32_16x16x32_bf16 v[24:27], v[156:159], v[212:215], v[24:27]
	v_mfma_f32_16x16x32_bf16 v[20:23], v[160:163], v[212:215], v[20:23]
	v_mfma_f32_16x16x32_bf16 v[16:19], v[164:167], v[212:215], v[16:19]
	ds_read_b128 v[212:215], v226 offset:12288
	v_mfma_f32_16x16x32_bf16 v[12:15], v[152:155], v[216:219], v[12:15]
	v_mfma_f32_16x16x32_bf16 v[8:11], v[156:159], v[216:219], v[8:11]
	v_mfma_f32_16x16x32_bf16 v[4:7], v[160:163], v[216:219], v[4:7]
	v_mfma_f32_16x16x32_bf16 v[0:3], v[164:167], v[216:219], v[0:3]
	s_waitcnt vmcnt(0) lgkmcnt(0)
	s_barrier
; #define G_LOAD(KT) do { _Pragma("unroll") for (int i = 0; i < 4; ++i) { ra[i] = *(const u32x4*)(Ag + (size_t)i * 64 * lda + (KT) * 64); rb[i] = *(const u32x4*)(Bg + (size_t)i * 64 * K + (KT) * 64); } } while (0)
; #define G_STORE(BUF) do { u16* ad = As + (BUF) * 256 * 64 + sto; u16* bd = Bs + (BUF) * 256 * 64 + sto; _Pragma("unroll") for (int i = 0; i < 4; ++i) { *(u32x4*)(ad + i * 64 * 64) = ra[i]; *(u32x4*)(bd + i * 64 * 64) = rb[i]; } } while (0)
; template <int EPI>
; DI void gemm_phase(const u16* __restrict__ A, int lda, const u16* __restrict__ Bt, int K, int N, u16* outb, int ldo,
;                    const float* r0, const float* r1, float* outf, char* lds, int bid, int nb) {
;     ...
;     for (int kt = 0; kt < nk; ++kt) {
;       const int cur = kt & 1;
;       if (kt + 1 < nk) G_LOAD(kt + 1);
;       G_MMA(cur, fo0);
;       G_MMA(cur, fo1);
;       if (kt + 1 < nk) G_STORE(cur ^ 1);
;       __syncthreads();
;     }
	v_mfma_f32_16x16x32_bf16 v[124:127], v[168:171], v[188:191], v[124:127]
	v_mfma_f32_16x16x32_bf16 v[120:123], v[176:179], v[188:191], v[120:123]
	v_mfma_f32_16x16x32_bf16 v[116:119], v[180:183], v[188:191], v[116:119]
	v_mfma_f32_16x16x32_bf16 v[112:115], v[184:187], v[188:191], v[112:115]
	ds_read_b128 v[188:191], v225 offset:0
	ds_read_b128 v[152:155], v227 offset:0
	v_mfma_f32_16x16x32_bf16 v[108:111], v[168:171], v[192:195], v[108:111]
	v_mfma_f32_16x16x32_bf16 v[104:107], v[176:179], v[192:195], v[104:107]
	v_mfma_f32_16x16x32_bf16 v[100:103], v[180:183], v[192:195], v[100:103]
	v_mfma_f32_16x16x32_bf16 v[96:99], v[184:187], v[192:195], v[96:99]
	ds_read_b128 v[192:195], v225 offset:2048
	ds_read_b128 v[156:159], v227 offset:2048
	v_mfma_f32_16x16x32_bf16 v[92:95], v[168:171], v[196:199], v[92:95]
	v_mfma_f32_16x16x32_bf16 v[88:91], v[176:179], v[196:199], v[88:91]
	v_mfma_f32_16x16x32_bf16 v[84:87], v[180:183], v[196:199], v[84:87]
	v_mfma_f32_16x16x32_bf16 v[80:83], v[184:187], v[196:199], v[80:83]
	ds_read_b128 v[196:199], v225 offset:4096
	ds_read_b128 v[160:163], v227 offset:4096
	v_mfma_f32_16x16x32_bf16 v[76:79], v[168:171], v[200:203], v[76:79]
	v_mfma_f32_16x16x32_bf16 v[72:75], v[176:179], v[200:203], v[72:75]
	v_mfma_f32_16x16x32_bf16 v[68:71], v[180:183], v[200:203], v[68:71]
	v_mfma_f32_16x16x32_bf16 v[64:67], v[184:187], v[200:203], v[64:67]
	ds_read_b128 v[200:203], v225 offset:6144
	ds_read_b128 v[164:167], v227 offset:6144
	v_mfma_f32_16x16x32_bf16 v[60:63], v[168:171], v[204:207], v[60:63]
	v_mfma_f32_16x16x32_bf16 v[56:59], v[176:179], v[204:207], v[56:59]
	v_mfma_f32_16x16x32_bf16 v[52:55], v[180:183], v[204:207], v[52:55]
	v_mfma_f32_16x16x32_bf16 v[48:51], v[184:187], v[204:207], v[48:51]
	ds_read_b128 v[204:207], v225 offset:8192
	ds_read_b128 v[216:219], v225 offset:14336
	v_mfma_f32_16x16x32_bf16 v[44:47], v[168:171], v[208:211], v[44:47]
	v_mfma_f32_16x16x32_bf16 v[40:43], v[176:179], v[208:211], v[40:43]
	v_mfma_f32_16x16x32_bf16 v[36:39], v[180:183], v[208:211], v[36:39]
	v_mfma_f32_16x16x32_bf16 v[32:35], v[184:187], v[208:211], v[32:35]
	ds_read_b128 v[208:211], v225 offset:10240
	v_mfma_f32_16x16x32_bf16 v[28:31], v[168:171], v[212:215], v[28:31]
	v_mfma_f32_16x16x32_bf16 v[24:27], v[176:179], v[212:215], v[24:27]
	v_mfma_f32_16x16x32_bf16 v[20:23], v[180:183], v[212:215], v[20:23]
	v_mfma_f32_16x16x32_bf16 v[16:19], v[184:187], v[212:215], v[16:19]
	ds_read_b128 v[212:215], v225 offset:12288
	v_mfma_f32_16x16x32_bf16 v[12:15], v[168:171], v[220:223], v[12:15]
	v_mfma_f32_16x16x32_bf16 v[8:11], v[176:179], v[220:223], v[8:11]
	v_mfma_f32_16x16x32_bf16 v[4:7], v[180:183], v[220:223], v[4:7]
	v_mfma_f32_16x16x32_bf16 v[0:3], v[184:187], v[220:223], v[0:3]
	v_xor_b32_e32 v226, 0x8000, v226
	v_xor_b32_e32 v228, 0x8000, v228
	s_waitcnt lgkmcnt(4)
	v_mfma_f32_16x16x32_bf16 v[124:127], v[152:155], v[188:191], v[124:127]
	v_mfma_f32_16x16x32_bf16 v[120:123], v[156:159], v[188:191], v[120:123]
	v_mfma_f32_16x16x32_bf16 v[116:119], v[160:163], v[188:191], v[116:119]
	v_mfma_f32_16x16x32_bf16 v[112:115], v[164:167], v[188:191], v[112:115]
	ds_read_b128 v[188:191], v226 offset:0
	ds_read_b128 v[168:171], v228 offset:0
	v_mfma_f32_16x16x32_bf16 v[108:111], v[152:155], v[192:195], v[108:111]
	v_mfma_f32_16x16x32_bf16 v[104:107], v[156:159], v[192:195], v[104:107]
	v_mfma_f32_16x16x32_bf16 v[100:103], v[160:163], v[192:195], v[100:103]
	v_mfma_f32_16x16x32_bf16 v[96:99], v[164:167], v[192:195], v[96:99]
	ds_read_b128 v[192:195], v226 offset:2048
	ds_read_b128 v[176:179], v228 offset:2048
	v_mfma_f32_16x16x32_bf16 v[92:95], v[152:155], v[196:199], v[92:95]
	v_mfma_f32_16x16x32_bf16 v[88:91], v[156:159], v[196:199], v[88:91]
	v_mfma_f32_16x16x32_bf16 v[84:87], v[160:163], v[196:199], v[84:87]
	v_mfma_f32_16x16x32_bf16 v[80:83], v[164:167], v[196:199], v[80:83]
	ds_read_b128 v[196:199], v226 offset:4096
	ds_read_b128 v[180:183], v228 offset:4096
	v_mfma_f32_16x16x32_bf16 v[76:79], v[152:155], v[200:203], v[76:79]
	v_mfma_f32_16x16x32_bf16 v[72:75], v[156:159], v[200:203], v[72:75]
	v_mfma_f32_16x16x32_bf16 v[68:71], v[160:163], v[200:203], v[68:71]
	v_mfma_f32_16x16x32_bf16 v[64:67], v[164:167], v[200:203], v[64:67]
	ds_read_b128 v[200:203], v226 offset:6144
	ds_read_b128 v[184:187], v228 offset:6144
	s_waitcnt lgkmcnt(11)
	v_mfma_f32_16x16x32_bf16 v[60:63], v[152:155], v[204:207], v[60:63]
	v_mfma_f32_16x16x32_bf16 v[56:59], v[156:159], v[204:207], v[56:59]
	v_mfma_f32_16x16x32_bf16 v[52:55], v[160:163], v[204:207], v[52:55]
	v_mfma_f32_16x16x32_bf16 v[48:51], v[164:167], v[204:207], v[48:51]
	ds_read_b128 v[204:207], v226 offset:8192
	ds_read_b128 v[220:223], v226 offset:14336
	s_waitcnt lgkmcnt(11)
	v_mfma_f32_16x16x32_bf16 v[44:47], v[152:155], v[208:211], v[44:47]
	v_mfma_f32_16x16x32_bf16 v[40:43], v[156:159], v[208:211], v[40:43]
	v_mfma_f32_16x16x32_bf16 v[36:39], v[160:163], v[208:211], v[36:39]
	v_mfma_f32_16x16x32_bf16 v[32:35], v[164:167], v[208:211], v[32:35]
	ds_read_b128 v[208:211], v226 offset:10240
	s_waitcnt lgkmcnt(11)
	v_mfma_f32_16x16x32_bf16 v[28:31], v[152:155], v[212:215], v[28:31]
	v_mfma_f32_16x16x32_bf16 v[24:27], v[156:159], v[212:215], v[24:27]
	v_mfma_f32_16x16x32_bf16 v[20:23], v[160:163], v[212:215], v[20:23]
	v_mfma_f32_16x16x32_bf16 v[16:19], v[164:167], v[212:215], v[16:19]
	ds_read_b128 v[212:215], v226 offset:12288
	v_mfma_f32_16x16x32_bf16 v[12:15], v[152:155], v[216:219], v[12:15]
	v_mfma_f32_16x16x32_bf16 v[8:11], v[156:159], v[216:219], v[8:11]
	v_mfma_f32_16x16x32_bf16 v[4:7], v[160:163], v[216:219], v[4:7]
	v_mfma_f32_16x16x32_bf16 v[0:3], v[164:167], v[216:219], v[0:3]
	s_waitcnt vmcnt(0) lgkmcnt(0)
	s_barrier
; #define G_STORE(BUF) do { u16* ad = As + (BUF) * 256 * 64 + sto; u16* bd = Bs + (BUF) * 256 * 64 + sto; _Pragma("unroll") for (int i = 0; i < 4; ++i) { *(u32x4*)(ad + i * 64 * 64) = ra[i]; *(u32x4*)(bd + i * 64 * 64) = rb[i]; } } while (0)
; template <int EPI>
; DI void gemm_phase(const u16* __restrict__ A, int lda, const u16* __restrict__ Bt, int K, int N, u16* outb, int ldo,
;                    const float* r0, const float* r1, float* outf, char* lds, int bid, int nb) {
;     ...
;       G_MMA(cur, fo0);
;       G_MMA(cur, fo1);
;       if (kt + 1 < nk) G_STORE(cur ^ 1);
;       __syncthreads();
;     }
;     ...
;     } else if constexpr (EPI == EPI_RESID) {
;       const int col = tn * 256 + wc * 64 + l15;
;       const float* rb_ = (tm * 256 < M_P) ? r0 : (r1 - (size_t)M_P * DM);
; #pragma unroll
;       for (int i = 0; i < 8; ++i)
; #pragma unroll
;         for (int r = 0; r < 4; ++r) {
;           const size_t i0 = (size_t)(mrow + i * 16 + r) * DM + col;
;           const float x0 = rb_[i0], x1 = rb_[i0 + 16], x2 = rb_[i0 + 32], x3 = rb_[i0 + 48];
;           outf[i0] = x0 + acc[i][0][r]; outf[i0 + 16] = x1 + acc[i][1][r]; outf[i0 + 32] = x2 + acc[i][2][r]; outf[i0 + 48] = x3 + acc[i][3][r];
;         }
	v_mfma_f32_16x16x32_bf16 v[124:127], v[168:171], v[188:191], v[124:127]
	v_mfma_f32_16x16x32_bf16 v[120:123], v[176:179], v[188:191], v[120:123]
	v_mfma_f32_16x16x32_bf16 v[116:119], v[180:183], v[188:191], v[116:119]
	v_mfma_f32_16x16x32_bf16 v[112:115], v[184:187], v[188:191], v[112:115]
	v_mfma_f32_16x16x32_bf16 v[108:111], v[168:171], v[192:195], v[108:111]
	v_mfma_f32_16x16x32_bf16 v[104:107], v[176:179], v[192:195], v[104:107]
	v_mfma_f32_16x16x32_bf16 v[100:103], v[180:183], v[192:195], v[100:103]
	v_mfma_f32_16x16x32_bf16 v[96:99], v[184:187], v[192:195], v[96:99]
	v_mfma_f32_16x16x32_bf16 v[92:95], v[168:171], v[196:199], v[92:95]
	v_mfma_f32_16x16x32_bf16 v[88:91], v[176:179], v[196:199], v[88:91]
	v_mfma_f32_16x16x32_bf16 v[84:87], v[180:183], v[196:199], v[84:87]
	v_mfma_f32_16x16x32_bf16 v[80:83], v[184:187], v[196:199], v[80:83]
	v_mfma_f32_16x16x32_bf16 v[76:79], v[168:171], v[200:203], v[76:79]
	v_mfma_f32_16x16x32_bf16 v[72:75], v[176:179], v[200:203], v[72:75]
	v_mfma_f32_16x16x32_bf16 v[68:71], v[180:183], v[200:203], v[68:71]
	v_mfma_f32_16x16x32_bf16 v[64:67], v[184:187], v[200:203], v[64:67]
	v_mfma_f32_16x16x32_bf16 v[60:63], v[168:171], v[204:207], v[60:63]
	v_mfma_f32_16x16x32_bf16 v[56:59], v[176:179], v[204:207], v[56:59]
	v_mfma_f32_16x16x32_bf16 v[52:55], v[180:183], v[204:207], v[52:55]
	v_mfma_f32_16x16x32_bf16 v[48:51], v[184:187], v[204:207], v[48:51]
	v_mfma_f32_16x16x32_bf16 v[44:47], v[168:171], v[208:211], v[44:47]
	v_mfma_f32_16x16x32_bf16 v[40:43], v[176:179], v[208:211], v[40:43]
	v_mfma_f32_16x16x32_bf16 v[36:39], v[180:183], v[208:211], v[36:39]
	v_mfma_f32_16x16x32_bf16 v[32:35], v[184:187], v[208:211], v[32:35]
	v_mfma_f32_16x16x32_bf16 v[28:31], v[168:171], v[212:215], v[28:31]
	v_mfma_f32_16x16x32_bf16 v[24:27], v[176:179], v[212:215], v[24:27]
	v_mfma_f32_16x16x32_bf16 v[20:23], v[180:183], v[212:215], v[20:23]
	v_mfma_f32_16x16x32_bf16 v[16:19], v[184:187], v[212:215], v[16:19]
	v_mfma_f32_16x16x32_bf16 v[12:15], v[168:171], v[220:223], v[12:15]
	v_mfma_f32_16x16x32_bf16 v[8:11], v[176:179], v[220:223], v[8:11]
	v_mfma_f32_16x16x32_bf16 v[4:7], v[180:183], v[220:223], v[4:7]
	v_mfma_f32_16x16x32_bf16 v[0:3], v[184:187], v[220:223], v[0:3]
	s_setprio 0
	s_nop 7
	s_nop 3
	v_and_b32_e32 v225, 15, v174
	v_lshrrev_b32_e32 v226, 8, v174
	v_lshl_or_b32 v225, v226, 7, v225
	v_bfe_u32 v226, v174, 6, 2
	v_bfe_u32 v227, v174, 4, 2
	v_lshlrev_b32_e32 v227, 2, v227
	v_add_u32_e32 v225, s39, v225
	v_lshl_add_u32 v226, v226, 6, v227
	v_add_u32_e32 v226, s40, v226
	v_lshlrev_b32_e32 v226, 2, v226
	v_lshl_add_u32 v224, v225, 12, v226
	v_mov_b32_e32 v229, v224
	v_add_u32_e32 v224, 0x0, v229
	global_load_dwordx4 v[152:155], v224, s[22:23] offset:0
	global_load_dwordx4 v[156:159], v224, s[22:23] offset:64
	global_load_dwordx4 v[160:163], v224, s[22:23] offset:128
	global_load_dwordx4 v[164:167], v224, s[22:23] offset:192
	v_add_u32_e32 v228, 0x10000, v229
	global_load_dwordx4 v[168:171], v228, s[22:23] offset:0
	global_load_dwordx4 v[176:179], v228, s[22:23] offset:64
	global_load_dwordx4 v[180:183], v228, s[22:23] offset:128
	global_load_dwordx4 v[184:187], v228, s[22:23] offset:192
	s_waitcnt vmcnt(4)
	v_add_f32_e32 v152, v124, v152
	v_add_f32_e32 v153, v125, v153
	v_add_f32_e32 v154, v126, v154
	v_add_f32_e32 v155, v127, v155
	v_add_f32_e32 v156, v120, v156
	v_add_f32_e32 v157, v121, v157
	v_add_f32_e32 v158, v122, v158
	v_add_f32_e32 v159, v123, v159
	v_add_f32_e32 v160, v116, v160
	v_add_f32_e32 v161, v117, v161
	v_add_f32_e32 v162, v118, v162
	v_add_f32_e32 v163, v119, v163
	v_add_f32_e32 v164, v112, v164
	v_add_f32_e32 v165, v113, v165
	v_add_f32_e32 v166, v114, v166
	v_add_f32_e32 v167, v115, v167
	global_store_dwordx4 v224, v[152:155], s[22:23] offset:0
	global_store_dwordx4 v224, v[156:159], s[22:23] offset:64
	global_store_dwordx4 v224, v[160:163], s[22:23] offset:128
	global_store_dwordx4 v224, v[164:167], s[22:23] offset:192
	s_nop 1
	v_add_u32_e32 v224, 0x20000, v229
	global_load_dwordx4 v[152:155], v224, s[22:23] offset:0
	global_load_dwordx4 v[156:159], v224, s[22:23] offset:64
	global_load_dwordx4 v[160:163], v224, s[22:23] offset:128
	global_load_dwordx4 v[164:167], v224, s[22:23] offset:192
	s_waitcnt vmcnt(8)
	v_add_f32_e32 v168, v108, v168
	v_add_f32_e32 v169, v109, v169
	v_add_f32_e32 v170, v110, v170
	v_add_f32_e32 v171, v111, v171
	v_add_f32_e32 v176, v104, v176
	v_add_f32_e32 v177, v105, v177
	v_add_f32_e32 v178, v106, v178
	v_add_f32_e32 v179, v107, v179
	v_add_f32_e32 v180, v100, v180
	v_add_f32_e32 v181, v101, v181
	v_add_f32_e32 v182, v102, v182
	v_add_f32_e32 v183, v103, v183
	v_add_f32_e32 v184, v96, v184
	v_add_f32_e32 v185, v97, v185
	v_add_f32_e32 v186, v98, v186
	v_add_f32_e32 v187, v99, v187
	global_store_dwordx4 v228, v[168:171], s[22:23] offset:0
	global_store_dwordx4 v228, v[176:179], s[22:23] offset:64
	global_store_dwordx4 v228, v[180:183], s[22:23] offset:128
	global_store_dwordx4 v228, v[184:187], s[22:23] offset:192
	s_nop 1
	v_add_u32_e32 v228, 0x30000, v229
	global_load_dwordx4 v[168:171], v228, s[22:23] offset:0
	global_load_dwordx4 v[176:179], v228, s[22:23] offset:64
	global_load_dwordx4 v[180:183], v228, s[22:23] offset:128
	global_load_dwordx4 v[184:187], v228, s[22:23] offset:192
	s_waitcnt vmcnt(8)
; template <int EPI>
; DI void gemm_phase(const u16* __restrict__ A, int lda, const u16* __restrict__ Bt, int K, int N, u16* outb, int ldo,
;                    const float* r0, const float* r1, float* outf, char* lds, int bid, int nb) {
;     ...
;     } else if constexpr (EPI == EPI_RESID) {
;       const int col = tn * 256 + wc * 64 + l15;
;       const float* rb_ = (tm * 256 < M_P) ? r0 : (r1 - (size_t)M_P * DM);
; #pragma unroll
;       for (int i = 0; i < 8; ++i)
; #pragma unroll
;         for (int r = 0; r < 4; ++r) {
;           const size_t i0 = (size_t)(mrow + i * 16 + r) * DM + col;
;           const float x0 = rb_[i0], x1 = rb_[i0 + 16], x2 = rb_[i0 + 32], x3 = rb_[i0 + 48];
;           outf[i0] = x0 + acc[i][0][r]; outf[i0 + 16] = x1 + acc[i][1][r]; outf[i0 + 32] = x2 + acc[i][2][r]; outf[i0 + 48] = x3 + acc[i][3][r];
;         }
	v_add_f32_e32 v152, v92, v152
	v_add_f32_e32 v153, v93, v153
	v_add_f32_e32 v154, v94, v154
	v_add_f32_e32 v155, v95, v155
	v_add_f32_e32 v156, v88, v156
	v_add_f32_e32 v157, v89, v157
	v_add_f32_e32 v158, v90, v158
	v_add_f32_e32 v159, v91, v159
	v_add_f32_e32 v160, v84, v160
	v_add_f32_e32 v161, v85, v161
	v_add_f32_e32 v162, v86, v162
	v_add_f32_e32 v163, v87, v163
	v_add_f32_e32 v164, v80, v164
	v_add_f32_e32 v165, v81, v165
	v_add_f32_e32 v166, v82, v166
	v_add_f32_e32 v167, v83, v167
	global_store_dwordx4 v224, v[152:155], s[22:23] offset:0
	global_store_dwordx4 v224, v[156:159], s[22:23] offset:64
	global_store_dwordx4 v224, v[160:163], s[22:23] offset:128
	global_store_dwordx4 v224, v[164:167], s[22:23] offset:192
	s_nop 1
	v_add_u32_e32 v224, 0x40000, v229
	global_load_dwordx4 v[152:155], v224, s[22:23] offset:0
	global_load_dwordx4 v[156:159], v224, s[22:23] offset:64
	global_load_dwordx4 v[160:163], v224, s[22:23] offset:128
	global_load_dwordx4 v[164:167], v224, s[22:23] offset:192
	s_waitcnt vmcnt(8)
	v_add_f32_e32 v168, v76, v168
	v_add_f32_e32 v169, v77, v169
	v_add_f32_e32 v170, v78, v170
	v_add_f32_e32 v171, v79, v171
	v_add_f32_e32 v176, v72, v176
	v_add_f32_e32 v177, v73, v177
	v_add_f32_e32 v178, v74, v178
	v_add_f32_e32 v179, v75, v179
	v_add_f32_e32 v180, v68, v180
	v_add_f32_e32 v181, v69, v181
	v_add_f32_e32 v182, v70, v182
	v_add_f32_e32 v183, v71, v183
	v_add_f32_e32 v184, v64, v184
	v_add_f32_e32 v185, v65, v185
	v_add_f32_e32 v186, v66, v186
	v_add_f32_e32 v187, v67, v187
	global_store_dwordx4 v228, v[168:171], s[22:23] offset:0
	global_store_dwordx4 v228, v[176:179], s[22:23] offset:64
	global_store_dwordx4 v228, v[180:183], s[22:23] offset:128
	global_store_dwordx4 v228, v[184:187], s[22:23] offset:192
	s_nop 1
	v_add_u32_e32 v228, 0x50000, v229
	global_load_dwordx4 v[168:171], v228, s[22:23] offset:0
	global_load_dwordx4 v[176:179], v228, s[22:23] offset:64
	global_load_dwordx4 v[180:183], v228, s[22:23] offset:128
	global_load_dwordx4 v[184:187], v228, s[22:23] offset:192
	s_waitcnt vmcnt(8)
	v_add_f32_e32 v152, v60, v152
	v_add_f32_e32 v153, v61, v153
	v_add_f32_e32 v154, v62, v154
	v_add_f32_e32 v155, v63, v155
	v_add_f32_e32 v156, v56, v156
	v_add_f32_e32 v157, v57, v157
	v_add_f32_e32 v158, v58, v158
	v_add_f32_e32 v159, v59, v159
	v_add_f32_e32 v160, v52, v160
	v_add_f32_e32 v161, v53, v161
	v_add_f32_e32 v162, v54, v162
	v_add_f32_e32 v163, v55, v163
	v_add_f32_e32 v164, v48, v164
	v_add_f32_e32 v165, v49, v165
	v_add_f32_e32 v166, v50, v166
	v_add_f32_e32 v167, v51, v167
	global_store_dwordx4 v224, v[152:155], s[22:23] offset:0
	global_store_dwordx4 v224, v[156:159], s[22:23] offset:64
	global_store_dwordx4 v224, v[160:163], s[22:23] offset:128
	global_store_dwordx4 v224, v[164:167], s[22:23] offset:192
	s_nop 1
	v_add_u32_e32 v224, 0x60000, v229
	global_load_dwordx4 v[152:155], v224, s[22:23] offset:0
	global_load_dwordx4 v[156:159], v224, s[22:23] offset:64
	global_load_dwordx4 v[160:163], v224, s[22:23] offset:128
	global_load_dwordx4 v[164:167], v224, s[22:23] offset:192
	s_waitcnt vmcnt(8)
	v_add_f32_e32 v168, v44, v168
	v_add_f32_e32 v169, v45, v169
	v_add_f32_e32 v170, v46, v170
	v_add_f32_e32 v171, v47, v171
	v_add_f32_e32 v176, v40, v176
	v_add_f32_e32 v177, v41, v177
	v_add_f32_e32 v178, v42, v178
	v_add_f32_e32 v179, v43, v179
	v_add_f32_e32 v180, v36, v180
	v_add_f32_e32 v181, v37, v181
	v_add_f32_e32 v182, v38, v182
	v_add_f32_e32 v183, v39, v183
	v_add_f32_e32 v184, v32, v184
	v_add_f32_e32 v185, v33, v185
	v_add_f32_e32 v186, v34, v186
	v_add_f32_e32 v187, v35, v187
	global_store_dwordx4 v228, v[168:171], s[22:23] offset:0
	global_store_dwordx4 v228, v[176:179], s[22:23] offset:64
	global_store_dwordx4 v228, v[180:183], s[22:23] offset:128
	global_store_dwordx4 v228, v[184:187], s[22:23] offset:192
	s_nop 1
	v_add_u32_e32 v228, 0x70000, v229
	global_load_dwordx4 v[168:171], v228, s[22:23] offset:0
	global_load_dwordx4 v[176:179], v228, s[22:23] offset:64
	global_load_dwordx4 v[180:183], v228, s[22:23] offset:128
	global_load_dwordx4 v[184:187], v228, s[22:23] offset:192
	s_waitcnt vmcnt(8)
	v_add_f32_e32 v152, v28, v152
	v_add_f32_e32 v153, v29, v153
	v_add_f32_e32 v154, v30, v154
	v_add_f32_e32 v155, v31, v155
	v_add_f32_e32 v156, v24, v156
	v_add_f32_e32 v157, v25, v157
	v_add_f32_e32 v158, v26, v158
	v_add_f32_e32 v159, v27, v159
	v_add_f32_e32 v160, v20, v160
	v_add_f32_e32 v161, v21, v161
	v_add_f32_e32 v162, v22, v162
	v_add_f32_e32 v163, v23, v163
	v_add_f32_e32 v164, v16, v164
	v_add_f32_e32 v165, v17, v165
	v_add_f32_e32 v166, v18, v166
	v_add_f32_e32 v167, v19, v167
	global_store_dwordx4 v224, v[152:155], s[22:23] offset:0
	global_store_dwordx4 v224, v[156:159], s[22:23] offset:64
	global_store_dwordx4 v224, v[160:163], s[22:23] offset:128
	global_store_dwordx4 v224, v[164:167], s[22:23] offset:192
	s_waitcnt vmcnt(4)
	v_add_f32_e32 v168, v12, v168
	v_add_f32_e32 v169, v13, v169
	v_add_f32_e32 v170, v14, v170
	v_add_f32_e32 v171, v15, v171
	v_add_f32_e32 v176, v8, v176
	v_add_f32_e32 v177, v9, v177
	v_add_f32_e32 v178, v10, v178
	v_add_f32_e32 v179, v11, v179
	v_add_f32_e32 v180, v4, v180
	v_add_f32_e32 v181, v5, v181
	v_add_f32_e32 v182, v6, v182
	v_add_f32_e32 v183, v7, v183
	v_add_f32_e32 v184, v0, v184
	v_add_f32_e32 v185, v1, v185
	v_add_f32_e32 v186, v2, v186
	v_add_f32_e32 v187, v3, v187
	global_store_dwordx4 v228, v[168:171], s[22:23] offset:0
	global_store_dwordx4 v228, v[176:179], s[22:23] offset:64
	global_store_dwordx4 v228, v[180:183], s[22:23] offset:128
	global_store_dwordx4 v228, v[184:187], s[22:23] offset:192
	s_add_i32 s14, s14, 1
	s_cmp_eq_u32 s14, s3
	s_cbranch_scc0 .LBB0_1177

; #define G_LOAD(KT) do { _Pragma("unroll") for (int i = 0; i < 4; ++i) { ra[i] = *(const u32x4*)(Ag + (size_t)i * 64 * lda + (KT) * 64); rb[i] = *(const u32x4*)(Bg + (size_t)i * 64 * K + (KT) * 64); } } while (0)
; #define G_STORE(BUF) do { u16* ad = As + (BUF) * 256 * 64 + sto; u16* bd = Bs + (BUF) * 256 * 64 + sto; _Pragma("unroll") for (int i = 0; i < 4; ++i) { *(u32x4*)(ad + i * 64 * 64) = ra[i]; *(u32x4*)(bd + i * 64 * 64) = rb[i]; } } while (0)
; template <int EPI>
; DI void gemm_phase(const u16* __restrict__ A, int lda, const u16* __restrict__ Bt, int K, int N, u16* outb, int ldo,
;                    const float* r0, const float* r1, float* outf, char* lds, int bid, int nb) {
;     ...
;   for (int it = 0; it < nIter; ++it) {
;     int tm, tn;
;     if (swz) { const int st = xcd + 8 * it, sm = st / nSN, sn = st - sm * nSN; tm = sm * GM + jb / GN; tn = sn * GN + (jb % GN); }
;     else { const int t = bid + it * nb; tm = t / nN; tn = t - tm * nN; }
;     const u16* Ag = A + (size_t)(tm * 256 + lrow) * lda + lch * 8;
;     const u16* Bg = Bt + (size_t)(tn * 256 + lrow) * K + lch * 8;
;     f32x4 acc[8][4];
; #pragma unroll
;     for (int i = 0; i < 8; ++i)
; #pragma unroll
;       for (int j = 0; j < 4; ++j) acc[i][j] = (f32x4){0.f, 0.f, 0.f, 0.f};
;     u32x4 ra[4], rb[4];
;     ...
;     G_LOAD(0);
;     G_STORE(0);
;     __syncthreads();
.LBB0_1301:
	s_lshl_b32 s41, s41, 8
	v_or_b32_e32 v0, s41, v138
	v_ashrrev_i32_e32 v1, 31, v0
	v_lshlrev_b64 v[64:65], 11, v[0:1]
	v_lshl_or_b32 v0, s40, 8, v138
	v_ashrrev_i32_e32 v1, 31, v0
	v_lshlrev_b64 v[66:67], 11, v[0:1]
	v_lshl_add_u64 v[0:1], v[128:129], 0, v[64:65]
	v_add_co_u32_e32 v4, vcc, 0x20000, v0
	v_lshl_add_u64 v[2:3], v[130:131], 0, v[66:67]
	s_nop 0
	v_addc_co_u32_e32 v5, vcc, 0, v1, vcc
	v_add_co_u32_e32 v6, vcc, 0x20000, v2
	s_nop 1
	v_readfirstlane_b32 s98, v0
	v_readfirstlane_b32 s99, v1
	s_nop 1
	v_readfirstlane_b32 s100, v2
	v_readfirstlane_b32 s101, v3
	v_addc_co_u32_e32 v7, vcc, 0, v3, vcc
	v_add_co_u32_e32 v4, vcc, 0x40000, v0
	s_mov_b32 s42, 0
	s_nop 0
	v_addc_co_u32_e32 v5, vcc, 0, v1, vcc
	v_add_co_u32_e32 v6, vcc, 0x40000, v2
	s_mov_b64 s[10:11], 0
	s_nop 0
	v_addc_co_u32_e32 v7, vcc, 0, v3, vcc
	v_add_co_u32_e32 v0, vcc, 0x60000, v0
	v_addc_co_u32_e32 v1, vcc, 0, v1, vcc
	v_add_co_u32_e32 v2, vcc, 0x60000, v2
	v_lshl_add_u64 v[134:135], v[132:133], 0, v[66:67]
	s_nop 0
	v_addc_co_u32_e32 v3, vcc, 0, v3, vcc
	v_mov_b32_e32 v0, 0
	v_mov_b32_e32 v1, v0
	v_mov_b32_e32 v2, v0
	v_mov_b32_e32 v3, v0
	v_mov_b32_e32 v4, v0
	v_mov_b32_e32 v5, v0
	v_mov_b32_e32 v6, v0
	v_mov_b32_e32 v7, v0
	v_mov_b32_e32 v8, v0
	v_mov_b32_e32 v9, v0
	v_mov_b32_e32 v10, v0
	v_mov_b32_e32 v11, v0
	v_mov_b32_e32 v12, v0
	v_mov_b32_e32 v13, v0
	v_mov_b32_e32 v14, v0
	v_mov_b32_e32 v15, v0
	v_mov_b32_e32 v16, v0
	v_mov_b32_e32 v17, v0
	v_mov_b32_e32 v18, v0
	v_mov_b32_e32 v19, v0
	v_mov_b32_e32 v20, v0
	v_mov_b32_e32 v21, v0
	v_mov_b32_e32 v22, v0
	v_mov_b32_e32 v23, v0
	v_mov_b32_e32 v24, v0
	v_mov_b32_e32 v25, v0
	v_mov_b32_e32 v26, v0
	v_mov_b32_e32 v27, v0
	v_mov_b32_e32 v28, v0
	v_mov_b32_e32 v29, v0
	v_mov_b32_e32 v30, v0
	v_lshl_add_u64 v[136:137], v[132:133], 0, v[64:65]
	v_mov_b32_e32 v31, v0
	v_mov_b32_e32 v64, v0
	v_mov_b32_e32 v65, v0
	v_mov_b32_e32 v66, v0
	v_mov_b32_e32 v67, v0
	v_mov_b32_e32 v68, v0
	v_mov_b32_e32 v69, v0
	v_mov_b32_e32 v70, v0
	v_mov_b32_e32 v71, v0
	v_mov_b32_e32 v72, v0
	v_mov_b32_e32 v73, v0
	v_mov_b32_e32 v74, v0
	v_mov_b32_e32 v75, v0
	v_mov_b32_e32 v76, v0
	v_mov_b32_e32 v77, v0
	v_mov_b32_e32 v78, v0
	v_mov_b32_e32 v79, v0
	v_mov_b32_e32 v80, v0
	v_mov_b32_e32 v81, v0
	v_mov_b32_e32 v82, v0
	v_mov_b32_e32 v83, v0
	v_mov_b32_e32 v84, v0
	v_mov_b32_e32 v85, v0
	v_mov_b32_e32 v86, v0
	v_mov_b32_e32 v87, v0
	v_mov_b32_e32 v32, v0
	v_mov_b32_e32 v33, v0
	v_mov_b32_e32 v34, v0
	v_mov_b32_e32 v35, v0
	v_mov_b32_e32 v36, v0
	v_mov_b32_e32 v37, v0
	v_mov_b32_e32 v38, v0
	v_mov_b32_e32 v39, v0
	v_mov_b32_e32 v40, v0
	v_mov_b32_e32 v41, v0
	v_mov_b32_e32 v42, v0
	v_mov_b32_e32 v43, v0
	v_mov_b32_e32 v44, v0
	v_mov_b32_e32 v45, v0
	v_mov_b32_e32 v46, v0
	v_mov_b32_e32 v47, v0
	v_mov_b32_e32 v48, v0
	v_mov_b32_e32 v49, v0
	v_mov_b32_e32 v50, v0
	v_mov_b32_e32 v51, v0
	v_mov_b32_e32 v52, v0
	v_mov_b32_e32 v53, v0
	v_mov_b32_e32 v54, v0
	v_mov_b32_e32 v55, v0
	v_mov_b32_e32 v56, v0
	v_mov_b32_e32 v57, v0
	v_mov_b32_e32 v58, v0
	v_mov_b32_e32 v59, v0
	v_mov_b32_e32 v60, v0
	v_mov_b32_e32 v61, v0
	v_mov_b32_e32 v62, v0
	v_mov_b32_e32 v63, v0
	v_mov_b32_e32 v88, v0
	v_mov_b32_e32 v89, v0
	v_mov_b32_e32 v90, v0
	v_mov_b32_e32 v91, v0
	v_mov_b32_e32 v92, v0
	v_mov_b32_e32 v93, v0
	v_mov_b32_e32 v94, v0
	v_mov_b32_e32 v95, v0
	v_mov_b32_e32 v96, v0
	v_mov_b32_e32 v97, v0
	v_mov_b32_e32 v98, v0
	v_mov_b32_e32 v99, v0
	v_mov_b32_e32 v100, v0
	v_mov_b32_e32 v101, v0
	v_mov_b32_e32 v102, v0
	v_mov_b32_e32 v103, v0
	v_mov_b32_e32 v104, v0
	v_mov_b32_e32 v105, v0
	v_mov_b32_e32 v106, v0
	v_mov_b32_e32 v107, v0
	v_mov_b32_e32 v108, v0
	v_mov_b32_e32 v109, v0
	v_mov_b32_e32 v110, v0
	v_mov_b32_e32 v111, v0
	v_mov_b32_e32 v112, v0
	v_mov_b32_e32 v113, v0
	v_mov_b32_e32 v114, v0
	v_mov_b32_e32 v115, v0
	v_mov_b32_e32 v116, v0
	v_mov_b32_e32 v117, v0
	v_mov_b32_e32 v118, v0
	v_mov_b32_e32 v119, v0
	v_mov_b32_e32 v120, v0
	v_mov_b32_e32 v121, v0
	v_mov_b32_e32 v122, v0
	v_mov_b32_e32 v123, v0
	v_mov_b32_e32 v124, v0
	v_mov_b32_e32 v125, v0
	v_mov_b32_e32 v126, v0
	v_mov_b32_e32 v127, v0
	v_and_b32_e32 v229, 63, v174
	v_lshrrev_b32_e32 v230, 3, v229
	v_mov_b32_e32 v233, 0x800
	v_mul_u32_u24_e32 v224, v230, v233
	v_bfe_u32 v231, v174, 4, 2
	v_bfe_u32 v232, v174, 6, 1
	v_lshl_or_b32 v232, v232, 2, v231
	v_and_b32_e32 v233, 7, v174
	v_xor_b32_e32 v232, v232, v233
	v_lshl_add_u32 v224, v232, 4, v224
	v_and_b32_e32 v229, 15, v174
	v_bfe_u32 v230, v174, 1, 3
	v_xor_b32_e32 v230, v230, v231
	v_lshlrev_b32_e32 v230, 4, v230
	v_lshl_or_b32 v230, v229, 7, v230
	v_lshrrev_b32_e32 v229, 8, v174
	v_lshl_or_b32 v225, v229, 14, v230
	v_bfe_u32 v229, v174, 6, 2
	v_lshl_or_b32 v227, v229, 13, v230
	v_or_b32_e32 v227, 0x10000, v227
	v_xor_b32_e32 v226, 64, v225
	v_xor_b32_e32 v228, 64, v227
	v_readfirstlane_b32 s97, v174
	s_lshl_b32 s97, s97, 4
	s_mov_b32 s28, 14
	s_add_u32 m0, s97, 0x0
	s_add_u32 s10, s98, 0x0
	s_addc_u32 s11, s99, 0
	global_load_lds_dwordx4 v224, s[10:11]
	s_add_u32 m0, s97, 0x10000
	s_add_u32 s10, s100, 0x0
	s_addc_u32 s11, s101, 0
	global_load_lds_dwordx4 v224, s[10:11]
	s_add_u32 m0, s97, 0x2000
	s_add_u32 s10, s98, 0x20000
	s_addc_u32 s11, s99, 0
	global_load_lds_dwordx4 v224, s[10:11]
	s_add_u32 m0, s97, 0x12000
	s_add_u32 s10, s100, 0x20000
	s_addc_u32 s11, s101, 0
	global_load_lds_dwordx4 v224, s[10:11]
	s_add_u32 m0, s97, 0x4000
	s_add_u32 s10, s98, 0x40000
	s_addc_u32 s11, s99, 0
	global_load_lds_dwordx4 v224, s[10:11]
	s_add_u32 m0, s97, 0x14000
	s_add_u32 s10, s100, 0x40000
	s_addc_u32 s11, s101, 0
	global_load_lds_dwordx4 v224, s[10:11]
	s_add_u32 m0, s97, 0x6000
	s_add_u32 s10, s98, 0x60000
	s_addc_u32 s11, s99, 0
	global_load_lds_dwordx4 v224, s[10:11]
	s_add_u32 m0, s97, 0x16000
	s_add_u32 s10, s100, 0x60000
	s_addc_u32 s11, s101, 0
	global_load_lds_dwordx4 v224, s[10:11]
	s_add_u32 m0, s97, 0x8000
	s_add_u32 s10, s98, 0x80
	s_addc_u32 s11, s99, 0
	global_load_lds_dwordx4 v224, s[10:11]
	s_add_u32 m0, s97, 0x18000
	s_add_u32 s10, s100, 0x80
	s_addc_u32 s11, s101, 0
	global_load_lds_dwordx4 v224, s[10:11]
	s_add_u32 m0, s97, 0xa000
	s_add_u32 s10, s98, 0x20080
	s_addc_u32 s11, s99, 0
	global_load_lds_dwordx4 v224, s[10:11]
	s_add_u32 m0, s97, 0x1a000
	s_add_u32 s10, s100, 0x20080
	s_addc_u32 s11, s101, 0
	global_load_lds_dwordx4 v224, s[10:11]
	s_add_u32 m0, s97, 0xc000
	s_add_u32 s10, s98, 0x40080
	s_addc_u32 s11, s99, 0
	global_load_lds_dwordx4 v224, s[10:11]
	s_add_u32 m0, s97, 0x1c000
	s_add_u32 s10, s100, 0x40080
	s_addc_u32 s11, s101, 0
	global_load_lds_dwordx4 v224, s[10:11]
	s_add_u32 m0, s97, 0xe000
	s_add_u32 s10, s98, 0x60080
	s_addc_u32 s11, s99, 0
	global_load_lds_dwordx4 v224, s[10:11]
	s_add_u32 m0, s97, 0x1e000
	s_add_u32 s10, s100, 0x60080
	s_addc_u32 s11, s101, 0
	global_load_lds_dwordx4 v224, s[10:11]
	s_add_u32 s98, s98, 0x100
	s_addc_u32 s99, s99, 0
	s_add_u32 s100, s100, 0x100
	s_addc_u32 s101, s101, 0
	s_waitcnt vmcnt(8)
	s_barrier
; #define G_LOAD(KT) do { _Pragma("unroll") for (int i = 0; i < 4; ++i) { ra[i] = *(const u32x4*)(Ag + (size_t)i * 64 * lda + (KT) * 64); rb[i] = *(const u32x4*)(Bg + (size_t)i * 64 * K + (KT) * 64); } } while (0)
; #define G_STORE(BUF) do { u16* ad = As + (BUF) * 256 * 64 + sto; u16* bd = Bs + (BUF) * 256 * 64 + sto; _Pragma("unroll") for (int i = 0; i < 4; ++i) { *(u32x4*)(ad + i * 64 * 64) = ra[i]; *(u32x4*)(bd + i * 64 * 64) = rb[i]; } } while (0)
; template <int EPI>
; DI void gemm_phase(const u16* __restrict__ A, int lda, const u16* __restrict__ Bt, int K, int N, u16* outb, int ldo,
;                    const float* r0, const float* r1, float* outf, char* lds, int bid, int nb) {
;     ...
;     G_LOAD(0);
;     G_STORE(0);
;     __syncthreads();
;     for (int kt = 0; kt < nk; ++kt) {
;       const int cur = kt & 1;
;       if (kt + 1 < nk) G_LOAD(kt + 1);
;       G_MMA(cur, fo0);
;       G_MMA(cur, fo1);
;       if (kt + 1 < nk) G_STORE(cur ^ 1);
;       __syncthreads();
;     }
	ds_read_b128 v[152:155], v227 offset:0
	ds_read_b128 v[156:159], v227 offset:2048
	ds_read_b128 v[160:163], v227 offset:4096
	ds_read_b128 v[164:167], v227 offset:6144
	ds_read_b128 v[188:191], v225 offset:0
	ds_read_b128 v[192:195], v225 offset:2048
	ds_read_b128 v[196:199], v225 offset:4096
	ds_read_b128 v[200:203], v225 offset:6144
	ds_read_b128 v[204:207], v225 offset:8192
	ds_read_b128 v[208:211], v225 offset:10240
	ds_read_b128 v[212:215], v225 offset:12288
	ds_read_b128 v[216:219], v225 offset:14336
	v_xor_b32_e32 v225, 0x8000, v225
	v_xor_b32_e32 v227, 0x8000, v227
	s_waitcnt lgkmcnt(0)
	s_bitcmp1_b32 s97, 12
	s_cbranch_scc0 .Lgm6_noprio
	s_setprio 1
.Lgm6_noprio:
.Lgm6_loop:
	s_waitcnt lgkmcnt(4)
	v_mfma_f32_16x16x32_bf16 v[124:127], v[152:155], v[188:191], v[124:127]
	v_mfma_f32_16x16x32_bf16 v[120:123], v[156:159], v[188:191], v[120:123]
	v_mfma_f32_16x16x32_bf16 v[116:119], v[160:163], v[188:191], v[116:119]
	v_mfma_f32_16x16x32_bf16 v[112:115], v[164:167], v[188:191], v[112:115]
	ds_read_b128 v[188:191], v226 offset:0
	ds_read_b128 v[168:171], v228 offset:0
	v_mfma_f32_16x16x32_bf16 v[108:111], v[152:155], v[192:195], v[108:111]
	v_mfma_f32_16x16x32_bf16 v[104:107], v[156:159], v[192:195], v[104:107]
	v_mfma_f32_16x16x32_bf16 v[100:103], v[160:163], v[192:195], v[100:103]
	v_mfma_f32_16x16x32_bf16 v[96:99], v[164:167], v[192:195], v[96:99]
	ds_read_b128 v[192:195], v226 offset:2048
	ds_read_b128 v[176:179], v228 offset:2048
	v_mfma_f32_16x16x32_bf16 v[92:95], v[152:155], v[196:199], v[92:95]
	v_mfma_f32_16x16x32_bf16 v[88:91], v[156:159], v[196:199], v[88:91]
	v_mfma_f32_16x16x32_bf16 v[84:87], v[160:163], v[196:199], v[84:87]
	v_mfma_f32_16x16x32_bf16 v[80:83], v[164:167], v[196:199], v[80:83]
	ds_read_b128 v[196:199], v226 offset:4096
	ds_read_b128 v[180:183], v228 offset:4096
	v_mfma_f32_16x16x32_bf16 v[76:79], v[152:155], v[200:203], v[76:79]
	v_mfma_f32_16x16x32_bf16 v[72:75], v[156:159], v[200:203], v[72:75]
	v_mfma_f32_16x16x32_bf16 v[68:71], v[160:163], v[200:203], v[68:71]
	v_mfma_f32_16x16x32_bf16 v[64:67], v[164:167], v[200:203], v[64:67]
	ds_read_b128 v[200:203], v226 offset:6144
	ds_read_b128 v[184:187], v228 offset:6144
	s_waitcnt lgkmcnt(11)
	v_mfma_f32_16x16x32_bf16 v[60:63], v[152:155], v[204:207], v[60:63]
	v_mfma_f32_16x16x32_bf16 v[56:59], v[156:159], v[204:207], v[56:59]
	v_mfma_f32_16x16x32_bf16 v[52:55], v[160:163], v[204:207], v[52:55]
	v_mfma_f32_16x16x32_bf16 v[48:51], v[164:167], v[204:207], v[48:51]
	ds_read_b128 v[204:207], v226 offset:8192
	ds_read_b128 v[220:223], v226 offset:14336
	s_waitcnt lgkmcnt(11)
	v_mfma_f32_16x16x32_bf16 v[44:47], v[152:155], v[208:211], v[44:47]
	v_mfma_f32_16x16x32_bf16 v[40:43], v[156:159], v[208:211], v[40:43]
	v_mfma_f32_16x16x32_bf16 v[36:39], v[160:163], v[208:211], v[36:39]
	v_mfma_f32_16x16x32_bf16 v[32:35], v[164:167], v[208:211], v[32:35]
	ds_read_b128 v[208:211], v226 offset:10240
	s_waitcnt lgkmcnt(11)
	v_mfma_f32_16x16x32_bf16 v[28:31], v[152:155], v[212:215], v[28:31]
	v_mfma_f32_16x16x32_bf16 v[24:27], v[156:159], v[212:215], v[24:27]
	v_mfma_f32_16x16x32_bf16 v[20:23], v[160:163], v[212:215], v[20:23]
	v_mfma_f32_16x16x32_bf16 v[16:19], v[164:167], v[212:215], v[16:19]
	ds_read_b128 v[212:215], v226 offset:12288
	v_mfma_f32_16x16x32_bf16 v[12:15], v[152:155], v[216:219], v[12:15]
	v_mfma_f32_16x16x32_bf16 v[8:11], v[156:159], v[216:219], v[8:11]
	v_mfma_f32_16x16x32_bf16 v[4:7], v[160:163], v[216:219], v[4:7]
	v_mfma_f32_16x16x32_bf16 v[0:3], v[164:167], v[216:219], v[0:3]
	s_waitcnt vmcnt(0) lgkmcnt(0)
	s_barrier
	v_mfma_f32_16x16x32_bf16 v[124:127], v[168:171], v[188:191], v[124:127]
	v_mfma_f32_16x16x32_bf16 v[120:123], v[176:179], v[188:191], v[120:123]
	v_mfma_f32_16x16x32_bf16 v[116:119], v[180:183], v[188:191], v[116:119]
	v_mfma_f32_16x16x32_bf16 v[112:115], v[184:187], v[188:191], v[112:115]
	ds_read_b128 v[188:191], v225 offset:0
	ds_read_b128 v[152:155], v227 offset:0
	s_add_u32 m0, s97, 0x0
	s_add_u32 s10, s98, 0x0
	s_addc_u32 s11, s99, 0
	global_load_lds_dwordx4 v224, s[10:11]
	v_mfma_f32_16x16x32_bf16 v[108:111], v[168:171], v[192:195], v[108:111]
	v_mfma_f32_16x16x32_bf16 v[104:107], v[176:179], v[192:195], v[104:107]
	v_mfma_f32_16x16x32_bf16 v[100:103], v[180:183], v[192:195], v[100:103]
	v_mfma_f32_16x16x32_bf16 v[96:99], v[184:187], v[192:195], v[96:99]
	ds_read_b128 v[192:195], v225 offset:2048
	ds_read_b128 v[156:159], v227 offset:2048
	s_add_u32 m0, s97, 0x10000
	s_add_u32 s10, s100, 0x0
	s_addc_u32 s11, s101, 0
	global_load_lds_dwordx4 v224, s[10:11]
	v_mfma_f32_16x16x32_bf16 v[92:95], v[168:171], v[196:199], v[92:95]
	v_mfma_f32_16x16x32_bf16 v[88:91], v[176:179], v[196:199], v[88:91]
	v_mfma_f32_16x16x32_bf16 v[84:87], v[180:183], v[196:199], v[84:87]
	v_mfma_f32_16x16x32_bf16 v[80:83], v[184:187], v[196:199], v[80:83]
	ds_read_b128 v[196:199], v225 offset:4096
	ds_read_b128 v[160:163], v227 offset:4096
	s_add_u32 m0, s97, 0x2000
	s_add_u32 s10, s98, 0x20000
	s_addc_u32 s11, s99, 0
	global_load_lds_dwordx4 v224, s[10:11]
	v_mfma_f32_16x16x32_bf16 v[76:79], v[168:171], v[200:203], v[76:79]
	v_mfma_f32_16x16x32_bf16 v[72:75], v[176:179], v[200:203], v[72:75]
	v_mfma_f32_16x16x32_bf16 v[68:71], v[180:183], v[200:203], v[68:71]
	v_mfma_f32_16x16x32_bf16 v[64:67], v[184:187], v[200:203], v[64:67]
	ds_read_b128 v[200:203], v225 offset:6144
	ds_read_b128 v[164:167], v227 offset:6144
	s_add_u32 m0, s97, 0x12000
	s_add_u32 s10, s100, 0x20000
	s_addc_u32 s11, s101, 0
	global_load_lds_dwordx4 v224, s[10:11]
	v_mfma_f32_16x16x32_bf16 v[60:63], v[168:171], v[204:207], v[60:63]
	v_mfma_f32_16x16x32_bf16 v[56:59], v[176:179], v[204:207], v[56:59]
; #define G_LOAD(KT) do { _Pragma("unroll") for (int i = 0; i < 4; ++i) { ra[i] = *(const u32x4*)(Ag + (size_t)i * 64 * lda + (KT) * 64); rb[i] = *(const u32x4*)(Bg + (size_t)i * 64 * K + (KT) * 64); } } while (0)
; #define G_STORE(BUF) do { u16* ad = As + (BUF) * 256 * 64 + sto; u16* bd = Bs + (BUF) * 256 * 64 + sto; _Pragma("unroll") for (int i = 0; i < 4; ++i) { *(u32x4*)(ad + i * 64 * 64) = ra[i]; *(u32x4*)(bd + i * 64 * 64) = rb[i]; } } while (0)
; template <int EPI>
; DI void gemm_phase(const u16* __restrict__ A, int lda, const u16* __restrict__ Bt, int K, int N, u16* outb, int ldo,
;                    const float* r0, const float* r1, float* outf, char* lds, int bid, int nb) {
;     ...
;     G_LOAD(0);
;     G_STORE(0);
;     __syncthreads();
;     for (int kt = 0; kt < nk; ++kt) {
;       const int cur = kt & 1;
;       if (kt + 1 < nk) G_LOAD(kt + 1);
;       G_MMA(cur, fo0);
;       G_MMA(cur, fo1);
;       if (kt + 1 < nk) G_STORE(cur ^ 1);
;       __syncthreads();
;     }
	v_mfma_f32_16x16x32_bf16 v[52:55], v[180:183], v[204:207], v[52:55]
	v_mfma_f32_16x16x32_bf16 v[48:51], v[184:187], v[204:207], v[48:51]
	ds_read_b128 v[204:207], v225 offset:8192
	ds_read_b128 v[216:219], v225 offset:14336
	s_add_u32 m0, s97, 0x4000
	s_add_u32 s10, s98, 0x40000
	s_addc_u32 s11, s99, 0
	global_load_lds_dwordx4 v224, s[10:11]
	v_mfma_f32_16x16x32_bf16 v[44:47], v[168:171], v[208:211], v[44:47]
	v_mfma_f32_16x16x32_bf16 v[40:43], v[176:179], v[208:211], v[40:43]
	v_mfma_f32_16x16x32_bf16 v[36:39], v[180:183], v[208:211], v[36:39]
	v_mfma_f32_16x16x32_bf16 v[32:35], v[184:187], v[208:211], v[32:35]
	ds_read_b128 v[208:211], v225 offset:10240
	s_add_u32 m0, s97, 0x14000
	s_add_u32 s10, s100, 0x40000
	s_addc_u32 s11, s101, 0
	global_load_lds_dwordx4 v224, s[10:11]
	v_mfma_f32_16x16x32_bf16 v[28:31], v[168:171], v[212:215], v[28:31]
	v_mfma_f32_16x16x32_bf16 v[24:27], v[176:179], v[212:215], v[24:27]
	v_mfma_f32_16x16x32_bf16 v[20:23], v[180:183], v[212:215], v[20:23]
	v_mfma_f32_16x16x32_bf16 v[16:19], v[184:187], v[212:215], v[16:19]
	ds_read_b128 v[212:215], v225 offset:12288
	s_add_u32 m0, s97, 0x6000
	s_add_u32 s10, s98, 0x60000
	s_addc_u32 s11, s99, 0
	global_load_lds_dwordx4 v224, s[10:11]
	v_mfma_f32_16x16x32_bf16 v[12:15], v[168:171], v[220:223], v[12:15]
	v_mfma_f32_16x16x32_bf16 v[8:11], v[176:179], v[220:223], v[8:11]
	v_mfma_f32_16x16x32_bf16 v[4:7], v[180:183], v[220:223], v[4:7]
	v_mfma_f32_16x16x32_bf16 v[0:3], v[184:187], v[220:223], v[0:3]
	s_add_u32 m0, s97, 0x16000
	s_add_u32 s10, s100, 0x60000
	s_addc_u32 s11, s101, 0
	global_load_lds_dwordx4 v224, s[10:11]
	v_xor_b32_e32 v225, 0x8000, v225
	v_xor_b32_e32 v227, 0x8000, v227
	v_xor_b32_e32 v226, 0x8000, v226
	v_xor_b32_e32 v228, 0x8000, v228
	s_xor_b32 s97, s97, 0x8000
	s_add_u32 s98, s98, 0x80
	s_addc_u32 s99, s99, 0
	s_add_u32 s100, s100, 0x80
	s_addc_u32 s101, s101, 0
	s_sub_u32 s28, s28, 1
	s_cmp_lg_u32 s28, 0
	s_cbranch_scc1 .Lgm6_loop
	s_waitcnt lgkmcnt(4)
	v_mfma_f32_16x16x32_bf16 v[124:127], v[152:155], v[188:191], v[124:127]
	v_mfma_f32_16x16x32_bf16 v[120:123], v[156:159], v[188:191], v[120:123]
	v_mfma_f32_16x16x32_bf16 v[116:119], v[160:163], v[188:191], v[116:119]
	v_mfma_f32_16x16x32_bf16 v[112:115], v[164:167], v[188:191], v[112:115]
	ds_read_b128 v[188:191], v226 offset:0
	ds_read_b128 v[168:171], v228 offset:0
	v_mfma_f32_16x16x32_bf16 v[108:111], v[152:155], v[192:195], v[108:111]
	v_mfma_f32_16x16x32_bf16 v[104:107], v[156:159], v[192:195], v[104:107]
	v_mfma_f32_16x16x32_bf16 v[100:103], v[160:163], v[192:195], v[100:103]
	v_mfma_f32_16x16x32_bf16 v[96:99], v[164:167], v[192:195], v[96:99]
	ds_read_b128 v[192:195], v226 offset:2048
	ds_read_b128 v[176:179], v228 offset:2048
	v_mfma_f32_16x16x32_bf16 v[92:95], v[152:155], v[196:199], v[92:95]
	v_mfma_f32_16x16x32_bf16 v[88:91], v[156:159], v[196:199], v[88:91]
	v_mfma_f32_16x16x32_bf16 v[84:87], v[160:163], v[196:199], v[84:87]
	v_mfma_f32_16x16x32_bf16 v[80:83], v[164:167], v[196:199], v[80:83]
	ds_read_b128 v[196:199], v226 offset:4096
	ds_read_b128 v[180:183], v228 offset:4096
	v_mfma_f32_16x16x32_bf16 v[76:79], v[152:155], v[200:203], v[76:79]
	v_mfma_f32_16x16x32_bf16 v[72:75], v[156:159], v[200:203], v[72:75]
	v_mfma_f32_16x16x32_bf16 v[68:71], v[160:163], v[200:203], v[68:71]
	v_mfma_f32_16x16x32_bf16 v[64:67], v[164:167], v[200:203], v[64:67]
	ds_read_b128 v[200:203], v226 offset:6144
	ds_read_b128 v[184:187], v228 offset:6144
	s_waitcnt lgkmcnt(11)
	v_mfma_f32_16x16x32_bf16 v[60:63], v[152:155], v[204:207], v[60:63]
	v_mfma_f32_16x16x32_bf16 v[56:59], v[156:159], v[204:207], v[56:59]
	v_mfma_f32_16x16x32_bf16 v[52:55], v[160:163], v[204:207], v[52:55]
	v_mfma_f32_16x16x32_bf16 v[48:51], v[164:167], v[204:207], v[48:51]
	ds_read_b128 v[204:207], v226 offset:8192
	ds_read_b128 v[220:223], v226 offset:14336
	s_waitcnt lgkmcnt(11)
	v_mfma_f32_16x16x32_bf16 v[44:47], v[152:155], v[208:211], v[44:47]
	v_mfma_f32_16x16x32_bf16 v[40:43], v[156:159], v[208:211], v[40:43]
	v_mfma_f32_16x16x32_bf16 v[36:39], v[160:163], v[208:211], v[36:39]
	v_mfma_f32_16x16x32_bf16 v[32:35], v[164:167], v[208:211], v[32:35]
	ds_read_b128 v[208:211], v226 offset:10240
	s_waitcnt lgkmcnt(11)
	v_mfma_f32_16x16x32_bf16 v[28:31], v[152:155], v[212:215], v[28:31]
	v_mfma_f32_16x16x32_bf16 v[24:27], v[156:159], v[212:215], v[24:27]
	v_mfma_f32_16x16x32_bf16 v[20:23], v[160:163], v[212:215], v[20:23]
	v_mfma_f32_16x16x32_bf16 v[16:19], v[164:167], v[212:215], v[16:19]
	ds_read_b128 v[212:215], v226 offset:12288
	v_mfma_f32_16x16x32_bf16 v[12:15], v[152:155], v[216:219], v[12:15]
	v_mfma_f32_16x16x32_bf16 v[8:11], v[156:159], v[216:219], v[8:11]
	v_mfma_f32_16x16x32_bf16 v[4:7], v[160:163], v[216:219], v[4:7]
	v_mfma_f32_16x16x32_bf16 v[0:3], v[164:167], v[216:219], v[0:3]
	s_waitcnt vmcnt(0) lgkmcnt(0)
	s_barrier
; #define G_LOAD(KT) do { _Pragma("unroll") for (int i = 0; i < 4; ++i) { ra[i] = *(const u32x4*)(Ag + (size_t)i * 64 * lda + (KT) * 64); rb[i] = *(const u32x4*)(Bg + (size_t)i * 64 * K + (KT) * 64); } } while (0)
; #define G_STORE(BUF) do { u16* ad = As + (BUF) * 256 * 64 + sto; u16* bd = Bs + (BUF) * 256 * 64 + sto; _Pragma("unroll") for (int i = 0; i < 4; ++i) { *(u32x4*)(ad + i * 64 * 64) = ra[i]; *(u32x4*)(bd + i * 64 * 64) = rb[i]; } } while (0)
; template <int EPI>
; DI void gemm_phase(const u16* __restrict__ A, int lda, const u16* __restrict__ Bt, int K, int N, u16* outb, int ldo,
;                    const float* r0, const float* r1, float* outf, char* lds, int bid, int nb) {
;     ...
;     for (int kt = 0; kt < nk; ++kt) {
;       const int cur = kt & 1;
;       if (kt + 1 < nk) G_LOAD(kt + 1);
;       G_MMA(cur, fo0);
;       G_MMA(cur, fo1);
;       if (kt + 1 < nk) G_STORE(cur ^ 1);
;       __syncthreads();
;     }
	v_mfma_f32_16x16x32_bf16 v[124:127], v[168:171], v[188:191], v[124:127]
	v_mfma_f32_16x16x32_bf16 v[120:123], v[176:179], v[188:191], v[120:123]
	v_mfma_f32_16x16x32_bf16 v[116:119], v[180:183], v[188:191], v[116:119]
	v_mfma_f32_16x16x32_bf16 v[112:115], v[184:187], v[188:191], v[112:115]
	ds_read_b128 v[188:191], v225 offset:0
	ds_read_b128 v[152:155], v227 offset:0
	v_mfma_f32_16x16x32_bf16 v[108:111], v[168:171], v[192:195], v[108:111]
	v_mfma_f32_16x16x32_bf16 v[104:107], v[176:179], v[192:195], v[104:107]
	v_mfma_f32_16x16x32_bf16 v[100:103], v[180:183], v[192:195], v[100:103]
	v_mfma_f32_16x16x32_bf16 v[96:99], v[184:187], v[192:195], v[96:99]
	ds_read_b128 v[192:195], v225 offset:2048
	ds_read_b128 v[156:159], v227 offset:2048
	v_mfma_f32_16x16x32_bf16 v[92:95], v[168:171], v[196:199], v[92:95]
	v_mfma_f32_16x16x32_bf16 v[88:91], v[176:179], v[196:199], v[88:91]
	v_mfma_f32_16x16x32_bf16 v[84:87], v[180:183], v[196:199], v[84:87]
	v_mfma_f32_16x16x32_bf16 v[80:83], v[184:187], v[196:199], v[80:83]
	ds_read_b128 v[196:199], v225 offset:4096
	ds_read_b128 v[160:163], v227 offset:4096
	v_mfma_f32_16x16x32_bf16 v[76:79], v[168:171], v[200:203], v[76:79]
	v_mfma_f32_16x16x32_bf16 v[72:75], v[176:179], v[200:203], v[72:75]
	v_mfma_f32_16x16x32_bf16 v[68:71], v[180:183], v[200:203], v[68:71]
	v_mfma_f32_16x16x32_bf16 v[64:67], v[184:187], v[200:203], v[64:67]
	ds_read_b128 v[200:203], v225 offset:6144
	ds_read_b128 v[164:167], v227 offset:6144
	v_mfma_f32_16x16x32_bf16 v[60:63], v[168:171], v[204:207], v[60:63]
	v_mfma_f32_16x16x32_bf16 v[56:59], v[176:179], v[204:207], v[56:59]
	v_mfma_f32_16x16x32_bf16 v[52:55], v[180:183], v[204:207], v[52:55]
	v_mfma_f32_16x16x32_bf16 v[48:51], v[184:187], v[204:207], v[48:51]
	ds_read_b128 v[204:207], v225 offset:8192
	ds_read_b128 v[216:219], v225 offset:14336
	v_mfma_f32_16x16x32_bf16 v[44:47], v[168:171], v[208:211], v[44:47]
	v_mfma_f32_16x16x32_bf16 v[40:43], v[176:179], v[208:211], v[40:43]
	v_mfma_f32_16x16x32_bf16 v[36:39], v[180:183], v[208:211], v[36:39]
	v_mfma_f32_16x16x32_bf16 v[32:35], v[184:187], v[208:211], v[32:35]
	ds_read_b128 v[208:211], v225 offset:10240
	v_mfma_f32_16x16x32_bf16 v[28:31], v[168:171], v[212:215], v[28:31]
	v_mfma_f32_16x16x32_bf16 v[24:27], v[176:179], v[212:215], v[24:27]
	v_mfma_f32_16x16x32_bf16 v[20:23], v[180:183], v[212:215], v[20:23]
	v_mfma_f32_16x16x32_bf16 v[16:19], v[184:187], v[212:215], v[16:19]
	ds_read_b128 v[212:215], v225 offset:12288
	v_mfma_f32_16x16x32_bf16 v[12:15], v[168:171], v[220:223], v[12:15]
	v_mfma_f32_16x16x32_bf16 v[8:11], v[176:179], v[220:223], v[8:11]
	v_mfma_f32_16x16x32_bf16 v[4:7], v[180:183], v[220:223], v[4:7]
	v_mfma_f32_16x16x32_bf16 v[0:3], v[184:187], v[220:223], v[0:3]
	v_xor_b32_e32 v226, 0x8000, v226
	v_xor_b32_e32 v228, 0x8000, v228
	s_waitcnt lgkmcnt(4)
	v_mfma_f32_16x16x32_bf16 v[124:127], v[152:155], v[188:191], v[124:127]
	v_mfma_f32_16x16x32_bf16 v[120:123], v[156:159], v[188:191], v[120:123]
	v_mfma_f32_16x16x32_bf16 v[116:119], v[160:163], v[188:191], v[116:119]
	v_mfma_f32_16x16x32_bf16 v[112:115], v[164:167], v[188:191], v[112:115]
	ds_read_b128 v[188:191], v226 offset:0
	ds_read_b128 v[168:171], v228 offset:0
	v_mfma_f32_16x16x32_bf16 v[108:111], v[152:155], v[192:195], v[108:111]
	v_mfma_f32_16x16x32_bf16 v[104:107], v[156:159], v[192:195], v[104:107]
	v_mfma_f32_16x16x32_bf16 v[100:103], v[160:163], v[192:195], v[100:103]
	v_mfma_f32_16x16x32_bf16 v[96:99], v[164:167], v[192:195], v[96:99]
	ds_read_b128 v[192:195], v226 offset:2048
	ds_read_b128 v[176:179], v228 offset:2048
	v_mfma_f32_16x16x32_bf16 v[92:95], v[152:155], v[196:199], v[92:95]
	v_mfma_f32_16x16x32_bf16 v[88:91], v[156:159], v[196:199], v[88:91]
	v_mfma_f32_16x16x32_bf16 v[84:87], v[160:163], v[196:199], v[84:87]
	v_mfma_f32_16x16x32_bf16 v[80:83], v[164:167], v[196:199], v[80:83]
	ds_read_b128 v[196:199], v226 offset:4096
	ds_read_b128 v[180:183], v228 offset:4096
	v_mfma_f32_16x16x32_bf16 v[76:79], v[152:155], v[200:203], v[76:79]
	v_mfma_f32_16x16x32_bf16 v[72:75], v[156:159], v[200:203], v[72:75]
	v_mfma_f32_16x16x32_bf16 v[68:71], v[160:163], v[200:203], v[68:71]
	v_mfma_f32_16x16x32_bf16 v[64:67], v[164:167], v[200:203], v[64:67]
	ds_read_b128 v[200:203], v226 offset:6144
	ds_read_b128 v[184:187], v228 offset:6144
	s_waitcnt lgkmcnt(11)
	v_mfma_f32_16x16x32_bf16 v[60:63], v[152:155], v[204:207], v[60:63]
	v_mfma_f32_16x16x32_bf16 v[56:59], v[156:159], v[204:207], v[56:59]
	v_mfma_f32_16x16x32_bf16 v[52:55], v[160:163], v[204:207], v[52:55]
	v_mfma_f32_16x16x32_bf16 v[48:51], v[164:167], v[204:207], v[48:51]
	ds_read_b128 v[204:207], v226 offset:8192
	ds_read_b128 v[220:223], v226 offset:14336
	s_waitcnt lgkmcnt(11)
	v_mfma_f32_16x16x32_bf16 v[44:47], v[152:155], v[208:211], v[44:47]
	v_mfma_f32_16x16x32_bf16 v[40:43], v[156:159], v[208:211], v[40:43]
	v_mfma_f32_16x16x32_bf16 v[36:39], v[160:163], v[208:211], v[36:39]
	v_mfma_f32_16x16x32_bf16 v[32:35], v[164:167], v[208:211], v[32:35]
	ds_read_b128 v[208:211], v226 offset:10240
	s_waitcnt lgkmcnt(11)
	v_mfma_f32_16x16x32_bf16 v[28:31], v[152:155], v[212:215], v[28:31]
	v_mfma_f32_16x16x32_bf16 v[24:27], v[156:159], v[212:215], v[24:27]
	v_mfma_f32_16x16x32_bf16 v[20:23], v[160:163], v[212:215], v[20:23]
	v_mfma_f32_16x16x32_bf16 v[16:19], v[164:167], v[212:215], v[16:19]
	ds_read_b128 v[212:215], v226 offset:12288
	v_mfma_f32_16x16x32_bf16 v[12:15], v[152:155], v[216:219], v[12:15]
	v_mfma_f32_16x16x32_bf16 v[8:11], v[156:159], v[216:219], v[8:11]
	v_mfma_f32_16x16x32_bf16 v[4:7], v[160:163], v[216:219], v[4:7]
	v_mfma_f32_16x16x32_bf16 v[0:3], v[164:167], v[216:219], v[0:3]
	s_waitcnt vmcnt(0) lgkmcnt(0)
	s_barrier
; DI u16 f2bf(float a) { return (u16)(pk2(a, 0.f) & 0xffffu); }
; DI float sigmoidf_(float x) { return __builtin_amdgcn_rcpf(1.f + __builtin_amdgcn_exp2f(-1.4426950408889634f * x)); }
; #define G_STORE(BUF) do { u16* ad = As + (BUF) * 256 * 64 + sto; u16* bd = Bs + (BUF) * 256 * 64 + sto; _Pragma("unroll") for (int i = 0; i < 4; ++i) { *(u32x4*)(ad + i * 64 * 64) = ra[i]; *(u32x4*)(bd + i * 64 * 64) = rb[i]; } } while (0)
; template <int EPI>
; DI void gemm_phase(const u16* __restrict__ A, int lda, const u16* __restrict__ Bt, int K, int N, u16* outb, int ldo,
;                    const float* r0, const float* r1, float* outf, char* lds, int bid, int nb) {
;     ...
;       G_MMA(cur, fo0);
;       G_MMA(cur, fo1);
;       if (kt + 1 < nk) G_STORE(cur ^ 1);
;       __syncthreads();
;     }
;     ...
;     } else {
;       const int col = (tn * 4 + wc) * 32 + l15;
; #pragma unroll
;       for (int i = 0; i < 8; ++i)
; #pragma unroll
;         for (int r = 0; r < 4; ++r) {
;           const float g0 = acc[i][0][r], u0 = acc[i][2][r], g1 = acc[i][1][r], u1 = acc[i][3][r];
;           u16* o0 = outb + (size_t)(mrow + i * 16 + r) * ldo + col;
;           o0[0] = f2bf(g0 * sigmoidf_(g0) * u0); o0[16] = f2bf(g1 * sigmoidf_(g1) * u1);
;         }
;     }
	v_mfma_f32_16x16x32_bf16 v[124:127], v[168:171], v[188:191], v[124:127]
	v_mfma_f32_16x16x32_bf16 v[120:123], v[176:179], v[188:191], v[120:123]
	v_mfma_f32_16x16x32_bf16 v[116:119], v[180:183], v[188:191], v[116:119]
	v_mfma_f32_16x16x32_bf16 v[112:115], v[184:187], v[188:191], v[112:115]
	v_mfma_f32_16x16x32_bf16 v[108:111], v[168:171], v[192:195], v[108:111]
	v_mfma_f32_16x16x32_bf16 v[104:107], v[176:179], v[192:195], v[104:107]
	v_mfma_f32_16x16x32_bf16 v[100:103], v[180:183], v[192:195], v[100:103]
	v_mfma_f32_16x16x32_bf16 v[96:99], v[184:187], v[192:195], v[96:99]
	v_mfma_f32_16x16x32_bf16 v[92:95], v[168:171], v[196:199], v[92:95]
	v_mfma_f32_16x16x32_bf16 v[88:91], v[176:179], v[196:199], v[88:91]
	v_mfma_f32_16x16x32_bf16 v[84:87], v[180:183], v[196:199], v[84:87]
	v_mfma_f32_16x16x32_bf16 v[80:83], v[184:187], v[196:199], v[80:83]
	v_mfma_f32_16x16x32_bf16 v[76:79], v[168:171], v[200:203], v[76:79]
	v_mfma_f32_16x16x32_bf16 v[72:75], v[176:179], v[200:203], v[72:75]
	v_mfma_f32_16x16x32_bf16 v[68:71], v[180:183], v[200:203], v[68:71]
	v_mfma_f32_16x16x32_bf16 v[64:67], v[184:187], v[200:203], v[64:67]
	v_mfma_f32_16x16x32_bf16 v[60:63], v[168:171], v[204:207], v[60:63]
	v_mfma_f32_16x16x32_bf16 v[56:59], v[176:179], v[204:207], v[56:59]
	v_mfma_f32_16x16x32_bf16 v[52:55], v[180:183], v[204:207], v[52:55]
	v_mfma_f32_16x16x32_bf16 v[48:51], v[184:187], v[204:207], v[48:51]
	v_mfma_f32_16x16x32_bf16 v[44:47], v[168:171], v[208:211], v[44:47]
	v_mfma_f32_16x16x32_bf16 v[40:43], v[176:179], v[208:211], v[40:43]
	v_mfma_f32_16x16x32_bf16 v[36:39], v[180:183], v[208:211], v[36:39]
	v_mfma_f32_16x16x32_bf16 v[32:35], v[184:187], v[208:211], v[32:35]
	v_mfma_f32_16x16x32_bf16 v[28:31], v[168:171], v[212:215], v[28:31]
	v_mfma_f32_16x16x32_bf16 v[24:27], v[176:179], v[212:215], v[24:27]
	v_mfma_f32_16x16x32_bf16 v[20:23], v[180:183], v[212:215], v[20:23]
	v_mfma_f32_16x16x32_bf16 v[16:19], v[184:187], v[212:215], v[16:19]
	v_mfma_f32_16x16x32_bf16 v[12:15], v[168:171], v[220:223], v[12:15]
	v_mfma_f32_16x16x32_bf16 v[8:11], v[176:179], v[220:223], v[8:11]
	v_mfma_f32_16x16x32_bf16 v[4:7], v[180:183], v[220:223], v[4:7]
	v_mfma_f32_16x16x32_bf16 v[0:3], v[184:187], v[220:223], v[0:3]
	s_setprio 0
	s_nop 7
	s_nop 3
	v_and_b32_e32 v225, 15, v174
	v_lshrrev_b32_e32 v226, 8, v174
	v_lshl_or_b32 v225, v226, 7, v225
	v_bfe_u32 v226, v174, 6, 2
	v_bfe_u32 v227, v174, 4, 2
	v_lshlrev_b32_e32 v227, 2, v227
	v_add_u32_e32 v225, s41, v225
	v_lshl_add_u32 v226, v226, 5, v227
	v_lshl_or_b32 v226, s40, 7, v226
	v_lshlrev_b32_e32 v226, 1, v226
	v_mov_b32_e32 v227, 0x1600
	v_mad_u32_u24 v224, v225, v227, v226
	v_mul_f32_e32 v188, 0xbfb8aa3b, v124
	v_mul_f32_e32 v189, 0xbfb8aa3b, v125
	v_mul_f32_e32 v190, 0xbfb8aa3b, v126
	v_mul_f32_e32 v191, 0xbfb8aa3b, v127
	v_exp_f32_e32 v188, v188
	v_exp_f32_e32 v189, v189
	v_exp_f32_e32 v190, v190
	v_exp_f32_e32 v191, v191
	v_add_f32_e32 v188, 1.0, v188
	v_add_f32_e32 v189, 1.0, v189
	v_add_f32_e32 v190, 1.0, v190
	v_add_f32_e32 v191, 1.0, v191
	v_rcp_f32_e32 v188, v188
	v_rcp_f32_e32 v189, v189
	v_rcp_f32_e32 v190, v190
	v_rcp_f32_e32 v191, v191
	v_mul_f32_e32 v188, v124, v188
	v_mul_f32_e32 v189, v125, v189
	v_mul_f32_e32 v190, v126, v190
	v_mul_f32_e32 v191, v127, v191
	v_mul_f32_e32 v188, v116, v188
	v_mul_f32_e32 v189, v117, v189
	v_mul_f32_e32 v190, v118, v190
	v_mul_f32_e32 v191, v119, v191
	v_cvt_pk_bf16_f32 v200, v188, v189
	v_cvt_pk_bf16_f32 v201, v190, v191
	global_store_dwordx2 v224, v[200:201], s[8:9] offset:0
	v_mul_f32_e32 v188, 0xbfb8aa3b, v120
	v_mul_f32_e32 v189, 0xbfb8aa3b, v121
	v_mul_f32_e32 v190, 0xbfb8aa3b, v122
	v_mul_f32_e32 v191, 0xbfb8aa3b, v123
	v_exp_f32_e32 v188, v188
	v_exp_f32_e32 v189, v189
	v_exp_f32_e32 v190, v190
	v_exp_f32_e32 v191, v191
	v_add_f32_e32 v188, 1.0, v188
	v_add_f32_e32 v189, 1.0, v189
	v_add_f32_e32 v190, 1.0, v190
	v_add_f32_e32 v191, 1.0, v191
	v_rcp_f32_e32 v188, v188
	v_rcp_f32_e32 v189, v189
	v_rcp_f32_e32 v190, v190
	v_rcp_f32_e32 v191, v191
	v_mul_f32_e32 v188, v120, v188
	v_mul_f32_e32 v189, v121, v189
	v_mul_f32_e32 v190, v122, v190
	v_mul_f32_e32 v191, v123, v191
	v_mul_f32_e32 v188, v112, v188
	v_mul_f32_e32 v189, v113, v189
	v_mul_f32_e32 v190, v114, v190
	v_mul_f32_e32 v191, v115, v191
	v_cvt_pk_bf16_f32 v202, v188, v189
	v_cvt_pk_bf16_f32 v203, v190, v191
	global_store_dwordx2 v224, v[202:203], s[8:9] offset:32
	v_add_u32_e32 v224, 0x16000, v224
	v_mul_f32_e32 v188, 0xbfb8aa3b, v108
	v_mul_f32_e32 v189, 0xbfb8aa3b, v109
	v_mul_f32_e32 v190, 0xbfb8aa3b, v110
	v_mul_f32_e32 v191, 0xbfb8aa3b, v111
	v_exp_f32_e32 v188, v188
	v_exp_f32_e32 v189, v189
	v_exp_f32_e32 v190, v190
	v_exp_f32_e32 v191, v191
	v_add_f32_e32 v188, 1.0, v188
	v_add_f32_e32 v189, 1.0, v189
	v_add_f32_e32 v190, 1.0, v190
	v_add_f32_e32 v191, 1.0, v191
	v_rcp_f32_e32 v188, v188
	v_rcp_f32_e32 v189, v189
	v_rcp_f32_e32 v190, v190
	v_rcp_f32_e32 v191, v191
	v_mul_f32_e32 v188, v108, v188
	v_mul_f32_e32 v189, v109, v189
	v_mul_f32_e32 v190, v110, v190
	v_mul_f32_e32 v191, v111, v191
	v_mul_f32_e32 v188, v100, v188
	v_mul_f32_e32 v189, v101, v189
	v_mul_f32_e32 v190, v102, v190
	v_mul_f32_e32 v191, v103, v191
	v_cvt_pk_bf16_f32 v204, v188, v189
	v_cvt_pk_bf16_f32 v205, v190, v191
	global_store_dwordx2 v224, v[204:205], s[8:9] offset:0
	v_mul_f32_e32 v188, 0xbfb8aa3b, v104
	v_mul_f32_e32 v189, 0xbfb8aa3b, v105
	v_mul_f32_e32 v190, 0xbfb8aa3b, v106
	v_mul_f32_e32 v191, 0xbfb8aa3b, v107
	v_exp_f32_e32 v188, v188
	v_exp_f32_e32 v189, v189
	v_exp_f32_e32 v190, v190
	v_exp_f32_e32 v191, v191
	v_add_f32_e32 v188, 1.0, v188
	v_add_f32_e32 v189, 1.0, v189
	v_add_f32_e32 v190, 1.0, v190
; DI u16 f2bf(float a) { return (u16)(pk2(a, 0.f) & 0xffffu); }
; DI float sigmoidf_(float x) { return __builtin_amdgcn_rcpf(1.f + __builtin_amdgcn_exp2f(-1.4426950408889634f * x)); }
; template <int EPI>
; DI void gemm_phase(const u16* __restrict__ A, int lda, const u16* __restrict__ Bt, int K, int N, u16* outb, int ldo,
;                    const float* r0, const float* r1, float* outf, char* lds, int bid, int nb) {
;     ...
;     } else {
;       const int col = (tn * 4 + wc) * 32 + l15;
; #pragma unroll
;       for (int i = 0; i < 8; ++i)
; #pragma unroll
;         for (int r = 0; r < 4; ++r) {
;           const float g0 = acc[i][0][r], u0 = acc[i][2][r], g1 = acc[i][1][r], u1 = acc[i][3][r];
;           u16* o0 = outb + (size_t)(mrow + i * 16 + r) * ldo + col;
;           o0[0] = f2bf(g0 * sigmoidf_(g0) * u0); o0[16] = f2bf(g1 * sigmoidf_(g1) * u1);
;         }
;     }
	v_add_f32_e32 v191, 1.0, v191
	v_rcp_f32_e32 v188, v188
	v_rcp_f32_e32 v189, v189
	v_rcp_f32_e32 v190, v190
	v_rcp_f32_e32 v191, v191
	v_mul_f32_e32 v188, v104, v188
	v_mul_f32_e32 v189, v105, v189
	v_mul_f32_e32 v190, v106, v190
	v_mul_f32_e32 v191, v107, v191
	v_mul_f32_e32 v188, v96, v188
	v_mul_f32_e32 v189, v97, v189
	v_mul_f32_e32 v190, v98, v190
	v_mul_f32_e32 v191, v99, v191
	v_cvt_pk_bf16_f32 v206, v188, v189
	v_cvt_pk_bf16_f32 v207, v190, v191
	global_store_dwordx2 v224, v[206:207], s[8:9] offset:32
	v_add_u32_e32 v224, 0x16000, v224
	v_mul_f32_e32 v188, 0xbfb8aa3b, v92
	v_mul_f32_e32 v189, 0xbfb8aa3b, v93
	v_mul_f32_e32 v190, 0xbfb8aa3b, v94
	v_mul_f32_e32 v191, 0xbfb8aa3b, v95
	v_exp_f32_e32 v188, v188
	v_exp_f32_e32 v189, v189
	v_exp_f32_e32 v190, v190
	v_exp_f32_e32 v191, v191
	v_add_f32_e32 v188, 1.0, v188
	v_add_f32_e32 v189, 1.0, v189
	v_add_f32_e32 v190, 1.0, v190
	v_add_f32_e32 v191, 1.0, v191
	v_rcp_f32_e32 v188, v188
	v_rcp_f32_e32 v189, v189
	v_rcp_f32_e32 v190, v190
	v_rcp_f32_e32 v191, v191
	v_mul_f32_e32 v188, v92, v188
	v_mul_f32_e32 v189, v93, v189
	v_mul_f32_e32 v190, v94, v190
	v_mul_f32_e32 v191, v95, v191
	v_mul_f32_e32 v188, v84, v188
	v_mul_f32_e32 v189, v85, v189
	v_mul_f32_e32 v190, v86, v190
	v_mul_f32_e32 v191, v87, v191
	v_cvt_pk_bf16_f32 v208, v188, v189
	v_cvt_pk_bf16_f32 v209, v190, v191
	global_store_dwordx2 v224, v[208:209], s[8:9] offset:0
	v_mul_f32_e32 v188, 0xbfb8aa3b, v88
	v_mul_f32_e32 v189, 0xbfb8aa3b, v89
	v_mul_f32_e32 v190, 0xbfb8aa3b, v90
	v_mul_f32_e32 v191, 0xbfb8aa3b, v91
	v_exp_f32_e32 v188, v188
	v_exp_f32_e32 v189, v189
	v_exp_f32_e32 v190, v190
	v_exp_f32_e32 v191, v191
	v_add_f32_e32 v188, 1.0, v188
	v_add_f32_e32 v189, 1.0, v189
	v_add_f32_e32 v190, 1.0, v190
	v_add_f32_e32 v191, 1.0, v191
	v_rcp_f32_e32 v188, v188
	v_rcp_f32_e32 v189, v189
	v_rcp_f32_e32 v190, v190
	v_rcp_f32_e32 v191, v191
	v_mul_f32_e32 v188, v88, v188
	v_mul_f32_e32 v189, v89, v189
	v_mul_f32_e32 v190, v90, v190
	v_mul_f32_e32 v191, v91, v191
	v_mul_f32_e32 v188, v80, v188
	v_mul_f32_e32 v189, v81, v189
	v_mul_f32_e32 v190, v82, v190
	v_mul_f32_e32 v191, v83, v191
	v_cvt_pk_bf16_f32 v210, v188, v189
	v_cvt_pk_bf16_f32 v211, v190, v191
	global_store_dwordx2 v224, v[210:211], s[8:9] offset:32
	v_add_u32_e32 v224, 0x16000, v224
	v_mul_f32_e32 v188, 0xbfb8aa3b, v76
	v_mul_f32_e32 v189, 0xbfb8aa3b, v77
	v_mul_f32_e32 v190, 0xbfb8aa3b, v78
	v_mul_f32_e32 v191, 0xbfb8aa3b, v79
	v_exp_f32_e32 v188, v188
	v_exp_f32_e32 v189, v189
	v_exp_f32_e32 v190, v190
	v_exp_f32_e32 v191, v191
	v_add_f32_e32 v188, 1.0, v188
	v_add_f32_e32 v189, 1.0, v189
	v_add_f32_e32 v190, 1.0, v190
	v_add_f32_e32 v191, 1.0, v191
	v_rcp_f32_e32 v188, v188
	v_rcp_f32_e32 v189, v189
	v_rcp_f32_e32 v190, v190
	v_rcp_f32_e32 v191, v191
	v_mul_f32_e32 v188, v76, v188
	v_mul_f32_e32 v189, v77, v189
	v_mul_f32_e32 v190, v78, v190
	v_mul_f32_e32 v191, v79, v191
	v_mul_f32_e32 v188, v68, v188
	v_mul_f32_e32 v189, v69, v189
	v_mul_f32_e32 v190, v70, v190
	v_mul_f32_e32 v191, v71, v191
	v_cvt_pk_bf16_f32 v212, v188, v189
	v_cvt_pk_bf16_f32 v213, v190, v191
	global_store_dwordx2 v224, v[212:213], s[8:9] offset:0
	v_mul_f32_e32 v188, 0xbfb8aa3b, v72
	v_mul_f32_e32 v189, 0xbfb8aa3b, v73
	v_mul_f32_e32 v190, 0xbfb8aa3b, v74
	v_mul_f32_e32 v191, 0xbfb8aa3b, v75
	v_exp_f32_e32 v188, v188
	v_exp_f32_e32 v189, v189
	v_exp_f32_e32 v190, v190
	v_exp_f32_e32 v191, v191
	v_add_f32_e32 v188, 1.0, v188
	v_add_f32_e32 v189, 1.0, v189
	v_add_f32_e32 v190, 1.0, v190
	v_add_f32_e32 v191, 1.0, v191
	v_rcp_f32_e32 v188, v188
	v_rcp_f32_e32 v189, v189
	v_rcp_f32_e32 v190, v190
	v_rcp_f32_e32 v191, v191
	v_mul_f32_e32 v188, v72, v188
	v_mul_f32_e32 v189, v73, v189
	v_mul_f32_e32 v190, v74, v190
	v_mul_f32_e32 v191, v75, v191
	v_mul_f32_e32 v188, v64, v188
	v_mul_f32_e32 v189, v65, v189
	v_mul_f32_e32 v190, v66, v190
	v_mul_f32_e32 v191, v67, v191
	v_cvt_pk_bf16_f32 v214, v188, v189
	v_cvt_pk_bf16_f32 v215, v190, v191
	global_store_dwordx2 v224, v[214:215], s[8:9] offset:32
	v_add_u32_e32 v224, 0x16000, v224
	v_mul_f32_e32 v188, 0xbfb8aa3b, v60
	v_mul_f32_e32 v189, 0xbfb8aa3b, v61
	v_mul_f32_e32 v190, 0xbfb8aa3b, v62
	v_mul_f32_e32 v191, 0xbfb8aa3b, v63
	v_exp_f32_e32 v188, v188
	v_exp_f32_e32 v189, v189
	v_exp_f32_e32 v190, v190
	v_exp_f32_e32 v191, v191
	v_add_f32_e32 v188, 1.0, v188
	v_add_f32_e32 v189, 1.0, v189
	v_add_f32_e32 v190, 1.0, v190
	v_add_f32_e32 v191, 1.0, v191
	v_rcp_f32_e32 v188, v188
	v_rcp_f32_e32 v189, v189
	v_rcp_f32_e32 v190, v190
	v_rcp_f32_e32 v191, v191
	v_mul_f32_e32 v188, v60, v188
	v_mul_f32_e32 v189, v61, v189
	v_mul_f32_e32 v190, v62, v190
	v_mul_f32_e32 v191, v63, v191
	v_mul_f32_e32 v188, v52, v188
	v_mul_f32_e32 v189, v53, v189
	v_mul_f32_e32 v190, v54, v190
	v_mul_f32_e32 v191, v55, v191
	v_cvt_pk_bf16_f32 v200, v188, v189
	v_cvt_pk_bf16_f32 v201, v190, v191
	global_store_dwordx2 v224, v[200:201], s[8:9] offset:0
	v_mul_f32_e32 v188, 0xbfb8aa3b, v56
	v_mul_f32_e32 v189, 0xbfb8aa3b, v57
	v_mul_f32_e32 v190, 0xbfb8aa3b, v58
	v_mul_f32_e32 v191, 0xbfb8aa3b, v59
	v_exp_f32_e32 v188, v188
	v_exp_f32_e32 v189, v189
	v_exp_f32_e32 v190, v190
	v_exp_f32_e32 v191, v191
	v_add_f32_e32 v188, 1.0, v188
	v_add_f32_e32 v189, 1.0, v189
	v_add_f32_e32 v190, 1.0, v190
	v_add_f32_e32 v191, 1.0, v191
	v_rcp_f32_e32 v188, v188
	v_rcp_f32_e32 v189, v189
	v_rcp_f32_e32 v190, v190
	v_rcp_f32_e32 v191, v191
	v_mul_f32_e32 v188, v56, v188
	v_mul_f32_e32 v189, v57, v189
	v_mul_f32_e32 v190, v58, v190
	v_mul_f32_e32 v191, v59, v191
	v_mul_f32_e32 v188, v48, v188
; DI u16 f2bf(float a) { return (u16)(pk2(a, 0.f) & 0xffffu); }
; DI float sigmoidf_(float x) { return __builtin_amdgcn_rcpf(1.f + __builtin_amdgcn_exp2f(-1.4426950408889634f * x)); }
; template <int EPI>
; DI void gemm_phase(const u16* __restrict__ A, int lda, const u16* __restrict__ Bt, int K, int N, u16* outb, int ldo,
;                    const float* r0, const float* r1, float* outf, char* lds, int bid, int nb) {
;     ...
;     } else {
;       const int col = (tn * 4 + wc) * 32 + l15;
; #pragma unroll
;       for (int i = 0; i < 8; ++i)
; #pragma unroll
;         for (int r = 0; r < 4; ++r) {
;           const float g0 = acc[i][0][r], u0 = acc[i][2][r], g1 = acc[i][1][r], u1 = acc[i][3][r];
;           u16* o0 = outb + (size_t)(mrow + i * 16 + r) * ldo + col;
;           o0[0] = f2bf(g0 * sigmoidf_(g0) * u0); o0[16] = f2bf(g1 * sigmoidf_(g1) * u1);
;         }
;     }
	v_mul_f32_e32 v189, v49, v189
	v_mul_f32_e32 v190, v50, v190
	v_mul_f32_e32 v191, v51, v191
	v_cvt_pk_bf16_f32 v202, v188, v189
	v_cvt_pk_bf16_f32 v203, v190, v191
	global_store_dwordx2 v224, v[202:203], s[8:9] offset:32
	v_add_u32_e32 v224, 0x16000, v224
	v_mul_f32_e32 v188, 0xbfb8aa3b, v44
	v_mul_f32_e32 v189, 0xbfb8aa3b, v45
	v_mul_f32_e32 v190, 0xbfb8aa3b, v46
	v_mul_f32_e32 v191, 0xbfb8aa3b, v47
	v_exp_f32_e32 v188, v188
	v_exp_f32_e32 v189, v189
	v_exp_f32_e32 v190, v190
	v_exp_f32_e32 v191, v191
	v_add_f32_e32 v188, 1.0, v188
	v_add_f32_e32 v189, 1.0, v189
	v_add_f32_e32 v190, 1.0, v190
	v_add_f32_e32 v191, 1.0, v191
	v_rcp_f32_e32 v188, v188
	v_rcp_f32_e32 v189, v189
	v_rcp_f32_e32 v190, v190
	v_rcp_f32_e32 v191, v191
	v_mul_f32_e32 v188, v44, v188
	v_mul_f32_e32 v189, v45, v189
	v_mul_f32_e32 v190, v46, v190
	v_mul_f32_e32 v191, v47, v191
	v_mul_f32_e32 v188, v36, v188
	v_mul_f32_e32 v189, v37, v189
	v_mul_f32_e32 v190, v38, v190
	v_mul_f32_e32 v191, v39, v191
	v_cvt_pk_bf16_f32 v204, v188, v189
	v_cvt_pk_bf16_f32 v205, v190, v191
	global_store_dwordx2 v224, v[204:205], s[8:9] offset:0
	v_mul_f32_e32 v188, 0xbfb8aa3b, v40
	v_mul_f32_e32 v189, 0xbfb8aa3b, v41
	v_mul_f32_e32 v190, 0xbfb8aa3b, v42
	v_mul_f32_e32 v191, 0xbfb8aa3b, v43
	v_exp_f32_e32 v188, v188
	v_exp_f32_e32 v189, v189
	v_exp_f32_e32 v190, v190
	v_exp_f32_e32 v191, v191
	v_add_f32_e32 v188, 1.0, v188
	v_add_f32_e32 v189, 1.0, v189
	v_add_f32_e32 v190, 1.0, v190
	v_add_f32_e32 v191, 1.0, v191
	v_rcp_f32_e32 v188, v188
	v_rcp_f32_e32 v189, v189
	v_rcp_f32_e32 v190, v190
	v_rcp_f32_e32 v191, v191
	v_mul_f32_e32 v188, v40, v188
	v_mul_f32_e32 v189, v41, v189
	v_mul_f32_e32 v190, v42, v190
	v_mul_f32_e32 v191, v43, v191
	v_mul_f32_e32 v188, v32, v188
	v_mul_f32_e32 v189, v33, v189
	v_mul_f32_e32 v190, v34, v190
	v_mul_f32_e32 v191, v35, v191
	v_cvt_pk_bf16_f32 v206, v188, v189
	v_cvt_pk_bf16_f32 v207, v190, v191
	global_store_dwordx2 v224, v[206:207], s[8:9] offset:32
	v_add_u32_e32 v224, 0x16000, v224
	v_mul_f32_e32 v188, 0xbfb8aa3b, v28
	v_mul_f32_e32 v189, 0xbfb8aa3b, v29
	v_mul_f32_e32 v190, 0xbfb8aa3b, v30
	v_mul_f32_e32 v191, 0xbfb8aa3b, v31
	v_exp_f32_e32 v188, v188
	v_exp_f32_e32 v189, v189
	v_exp_f32_e32 v190, v190
	v_exp_f32_e32 v191, v191
	v_add_f32_e32 v188, 1.0, v188
	v_add_f32_e32 v189, 1.0, v189
	v_add_f32_e32 v190, 1.0, v190
	v_add_f32_e32 v191, 1.0, v191
	v_rcp_f32_e32 v188, v188
	v_rcp_f32_e32 v189, v189
	v_rcp_f32_e32 v190, v190
	v_rcp_f32_e32 v191, v191
	v_mul_f32_e32 v188, v28, v188
	v_mul_f32_e32 v189, v29, v189
	v_mul_f32_e32 v190, v30, v190
	v_mul_f32_e32 v191, v31, v191
	v_mul_f32_e32 v188, v20, v188
	v_mul_f32_e32 v189, v21, v189
	v_mul_f32_e32 v190, v22, v190
	v_mul_f32_e32 v191, v23, v191
	v_cvt_pk_bf16_f32 v208, v188, v189
	v_cvt_pk_bf16_f32 v209, v190, v191
	global_store_dwordx2 v224, v[208:209], s[8:9] offset:0
	v_mul_f32_e32 v188, 0xbfb8aa3b, v24
	v_mul_f32_e32 v189, 0xbfb8aa3b, v25
	v_mul_f32_e32 v190, 0xbfb8aa3b, v26
	v_mul_f32_e32 v191, 0xbfb8aa3b, v27
	v_exp_f32_e32 v188, v188
	v_exp_f32_e32 v189, v189
	v_exp_f32_e32 v190, v190
	v_exp_f32_e32 v191, v191
	v_add_f32_e32 v188, 1.0, v188
	v_add_f32_e32 v189, 1.0, v189
	v_add_f32_e32 v190, 1.0, v190
	v_add_f32_e32 v191, 1.0, v191
	v_rcp_f32_e32 v188, v188
	v_rcp_f32_e32 v189, v189
	v_rcp_f32_e32 v190, v190
	v_rcp_f32_e32 v191, v191
	v_mul_f32_e32 v188, v24, v188
	v_mul_f32_e32 v189, v25, v189
	v_mul_f32_e32 v190, v26, v190
	v_mul_f32_e32 v191, v27, v191
	v_mul_f32_e32 v188, v16, v188
	v_mul_f32_e32 v189, v17, v189
	v_mul_f32_e32 v190, v18, v190
	v_mul_f32_e32 v191, v19, v191
	v_cvt_pk_bf16_f32 v210, v188, v189
	v_cvt_pk_bf16_f32 v211, v190, v191
	global_store_dwordx2 v224, v[210:211], s[8:9] offset:32
	v_add_u32_e32 v224, 0x16000, v224
	v_mul_f32_e32 v188, 0xbfb8aa3b, v12
	v_mul_f32_e32 v189, 0xbfb8aa3b, v13
	v_mul_f32_e32 v190, 0xbfb8aa3b, v14
	v_mul_f32_e32 v191, 0xbfb8aa3b, v15
	v_exp_f32_e32 v188, v188
	v_exp_f32_e32 v189, v189
	v_exp_f32_e32 v190, v190
	v_exp_f32_e32 v191, v191
	v_add_f32_e32 v188, 1.0, v188
	v_add_f32_e32 v189, 1.0, v189
	v_add_f32_e32 v190, 1.0, v190
	v_add_f32_e32 v191, 1.0, v191
	v_rcp_f32_e32 v188, v188
	v_rcp_f32_e32 v189, v189
	v_rcp_f32_e32 v190, v190
	v_rcp_f32_e32 v191, v191
	v_mul_f32_e32 v188, v12, v188
	v_mul_f32_e32 v189, v13, v189
	v_mul_f32_e32 v190, v14, v190
	v_mul_f32_e32 v191, v15, v191
	v_mul_f32_e32 v188, v4, v188
	v_mul_f32_e32 v189, v5, v189
	v_mul_f32_e32 v190, v6, v190
	v_mul_f32_e32 v191, v7, v191
	v_cvt_pk_bf16_f32 v212, v188, v189
	v_cvt_pk_bf16_f32 v213, v190, v191
	global_store_dwordx2 v224, v[212:213], s[8:9] offset:0
	v_mul_f32_e32 v188, 0xbfb8aa3b, v8
	v_mul_f32_e32 v189, 0xbfb8aa3b, v9
	v_mul_f32_e32 v190, 0xbfb8aa3b, v10
	v_mul_f32_e32 v191, 0xbfb8aa3b, v11
	v_exp_f32_e32 v188, v188
	v_exp_f32_e32 v189, v189
	v_exp_f32_e32 v190, v190
	v_exp_f32_e32 v191, v191
	v_add_f32_e32 v188, 1.0, v188
	v_add_f32_e32 v189, 1.0, v189
	v_add_f32_e32 v190, 1.0, v190
	v_add_f32_e32 v191, 1.0, v191
	v_rcp_f32_e32 v188, v188
	v_rcp_f32_e32 v189, v189
	v_rcp_f32_e32 v190, v190
	v_rcp_f32_e32 v191, v191
	v_mul_f32_e32 v188, v8, v188
	v_mul_f32_e32 v189, v9, v189
	v_mul_f32_e32 v190, v10, v190
	v_mul_f32_e32 v191, v11, v191
	v_mul_f32_e32 v188, v0, v188
	v_mul_f32_e32 v189, v1, v189
	v_mul_f32_e32 v190, v2, v190
	v_mul_f32_e32 v191, v3, v191
	v_cvt_pk_bf16_f32 v214, v188, v189
	v_cvt_pk_bf16_f32 v215, v190, v191
	global_store_dwordx2 v224, v[214:215], s[8:9] offset:32
	s_add_i32 s17, s17, 1
	s_cmp_eq_u32 s17, s3
	s_cbranch_scc0 .LBB0_1297

; #define G_LOAD(KT) do { _Pragma("unroll") for (int i = 0; i < 4; ++i) { ra[i] = *(const u32x4*)(Ag + (size_t)i * 64 * lda + (KT) * 64); rb[i] = *(const u32x4*)(Bg + (size_t)i * 64 * K + (KT) * 64); } } while (0)
; #define G_STORE(BUF) do { u16* ad = As + (BUF) * 256 * 64 + sto; u16* bd = Bs + (BUF) * 256 * 64 + sto; _Pragma("unroll") for (int i = 0; i < 4; ++i) { *(u32x4*)(ad + i * 64 * 64) = ra[i]; *(u32x4*)(bd + i * 64 * 64) = rb[i]; } } while (0)
; template <int EPI>
; DI void gemm_phase(const u16* __restrict__ A, int lda, const u16* __restrict__ Bt, int K, int N, u16* outb, int ldo,
;                    const float* r0, const float* r1, float* outf, char* lds, int bid, int nb) {
;     ...
;   for (int it = 0; it < nIter; ++it) {
;     int tm, tn;
;     if (swz) { const int st = xcd + 8 * it, sm = st / nSN, sn = st - sm * nSN; tm = sm * GM + jb / GN; tn = sn * GN + (jb % GN); }
;     else { const int t = bid + it * nb; tm = t / nN; tn = t - tm * nN; }
;     const u16* Ag = A + (size_t)(tm * 256 + lrow) * lda + lch * 8;
;     const u16* Bg = Bt + (size_t)(tn * 256 + lrow) * K + lch * 8;
;     f32x4 acc[8][4];
; #pragma unroll
;     for (int i = 0; i < 8; ++i)
; #pragma unroll
;       for (int j = 0; j < 4; ++j) acc[i][j] = (f32x4){0.f, 0.f, 0.f, 0.f};
;     u32x4 ra[4], rb[4];
;     ...
;     G_LOAD(0);
;     G_STORE(0);
;     __syncthreads();
.LBB0_1363:
	s_lshl_b32 s37, s37, 8
	v_or_b32_e32 v60, s37, v138
	s_lshl_b32 s38, s38, 8
	v_mad_i64_i32 v[0:1], s[8:9], v60, s15, v[128:129]
	v_or_b32_e32 v61, s38, v138
	v_add_co_u32_e32 v4, vcc, 0x58000, v0
	v_mad_i64_i32 v[2:3], s[8:9], v61, s15, v[130:131]
	s_nop 0
	v_addc_co_u32_e32 v5, vcc, 0, v1, vcc
	v_add_co_u32_e32 v6, vcc, 0x58000, v2
	s_nop 1
	v_readfirstlane_b32 s98, v0
	v_readfirstlane_b32 s99, v1
	s_nop 1
	v_readfirstlane_b32 s100, v2
	v_readfirstlane_b32 s101, v3
	v_addc_co_u32_e32 v7, vcc, 0, v3, vcc
	v_add_co_u32_e32 v4, vcc, 0xb0000, v0
	s_mov_b32 s39, 0
	s_nop 0
	v_addc_co_u32_e32 v5, vcc, 0, v1, vcc
	v_add_co_u32_e32 v6, vcc, 0xb0000, v2
	s_mov_b64 s[8:9], 0
	s_nop 0
	v_addc_co_u32_e32 v7, vcc, 0, v3, vcc
	v_add_co_u32_e32 v0, vcc, 0x108000, v0
	v_addc_co_u32_e32 v1, vcc, 0, v1, vcc
	v_add_co_u32_e32 v2, vcc, 0x108000, v2
	v_mad_i64_i32 v[134:135], s[28:29], v60, s15, v[132:133]
	s_nop 0
	v_addc_co_u32_e32 v3, vcc, 0, v3, vcc
	v_mov_b32_e32 v0, 0
	v_mov_b32_e32 v1, v0
	v_mov_b32_e32 v2, v0
	v_mov_b32_e32 v3, v0
	v_mov_b32_e32 v4, v0
	v_mov_b32_e32 v5, v0
	v_mov_b32_e32 v6, v0
	v_mov_b32_e32 v7, v0
	v_mov_b32_e32 v8, v0
	v_mov_b32_e32 v9, v0
	v_mov_b32_e32 v10, v0
	v_mov_b32_e32 v11, v0
	v_mov_b32_e32 v12, v0
	v_mov_b32_e32 v13, v0
	v_mov_b32_e32 v14, v0
	v_mov_b32_e32 v15, v0
	v_mov_b32_e32 v16, v0
	v_mov_b32_e32 v17, v0
	v_mov_b32_e32 v18, v0
	v_mov_b32_e32 v19, v0
	v_mov_b32_e32 v20, v0
	v_mov_b32_e32 v21, v0
	v_mov_b32_e32 v22, v0
	v_mov_b32_e32 v23, v0
	v_mov_b32_e32 v24, v0
	v_mov_b32_e32 v25, v0
	v_mov_b32_e32 v26, v0
	v_mov_b32_e32 v27, v0
	v_mad_i64_i32 v[136:137], s[28:29], v61, s15, v[132:133]
	v_mov_b32_e32 v60, v0
	v_mov_b32_e32 v61, v0
	v_mov_b32_e32 v62, v0
	v_mov_b32_e32 v63, v0
	v_mov_b32_e32 v64, v0
	v_mov_b32_e32 v65, v0
	v_mov_b32_e32 v66, v0
	v_mov_b32_e32 v67, v0
	v_mov_b32_e32 v68, v0
	v_mov_b32_e32 v69, v0
	v_mov_b32_e32 v70, v0
	v_mov_b32_e32 v71, v0
	v_mov_b32_e32 v72, v0
	v_mov_b32_e32 v73, v0
	v_mov_b32_e32 v74, v0
	v_mov_b32_e32 v75, v0
	v_mov_b32_e32 v76, v0
	v_mov_b32_e32 v77, v0
	v_mov_b32_e32 v78, v0
	v_mov_b32_e32 v79, v0
	v_mov_b32_e32 v80, v0
	v_mov_b32_e32 v81, v0
	v_mov_b32_e32 v82, v0
	v_mov_b32_e32 v83, v0
	v_mov_b32_e32 v28, v0
	v_mov_b32_e32 v29, v0
	v_mov_b32_e32 v30, v0
	v_mov_b32_e32 v31, v0
	v_mov_b32_e32 v32, v0
	v_mov_b32_e32 v33, v0
	v_mov_b32_e32 v34, v0
	v_mov_b32_e32 v35, v0
	v_mov_b32_e32 v36, v0
	v_mov_b32_e32 v37, v0
	v_mov_b32_e32 v38, v0
	v_mov_b32_e32 v39, v0
	v_mov_b32_e32 v40, v0
	v_mov_b32_e32 v41, v0
	v_mov_b32_e32 v42, v0
	v_mov_b32_e32 v43, v0
	v_mov_b32_e32 v44, v0
	v_mov_b32_e32 v45, v0
	v_mov_b32_e32 v46, v0
	v_mov_b32_e32 v47, v0
	v_mov_b32_e32 v48, v0
	v_mov_b32_e32 v49, v0
	v_mov_b32_e32 v50, v0
	v_mov_b32_e32 v51, v0
	v_mov_b32_e32 v52, v0
	v_mov_b32_e32 v53, v0
	v_mov_b32_e32 v54, v0
	v_mov_b32_e32 v55, v0
	v_mov_b32_e32 v56, v0
	v_mov_b32_e32 v57, v0
	v_mov_b32_e32 v58, v0
	v_mov_b32_e32 v59, v0
	v_mov_b32_e32 v84, v0
	v_mov_b32_e32 v85, v0
	v_mov_b32_e32 v86, v0
	v_mov_b32_e32 v87, v0
	v_mov_b32_e32 v88, v0
	v_mov_b32_e32 v89, v0
	v_mov_b32_e32 v90, v0
	v_mov_b32_e32 v91, v0
	v_mov_b32_e32 v92, v0
	v_mov_b32_e32 v93, v0
	v_mov_b32_e32 v94, v0
	v_mov_b32_e32 v95, v0
	v_mov_b32_e32 v96, v0
	v_mov_b32_e32 v97, v0
	v_mov_b32_e32 v98, v0
	v_mov_b32_e32 v99, v0
	v_mov_b32_e32 v100, v0
	v_mov_b32_e32 v101, v0
	v_mov_b32_e32 v102, v0
	v_mov_b32_e32 v103, v0
	v_mov_b32_e32 v104, v0
	v_mov_b32_e32 v105, v0
	v_mov_b32_e32 v106, v0
	v_mov_b32_e32 v107, v0
	v_mov_b32_e32 v108, v0
	v_mov_b32_e32 v109, v0
	v_mov_b32_e32 v110, v0
	v_mov_b32_e32 v111, v0
	v_mov_b32_e32 v112, v0
	v_mov_b32_e32 v113, v0
	v_mov_b32_e32 v114, v0
	v_mov_b32_e32 v115, v0
	v_mov_b32_e32 v116, v0
	v_mov_b32_e32 v117, v0
	v_mov_b32_e32 v118, v0
	v_mov_b32_e32 v119, v0
	v_mov_b32_e32 v120, v0
	v_mov_b32_e32 v121, v0
	v_mov_b32_e32 v122, v0
	v_mov_b32_e32 v123, v0
	v_mov_b32_e32 v124, v0
	v_mov_b32_e32 v125, v0
	v_mov_b32_e32 v126, v0
	v_mov_b32_e32 v127, v0
	v_and_b32_e32 v229, 63, v174
	v_lshrrev_b32_e32 v230, 3, v229
	v_mov_b32_e32 v233, 0x1600
	v_mul_u32_u24_e32 v224, v230, v233
	v_bfe_u32 v231, v174, 4, 2
	v_bfe_u32 v232, v174, 6, 1
	v_lshl_or_b32 v232, v232, 2, v231
	v_and_b32_e32 v233, 7, v174
	v_xor_b32_e32 v232, v232, v233
	v_lshl_add_u32 v224, v232, 4, v224
	v_and_b32_e32 v229, 15, v174
	v_bfe_u32 v230, v174, 1, 3
	v_xor_b32_e32 v230, v230, v231
	v_lshlrev_b32_e32 v230, 4, v230
	v_lshl_or_b32 v230, v229, 7, v230
	v_lshrrev_b32_e32 v229, 8, v174
	v_lshl_or_b32 v225, v229, 14, v230
	v_bfe_u32 v229, v174, 6, 2
	v_lshl_or_b32 v227, v229, 13, v230
	v_or_b32_e32 v227, 0x10000, v227
	v_xor_b32_e32 v226, 64, v225
	v_xor_b32_e32 v228, 64, v227
	v_readfirstlane_b32 s97, v174
	s_lshl_b32 s97, s97, 4
	s_mov_b32 s28, 42
	s_add_u32 m0, s97, 0x0
	s_add_u32 s8, s98, 0x0
	s_addc_u32 s9, s99, 0
	global_load_lds_dwordx4 v224, s[8:9]
	s_add_u32 m0, s97, 0x10000
	s_add_u32 s8, s100, 0x0
	s_addc_u32 s9, s101, 0
	global_load_lds_dwordx4 v224, s[8:9]
	s_add_u32 m0, s97, 0x2000
	s_add_u32 s8, s98, 0x58000
	s_addc_u32 s9, s99, 0
	global_load_lds_dwordx4 v224, s[8:9]
	s_add_u32 m0, s97, 0x12000
	s_add_u32 s8, s100, 0x58000
	s_addc_u32 s9, s101, 0
	global_load_lds_dwordx4 v224, s[8:9]
	s_add_u32 m0, s97, 0x4000
	s_add_u32 s8, s98, 0xb0000
	s_addc_u32 s9, s99, 0
	global_load_lds_dwordx4 v224, s[8:9]
	s_add_u32 m0, s97, 0x14000
	s_add_u32 s8, s100, 0xb0000
	s_addc_u32 s9, s101, 0
	global_load_lds_dwordx4 v224, s[8:9]
	s_add_u32 m0, s97, 0x6000
	s_add_u32 s8, s98, 0x108000
	s_addc_u32 s9, s99, 0
	global_load_lds_dwordx4 v224, s[8:9]
	s_add_u32 m0, s97, 0x16000
	s_add_u32 s8, s100, 0x108000
	s_addc_u32 s9, s101, 0
	global_load_lds_dwordx4 v224, s[8:9]
	s_add_u32 m0, s97, 0x8000
	s_add_u32 s8, s98, 0x80
	s_addc_u32 s9, s99, 0
	global_load_lds_dwordx4 v224, s[8:9]
	s_add_u32 m0, s97, 0x18000
	s_add_u32 s8, s100, 0x80
	s_addc_u32 s9, s101, 0
	global_load_lds_dwordx4 v224, s[8:9]
	s_add_u32 m0, s97, 0xa000
	s_add_u32 s8, s98, 0x58080
	s_addc_u32 s9, s99, 0
	global_load_lds_dwordx4 v224, s[8:9]
	s_add_u32 m0, s97, 0x1a000
	s_add_u32 s8, s100, 0x58080
	s_addc_u32 s9, s101, 0
	global_load_lds_dwordx4 v224, s[8:9]
	s_add_u32 m0, s97, 0xc000
	s_add_u32 s8, s98, 0xb0080
	s_addc_u32 s9, s99, 0
	global_load_lds_dwordx4 v224, s[8:9]
	s_add_u32 m0, s97, 0x1c000
	s_add_u32 s8, s100, 0xb0080
	s_addc_u32 s9, s101, 0
	global_load_lds_dwordx4 v224, s[8:9]
	s_add_u32 m0, s97, 0xe000
	s_add_u32 s8, s98, 0x108080
	s_addc_u32 s9, s99, 0
	global_load_lds_dwordx4 v224, s[8:9]
	s_add_u32 m0, s97, 0x1e000
	s_add_u32 s8, s100, 0x108080
	s_addc_u32 s9, s101, 0
	global_load_lds_dwordx4 v224, s[8:9]
	s_add_u32 s98, s98, 0x100
	s_addc_u32 s99, s99, 0
	s_add_u32 s100, s100, 0x100
	s_addc_u32 s101, s101, 0
	s_waitcnt vmcnt(8)
	s_barrier
; #define G_LOAD(KT) do { _Pragma("unroll") for (int i = 0; i < 4; ++i) { ra[i] = *(const u32x4*)(Ag + (size_t)i * 64 * lda + (KT) * 64); rb[i] = *(const u32x4*)(Bg + (size_t)i * 64 * K + (KT) * 64); } } while (0)
; #define G_STORE(BUF) do { u16* ad = As + (BUF) * 256 * 64 + sto; u16* bd = Bs + (BUF) * 256 * 64 + sto; _Pragma("unroll") for (int i = 0; i < 4; ++i) { *(u32x4*)(ad + i * 64 * 64) = ra[i]; *(u32x4*)(bd + i * 64 * 64) = rb[i]; } } while (0)
; template <int EPI>
; DI void gemm_phase(const u16* __restrict__ A, int lda, const u16* __restrict__ Bt, int K, int N, u16* outb, int ldo,
;                    const float* r0, const float* r1, float* outf, char* lds, int bid, int nb) {
;     ...
;     G_LOAD(0);
;     G_STORE(0);
;     __syncthreads();
;     for (int kt = 0; kt < nk; ++kt) {
;       const int cur = kt & 1;
;       if (kt + 1 < nk) G_LOAD(kt + 1);
;       G_MMA(cur, fo0);
;       G_MMA(cur, fo1);
;       if (kt + 1 < nk) G_STORE(cur ^ 1);
;       __syncthreads();
;     }
	ds_read_b128 v[152:155], v227 offset:0
	ds_read_b128 v[156:159], v227 offset:2048
	ds_read_b128 v[160:163], v227 offset:4096
	ds_read_b128 v[164:167], v227 offset:6144
	ds_read_b128 v[188:191], v225 offset:0
	ds_read_b128 v[192:195], v225 offset:2048
	ds_read_b128 v[196:199], v225 offset:4096
	ds_read_b128 v[200:203], v225 offset:6144
	ds_read_b128 v[204:207], v225 offset:8192
	ds_read_b128 v[208:211], v225 offset:10240
	ds_read_b128 v[212:215], v225 offset:12288
	ds_read_b128 v[216:219], v225 offset:14336
	v_xor_b32_e32 v225, 0x8000, v225
	v_xor_b32_e32 v227, 0x8000, v227
	s_waitcnt lgkmcnt(0)
	s_bitcmp1_b32 s97, 12
	s_cbranch_scc0 .Lgm7_noprio
	s_setprio 1
.Lgm7_noprio:
.Lgm7_loop:
	s_waitcnt lgkmcnt(4)
	v_mfma_f32_16x16x32_bf16 v[124:127], v[152:155], v[188:191], v[124:127]
	v_mfma_f32_16x16x32_bf16 v[120:123], v[156:159], v[188:191], v[120:123]
	v_mfma_f32_16x16x32_bf16 v[116:119], v[160:163], v[188:191], v[116:119]
	v_mfma_f32_16x16x32_bf16 v[112:115], v[164:167], v[188:191], v[112:115]
	ds_read_b128 v[188:191], v226 offset:0
	ds_read_b128 v[168:171], v228 offset:0
	v_mfma_f32_16x16x32_bf16 v[108:111], v[152:155], v[192:195], v[108:111]
	v_mfma_f32_16x16x32_bf16 v[104:107], v[156:159], v[192:195], v[104:107]
	v_mfma_f32_16x16x32_bf16 v[100:103], v[160:163], v[192:195], v[100:103]
	v_mfma_f32_16x16x32_bf16 v[96:99], v[164:167], v[192:195], v[96:99]
	ds_read_b128 v[192:195], v226 offset:2048
	ds_read_b128 v[176:179], v228 offset:2048
	v_mfma_f32_16x16x32_bf16 v[92:95], v[152:155], v[196:199], v[92:95]
	v_mfma_f32_16x16x32_bf16 v[88:91], v[156:159], v[196:199], v[88:91]
	v_mfma_f32_16x16x32_bf16 v[84:87], v[160:163], v[196:199], v[84:87]
	v_mfma_f32_16x16x32_bf16 v[80:83], v[164:167], v[196:199], v[80:83]
	ds_read_b128 v[196:199], v226 offset:4096
	ds_read_b128 v[180:183], v228 offset:4096
	v_mfma_f32_16x16x32_bf16 v[76:79], v[152:155], v[200:203], v[76:79]
	v_mfma_f32_16x16x32_bf16 v[72:75], v[156:159], v[200:203], v[72:75]
	v_mfma_f32_16x16x32_bf16 v[68:71], v[160:163], v[200:203], v[68:71]
	v_mfma_f32_16x16x32_bf16 v[64:67], v[164:167], v[200:203], v[64:67]
	ds_read_b128 v[200:203], v226 offset:6144
	ds_read_b128 v[184:187], v228 offset:6144
	s_waitcnt lgkmcnt(11)
	v_mfma_f32_16x16x32_bf16 v[60:63], v[152:155], v[204:207], v[60:63]
	v_mfma_f32_16x16x32_bf16 v[56:59], v[156:159], v[204:207], v[56:59]
	v_mfma_f32_16x16x32_bf16 v[52:55], v[160:163], v[204:207], v[52:55]
	v_mfma_f32_16x16x32_bf16 v[48:51], v[164:167], v[204:207], v[48:51]
	ds_read_b128 v[204:207], v226 offset:8192
	ds_read_b128 v[220:223], v226 offset:14336
	s_waitcnt lgkmcnt(11)
	v_mfma_f32_16x16x32_bf16 v[44:47], v[152:155], v[208:211], v[44:47]
	v_mfma_f32_16x16x32_bf16 v[40:43], v[156:159], v[208:211], v[40:43]
	v_mfma_f32_16x16x32_bf16 v[36:39], v[160:163], v[208:211], v[36:39]
	v_mfma_f32_16x16x32_bf16 v[32:35], v[164:167], v[208:211], v[32:35]
	ds_read_b128 v[208:211], v226 offset:10240
	s_waitcnt lgkmcnt(11)
	v_mfma_f32_16x16x32_bf16 v[28:31], v[152:155], v[212:215], v[28:31]
	v_mfma_f32_16x16x32_bf16 v[24:27], v[156:159], v[212:215], v[24:27]
	v_mfma_f32_16x16x32_bf16 v[20:23], v[160:163], v[212:215], v[20:23]
	v_mfma_f32_16x16x32_bf16 v[16:19], v[164:167], v[212:215], v[16:19]
	ds_read_b128 v[212:215], v226 offset:12288
	v_mfma_f32_16x16x32_bf16 v[12:15], v[152:155], v[216:219], v[12:15]
	v_mfma_f32_16x16x32_bf16 v[8:11], v[156:159], v[216:219], v[8:11]
	v_mfma_f32_16x16x32_bf16 v[4:7], v[160:163], v[216:219], v[4:7]
	v_mfma_f32_16x16x32_bf16 v[0:3], v[164:167], v[216:219], v[0:3]
	s_waitcnt vmcnt(0) lgkmcnt(0)
	s_barrier
	v_mfma_f32_16x16x32_bf16 v[124:127], v[168:171], v[188:191], v[124:127]
	v_mfma_f32_16x16x32_bf16 v[120:123], v[176:179], v[188:191], v[120:123]
	v_mfma_f32_16x16x32_bf16 v[116:119], v[180:183], v[188:191], v[116:119]
	v_mfma_f32_16x16x32_bf16 v[112:115], v[184:187], v[188:191], v[112:115]
	ds_read_b128 v[188:191], v225 offset:0
	ds_read_b128 v[152:155], v227 offset:0
	s_add_u32 m0, s97, 0x0
	s_add_u32 s8, s98, 0x0
	s_addc_u32 s9, s99, 0
	global_load_lds_dwordx4 v224, s[8:9]
	v_mfma_f32_16x16x32_bf16 v[108:111], v[168:171], v[192:195], v[108:111]
	v_mfma_f32_16x16x32_bf16 v[104:107], v[176:179], v[192:195], v[104:107]
	v_mfma_f32_16x16x32_bf16 v[100:103], v[180:183], v[192:195], v[100:103]
	v_mfma_f32_16x16x32_bf16 v[96:99], v[184:187], v[192:195], v[96:99]
	ds_read_b128 v[192:195], v225 offset:2048
	ds_read_b128 v[156:159], v227 offset:2048
	s_add_u32 m0, s97, 0x10000
	s_add_u32 s8, s100, 0x0
	s_addc_u32 s9, s101, 0
	global_load_lds_dwordx4 v224, s[8:9]
	v_mfma_f32_16x16x32_bf16 v[92:95], v[168:171], v[196:199], v[92:95]
	v_mfma_f32_16x16x32_bf16 v[88:91], v[176:179], v[196:199], v[88:91]
	v_mfma_f32_16x16x32_bf16 v[84:87], v[180:183], v[196:199], v[84:87]
	v_mfma_f32_16x16x32_bf16 v[80:83], v[184:187], v[196:199], v[80:83]
	ds_read_b128 v[196:199], v225 offset:4096
	ds_read_b128 v[160:163], v227 offset:4096
	s_add_u32 m0, s97, 0x2000
	s_add_u32 s8, s98, 0x58000
	s_addc_u32 s9, s99, 0
	global_load_lds_dwordx4 v224, s[8:9]
	v_mfma_f32_16x16x32_bf16 v[76:79], v[168:171], v[200:203], v[76:79]
	v_mfma_f32_16x16x32_bf16 v[72:75], v[176:179], v[200:203], v[72:75]
	v_mfma_f32_16x16x32_bf16 v[68:71], v[180:183], v[200:203], v[68:71]
	v_mfma_f32_16x16x32_bf16 v[64:67], v[184:187], v[200:203], v[64:67]
	ds_read_b128 v[200:203], v225 offset:6144
	ds_read_b128 v[164:167], v227 offset:6144
	s_add_u32 m0, s97, 0x12000
	s_add_u32 s8, s100, 0x58000
	s_addc_u32 s9, s101, 0
	global_load_lds_dwordx4 v224, s[8:9]
	v_mfma_f32_16x16x32_bf16 v[60:63], v[168:171], v[204:207], v[60:63]
	v_mfma_f32_16x16x32_bf16 v[56:59], v[176:179], v[204:207], v[56:59]
; #define G_LOAD(KT) do { _Pragma("unroll") for (int i = 0; i < 4; ++i) { ra[i] = *(const u32x4*)(Ag + (size_t)i * 64 * lda + (KT) * 64); rb[i] = *(const u32x4*)(Bg + (size_t)i * 64 * K + (KT) * 64); } } while (0)
; #define G_STORE(BUF) do { u16* ad = As + (BUF) * 256 * 64 + sto; u16* bd = Bs + (BUF) * 256 * 64 + sto; _Pragma("unroll") for (int i = 0; i < 4; ++i) { *(u32x4*)(ad + i * 64 * 64) = ra[i]; *(u32x4*)(bd + i * 64 * 64) = rb[i]; } } while (0)
; template <int EPI>
; DI void gemm_phase(const u16* __restrict__ A, int lda, const u16* __restrict__ Bt, int K, int N, u16* outb, int ldo,
;                    const float* r0, const float* r1, float* outf, char* lds, int bid, int nb) {
;     ...
;     G_LOAD(0);
;     G_STORE(0);
;     __syncthreads();
;     for (int kt = 0; kt < nk; ++kt) {
;       const int cur = kt & 1;
;       if (kt + 1 < nk) G_LOAD(kt + 1);
;       G_MMA(cur, fo0);
;       G_MMA(cur, fo1);
;       if (kt + 1 < nk) G_STORE(cur ^ 1);
;       __syncthreads();
;     }
	v_mfma_f32_16x16x32_bf16 v[52:55], v[180:183], v[204:207], v[52:55]
	v_mfma_f32_16x16x32_bf16 v[48:51], v[184:187], v[204:207], v[48:51]
	ds_read_b128 v[204:207], v225 offset:8192
	ds_read_b128 v[216:219], v225 offset:14336
	s_add_u32 m0, s97, 0x4000
	s_add_u32 s8, s98, 0xb0000
	s_addc_u32 s9, s99, 0
	global_load_lds_dwordx4 v224, s[8:9]
	v_mfma_f32_16x16x32_bf16 v[44:47], v[168:171], v[208:211], v[44:47]
	v_mfma_f32_16x16x32_bf16 v[40:43], v[176:179], v[208:211], v[40:43]
	v_mfma_f32_16x16x32_bf16 v[36:39], v[180:183], v[208:211], v[36:39]
	v_mfma_f32_16x16x32_bf16 v[32:35], v[184:187], v[208:211], v[32:35]
	ds_read_b128 v[208:211], v225 offset:10240
	s_add_u32 m0, s97, 0x14000
	s_add_u32 s8, s100, 0xb0000
	s_addc_u32 s9, s101, 0
	global_load_lds_dwordx4 v224, s[8:9]
	v_mfma_f32_16x16x32_bf16 v[28:31], v[168:171], v[212:215], v[28:31]
	v_mfma_f32_16x16x32_bf16 v[24:27], v[176:179], v[212:215], v[24:27]
	v_mfma_f32_16x16x32_bf16 v[20:23], v[180:183], v[212:215], v[20:23]
	v_mfma_f32_16x16x32_bf16 v[16:19], v[184:187], v[212:215], v[16:19]
	ds_read_b128 v[212:215], v225 offset:12288
	s_add_u32 m0, s97, 0x6000
	s_add_u32 s8, s98, 0x108000
	s_addc_u32 s9, s99, 0
	global_load_lds_dwordx4 v224, s[8:9]
	v_mfma_f32_16x16x32_bf16 v[12:15], v[168:171], v[220:223], v[12:15]
	v_mfma_f32_16x16x32_bf16 v[8:11], v[176:179], v[220:223], v[8:11]
	v_mfma_f32_16x16x32_bf16 v[4:7], v[180:183], v[220:223], v[4:7]
	v_mfma_f32_16x16x32_bf16 v[0:3], v[184:187], v[220:223], v[0:3]
	s_add_u32 m0, s97, 0x16000
	s_add_u32 s8, s100, 0x108000
	s_addc_u32 s9, s101, 0
	global_load_lds_dwordx4 v224, s[8:9]
	v_xor_b32_e32 v225, 0x8000, v225
	v_xor_b32_e32 v227, 0x8000, v227
	v_xor_b32_e32 v226, 0x8000, v226
	v_xor_b32_e32 v228, 0x8000, v228
	s_xor_b32 s97, s97, 0x8000
	s_add_u32 s98, s98, 0x80
	s_addc_u32 s99, s99, 0
	s_add_u32 s100, s100, 0x80
	s_addc_u32 s101, s101, 0
	s_sub_u32 s28, s28, 1
	s_cmp_lg_u32 s28, 0
	s_cbranch_scc1 .Lgm7_loop
	s_waitcnt lgkmcnt(4)
	v_mfma_f32_16x16x32_bf16 v[124:127], v[152:155], v[188:191], v[124:127]
	v_mfma_f32_16x16x32_bf16 v[120:123], v[156:159], v[188:191], v[120:123]
	v_mfma_f32_16x16x32_bf16 v[116:119], v[160:163], v[188:191], v[116:119]
	v_mfma_f32_16x16x32_bf16 v[112:115], v[164:167], v[188:191], v[112:115]
	ds_read_b128 v[188:191], v226 offset:0
	ds_read_b128 v[168:171], v228 offset:0
	v_mfma_f32_16x16x32_bf16 v[108:111], v[152:155], v[192:195], v[108:111]
	v_mfma_f32_16x16x32_bf16 v[104:107], v[156:159], v[192:195], v[104:107]
	v_mfma_f32_16x16x32_bf16 v[100:103], v[160:163], v[192:195], v[100:103]
	v_mfma_f32_16x16x32_bf16 v[96:99], v[164:167], v[192:195], v[96:99]
	ds_read_b128 v[192:195], v226 offset:2048
	ds_read_b128 v[176:179], v228 offset:2048
	v_mfma_f32_16x16x32_bf16 v[92:95], v[152:155], v[196:199], v[92:95]
	v_mfma_f32_16x16x32_bf16 v[88:91], v[156:159], v[196:199], v[88:91]
	v_mfma_f32_16x16x32_bf16 v[84:87], v[160:163], v[196:199], v[84:87]
	v_mfma_f32_16x16x32_bf16 v[80:83], v[164:167], v[196:199], v[80:83]
	ds_read_b128 v[196:199], v226 offset:4096
	ds_read_b128 v[180:183], v228 offset:4096
	v_mfma_f32_16x16x32_bf16 v[76:79], v[152:155], v[200:203], v[76:79]
	v_mfma_f32_16x16x32_bf16 v[72:75], v[156:159], v[200:203], v[72:75]
	v_mfma_f32_16x16x32_bf16 v[68:71], v[160:163], v[200:203], v[68:71]
	v_mfma_f32_16x16x32_bf16 v[64:67], v[164:167], v[200:203], v[64:67]
	ds_read_b128 v[200:203], v226 offset:6144
	ds_read_b128 v[184:187], v228 offset:6144
	s_waitcnt lgkmcnt(11)
	v_mfma_f32_16x16x32_bf16 v[60:63], v[152:155], v[204:207], v[60:63]
	v_mfma_f32_16x16x32_bf16 v[56:59], v[156:159], v[204:207], v[56:59]
	v_mfma_f32_16x16x32_bf16 v[52:55], v[160:163], v[204:207], v[52:55]
	v_mfma_f32_16x16x32_bf16 v[48:51], v[164:167], v[204:207], v[48:51]
	ds_read_b128 v[204:207], v226 offset:8192
	ds_read_b128 v[220:223], v226 offset:14336
	s_waitcnt lgkmcnt(11)
	v_mfma_f32_16x16x32_bf16 v[44:47], v[152:155], v[208:211], v[44:47]
	v_mfma_f32_16x16x32_bf16 v[40:43], v[156:159], v[208:211], v[40:43]
	v_mfma_f32_16x16x32_bf16 v[36:39], v[160:163], v[208:211], v[36:39]
	v_mfma_f32_16x16x32_bf16 v[32:35], v[164:167], v[208:211], v[32:35]
	ds_read_b128 v[208:211], v226 offset:10240
	s_waitcnt lgkmcnt(11)
	v_mfma_f32_16x16x32_bf16 v[28:31], v[152:155], v[212:215], v[28:31]
	v_mfma_f32_16x16x32_bf16 v[24:27], v[156:159], v[212:215], v[24:27]
	v_mfma_f32_16x16x32_bf16 v[20:23], v[160:163], v[212:215], v[20:23]
	v_mfma_f32_16x16x32_bf16 v[16:19], v[164:167], v[212:215], v[16:19]
	ds_read_b128 v[212:215], v226 offset:12288
	v_mfma_f32_16x16x32_bf16 v[12:15], v[152:155], v[216:219], v[12:15]
	v_mfma_f32_16x16x32_bf16 v[8:11], v[156:159], v[216:219], v[8:11]
	v_mfma_f32_16x16x32_bf16 v[4:7], v[160:163], v[216:219], v[4:7]
	v_mfma_f32_16x16x32_bf16 v[0:3], v[164:167], v[216:219], v[0:3]
	s_waitcnt vmcnt(0) lgkmcnt(0)
	s_barrier
; #define G_LOAD(KT) do { _Pragma("unroll") for (int i = 0; i < 4; ++i) { ra[i] = *(const u32x4*)(Ag + (size_t)i * 64 * lda + (KT) * 64); rb[i] = *(const u32x4*)(Bg + (size_t)i * 64 * K + (KT) * 64); } } while (0)
; #define G_STORE(BUF) do { u16* ad = As + (BUF) * 256 * 64 + sto; u16* bd = Bs + (BUF) * 256 * 64 + sto; _Pragma("unroll") for (int i = 0; i < 4; ++i) { *(u32x4*)(ad + i * 64 * 64) = ra[i]; *(u32x4*)(bd + i * 64 * 64) = rb[i]; } } while (0)
; template <int EPI>
; DI void gemm_phase(const u16* __restrict__ A, int lda, const u16* __restrict__ Bt, int K, int N, u16* outb, int ldo,
;                    const float* r0, const float* r1, float* outf, char* lds, int bid, int nb) {
;     ...
;     G_LOAD(0);
;     G_STORE(0);
;     __syncthreads();
;     for (int kt = 0; kt < nk; ++kt) {
;       const int cur = kt & 1;
;       if (kt + 1 < nk) G_LOAD(kt + 1);
;       G_MMA(cur, fo0);
;       G_MMA(cur, fo1);
;       if (kt + 1 < nk) G_STORE(cur ^ 1);
;       __syncthreads();
;     }
	v_mfma_f32_16x16x32_bf16 v[124:127], v[168:171], v[188:191], v[124:127]
	v_mfma_f32_16x16x32_bf16 v[120:123], v[176:179], v[188:191], v[120:123]
	v_mfma_f32_16x16x32_bf16 v[116:119], v[180:183], v[188:191], v[116:119]
	v_mfma_f32_16x16x32_bf16 v[112:115], v[184:187], v[188:191], v[112:115]
	ds_read_b128 v[188:191], v225 offset:0
	ds_read_b128 v[152:155], v227 offset:0
	v_mfma_f32_16x16x32_bf16 v[108:111], v[168:171], v[192:195], v[108:111]
	v_mfma_f32_16x16x32_bf16 v[104:107], v[176:179], v[192:195], v[104:107]
	v_mfma_f32_16x16x32_bf16 v[100:103], v[180:183], v[192:195], v[100:103]
	v_mfma_f32_16x16x32_bf16 v[96:99], v[184:187], v[192:195], v[96:99]
	ds_read_b128 v[192:195], v225 offset:2048
	ds_read_b128 v[156:159], v227 offset:2048
	v_mfma_f32_16x16x32_bf16 v[92:95], v[168:171], v[196:199], v[92:95]
	v_mfma_f32_16x16x32_bf16 v[88:91], v[176:179], v[196:199], v[88:91]
	v_mfma_f32_16x16x32_bf16 v[84:87], v[180:183], v[196:199], v[84:87]
	v_mfma_f32_16x16x32_bf16 v[80:83], v[184:187], v[196:199], v[80:83]
	ds_read_b128 v[196:199], v225 offset:4096
	ds_read_b128 v[160:163], v227 offset:4096
	v_mfma_f32_16x16x32_bf16 v[76:79], v[168:171], v[200:203], v[76:79]
	v_mfma_f32_16x16x32_bf16 v[72:75], v[176:179], v[200:203], v[72:75]
	v_mfma_f32_16x16x32_bf16 v[68:71], v[180:183], v[200:203], v[68:71]
	v_mfma_f32_16x16x32_bf16 v[64:67], v[184:187], v[200:203], v[64:67]
	ds_read_b128 v[200:203], v225 offset:6144
	ds_read_b128 v[164:167], v227 offset:6144
	v_mfma_f32_16x16x32_bf16 v[60:63], v[168:171], v[204:207], v[60:63]
	v_mfma_f32_16x16x32_bf16 v[56:59], v[176:179], v[204:207], v[56:59]
	v_mfma_f32_16x16x32_bf16 v[52:55], v[180:183], v[204:207], v[52:55]
	v_mfma_f32_16x16x32_bf16 v[48:51], v[184:187], v[204:207], v[48:51]
	ds_read_b128 v[204:207], v225 offset:8192
	ds_read_b128 v[216:219], v225 offset:14336
	v_mfma_f32_16x16x32_bf16 v[44:47], v[168:171], v[208:211], v[44:47]
	v_mfma_f32_16x16x32_bf16 v[40:43], v[176:179], v[208:211], v[40:43]
	v_mfma_f32_16x16x32_bf16 v[36:39], v[180:183], v[208:211], v[36:39]
	v_mfma_f32_16x16x32_bf16 v[32:35], v[184:187], v[208:211], v[32:35]
	ds_read_b128 v[208:211], v225 offset:10240
	v_mfma_f32_16x16x32_bf16 v[28:31], v[168:171], v[212:215], v[28:31]
	v_mfma_f32_16x16x32_bf16 v[24:27], v[176:179], v[212:215], v[24:27]
	v_mfma_f32_16x16x32_bf16 v[20:23], v[180:183], v[212:215], v[20:23]
	v_mfma_f32_16x16x32_bf16 v[16:19], v[184:187], v[212:215], v[16:19]
	ds_read_b128 v[212:215], v225 offset:12288
	v_mfma_f32_16x16x32_bf16 v[12:15], v[168:171], v[220:223], v[12:15]
	v_mfma_f32_16x16x32_bf16 v[8:11], v[176:179], v[220:223], v[8:11]
	v_mfma_f32_16x16x32_bf16 v[4:7], v[180:183], v[220:223], v[4:7]
	v_mfma_f32_16x16x32_bf16 v[0:3], v[184:187], v[220:223], v[0:3]
	v_xor_b32_e32 v226, 0x8000, v226
	v_xor_b32_e32 v228, 0x8000, v228
	s_waitcnt lgkmcnt(4)
	v_mfma_f32_16x16x32_bf16 v[124:127], v[152:155], v[188:191], v[124:127]
	v_mfma_f32_16x16x32_bf16 v[120:123], v[156:159], v[188:191], v[120:123]
	v_mfma_f32_16x16x32_bf16 v[116:119], v[160:163], v[188:191], v[116:119]
	v_mfma_f32_16x16x32_bf16 v[112:115], v[164:167], v[188:191], v[112:115]
	ds_read_b128 v[188:191], v226 offset:0
	ds_read_b128 v[168:171], v228 offset:0
	v_mfma_f32_16x16x32_bf16 v[108:111], v[152:155], v[192:195], v[108:111]
	v_mfma_f32_16x16x32_bf16 v[104:107], v[156:159], v[192:195], v[104:107]
	v_mfma_f32_16x16x32_bf16 v[100:103], v[160:163], v[192:195], v[100:103]
	v_mfma_f32_16x16x32_bf16 v[96:99], v[164:167], v[192:195], v[96:99]
	ds_read_b128 v[192:195], v226 offset:2048
	ds_read_b128 v[176:179], v228 offset:2048
	v_mfma_f32_16x16x32_bf16 v[92:95], v[152:155], v[196:199], v[92:95]
	v_mfma_f32_16x16x32_bf16 v[88:91], v[156:159], v[196:199], v[88:91]
	v_mfma_f32_16x16x32_bf16 v[84:87], v[160:163], v[196:199], v[84:87]
	v_mfma_f32_16x16x32_bf16 v[80:83], v[164:167], v[196:199], v[80:83]
	ds_read_b128 v[196:199], v226 offset:4096
	ds_read_b128 v[180:183], v228 offset:4096
	v_mfma_f32_16x16x32_bf16 v[76:79], v[152:155], v[200:203], v[76:79]
	v_mfma_f32_16x16x32_bf16 v[72:75], v[156:159], v[200:203], v[72:75]
	v_mfma_f32_16x16x32_bf16 v[68:71], v[160:163], v[200:203], v[68:71]
	v_mfma_f32_16x16x32_bf16 v[64:67], v[164:167], v[200:203], v[64:67]
	ds_read_b128 v[200:203], v226 offset:6144
	ds_read_b128 v[184:187], v228 offset:6144
	s_waitcnt lgkmcnt(11)
	v_mfma_f32_16x16x32_bf16 v[60:63], v[152:155], v[204:207], v[60:63]
	v_mfma_f32_16x16x32_bf16 v[56:59], v[156:159], v[204:207], v[56:59]
	v_mfma_f32_16x16x32_bf16 v[52:55], v[160:163], v[204:207], v[52:55]
	v_mfma_f32_16x16x32_bf16 v[48:51], v[164:167], v[204:207], v[48:51]
	ds_read_b128 v[204:207], v226 offset:8192
	ds_read_b128 v[220:223], v226 offset:14336
	s_waitcnt lgkmcnt(11)
	v_mfma_f32_16x16x32_bf16 v[44:47], v[152:155], v[208:211], v[44:47]
	v_mfma_f32_16x16x32_bf16 v[40:43], v[156:159], v[208:211], v[40:43]
	v_mfma_f32_16x16x32_bf16 v[36:39], v[160:163], v[208:211], v[36:39]
	v_mfma_f32_16x16x32_bf16 v[32:35], v[164:167], v[208:211], v[32:35]
	ds_read_b128 v[208:211], v226 offset:10240
	s_waitcnt lgkmcnt(11)
	v_mfma_f32_16x16x32_bf16 v[28:31], v[152:155], v[212:215], v[28:31]
	v_mfma_f32_16x16x32_bf16 v[24:27], v[156:159], v[212:215], v[24:27]
	v_mfma_f32_16x16x32_bf16 v[20:23], v[160:163], v[212:215], v[20:23]
	v_mfma_f32_16x16x32_bf16 v[16:19], v[164:167], v[212:215], v[16:19]
	ds_read_b128 v[212:215], v226 offset:12288
	v_mfma_f32_16x16x32_bf16 v[12:15], v[152:155], v[216:219], v[12:15]
	v_mfma_f32_16x16x32_bf16 v[8:11], v[156:159], v[216:219], v[8:11]
	v_mfma_f32_16x16x32_bf16 v[4:7], v[160:163], v[216:219], v[4:7]
	v_mfma_f32_16x16x32_bf16 v[0:3], v[164:167], v[216:219], v[0:3]
	s_waitcnt vmcnt(0) lgkmcnt(0)
	s_barrier
; #define G_STORE(BUF) do { u16* ad = As + (BUF) * 256 * 64 + sto; u16* bd = Bs + (BUF) * 256 * 64 + sto; _Pragma("unroll") for (int i = 0; i < 4; ++i) { *(u32x4*)(ad + i * 64 * 64) = ra[i]; *(u32x4*)(bd + i * 64 * 64) = rb[i]; } } while (0)
; template <int EPI>
; DI void gemm_phase(const u16* __restrict__ A, int lda, const u16* __restrict__ Bt, int K, int N, u16* outb, int ldo,
;                    const float* r0, const float* r1, float* outf, char* lds, int bid, int nb) {
;     ...
;       G_MMA(cur, fo0);
;       G_MMA(cur, fo1);
;       if (kt + 1 < nk) G_STORE(cur ^ 1);
;       __syncthreads();
;     ...
;     } else if constexpr (EPI == EPI_RESID) {
;       const int col = tn * 256 + wc * 64 + l15;
;       const float* rb_ = (tm * 256 < M_P) ? r0 : (r1 - (size_t)M_P * DM);
; #pragma unroll
;       for (int i = 0; i < 8; ++i)
; #pragma unroll
;         for (int r = 0; r < 4; ++r) {
;           const size_t i0 = (size_t)(mrow + i * 16 + r) * DM + col;
;           const float x0 = rb_[i0], x1 = rb_[i0 + 16], x2 = rb_[i0 + 32], x3 = rb_[i0 + 48];
;           outf[i0] = x0 + acc[i][0][r]; outf[i0 + 16] = x1 + acc[i][1][r]; outf[i0 + 32] = x2 + acc[i][2][r]; outf[i0 + 48] = x3 + acc[i][3][r];
;         }
	v_mfma_f32_16x16x32_bf16 v[124:127], v[168:171], v[188:191], v[124:127]
	v_mfma_f32_16x16x32_bf16 v[120:123], v[176:179], v[188:191], v[120:123]
	v_mfma_f32_16x16x32_bf16 v[116:119], v[180:183], v[188:191], v[116:119]
	v_mfma_f32_16x16x32_bf16 v[112:115], v[184:187], v[188:191], v[112:115]
	v_mfma_f32_16x16x32_bf16 v[108:111], v[168:171], v[192:195], v[108:111]
	v_mfma_f32_16x16x32_bf16 v[104:107], v[176:179], v[192:195], v[104:107]
	v_mfma_f32_16x16x32_bf16 v[100:103], v[180:183], v[192:195], v[100:103]
	v_mfma_f32_16x16x32_bf16 v[96:99], v[184:187], v[192:195], v[96:99]
	v_mfma_f32_16x16x32_bf16 v[92:95], v[168:171], v[196:199], v[92:95]
	v_mfma_f32_16x16x32_bf16 v[88:91], v[176:179], v[196:199], v[88:91]
	v_mfma_f32_16x16x32_bf16 v[84:87], v[180:183], v[196:199], v[84:87]
	v_mfma_f32_16x16x32_bf16 v[80:83], v[184:187], v[196:199], v[80:83]
	v_mfma_f32_16x16x32_bf16 v[76:79], v[168:171], v[200:203], v[76:79]
	v_mfma_f32_16x16x32_bf16 v[72:75], v[176:179], v[200:203], v[72:75]
	v_mfma_f32_16x16x32_bf16 v[68:71], v[180:183], v[200:203], v[68:71]
	v_mfma_f32_16x16x32_bf16 v[64:67], v[184:187], v[200:203], v[64:67]
	v_mfma_f32_16x16x32_bf16 v[60:63], v[168:171], v[204:207], v[60:63]
	v_mfma_f32_16x16x32_bf16 v[56:59], v[176:179], v[204:207], v[56:59]
	v_mfma_f32_16x16x32_bf16 v[52:55], v[180:183], v[204:207], v[52:55]
	v_mfma_f32_16x16x32_bf16 v[48:51], v[184:187], v[204:207], v[48:51]
	v_mfma_f32_16x16x32_bf16 v[44:47], v[168:171], v[208:211], v[44:47]
	v_mfma_f32_16x16x32_bf16 v[40:43], v[176:179], v[208:211], v[40:43]
	v_mfma_f32_16x16x32_bf16 v[36:39], v[180:183], v[208:211], v[36:39]
	v_mfma_f32_16x16x32_bf16 v[32:35], v[184:187], v[208:211], v[32:35]
	v_mfma_f32_16x16x32_bf16 v[28:31], v[168:171], v[212:215], v[28:31]
	v_mfma_f32_16x16x32_bf16 v[24:27], v[176:179], v[212:215], v[24:27]
	v_mfma_f32_16x16x32_bf16 v[20:23], v[180:183], v[212:215], v[20:23]
	v_mfma_f32_16x16x32_bf16 v[16:19], v[184:187], v[212:215], v[16:19]
	v_mfma_f32_16x16x32_bf16 v[12:15], v[168:171], v[220:223], v[12:15]
	v_mfma_f32_16x16x32_bf16 v[8:11], v[176:179], v[220:223], v[8:11]
	v_mfma_f32_16x16x32_bf16 v[4:7], v[180:183], v[220:223], v[4:7]
	v_mfma_f32_16x16x32_bf16 v[0:3], v[184:187], v[220:223], v[0:3]
	s_setprio 0
	s_nop 7
	s_nop 3
	v_and_b32_e32 v225, 15, v174
	v_lshrrev_b32_e32 v226, 8, v174
	v_lshl_or_b32 v225, v226, 7, v225
	v_bfe_u32 v226, v174, 6, 2
	v_bfe_u32 v227, v174, 4, 2
	v_lshlrev_b32_e32 v227, 2, v227
	v_add_u32_e32 v225, s37, v225
	v_lshl_add_u32 v226, v226, 6, v227
	v_add_u32_e32 v226, s38, v226
	v_lshlrev_b32_e32 v226, 2, v226
	v_lshl_add_u32 v224, v225, 12, v226
	v_mov_b32_e32 v229, v224
	v_add_u32_e32 v224, 0x0, v229
	global_load_dwordx4 v[152:155], v224, s[22:23] offset:0
	global_load_dwordx4 v[156:159], v224, s[22:23] offset:64
	global_load_dwordx4 v[160:163], v224, s[22:23] offset:128
	global_load_dwordx4 v[164:167], v224, s[22:23] offset:192
	v_add_u32_e32 v228, 0x10000, v229
	global_load_dwordx4 v[168:171], v228, s[22:23] offset:0
	global_load_dwordx4 v[176:179], v228, s[22:23] offset:64
	global_load_dwordx4 v[180:183], v228, s[22:23] offset:128
	global_load_dwordx4 v[184:187], v228, s[22:23] offset:192
	s_waitcnt vmcnt(4)
	v_add_f32_e32 v152, v124, v152
	v_add_f32_e32 v153, v125, v153
	v_add_f32_e32 v154, v126, v154
	v_add_f32_e32 v155, v127, v155
	v_add_f32_e32 v156, v120, v156
	v_add_f32_e32 v157, v121, v157
	v_add_f32_e32 v158, v122, v158
	v_add_f32_e32 v159, v123, v159
	v_add_f32_e32 v160, v116, v160
	v_add_f32_e32 v161, v117, v161
	v_add_f32_e32 v162, v118, v162
	v_add_f32_e32 v163, v119, v163
	v_add_f32_e32 v164, v112, v164
	v_add_f32_e32 v165, v113, v165
	v_add_f32_e32 v166, v114, v166
	v_add_f32_e32 v167, v115, v167
	global_store_dwordx4 v224, v[152:155], s[22:23] offset:0
	global_store_dwordx4 v224, v[156:159], s[22:23] offset:64
	global_store_dwordx4 v224, v[160:163], s[22:23] offset:128
	global_store_dwordx4 v224, v[164:167], s[22:23] offset:192
	s_nop 1
	v_add_u32_e32 v224, 0x20000, v229
	global_load_dwordx4 v[152:155], v224, s[22:23] offset:0
	global_load_dwordx4 v[156:159], v224, s[22:23] offset:64
	global_load_dwordx4 v[160:163], v224, s[22:23] offset:128
	global_load_dwordx4 v[164:167], v224, s[22:23] offset:192
	s_waitcnt vmcnt(8)
	v_add_f32_e32 v168, v108, v168
	v_add_f32_e32 v169, v109, v169
	v_add_f32_e32 v170, v110, v170
	v_add_f32_e32 v171, v111, v171
	v_add_f32_e32 v176, v104, v176
	v_add_f32_e32 v177, v105, v177
	v_add_f32_e32 v178, v106, v178
	v_add_f32_e32 v179, v107, v179
	v_add_f32_e32 v180, v100, v180
	v_add_f32_e32 v181, v101, v181
	v_add_f32_e32 v182, v102, v182
	v_add_f32_e32 v183, v103, v183
	v_add_f32_e32 v184, v96, v184
	v_add_f32_e32 v185, v97, v185
	v_add_f32_e32 v186, v98, v186
	v_add_f32_e32 v187, v99, v187
	global_store_dwordx4 v228, v[168:171], s[22:23] offset:0
	global_store_dwordx4 v228, v[176:179], s[22:23] offset:64
	global_store_dwordx4 v228, v[180:183], s[22:23] offset:128
	global_store_dwordx4 v228, v[184:187], s[22:23] offset:192
	s_nop 1
	v_add_u32_e32 v228, 0x30000, v229
	global_load_dwordx4 v[168:171], v228, s[22:23] offset:0
	global_load_dwordx4 v[176:179], v228, s[22:23] offset:64
	global_load_dwordx4 v[180:183], v228, s[22:23] offset:128
	global_load_dwordx4 v[184:187], v228, s[22:23] offset:192
	s_waitcnt vmcnt(8)
; template <int EPI>
; DI void gemm_phase(const u16* __restrict__ A, int lda, const u16* __restrict__ Bt, int K, int N, u16* outb, int ldo,
;                    const float* r0, const float* r1, float* outf, char* lds, int bid, int nb) {
;     ...
;       for (int i = 0; i < 8; ++i)
; #pragma unroll
;         for (int r = 0; r < 4; ++r) {
;           const size_t i0 = (size_t)(mrow + i * 16 + r) * DM + col;
;           const float x0 = rb_[i0], x1 = rb_[i0 + 16], x2 = rb_[i0 + 32], x3 = rb_[i0 + 48];
;           outf[i0] = x0 + acc[i][0][r]; outf[i0 + 16] = x1 + acc[i][1][r]; outf[i0 + 32] = x2 + acc[i][2][r]; outf[i0 + 48] = x3 + acc[i][3][r];
;         }
	v_add_f32_e32 v152, v92, v152
	v_add_f32_e32 v153, v93, v153
	v_add_f32_e32 v154, v94, v154
	v_add_f32_e32 v155, v95, v155
	v_add_f32_e32 v156, v88, v156
	v_add_f32_e32 v157, v89, v157
	v_add_f32_e32 v158, v90, v158
	v_add_f32_e32 v159, v91, v159
	v_add_f32_e32 v160, v84, v160
	v_add_f32_e32 v161, v85, v161
	v_add_f32_e32 v162, v86, v162
	v_add_f32_e32 v163, v87, v163
	v_add_f32_e32 v164, v80, v164
	v_add_f32_e32 v165, v81, v165
	v_add_f32_e32 v166, v82, v166
	v_add_f32_e32 v167, v83, v167
	global_store_dwordx4 v224, v[152:155], s[22:23] offset:0
	global_store_dwordx4 v224, v[156:159], s[22:23] offset:64
	global_store_dwordx4 v224, v[160:163], s[22:23] offset:128
	global_store_dwordx4 v224, v[164:167], s[22:23] offset:192
	s_nop 1
	v_add_u32_e32 v224, 0x40000, v229
	global_load_dwordx4 v[152:155], v224, s[22:23] offset:0
	global_load_dwordx4 v[156:159], v224, s[22:23] offset:64
	global_load_dwordx4 v[160:163], v224, s[22:23] offset:128
	global_load_dwordx4 v[164:167], v224, s[22:23] offset:192
	s_waitcnt vmcnt(8)
	v_add_f32_e32 v168, v76, v168
	v_add_f32_e32 v169, v77, v169
	v_add_f32_e32 v170, v78, v170
	v_add_f32_e32 v171, v79, v171
	v_add_f32_e32 v176, v72, v176
	v_add_f32_e32 v177, v73, v177
	v_add_f32_e32 v178, v74, v178
	v_add_f32_e32 v179, v75, v179
	v_add_f32_e32 v180, v68, v180
	v_add_f32_e32 v181, v69, v181
	v_add_f32_e32 v182, v70, v182
	v_add_f32_e32 v183, v71, v183
	v_add_f32_e32 v184, v64, v184
	v_add_f32_e32 v185, v65, v185
	v_add_f32_e32 v186, v66, v186
	v_add_f32_e32 v187, v67, v187
	global_store_dwordx4 v228, v[168:171], s[22:23] offset:0
	global_store_dwordx4 v228, v[176:179], s[22:23] offset:64
	global_store_dwordx4 v228, v[180:183], s[22:23] offset:128
	global_store_dwordx4 v228, v[184:187], s[22:23] offset:192
	s_nop 1
	v_add_u32_e32 v228, 0x50000, v229
	global_load_dwordx4 v[168:171], v228, s[22:23] offset:0
	global_load_dwordx4 v[176:179], v228, s[22:23] offset:64
	global_load_dwordx4 v[180:183], v228, s[22:23] offset:128
	global_load_dwordx4 v[184:187], v228, s[22:23] offset:192
	s_waitcnt vmcnt(8)
	v_add_f32_e32 v152, v60, v152
	v_add_f32_e32 v153, v61, v153
	v_add_f32_e32 v154, v62, v154
	v_add_f32_e32 v155, v63, v155
	v_add_f32_e32 v156, v56, v156
	v_add_f32_e32 v157, v57, v157
	v_add_f32_e32 v158, v58, v158
	v_add_f32_e32 v159, v59, v159
	v_add_f32_e32 v160, v52, v160
	v_add_f32_e32 v161, v53, v161
	v_add_f32_e32 v162, v54, v162
	v_add_f32_e32 v163, v55, v163
	v_add_f32_e32 v164, v48, v164
	v_add_f32_e32 v165, v49, v165
	v_add_f32_e32 v166, v50, v166
	v_add_f32_e32 v167, v51, v167
	global_store_dwordx4 v224, v[152:155], s[22:23] offset:0
	global_store_dwordx4 v224, v[156:159], s[22:23] offset:64
	global_store_dwordx4 v224, v[160:163], s[22:23] offset:128
	global_store_dwordx4 v224, v[164:167], s[22:23] offset:192
	s_nop 1
	v_add_u32_e32 v224, 0x60000, v229
	global_load_dwordx4 v[152:155], v224, s[22:23] offset:0
	global_load_dwordx4 v[156:159], v224, s[22:23] offset:64
	global_load_dwordx4 v[160:163], v224, s[22:23] offset:128
	global_load_dwordx4 v[164:167], v224, s[22:23] offset:192
	s_waitcnt vmcnt(8)
	v_add_f32_e32 v168, v44, v168
	v_add_f32_e32 v169, v45, v169
	v_add_f32_e32 v170, v46, v170
	v_add_f32_e32 v171, v47, v171
	v_add_f32_e32 v176, v40, v176
	v_add_f32_e32 v177, v41, v177
	v_add_f32_e32 v178, v42, v178
	v_add_f32_e32 v179, v43, v179
	v_add_f32_e32 v180, v36, v180
	v_add_f32_e32 v181, v37, v181
	v_add_f32_e32 v182, v38, v182
	v_add_f32_e32 v183, v39, v183
	v_add_f32_e32 v184, v32, v184
	v_add_f32_e32 v185, v33, v185
	v_add_f32_e32 v186, v34, v186
	v_add_f32_e32 v187, v35, v187
	global_store_dwordx4 v228, v[168:171], s[22:23] offset:0
	global_store_dwordx4 v228, v[176:179], s[22:23] offset:64
	global_store_dwordx4 v228, v[180:183], s[22:23] offset:128
	global_store_dwordx4 v228, v[184:187], s[22:23] offset:192
	s_nop 1
	v_add_u32_e32 v228, 0x70000, v229
	global_load_dwordx4 v[168:171], v228, s[22:23] offset:0
	global_load_dwordx4 v[176:179], v228, s[22:23] offset:64
	global_load_dwordx4 v[180:183], v228, s[22:23] offset:128
	global_load_dwordx4 v[184:187], v228, s[22:23] offset:192
	s_waitcnt vmcnt(8)
	v_add_f32_e32 v152, v28, v152
	v_add_f32_e32 v153, v29, v153
	v_add_f32_e32 v154, v30, v154
	v_add_f32_e32 v155, v31, v155
	v_add_f32_e32 v156, v24, v156
	v_add_f32_e32 v157, v25, v157
	v_add_f32_e32 v158, v26, v158
	v_add_f32_e32 v159, v27, v159
	v_add_f32_e32 v160, v20, v160
	v_add_f32_e32 v161, v21, v161
	v_add_f32_e32 v162, v22, v162
	v_add_f32_e32 v163, v23, v163
	v_add_f32_e32 v164, v16, v164
	v_add_f32_e32 v165, v17, v165
	v_add_f32_e32 v166, v18, v166
	v_add_f32_e32 v167, v19, v167
	global_store_dwordx4 v224, v[152:155], s[22:23] offset:0
	global_store_dwordx4 v224, v[156:159], s[22:23] offset:64
	global_store_dwordx4 v224, v[160:163], s[22:23] offset:128
	global_store_dwordx4 v224, v[164:167], s[22:23] offset:192
	s_waitcnt vmcnt(4)
	v_add_f32_e32 v168, v12, v168
	v_add_f32_e32 v169, v13, v169
	v_add_f32_e32 v170, v14, v170
	v_add_f32_e32 v171, v15, v171
	v_add_f32_e32 v176, v8, v176
	v_add_f32_e32 v177, v9, v177
	v_add_f32_e32 v178, v10, v178
	v_add_f32_e32 v179, v11, v179
	v_add_f32_e32 v180, v4, v180
	v_add_f32_e32 v181, v5, v181
	v_add_f32_e32 v182, v6, v182
	v_add_f32_e32 v183, v7, v183
	v_add_f32_e32 v184, v0, v184
	v_add_f32_e32 v185, v1, v185
	v_add_f32_e32 v186, v2, v186
	v_add_f32_e32 v187, v3, v187
	global_store_dwordx4 v228, v[168:171], s[22:23] offset:0
	global_store_dwordx4 v228, v[176:179], s[22:23] offset:64
	global_store_dwordx4 v228, v[180:183], s[22:23] offset:128
	global_store_dwordx4 v228, v[184:187], s[22:23] offset:192
	s_add_i32 s14, s14, 1
	s_cmp_eq_u32 s14, s3
	s_cbranch_scc0 .LBB0_1359
